# GEMM mainloops: LDS fragment reads double-buffered (issued one MFMA group ahead) in 5 gemm instances
# speedup vs baseline: 1.0058x; 1.0058x over previous
; #define MFMA(a, b, c) __builtin_amdgcn_mfma_f32_32x32x16_bf16((a), (b), (c), 0, 0, 0)
; #define WAIT_V(n) asm volatile("s_waitcnt vmcnt(%0)" ::"n"(n) : "memory")
; #define RAW_BARRIER() do { asm volatile("s_waitcnt lgkmcnt(0)" ::: "memory"); __builtin_amdgcn_s_barrier(); asm volatile("" ::: "memory"); } while (0)
; DI void gemm_tile(const u16* __restrict__ X, int ldx, const u16* __restrict__ Wt, int ldw, int K, char* smem,
;                   f32x16 (&acc)[2][2]) {
;     ...
;   const int nk = K / 64;
;   const u16* src[6];
; #pragma unroll
;   for (int i = 0; i < 6; ++i) {
;     const int R = 8 * (wave + 8 * i) + (lane >> 3);
;     const int c = (lane & 7) ^ ((R >> 1) & 7);
;     src[i] = (i < 4) ? (X + (size_t)R * ldx + c * 8) : (Wt + (size_t)(R - 256) * ldw + c * 8);
;   }
;     ...
;   int offA[2], offB[2], xa[2], xb[2];
; #pragma unroll
;   for (int ft = 0; ft < 2; ++ft) { const int R = 256 + fw * 64 + ft * 32 + lr; offA[ft] = R * 128; xa[ft] = (R >> 1) & 7; }
; #pragma unroll
;   for (int tt = 0; tt < 2; ++tt) { const int R = tq * 64 + tt * 32 + lr; offB[tt] = R * 128; xb[tt] = (R >> 1) & 7; }
;   GLDS_STAGE(0, 0); GLDS_STAGE(1, 1); WAIT_V(6); RAW_BARRIER();
;   int cur = 0;
;   for (int kt = 0; kt < nk; ++kt) {
;     const int nxt = (cur >= 1) ? cur - 1 : 2;
;     if (kt + 2 < nk) GLDS_STAGE(nxt, kt + 2);
;     __builtin_amdgcn_sched_barrier(0);
;     const char* st = smem + cur * G_STAGE;
; #pragma unroll
;     for (int ks = 0; ks < 4; ++ks) {
;       bf16x8 a[2], b[2];
; #pragma unroll
;       for (int ft = 0; ft < 2; ++ft) a[ft] = *reinterpret_cast<const bf16x8*>(st + offA[ft] + (((ks * 2 + lh) ^ xa[ft]) << 4));
; #pragma unroll
;       for (int tt = 0; tt < 2; ++tt) b[tt] = *reinterpret_cast<const bf16x8*>(st + offB[tt] + (((ks * 2 + lh) ^ xb[tt]) << 4));
; #pragma unroll
;       for (int ft = 0; ft < 2; ++ft)
; #pragma unroll
;         for (int tt = 0; tt < 2; ++tt) acc[ft][tt] = MFMA(a[ft], b[tt], acc[ft][tt]);
;     }
;     if (kt + 2 < nk) { WAIT_V(6); } else { WAIT_V(0); }
;     RAW_BARRIER();
; DI void phase_inproj(const Params& p, char* smem) {
;     ...
;       int u = t - n_in; int which = u >> 6; int r = u & 63; int mt = r >> 3, nt = r & 7;
;       const u16* W = (const u16*)(p.ws + (which == 0 ? OFF_WK : OFF_WV));
;       gemm_tile(memb + (size_t)mt * 256 * 1024, 1024, W + (size_t)nt * 128 * 1024, 1024, 1024, smem, acc);
.LBB0_145:
	s_bfe_u32 s8, s10, 0x30003
	s_and_b32 s9, s10, 7
	s_and_b32 s11, s10, 0x7fffffc0
	s_cmpk_lg_i32 s11, 0xd80
	s_cselect_b64 s[6:7], -1, 0
	s_cmpk_eq_i32 s11, 0xd80
	s_mov_b32 s11, 0x8ac0000
	s_cselect_b32 s11, s11, 0x8cc0000
	s_add_u32 s11, s96, s11
	s_addc_u32 s13, s97, 0
	s_lshl_b32 s9, s9, 18
	s_add_u32 s12, s11, s9
	s_addc_u32 s13, s13, 0
	s_lshl_b32 s18, s8, 19
	v_lshl_add_u64 v[0:1], v[90:91], 0, s[18:19]
	v_lshl_add_u64 v[66:67], v[0:1], 0, v[86:87]
	s_mov_b64 s[16:17], 0x40000
	v_lshl_add_u64 v[2:3], v[66:67], 0, s[16:17]
	s_mov_b64 s[16:17], 0x60000
	v_lshl_add_u64 v[4:5], v[66:67], 0, s[16:17]
	v_lshl_add_u64 v[6:7], s[12:13], 0, v[84:85]
	v_readfirstlane_b32 s17, v101
	s_mov_b64 s[14:15], 0x20000
	v_lshl_add_u64 v[64:65], v[6:7], 0, v[86:87]
	s_mov_b32 m0, s17
	v_readfirstlane_b32 s16, v211
	v_lshl_add_u64 v[0:1], v[66:67], 0, s[14:15]
	v_lshl_add_u64 v[6:7], v[64:65], 0, s[14:15]
	global_load_lds_dwordx4 v[66:67], off
	s_mov_b32 m0, s16
	v_readfirstlane_b32 s15, v214
	global_load_lds_dwordx4 v[0:1], off
	s_mov_b32 m0, s15
	v_readfirstlane_b32 s14, v215
	global_load_lds_dwordx4 v[2:3], off
	s_mov_b32 m0, s14
	v_readfirstlane_b32 s13, v216
	global_load_lds_dwordx4 v[4:5], off
	s_mov_b32 m0, s13
	v_readfirstlane_b32 s12, v217
	global_load_lds_dwordx4 v[64:65], off
	s_mov_b32 m0, s12
	s_mov_b64 s[24:25], 0x80
	v_readfirstlane_b32 s11, v103
	global_load_lds_dwordx4 v[6:7], off
	v_lshl_add_u64 v[0:1], v[66:67], 0, s[24:25]
	s_mov_b32 m0, s11
	s_mov_b64 s[30:31], 0x20080
	v_readfirstlane_b32 s9, v218
	global_load_lds_dwordx4 v[0:1], off
	v_lshl_add_u64 v[0:1], v[66:67], 0, s[30:31]
	s_mov_b32 m0, s9
	s_mov_b64 s[34:35], 0x40080
	v_readfirstlane_b32 s18, v219
	global_load_lds_dwordx4 v[0:1], off
	v_lshl_add_u64 v[0:1], v[66:67], 0, s[34:35]
	s_mov_b32 m0, s18
	s_mov_b64 s[34:35], 0x60080
	v_readfirstlane_b32 s18, v220
	global_load_lds_dwordx4 v[0:1], off
	v_lshl_add_u64 v[0:1], v[66:67], 0, s[34:35]
	s_mov_b32 m0, s18
	v_readfirstlane_b32 s18, v221
	global_load_lds_dwordx4 v[0:1], off
	v_lshl_add_u64 v[0:1], v[64:65], 0, s[24:25]
	s_mov_b32 m0, s18
	v_readfirstlane_b32 s18, v222
	global_load_lds_dwordx4 v[0:1], off
	v_lshl_add_u64 v[0:1], v[64:65], 0, s[30:31]
	s_mov_b32 m0, s18
	s_mov_b64 s[24:25], 0x100
	global_load_lds_dwordx4 v[0:1], off
	s_waitcnt vmcnt(6)
	v_readfirstlane_b32 s70, v121
	s_waitcnt lgkmcnt(0)
	s_barrier
	v_lshl_add_u64 v[0:1], v[66:67], 0, s[24:25]
	s_mov_b32 m0, s70
	s_mov_b64 s[48:49], 0x20100
	v_readfirstlane_b32 s55, v123
	global_load_lds_dwordx4 v[0:1], off
	v_lshl_add_u64 v[0:1], v[66:67], 0, s[48:49]
	s_mov_b32 m0, s55
	s_mov_b64 s[30:31], 0x40100
	v_readfirstlane_b32 s35, v125
	global_load_lds_dwordx4 v[0:1], off
	v_lshl_add_u64 v[0:1], v[66:67], 0, s[30:31]
	s_mov_b32 m0, s35
	s_mov_b64 s[30:31], 0x60100
	v_readfirstlane_b32 s54, v127
	global_load_lds_dwordx4 v[0:1], off
	v_lshl_add_u64 v[0:1], v[66:67], 0, s[30:31]
	s_mov_b32 m0, s54
	v_readfirstlane_b32 s31, v163
	global_load_lds_dwordx4 v[0:1], off
	v_lshl_add_u64 v[0:1], v[64:65], 0, s[24:25]
	s_mov_b32 m0, s31
	v_readfirstlane_b32 s34, v165
	global_load_lds_dwordx4 v[0:1], off
	v_lshl_add_u64 v[0:1], v[64:65], 0, s[48:49]
	s_mov_b32 m0, s34
	s_nop 0
	global_load_lds_dwordx4 v[0:1], off
	ds_read_b128 v[0:3], v223 offset:32768
	ds_read_b128 v[4:7], v223 offset:36864
	ds_read_b128 v[8:11], v224
	ds_read_b128 v[12:15], v224 offset:4096
	ds_read_b128 v[68:71], v225 offset:32768
	ds_read_b128 v[72:75], v225 offset:36864
	ds_read_b128 v[76:79], v226
	ds_read_b128 v[80:83], v226 offset:4096
	s_mov_b64 s[24:25], 0x180
	s_mov_b32 m0, s17
	s_waitcnt lgkmcnt(0)
	v_mfma_f32_32x32x16_bf16 v[48:63], v[0:3], v[8:11], 0
	s_mov_b64 s[48:49], 0x40180
	v_mfma_f32_32x32x16_bf16 v[16:31], v[0:3], v[12:15], 0
	v_mfma_f32_32x32x16_bf16 v[32:47], v[4:7], v[8:11], 0
	v_mfma_f32_32x32x16_bf16 v[0:15], v[4:7], v[12:15], 0
	ds_read_b128 v[184:187], v227 offset:32768
	ds_read_b128 v[188:191], v227 offset:36864
	ds_read_b128 v[192:195], v228
	ds_read_b128 v[196:199], v228 offset:4096
	s_waitcnt lgkmcnt(4)
	v_mfma_f32_32x32x16_bf16 v[48:63], v[68:71], v[76:79], v[48:63]
	v_mfma_f32_32x32x16_bf16 v[16:31], v[68:71], v[80:83], v[16:31]
	v_mfma_f32_32x32x16_bf16 v[32:47], v[72:75], v[76:79], v[32:47]
	v_mfma_f32_32x32x16_bf16 v[0:15], v[72:75], v[80:83], v[0:15]
	ds_read_b128 v[68:71], v229 offset:32768
	ds_read_b128 v[72:75], v229 offset:36864
	ds_read_b128 v[76:79], v230
	ds_read_b128 v[80:83], v230 offset:4096
	s_waitcnt lgkmcnt(4)
	v_mfma_f32_32x32x16_bf16 v[48:63], v[184:187], v[192:195], v[48:63]
	v_mfma_f32_32x32x16_bf16 v[16:31], v[184:187], v[196:199], v[16:31]
	v_mfma_f32_32x32x16_bf16 v[32:47], v[188:191], v[192:195], v[32:47]
	v_mfma_f32_32x32x16_bf16 v[0:15], v[188:191], v[196:199], v[0:15]
	s_waitcnt vmcnt(6)
	s_waitcnt lgkmcnt(0)
	s_barrier
; #define MFMA(a, b, c) __builtin_amdgcn_mfma_f32_32x32x16_bf16((a), (b), (c), 0, 0, 0)
; #define WAIT_V(n) asm volatile("s_waitcnt vmcnt(%0)" ::"n"(n) : "memory")
; #define RAW_BARRIER() do { asm volatile("s_waitcnt lgkmcnt(0)" ::: "memory"); __builtin_amdgcn_s_barrier(); asm volatile("" ::: "memory"); } while (0)
; #define GLDS_STAGE(slot, kt) do { _Pragma("unroll") for (int i = 0; i < 6; ++i) \
;     __builtin_amdgcn_global_load_lds((const unsigned*)(src[i] + (kt) * 64), (__attribute__((address_space(3))) unsigned*)(smem + (slot) * G_STAGE + (wave + 8 * i) * 1024), 16, 0, 0); } while (0)
; DI void gemm_tile(const u16* __restrict__ X, int ldx, const u16* __restrict__ Wt, int ldw, int K, char* smem,
;                   f32x16 (&acc)[2][2]) {
;     ...
;   for (int kt = 0; kt < nk; ++kt) {
;     const int nxt = (cur >= 1) ? cur - 1 : 2;
;     if (kt + 2 < nk) GLDS_STAGE(nxt, kt + 2);
;     __builtin_amdgcn_sched_barrier(0);
;     const char* st = smem + cur * G_STAGE;
; #pragma unroll
;     for (int ks = 0; ks < 4; ++ks) {
;       bf16x8 a[2], b[2];
; #pragma unroll
;       for (int ft = 0; ft < 2; ++ft) a[ft] = *reinterpret_cast<const bf16x8*>(st + offA[ft] + (((ks * 2 + lh) ^ xa[ft]) << 4));
; #pragma unroll
;       for (int tt = 0; tt < 2; ++tt) b[tt] = *reinterpret_cast<const bf16x8*>(st + offB[tt] + (((ks * 2 + lh) ^ xb[tt]) << 4));
; #pragma unroll
;       for (int ft = 0; ft < 2; ++ft)
; #pragma unroll
;         for (int tt = 0; tt < 2; ++tt) acc[ft][tt] = MFMA(a[ft], b[tt], acc[ft][tt]);
;     }
;     if (kt + 2 < nk) { WAIT_V(6); } else { WAIT_V(0); }
;     RAW_BARRIER();
;     cur = (cur == 2) ? 0 : cur + 1;
	ds_read_b128 v[184:187], v231 offset:32768
	ds_read_b128 v[188:191], v231 offset:36864
	ds_read_b128 v[192:195], v224 offset:49152
	ds_read_b128 v[196:199], v224 offset:53248
	s_waitcnt lgkmcnt(4)
	v_mfma_f32_32x32x16_bf16 v[48:63], v[68:71], v[76:79], v[48:63]
	v_mfma_f32_32x32x16_bf16 v[16:31], v[68:71], v[80:83], v[16:31]
	v_lshl_add_u64 v[68:69], v[66:67], 0, s[24:25]
	global_load_lds_dwordx4 v[68:69], off
	v_lshl_add_u64 v[68:69], v[66:67], 0, s[50:51]
	s_mov_b32 m0, s16
	s_nop 0
	global_load_lds_dwordx4 v[68:69], off
	v_lshl_add_u64 v[68:69], v[66:67], 0, s[48:49]
	s_mov_b32 m0, s15
	s_mov_b64 s[48:49], 0x60180
	global_load_lds_dwordx4 v[68:69], off
	v_lshl_add_u64 v[68:69], v[66:67], 0, s[48:49]
	s_mov_b32 m0, s14
	v_mfma_f32_32x32x16_bf16 v[32:47], v[72:75], v[76:79], v[32:47]
	global_load_lds_dwordx4 v[68:69], off
	v_lshl_add_u64 v[68:69], v[64:65], 0, s[24:25]
	s_mov_b32 m0, s13
	s_nop 0
	global_load_lds_dwordx4 v[68:69], off
	v_lshl_add_u64 v[68:69], v[64:65], 0, s[50:51]
	s_mov_b32 m0, s12
	v_mfma_f32_32x32x16_bf16 v[0:15], v[72:75], v[80:83], v[0:15]
	global_load_lds_dwordx4 v[68:69], off
	s_mov_b32 m0, s11
	s_mov_b64 s[24:25], 0x40200
	v_readfirstlane_b32 s18, v173
	ds_read_b128 v[68:71], v232 offset:32768
	ds_read_b128 v[72:75], v232 offset:36864
	ds_read_b128 v[76:79], v226 offset:49152
	ds_read_b128 v[80:83], v226 offset:53248
	s_waitcnt lgkmcnt(4)
	v_mfma_f32_32x32x16_bf16 v[48:63], v[184:187], v[192:195], v[48:63]
	v_readfirstlane_b32 s30, v202
	v_mfma_f32_32x32x16_bf16 v[16:31], v[184:187], v[196:199], v[16:31]
	v_mfma_f32_32x32x16_bf16 v[32:47], v[188:191], v[192:195], v[32:47]
	v_mfma_f32_32x32x16_bf16 v[0:15], v[188:191], v[196:199], v[0:15]
	ds_read_b128 v[184:187], v233 offset:32768
	ds_read_b128 v[188:191], v233 offset:36864
	ds_read_b128 v[192:195], v228 offset:49152
	ds_read_b128 v[196:199], v228 offset:53248
	s_waitcnt lgkmcnt(4)
	v_mfma_f32_32x32x16_bf16 v[48:63], v[68:71], v[76:79], v[48:63]
	v_mfma_f32_32x32x16_bf16 v[16:31], v[68:71], v[80:83], v[16:31]
	v_mfma_f32_32x32x16_bf16 v[32:47], v[72:75], v[76:79], v[32:47]
	v_mfma_f32_32x32x16_bf16 v[0:15], v[72:75], v[80:83], v[0:15]
	ds_read_b128 v[68:71], v234 offset:32768
	ds_read_b128 v[72:75], v234 offset:36864
	ds_read_b128 v[76:79], v230 offset:49152
	ds_read_b128 v[80:83], v230 offset:53248
	s_waitcnt lgkmcnt(4)
	v_mfma_f32_32x32x16_bf16 v[48:63], v[184:187], v[192:195], v[48:63]
	v_mfma_f32_32x32x16_bf16 v[16:31], v[184:187], v[196:199], v[16:31]
	v_mfma_f32_32x32x16_bf16 v[32:47], v[188:191], v[192:195], v[32:47]
	v_mfma_f32_32x32x16_bf16 v[0:15], v[188:191], v[196:199], v[0:15]
	s_waitcnt vmcnt(6)
	s_waitcnt lgkmcnt(0)
	s_barrier
	ds_read_b128 v[184:187], v235 offset:32768
	ds_read_b128 v[188:191], v235 offset:36864
	ds_read_b128 v[192:195], v236
	ds_read_b128 v[196:199], v236 offset:4096
	s_waitcnt lgkmcnt(4)
	v_mfma_f32_32x32x16_bf16 v[48:63], v[68:71], v[76:79], v[48:63]
	v_mfma_f32_32x32x16_bf16 v[16:31], v[68:71], v[80:83], v[16:31]
	v_lshl_add_u64 v[68:69], v[66:67], 0, s[58:59]
	global_load_lds_dwordx4 v[68:69], off
	v_lshl_add_u64 v[68:69], v[66:67], 0, s[60:61]
	s_mov_b32 m0, s9
	s_nop 0
	global_load_lds_dwordx4 v[68:69], off
	v_lshl_add_u64 v[68:69], v[66:67], 0, s[24:25]
	s_mov_b32 m0, s18
	s_mov_b64 s[24:25], 0x60200
	global_load_lds_dwordx4 v[68:69], off
	v_lshl_add_u64 v[68:69], v[66:67], 0, s[24:25]
	v_readfirstlane_b32 s25, v200
	s_mov_b32 m0, s25
	v_readfirstlane_b32 s24, v201
	global_load_lds_dwordx4 v[68:69], off
	v_lshl_add_u64 v[68:69], v[64:65], 0, s[58:59]
	s_mov_b32 m0, s24
	v_mfma_f32_32x32x16_bf16 v[32:47], v[72:75], v[76:79], v[32:47]
	global_load_lds_dwordx4 v[68:69], off
	v_lshl_add_u64 v[68:69], v[64:65], 0, s[60:61]
	s_mov_b32 m0, s30
	s_nop 0
	global_load_lds_dwordx4 v[68:69], off
	v_mfma_f32_32x32x16_bf16 v[0:15], v[72:75], v[80:83], v[0:15]
	s_mov_b32 m0, s70
	s_mov_b64 s[48:49], 0x40280
	ds_read_b128 v[68:71], v237 offset:32768
	ds_read_b128 v[72:75], v237 offset:36864
	ds_read_b128 v[76:79], v238
	ds_read_b128 v[80:83], v238 offset:4096
	s_waitcnt lgkmcnt(4)
	v_mfma_f32_32x32x16_bf16 v[48:63], v[184:187], v[192:195], v[48:63]
	v_mfma_f32_32x32x16_bf16 v[16:31], v[184:187], v[196:199], v[16:31]
	v_mfma_f32_32x32x16_bf16 v[32:47], v[188:191], v[192:195], v[32:47]
	v_mfma_f32_32x32x16_bf16 v[0:15], v[188:191], v[196:199], v[0:15]
	ds_read_b128 v[184:187], v239 offset:32768
	ds_read_b128 v[188:191], v239 offset:36864
	ds_read_b128 v[192:195], v240
	ds_read_b128 v[196:199], v240 offset:4096
	s_waitcnt lgkmcnt(4)
	v_mfma_f32_32x32x16_bf16 v[48:63], v[68:71], v[76:79], v[48:63]
	v_mfma_f32_32x32x16_bf16 v[16:31], v[68:71], v[80:83], v[16:31]
	v_mfma_f32_32x32x16_bf16 v[32:47], v[72:75], v[76:79], v[32:47]
	v_mfma_f32_32x32x16_bf16 v[0:15], v[72:75], v[80:83], v[0:15]
	ds_read_b128 v[68:71], v241 offset:32768
	ds_read_b128 v[72:75], v241 offset:36864
	ds_read_b128 v[76:79], v242
	ds_read_b128 v[80:83], v242 offset:4096
	s_waitcnt lgkmcnt(4)
	v_mfma_f32_32x32x16_bf16 v[48:63], v[184:187], v[192:195], v[48:63]
	v_mfma_f32_32x32x16_bf16 v[16:31], v[184:187], v[196:199], v[16:31]
	v_mfma_f32_32x32x16_bf16 v[32:47], v[188:191], v[192:195], v[32:47]
	v_mfma_f32_32x32x16_bf16 v[0:15], v[188:191], v[196:199], v[0:15]
	s_waitcnt vmcnt(6)
	s_waitcnt lgkmcnt(0)
	s_barrier
; #define MFMA(a, b, c) __builtin_amdgcn_mfma_f32_32x32x16_bf16((a), (b), (c), 0, 0, 0)
; #define WAIT_V(n) asm volatile("s_waitcnt vmcnt(%0)" ::"n"(n) : "memory")
; #define RAW_BARRIER() do { asm volatile("s_waitcnt lgkmcnt(0)" ::: "memory"); __builtin_amdgcn_s_barrier(); asm volatile("" ::: "memory"); } while (0)
; #define GLDS_STAGE(slot, kt) do { _Pragma("unroll") for (int i = 0; i < 6; ++i) \
;     __builtin_amdgcn_global_load_lds((const unsigned*)(src[i] + (kt) * 64), (__attribute__((address_space(3))) unsigned*)(smem + (slot) * G_STAGE + (wave + 8 * i) * 1024), 16, 0, 0); } while (0)
; DI void gemm_tile(const u16* __restrict__ X, int ldx, const u16* __restrict__ Wt, int ldw, int K, char* smem,
;                   f32x16 (&acc)[2][2]) {
;     ...
;   for (int kt = 0; kt < nk; ++kt) {
;     const int nxt = (cur >= 1) ? cur - 1 : 2;
;     if (kt + 2 < nk) GLDS_STAGE(nxt, kt + 2);
;     __builtin_amdgcn_sched_barrier(0);
;     const char* st = smem + cur * G_STAGE;
; #pragma unroll
;     for (int ks = 0; ks < 4; ++ks) {
;       bf16x8 a[2], b[2];
; #pragma unroll
;       for (int ft = 0; ft < 2; ++ft) a[ft] = *reinterpret_cast<const bf16x8*>(st + offA[ft] + (((ks * 2 + lh) ^ xa[ft]) << 4));
; #pragma unroll
;       for (int tt = 0; tt < 2; ++tt) b[tt] = *reinterpret_cast<const bf16x8*>(st + offB[tt] + (((ks * 2 + lh) ^ xb[tt]) << 4));
; #pragma unroll
;       for (int ft = 0; ft < 2; ++ft)
; #pragma unroll
;         for (int tt = 0; tt < 2; ++tt) acc[ft][tt] = MFMA(a[ft], b[tt], acc[ft][tt]);
;     }
;     if (kt + 2 < nk) { WAIT_V(6); } else { WAIT_V(0); }
;     RAW_BARRIER();
;     cur = (cur == 2) ? 0 : cur + 1;
	ds_read_b128 v[184:187], v223 offset:32768
	ds_read_b128 v[188:191], v223 offset:36864
	ds_read_b128 v[192:195], v224
	ds_read_b128 v[196:199], v224 offset:4096
	s_waitcnt lgkmcnt(4)
	v_mfma_f32_32x32x16_bf16 v[48:63], v[68:71], v[76:79], v[48:63]
	v_mfma_f32_32x32x16_bf16 v[16:31], v[68:71], v[80:83], v[16:31]
	v_lshl_add_u64 v[68:69], v[66:67], 0, s[66:67]
	global_load_lds_dwordx4 v[68:69], off
	v_lshl_add_u64 v[68:69], v[66:67], 0, s[68:69]
	s_mov_b32 m0, s55
	s_nop 0
	global_load_lds_dwordx4 v[68:69], off
	v_lshl_add_u64 v[68:69], v[66:67], 0, s[48:49]
	s_mov_b32 m0, s35
	s_mov_b64 s[48:49], 0x60280
	global_load_lds_dwordx4 v[68:69], off
	v_lshl_add_u64 v[68:69], v[66:67], 0, s[48:49]
	s_mov_b32 m0, s54
	v_mfma_f32_32x32x16_bf16 v[32:47], v[72:75], v[76:79], v[32:47]
	global_load_lds_dwordx4 v[68:69], off
	v_lshl_add_u64 v[68:69], v[64:65], 0, s[66:67]
	s_mov_b32 m0, s31
	s_nop 0
	global_load_lds_dwordx4 v[68:69], off
	v_lshl_add_u64 v[68:69], v[64:65], 0, s[68:69]
	s_mov_b32 m0, s34
	v_mfma_f32_32x32x16_bf16 v[0:15], v[72:75], v[80:83], v[0:15]
	global_load_lds_dwordx4 v[68:69], off
	s_mov_b32 m0, s17
	s_mov_b64 s[48:49], 0x40300
	ds_read_b128 v[68:71], v225 offset:32768
	ds_read_b128 v[72:75], v225 offset:36864
	ds_read_b128 v[76:79], v226
	ds_read_b128 v[80:83], v226 offset:4096
	s_waitcnt lgkmcnt(4)
	v_mfma_f32_32x32x16_bf16 v[48:63], v[184:187], v[192:195], v[48:63]
	v_mfma_f32_32x32x16_bf16 v[16:31], v[184:187], v[196:199], v[16:31]
	v_mfma_f32_32x32x16_bf16 v[32:47], v[188:191], v[192:195], v[32:47]
	v_mfma_f32_32x32x16_bf16 v[0:15], v[188:191], v[196:199], v[0:15]
	ds_read_b128 v[184:187], v227 offset:32768
	ds_read_b128 v[188:191], v227 offset:36864
	ds_read_b128 v[192:195], v228
	ds_read_b128 v[196:199], v228 offset:4096
	s_waitcnt lgkmcnt(4)
	v_mfma_f32_32x32x16_bf16 v[48:63], v[68:71], v[76:79], v[48:63]
	v_mfma_f32_32x32x16_bf16 v[16:31], v[68:71], v[80:83], v[16:31]
	v_mfma_f32_32x32x16_bf16 v[32:47], v[72:75], v[76:79], v[32:47]
	v_mfma_f32_32x32x16_bf16 v[0:15], v[72:75], v[80:83], v[0:15]
	ds_read_b128 v[68:71], v229 offset:32768
	ds_read_b128 v[72:75], v229 offset:36864
	ds_read_b128 v[76:79], v230
	ds_read_b128 v[80:83], v230 offset:4096
	s_waitcnt lgkmcnt(4)
	v_mfma_f32_32x32x16_bf16 v[48:63], v[184:187], v[192:195], v[48:63]
	v_mfma_f32_32x32x16_bf16 v[16:31], v[184:187], v[196:199], v[16:31]
	v_mfma_f32_32x32x16_bf16 v[32:47], v[188:191], v[192:195], v[32:47]
	v_mfma_f32_32x32x16_bf16 v[0:15], v[188:191], v[196:199], v[0:15]
	s_waitcnt vmcnt(6)
	s_waitcnt lgkmcnt(0)
	s_barrier
	ds_read_b128 v[184:187], v231 offset:32768
	ds_read_b128 v[188:191], v231 offset:36864
	ds_read_b128 v[192:195], v224 offset:49152
	ds_read_b128 v[196:199], v224 offset:53248
	s_waitcnt lgkmcnt(4)
	v_mfma_f32_32x32x16_bf16 v[48:63], v[68:71], v[76:79], v[48:63]
	v_mfma_f32_32x32x16_bf16 v[16:31], v[68:71], v[80:83], v[16:31]
	v_lshl_add_u64 v[68:69], v[66:67], 0, s[74:75]
	global_load_lds_dwordx4 v[68:69], off
	v_lshl_add_u64 v[68:69], v[66:67], 0, s[76:77]
	s_mov_b32 m0, s16
	s_nop 0
	global_load_lds_dwordx4 v[68:69], off
	v_lshl_add_u64 v[68:69], v[66:67], 0, s[48:49]
	s_mov_b32 m0, s15
	s_mov_b64 s[48:49], 0x60300
	global_load_lds_dwordx4 v[68:69], off
	v_lshl_add_u64 v[68:69], v[66:67], 0, s[48:49]
	s_mov_b32 m0, s14
	v_mfma_f32_32x32x16_bf16 v[32:47], v[72:75], v[76:79], v[32:47]
	global_load_lds_dwordx4 v[68:69], off
	v_lshl_add_u64 v[68:69], v[64:65], 0, s[74:75]
	s_mov_b32 m0, s13
	s_nop 0
	global_load_lds_dwordx4 v[68:69], off
	v_lshl_add_u64 v[68:69], v[64:65], 0, s[76:77]
	s_mov_b32 m0, s12
	v_mfma_f32_32x32x16_bf16 v[0:15], v[72:75], v[80:83], v[0:15]
	global_load_lds_dwordx4 v[68:69], off
	s_mov_b32 m0, s11
	s_mov_b64 s[48:49], 0x40380
	ds_read_b128 v[68:71], v232 offset:32768
	ds_read_b128 v[72:75], v232 offset:36864
	ds_read_b128 v[76:79], v226 offset:49152
	ds_read_b128 v[80:83], v226 offset:53248
	s_waitcnt lgkmcnt(4)
	v_mfma_f32_32x32x16_bf16 v[48:63], v[184:187], v[192:195], v[48:63]
	v_mfma_f32_32x32x16_bf16 v[16:31], v[184:187], v[196:199], v[16:31]
	v_mfma_f32_32x32x16_bf16 v[32:47], v[188:191], v[192:195], v[32:47]
	v_mfma_f32_32x32x16_bf16 v[0:15], v[188:191], v[196:199], v[0:15]
	ds_read_b128 v[184:187], v233 offset:32768
	ds_read_b128 v[188:191], v233 offset:36864
	ds_read_b128 v[192:195], v228 offset:49152
	ds_read_b128 v[196:199], v228 offset:53248
	s_waitcnt lgkmcnt(4)
	v_mfma_f32_32x32x16_bf16 v[48:63], v[68:71], v[76:79], v[48:63]
	v_mfma_f32_32x32x16_bf16 v[16:31], v[68:71], v[80:83], v[16:31]
	v_mfma_f32_32x32x16_bf16 v[32:47], v[72:75], v[76:79], v[32:47]
	v_mfma_f32_32x32x16_bf16 v[0:15], v[72:75], v[80:83], v[0:15]
	ds_read_b128 v[68:71], v234 offset:32768
	ds_read_b128 v[72:75], v234 offset:36864
	ds_read_b128 v[76:79], v230 offset:49152
	ds_read_b128 v[80:83], v230 offset:53248
	s_waitcnt lgkmcnt(4)
	v_mfma_f32_32x32x16_bf16 v[48:63], v[184:187], v[192:195], v[48:63]
	v_mfma_f32_32x32x16_bf16 v[16:31], v[184:187], v[196:199], v[16:31]
	v_mfma_f32_32x32x16_bf16 v[32:47], v[188:191], v[192:195], v[32:47]
	v_mfma_f32_32x32x16_bf16 v[0:15], v[188:191], v[196:199], v[0:15]
	s_waitcnt vmcnt(6)
	s_waitcnt lgkmcnt(0)
	s_barrier
; #define MFMA(a, b, c) __builtin_amdgcn_mfma_f32_32x32x16_bf16((a), (b), (c), 0, 0, 0)
; #define WAIT_V(n) asm volatile("s_waitcnt vmcnt(%0)" ::"n"(n) : "memory")
; #define RAW_BARRIER() do { asm volatile("s_waitcnt lgkmcnt(0)" ::: "memory"); __builtin_amdgcn_s_barrier(); asm volatile("" ::: "memory"); } while (0)
; #define GLDS_STAGE(slot, kt) do { _Pragma("unroll") for (int i = 0; i < 6; ++i) \
;     __builtin_amdgcn_global_load_lds((const unsigned*)(src[i] + (kt) * 64), (__attribute__((address_space(3))) unsigned*)(smem + (slot) * G_STAGE + (wave + 8 * i) * 1024), 16, 0, 0); } while (0)
; DI void gemm_tile(const u16* __restrict__ X, int ldx, const u16* __restrict__ Wt, int ldw, int K, char* smem,
;                   f32x16 (&acc)[2][2]) {
;     ...
;   for (int kt = 0; kt < nk; ++kt) {
;     const int nxt = (cur >= 1) ? cur - 1 : 2;
;     if (kt + 2 < nk) GLDS_STAGE(nxt, kt + 2);
;     __builtin_amdgcn_sched_barrier(0);
;     const char* st = smem + cur * G_STAGE;
; #pragma unroll
;     for (int ks = 0; ks < 4; ++ks) {
;       bf16x8 a[2], b[2];
; #pragma unroll
;       for (int ft = 0; ft < 2; ++ft) a[ft] = *reinterpret_cast<const bf16x8*>(st + offA[ft] + (((ks * 2 + lh) ^ xa[ft]) << 4));
; #pragma unroll
;       for (int tt = 0; tt < 2; ++tt) b[tt] = *reinterpret_cast<const bf16x8*>(st + offB[tt] + (((ks * 2 + lh) ^ xb[tt]) << 4));
; #pragma unroll
;       for (int ft = 0; ft < 2; ++ft)
; #pragma unroll
;         for (int tt = 0; tt < 2; ++tt) acc[ft][tt] = MFMA(a[ft], b[tt], acc[ft][tt]);
;     }
;     if (kt + 2 < nk) { WAIT_V(6); } else { WAIT_V(0); }
;     RAW_BARRIER();
;     cur = (cur == 2) ? 0 : cur + 1;
	ds_read_b128 v[184:187], v235 offset:32768
	ds_read_b128 v[188:191], v235 offset:36864
	ds_read_b128 v[192:195], v236
	ds_read_b128 v[196:199], v236 offset:4096
	s_waitcnt lgkmcnt(4)
	v_mfma_f32_32x32x16_bf16 v[48:63], v[68:71], v[76:79], v[48:63]
	v_mfma_f32_32x32x16_bf16 v[16:31], v[68:71], v[80:83], v[16:31]
	v_lshl_add_u64 v[68:69], v[66:67], 0, s[40:41]
	global_load_lds_dwordx4 v[68:69], off
	v_lshl_add_u64 v[68:69], v[66:67], 0, s[0:1]
	s_mov_b32 m0, s9
	s_nop 0
	global_load_lds_dwordx4 v[68:69], off
	v_lshl_add_u64 v[68:69], v[66:67], 0, s[48:49]
	s_mov_b32 m0, s18
	s_mov_b64 s[48:49], 0x60380
	global_load_lds_dwordx4 v[68:69], off
	v_lshl_add_u64 v[68:69], v[66:67], 0, s[48:49]
	s_mov_b32 m0, s25
	v_mfma_f32_32x32x16_bf16 v[32:47], v[72:75], v[76:79], v[32:47]
	global_load_lds_dwordx4 v[68:69], off
	v_lshl_add_u64 v[68:69], v[64:65], 0, s[40:41]
	s_mov_b32 m0, s24
	s_nop 0
	global_load_lds_dwordx4 v[68:69], off
	v_lshl_add_u64 v[68:69], v[64:65], 0, s[0:1]
	s_mov_b32 m0, s30
	v_mfma_f32_32x32x16_bf16 v[0:15], v[72:75], v[80:83], v[0:15]
	global_load_lds_dwordx4 v[68:69], off
	s_mov_b32 m0, s70
	s_mov_b64 s[48:49], 0x40400
	ds_read_b128 v[68:71], v237 offset:32768
	ds_read_b128 v[72:75], v237 offset:36864
	ds_read_b128 v[76:79], v238
	ds_read_b128 v[80:83], v238 offset:4096
	s_waitcnt lgkmcnt(4)
	v_mfma_f32_32x32x16_bf16 v[48:63], v[184:187], v[192:195], v[48:63]
	v_mfma_f32_32x32x16_bf16 v[16:31], v[184:187], v[196:199], v[16:31]
	v_mfma_f32_32x32x16_bf16 v[32:47], v[188:191], v[192:195], v[32:47]
	v_mfma_f32_32x32x16_bf16 v[0:15], v[188:191], v[196:199], v[0:15]
	ds_read_b128 v[184:187], v239 offset:32768
	ds_read_b128 v[188:191], v239 offset:36864
	ds_read_b128 v[192:195], v240
	ds_read_b128 v[196:199], v240 offset:4096
	s_waitcnt lgkmcnt(4)
	v_mfma_f32_32x32x16_bf16 v[48:63], v[68:71], v[76:79], v[48:63]
	v_mfma_f32_32x32x16_bf16 v[16:31], v[68:71], v[80:83], v[16:31]
	v_mfma_f32_32x32x16_bf16 v[32:47], v[72:75], v[76:79], v[32:47]
	v_mfma_f32_32x32x16_bf16 v[0:15], v[72:75], v[80:83], v[0:15]
	ds_read_b128 v[68:71], v241 offset:32768
	ds_read_b128 v[72:75], v241 offset:36864
	ds_read_b128 v[76:79], v242
	ds_read_b128 v[80:83], v242 offset:4096
	s_waitcnt lgkmcnt(4)
	v_mfma_f32_32x32x16_bf16 v[48:63], v[184:187], v[192:195], v[48:63]
	v_mfma_f32_32x32x16_bf16 v[16:31], v[184:187], v[196:199], v[16:31]
	v_mfma_f32_32x32x16_bf16 v[32:47], v[188:191], v[192:195], v[32:47]
	v_mfma_f32_32x32x16_bf16 v[0:15], v[188:191], v[196:199], v[0:15]
	s_waitcnt vmcnt(6)
	s_waitcnt lgkmcnt(0)
	s_barrier
	ds_read_b128 v[184:187], v223 offset:32768
	ds_read_b128 v[188:191], v223 offset:36864
	ds_read_b128 v[192:195], v224
	ds_read_b128 v[196:199], v224 offset:4096
	s_waitcnt lgkmcnt(4)
	v_mfma_f32_32x32x16_bf16 v[48:63], v[68:71], v[76:79], v[48:63]
	v_mfma_f32_32x32x16_bf16 v[16:31], v[68:71], v[80:83], v[16:31]
	v_lshl_add_u64 v[68:69], v[66:67], 0, s[4:5]
	global_load_lds_dwordx4 v[68:69], off
	v_lshl_add_u64 v[68:69], v[66:67], 0, s[26:27]
	s_mov_b32 m0, s55
	s_nop 0
	global_load_lds_dwordx4 v[68:69], off
	v_lshl_add_u64 v[68:69], v[66:67], 0, s[48:49]
	s_mov_b32 m0, s35
	s_mov_b64 s[48:49], 0x60400
	global_load_lds_dwordx4 v[68:69], off
	v_lshl_add_u64 v[68:69], v[66:67], 0, s[48:49]
	s_mov_b32 m0, s54
	v_mfma_f32_32x32x16_bf16 v[32:47], v[72:75], v[76:79], v[32:47]
	global_load_lds_dwordx4 v[68:69], off
	v_lshl_add_u64 v[68:69], v[64:65], 0, s[4:5]
	s_mov_b32 m0, s31
	s_nop 0
	global_load_lds_dwordx4 v[68:69], off
	v_lshl_add_u64 v[68:69], v[64:65], 0, s[26:27]
	s_mov_b32 m0, s34
	v_mfma_f32_32x32x16_bf16 v[0:15], v[72:75], v[80:83], v[0:15]
	global_load_lds_dwordx4 v[68:69], off
	s_mov_b32 m0, s17
	ds_read_b128 v[68:71], v225 offset:32768
	ds_read_b128 v[72:75], v225 offset:36864
	ds_read_b128 v[76:79], v226
	ds_read_b128 v[80:83], v226 offset:4096
	s_waitcnt lgkmcnt(4)
	v_mfma_f32_32x32x16_bf16 v[48:63], v[184:187], v[192:195], v[48:63]
	v_mfma_f32_32x32x16_bf16 v[16:31], v[184:187], v[196:199], v[16:31]
	v_mfma_f32_32x32x16_bf16 v[32:47], v[188:191], v[192:195], v[32:47]
	v_mfma_f32_32x32x16_bf16 v[0:15], v[188:191], v[196:199], v[0:15]
	ds_read_b128 v[184:187], v227 offset:32768
	ds_read_b128 v[188:191], v227 offset:36864
	ds_read_b128 v[192:195], v228
	ds_read_b128 v[196:199], v228 offset:4096
	s_waitcnt lgkmcnt(4)
	v_mfma_f32_32x32x16_bf16 v[48:63], v[68:71], v[76:79], v[48:63]
	v_mfma_f32_32x32x16_bf16 v[16:31], v[68:71], v[80:83], v[16:31]
	v_mfma_f32_32x32x16_bf16 v[32:47], v[72:75], v[76:79], v[32:47]
	v_mfma_f32_32x32x16_bf16 v[0:15], v[72:75], v[80:83], v[0:15]
	ds_read_b128 v[68:71], v229 offset:32768
	ds_read_b128 v[72:75], v229 offset:36864
	ds_read_b128 v[76:79], v230
	ds_read_b128 v[80:83], v230 offset:4096
	s_waitcnt lgkmcnt(4)
	v_mfma_f32_32x32x16_bf16 v[48:63], v[184:187], v[192:195], v[48:63]
	v_mfma_f32_32x32x16_bf16 v[16:31], v[184:187], v[196:199], v[16:31]
	v_mfma_f32_32x32x16_bf16 v[32:47], v[188:191], v[192:195], v[32:47]
	v_mfma_f32_32x32x16_bf16 v[0:15], v[188:191], v[196:199], v[0:15]
	s_waitcnt vmcnt(6)
	s_waitcnt lgkmcnt(0)
	s_barrier
; #define MFMA(a, b, c) __builtin_amdgcn_mfma_f32_32x32x16_bf16((a), (b), (c), 0, 0, 0)
; #define WAIT_V(n) asm volatile("s_waitcnt vmcnt(%0)" ::"n"(n) : "memory")
; #define RAW_BARRIER() do { asm volatile("s_waitcnt lgkmcnt(0)" ::: "memory"); __builtin_amdgcn_s_barrier(); asm volatile("" ::: "memory"); } while (0)
; #define GLDS_STAGE(slot, kt) do { _Pragma("unroll") for (int i = 0; i < 6; ++i) \
;     __builtin_amdgcn_global_load_lds((const unsigned*)(src[i] + (kt) * 64), (__attribute__((address_space(3))) unsigned*)(smem + (slot) * G_STAGE + (wave + 8 * i) * 1024), 16, 0, 0); } while (0)
; DI void gemm_tile(const u16* __restrict__ X, int ldx, const u16* __restrict__ Wt, int ldw, int K, char* smem,
;                   f32x16 (&acc)[2][2]) {
;     ...
;   for (int kt = 0; kt < nk; ++kt) {
;     const int nxt = (cur >= 1) ? cur - 1 : 2;
;     if (kt + 2 < nk) GLDS_STAGE(nxt, kt + 2);
;     __builtin_amdgcn_sched_barrier(0);
;     const char* st = smem + cur * G_STAGE;
; #pragma unroll
;     for (int ks = 0; ks < 4; ++ks) {
;       bf16x8 a[2], b[2];
; #pragma unroll
;       for (int ft = 0; ft < 2; ++ft) a[ft] = *reinterpret_cast<const bf16x8*>(st + offA[ft] + (((ks * 2 + lh) ^ xa[ft]) << 4));
; #pragma unroll
;       for (int tt = 0; tt < 2; ++tt) b[tt] = *reinterpret_cast<const bf16x8*>(st + offB[tt] + (((ks * 2 + lh) ^ xb[tt]) << 4));
; #pragma unroll
;       for (int ft = 0; ft < 2; ++ft)
; #pragma unroll
;         for (int tt = 0; tt < 2; ++tt) acc[ft][tt] = MFMA(a[ft], b[tt], acc[ft][tt]);
;     }
;     if (kt + 2 < nk) { WAIT_V(6); } else { WAIT_V(0); }
;     RAW_BARRIER();
;     cur = (cur == 2) ? 0 : cur + 1;
	ds_read_b128 v[184:187], v231 offset:32768
	ds_read_b128 v[188:191], v231 offset:36864
	ds_read_b128 v[192:195], v224 offset:49152
	ds_read_b128 v[196:199], v224 offset:53248
	s_waitcnt lgkmcnt(4)
	v_mfma_f32_32x32x16_bf16 v[48:63], v[68:71], v[76:79], v[48:63]
	v_mfma_f32_32x32x16_bf16 v[16:31], v[68:71], v[80:83], v[16:31]
	v_lshl_add_u64 v[68:69], v[66:67], 0, s[38:39]
	global_load_lds_dwordx4 v[68:69], off
	v_lshl_add_u64 v[68:69], v[66:67], 0, s[44:45]
	s_mov_b32 m0, s16
	s_mov_b64 s[16:17], 0x40480
	global_load_lds_dwordx4 v[68:69], off
	v_lshl_add_u64 v[68:69], v[66:67], 0, s[16:17]
	s_mov_b32 m0, s15
	s_mov_b64 s[16:17], 0x60480
	global_load_lds_dwordx4 v[68:69], off
	v_lshl_add_u64 v[68:69], v[66:67], 0, s[16:17]
	s_mov_b32 m0, s14
	v_mfma_f32_32x32x16_bf16 v[32:47], v[72:75], v[76:79], v[32:47]
	global_load_lds_dwordx4 v[68:69], off
	v_lshl_add_u64 v[68:69], v[64:65], 0, s[38:39]
	s_mov_b32 m0, s13
	s_nop 0
	global_load_lds_dwordx4 v[68:69], off
	v_lshl_add_u64 v[68:69], v[64:65], 0, s[44:45]
	s_mov_b32 m0, s12
	v_mfma_f32_32x32x16_bf16 v[0:15], v[72:75], v[80:83], v[0:15]
	global_load_lds_dwordx4 v[68:69], off
	s_mov_b32 m0, s11
	s_mov_b64 s[12:13], 0x40500
	ds_read_b128 v[68:71], v232 offset:32768
	ds_read_b128 v[72:75], v232 offset:36864
	ds_read_b128 v[76:79], v226 offset:49152
	ds_read_b128 v[80:83], v226 offset:53248
	s_waitcnt lgkmcnt(4)
	v_mfma_f32_32x32x16_bf16 v[48:63], v[184:187], v[192:195], v[48:63]
	v_mfma_f32_32x32x16_bf16 v[16:31], v[184:187], v[196:199], v[16:31]
	v_mfma_f32_32x32x16_bf16 v[32:47], v[188:191], v[192:195], v[32:47]
	v_mfma_f32_32x32x16_bf16 v[0:15], v[188:191], v[196:199], v[0:15]
	ds_read_b128 v[184:187], v233 offset:32768
	ds_read_b128 v[188:191], v233 offset:36864
	ds_read_b128 v[192:195], v228 offset:49152
	ds_read_b128 v[196:199], v228 offset:53248
	s_waitcnt lgkmcnt(4)
	v_mfma_f32_32x32x16_bf16 v[48:63], v[68:71], v[76:79], v[48:63]
	v_mfma_f32_32x32x16_bf16 v[16:31], v[68:71], v[80:83], v[16:31]
	v_mfma_f32_32x32x16_bf16 v[32:47], v[72:75], v[76:79], v[32:47]
	v_mfma_f32_32x32x16_bf16 v[0:15], v[72:75], v[80:83], v[0:15]
	ds_read_b128 v[68:71], v234 offset:32768
	ds_read_b128 v[72:75], v234 offset:36864
	ds_read_b128 v[76:79], v230 offset:49152
	ds_read_b128 v[80:83], v230 offset:53248
	s_waitcnt lgkmcnt(4)
	v_mfma_f32_32x32x16_bf16 v[48:63], v[184:187], v[192:195], v[48:63]
	v_mfma_f32_32x32x16_bf16 v[16:31], v[184:187], v[196:199], v[16:31]
	v_mfma_f32_32x32x16_bf16 v[32:47], v[188:191], v[192:195], v[32:47]
	v_mfma_f32_32x32x16_bf16 v[0:15], v[188:191], v[196:199], v[0:15]
	s_waitcnt vmcnt(6)
	s_waitcnt lgkmcnt(0)
	s_barrier
	ds_read_b128 v[184:187], v235 offset:32768
	ds_read_b128 v[188:191], v235 offset:36864
	ds_read_b128 v[192:195], v236
	ds_read_b128 v[196:199], v236 offset:4096
	s_waitcnt lgkmcnt(4)
	v_mfma_f32_32x32x16_bf16 v[48:63], v[68:71], v[76:79], v[48:63]
	v_mfma_f32_32x32x16_bf16 v[16:31], v[68:71], v[80:83], v[16:31]
	v_lshl_add_u64 v[68:69], v[66:67], 0, s[56:57]
	global_load_lds_dwordx4 v[68:69], off
	v_lshl_add_u64 v[68:69], v[66:67], 0, s[62:63]
	s_mov_b32 m0, s9
	s_nop 0
	global_load_lds_dwordx4 v[68:69], off
	v_lshl_add_u64 v[68:69], v[66:67], 0, s[12:13]
	s_mov_b32 m0, s18
	s_mov_b64 s[12:13], 0x60500
	global_load_lds_dwordx4 v[68:69], off
	v_lshl_add_u64 v[68:69], v[66:67], 0, s[12:13]
	s_mov_b32 m0, s25
	v_mfma_f32_32x32x16_bf16 v[32:47], v[72:75], v[76:79], v[32:47]
	global_load_lds_dwordx4 v[68:69], off
	v_lshl_add_u64 v[68:69], v[64:65], 0, s[56:57]
	s_mov_b32 m0, s24
	s_nop 0
	global_load_lds_dwordx4 v[68:69], off
	v_lshl_add_u64 v[68:69], v[64:65], 0, s[62:63]
	s_mov_b32 m0, s30
	v_mfma_f32_32x32x16_bf16 v[0:15], v[72:75], v[80:83], v[0:15]
	global_load_lds_dwordx4 v[68:69], off
	v_readfirstlane_b32 s30, v121
	s_mov_b32 m0, s30
	v_readfirstlane_b32 s15, v123
	ds_read_b128 v[68:71], v237 offset:32768
	ds_read_b128 v[72:75], v237 offset:36864
	ds_read_b128 v[76:79], v238
	ds_read_b128 v[80:83], v238 offset:4096
	s_waitcnt lgkmcnt(4)
	v_mfma_f32_32x32x16_bf16 v[48:63], v[184:187], v[192:195], v[48:63]
	s_mov_b64 s[12:13], 0x40580
	v_readfirstlane_b32 s16, v125
	v_readfirstlane_b32 s18, v127
	v_readfirstlane_b32 s17, v163
	v_readfirstlane_b32 s24, v165
	v_mfma_f32_32x32x16_bf16 v[16:31], v[184:187], v[196:199], v[16:31]
	v_mfma_f32_32x32x16_bf16 v[32:47], v[188:191], v[192:195], v[32:47]
	v_mfma_f32_32x32x16_bf16 v[0:15], v[188:191], v[196:199], v[0:15]
	ds_read_b128 v[184:187], v239 offset:32768
	ds_read_b128 v[188:191], v239 offset:36864
	ds_read_b128 v[192:195], v240
	ds_read_b128 v[196:199], v240 offset:4096
	s_waitcnt lgkmcnt(4)
	v_mfma_f32_32x32x16_bf16 v[48:63], v[68:71], v[76:79], v[48:63]
	v_mfma_f32_32x32x16_bf16 v[16:31], v[68:71], v[80:83], v[16:31]
	v_mfma_f32_32x32x16_bf16 v[32:47], v[72:75], v[76:79], v[32:47]
	v_mfma_f32_32x32x16_bf16 v[0:15], v[72:75], v[80:83], v[0:15]
	ds_read_b128 v[68:71], v241 offset:32768
	ds_read_b128 v[72:75], v241 offset:36864
	ds_read_b128 v[76:79], v242
	ds_read_b128 v[80:83], v242 offset:4096
	s_waitcnt lgkmcnt(4)
	v_mfma_f32_32x32x16_bf16 v[48:63], v[184:187], v[192:195], v[48:63]
	v_mfma_f32_32x32x16_bf16 v[16:31], v[184:187], v[196:199], v[16:31]
	v_mfma_f32_32x32x16_bf16 v[32:47], v[188:191], v[192:195], v[32:47]
	v_mfma_f32_32x32x16_bf16 v[0:15], v[188:191], v[196:199], v[0:15]
	s_waitcnt vmcnt(6)
	s_waitcnt lgkmcnt(0)
	s_barrier
; #define MFMA(a, b, c) __builtin_amdgcn_mfma_f32_32x32x16_bf16((a), (b), (c), 0, 0, 0)
; #define WAIT_V(n) asm volatile("s_waitcnt vmcnt(%0)" ::"n"(n) : "memory")
; #define RAW_BARRIER() do { asm volatile("s_waitcnt lgkmcnt(0)" ::: "memory"); __builtin_amdgcn_s_barrier(); asm volatile("" ::: "memory"); } while (0)
; #define GLDS_STAGE(slot, kt) do { _Pragma("unroll") for (int i = 0; i < 6; ++i) \
;     __builtin_amdgcn_global_load_lds((const unsigned*)(src[i] + (kt) * 64), (__attribute__((address_space(3))) unsigned*)(smem + (slot) * G_STAGE + (wave + 8 * i) * 1024), 16, 0, 0); } while (0)
; DI void gemm_tile(const u16* __restrict__ X, int ldx, const u16* __restrict__ Wt, int ldw, int K, char* smem,
;                   f32x16 (&acc)[2][2]) {
;     ...
;   for (int kt = 0; kt < nk; ++kt) {
;     const int nxt = (cur >= 1) ? cur - 1 : 2;
;     if (kt + 2 < nk) GLDS_STAGE(nxt, kt + 2);
;     __builtin_amdgcn_sched_barrier(0);
;     const char* st = smem + cur * G_STAGE;
; #pragma unroll
;     for (int ks = 0; ks < 4; ++ks) {
;       bf16x8 a[2], b[2];
; #pragma unroll
;       for (int ft = 0; ft < 2; ++ft) a[ft] = *reinterpret_cast<const bf16x8*>(st + offA[ft] + (((ks * 2 + lh) ^ xa[ft]) << 4));
; #pragma unroll
;       for (int tt = 0; tt < 2; ++tt) b[tt] = *reinterpret_cast<const bf16x8*>(st + offB[tt] + (((ks * 2 + lh) ^ xb[tt]) << 4));
; #pragma unroll
;       for (int ft = 0; ft < 2; ++ft)
; #pragma unroll
;         for (int tt = 0; tt < 2; ++tt) acc[ft][tt] = MFMA(a[ft], b[tt], acc[ft][tt]);
;     }
;     if (kt + 2 < nk) { WAIT_V(6); } else { WAIT_V(0); }
;     RAW_BARRIER();
;     cur = (cur == 2) ? 0 : cur + 1;
	ds_read_b128 v[184:187], v223 offset:32768
	ds_read_b128 v[188:191], v223 offset:36864
	ds_read_b128 v[192:195], v224
	ds_read_b128 v[196:199], v224 offset:4096
	s_waitcnt lgkmcnt(4)
	v_mfma_f32_32x32x16_bf16 v[48:63], v[68:71], v[76:79], v[48:63]
	v_mfma_f32_32x32x16_bf16 v[16:31], v[68:71], v[80:83], v[16:31]
	v_lshl_add_u64 v[68:69], v[66:67], 0, s[72:73]
	global_load_lds_dwordx4 v[68:69], off
	v_lshl_add_u64 v[68:69], v[66:67], 0, s[84:85]
	s_mov_b32 m0, s15
	s_nop 0
	global_load_lds_dwordx4 v[68:69], off
	v_lshl_add_u64 v[68:69], v[66:67], 0, s[12:13]
	s_mov_b32 m0, s16
	s_mov_b64 s[12:13], 0x60580
	global_load_lds_dwordx4 v[68:69], off
	v_lshl_add_u64 v[68:69], v[66:67], 0, s[12:13]
	s_mov_b32 m0, s18
	v_mfma_f32_32x32x16_bf16 v[32:47], v[72:75], v[76:79], v[32:47]
	global_load_lds_dwordx4 v[68:69], off
	v_lshl_add_u64 v[68:69], v[64:65], 0, s[72:73]
	s_mov_b32 m0, s17
	s_nop 0
	global_load_lds_dwordx4 v[68:69], off
	v_lshl_add_u64 v[68:69], v[64:65], 0, s[84:85]
	s_mov_b32 m0, s24
	v_mfma_f32_32x32x16_bf16 v[0:15], v[72:75], v[80:83], v[0:15]
	global_load_lds_dwordx4 v[68:69], off
	v_readfirstlane_b32 s25, v101
	s_mov_b32 m0, s25
	v_readfirstlane_b32 s9, v211
	ds_read_b128 v[68:71], v225 offset:32768
	ds_read_b128 v[72:75], v225 offset:36864
	ds_read_b128 v[76:79], v226
	ds_read_b128 v[80:83], v226 offset:4096
	s_waitcnt lgkmcnt(4)
	v_mfma_f32_32x32x16_bf16 v[48:63], v[184:187], v[192:195], v[48:63]
	s_mov_b64 s[12:13], 0x40600
	v_readfirstlane_b32 s11, v214
	v_readfirstlane_b32 s14, v217
	v_mfma_f32_32x32x16_bf16 v[16:31], v[184:187], v[196:199], v[16:31]
	v_mfma_f32_32x32x16_bf16 v[32:47], v[188:191], v[192:195], v[32:47]
	v_mfma_f32_32x32x16_bf16 v[0:15], v[188:191], v[196:199], v[0:15]
	ds_read_b128 v[184:187], v227 offset:32768
	ds_read_b128 v[188:191], v227 offset:36864
	ds_read_b128 v[192:195], v228
	ds_read_b128 v[196:199], v228 offset:4096
	s_waitcnt lgkmcnt(4)
	v_mfma_f32_32x32x16_bf16 v[48:63], v[68:71], v[76:79], v[48:63]
	v_mfma_f32_32x32x16_bf16 v[16:31], v[68:71], v[80:83], v[16:31]
	v_mfma_f32_32x32x16_bf16 v[32:47], v[72:75], v[76:79], v[32:47]
	v_mfma_f32_32x32x16_bf16 v[0:15], v[72:75], v[80:83], v[0:15]
	ds_read_b128 v[68:71], v229 offset:32768
	ds_read_b128 v[72:75], v229 offset:36864
	ds_read_b128 v[76:79], v230
	ds_read_b128 v[80:83], v230 offset:4096
	s_waitcnt lgkmcnt(4)
	v_mfma_f32_32x32x16_bf16 v[48:63], v[184:187], v[192:195], v[48:63]
	v_mfma_f32_32x32x16_bf16 v[16:31], v[184:187], v[196:199], v[16:31]
	v_mfma_f32_32x32x16_bf16 v[32:47], v[188:191], v[192:195], v[32:47]
	v_mfma_f32_32x32x16_bf16 v[0:15], v[188:191], v[196:199], v[0:15]
	s_waitcnt vmcnt(6)
	s_waitcnt lgkmcnt(0)
	s_barrier
	ds_read_b128 v[184:187], v231 offset:32768
	ds_read_b128 v[188:191], v231 offset:36864
	ds_read_b128 v[192:195], v224 offset:49152
	ds_read_b128 v[196:199], v224 offset:53248
	s_waitcnt lgkmcnt(4)
	v_mfma_f32_32x32x16_bf16 v[48:63], v[68:71], v[76:79], v[48:63]
	v_mfma_f32_32x32x16_bf16 v[16:31], v[68:71], v[80:83], v[16:31]
	v_lshl_add_u64 v[68:69], v[66:67], 0, s[22:23]
	global_load_lds_dwordx4 v[68:69], off
	v_lshl_add_u64 v[68:69], v[66:67], 0, s[28:29]
	s_mov_b32 m0, s9
	s_nop 0
	global_load_lds_dwordx4 v[68:69], off
	v_lshl_add_u64 v[68:69], v[66:67], 0, s[12:13]
	s_mov_b32 m0, s11
	s_mov_b64 s[12:13], 0x60600
	global_load_lds_dwordx4 v[68:69], off
	v_lshl_add_u64 v[68:69], v[66:67], 0, s[12:13]
	v_readfirstlane_b32 s13, v215
	s_mov_b32 m0, s13
	v_readfirstlane_b32 s12, v216
	global_load_lds_dwordx4 v[68:69], off
	v_lshl_add_u64 v[68:69], v[64:65], 0, s[22:23]
	s_mov_b32 m0, s12
	v_mfma_f32_32x32x16_bf16 v[32:47], v[72:75], v[76:79], v[32:47]
	global_load_lds_dwordx4 v[68:69], off
	v_lshl_add_u64 v[68:69], v[64:65], 0, s[28:29]
	s_mov_b32 m0, s14
	s_nop 0
	global_load_lds_dwordx4 v[68:69], off
	v_mfma_f32_32x32x16_bf16 v[0:15], v[72:75], v[80:83], v[0:15]
	v_readfirstlane_b32 s31, v103
	s_mov_b32 m0, s31
	v_readfirstlane_b32 s31, v218
	ds_read_b128 v[68:71], v232 offset:32768
	ds_read_b128 v[72:75], v232 offset:36864
	ds_read_b128 v[76:79], v226 offset:49152
	ds_read_b128 v[80:83], v226 offset:53248
	s_waitcnt lgkmcnt(4)
	v_mfma_f32_32x32x16_bf16 v[48:63], v[184:187], v[192:195], v[48:63]
	s_mov_b64 s[34:35], 0x40680
	v_mfma_f32_32x32x16_bf16 v[16:31], v[184:187], v[196:199], v[16:31]
	v_mfma_f32_32x32x16_bf16 v[32:47], v[188:191], v[192:195], v[32:47]
	v_mfma_f32_32x32x16_bf16 v[0:15], v[188:191], v[196:199], v[0:15]
	ds_read_b128 v[184:187], v233 offset:32768
	ds_read_b128 v[188:191], v233 offset:36864
	ds_read_b128 v[192:195], v228 offset:49152
	ds_read_b128 v[196:199], v228 offset:53248
	s_waitcnt lgkmcnt(4)
	v_mfma_f32_32x32x16_bf16 v[48:63], v[68:71], v[76:79], v[48:63]
	v_mfma_f32_32x32x16_bf16 v[16:31], v[68:71], v[80:83], v[16:31]
	v_mfma_f32_32x32x16_bf16 v[32:47], v[72:75], v[76:79], v[32:47]
	v_mfma_f32_32x32x16_bf16 v[0:15], v[72:75], v[80:83], v[0:15]
	ds_read_b128 v[68:71], v234 offset:32768
	ds_read_b128 v[72:75], v234 offset:36864
	ds_read_b128 v[76:79], v230 offset:49152
	ds_read_b128 v[80:83], v230 offset:53248
	s_waitcnt lgkmcnt(4)
	v_mfma_f32_32x32x16_bf16 v[48:63], v[184:187], v[192:195], v[48:63]
	v_mfma_f32_32x32x16_bf16 v[16:31], v[184:187], v[196:199], v[16:31]
	v_mfma_f32_32x32x16_bf16 v[32:47], v[188:191], v[192:195], v[32:47]
	v_mfma_f32_32x32x16_bf16 v[0:15], v[188:191], v[196:199], v[0:15]
	s_waitcnt vmcnt(6)
	s_waitcnt lgkmcnt(0)
	s_barrier
; #define MFMA(a, b, c) __builtin_amdgcn_mfma_f32_32x32x16_bf16((a), (b), (c), 0, 0, 0)
; #define WAIT_V(n) asm volatile("s_waitcnt vmcnt(%0)" ::"n"(n) : "memory")
; #define RAW_BARRIER() do { asm volatile("s_waitcnt lgkmcnt(0)" ::: "memory"); __builtin_amdgcn_s_barrier(); asm volatile("" ::: "memory"); } while (0)
; #define GLDS_STAGE(slot, kt) do { _Pragma("unroll") for (int i = 0; i < 6; ++i) \
;     __builtin_amdgcn_global_load_lds((const unsigned*)(src[i] + (kt) * 64), (__attribute__((address_space(3))) unsigned*)(smem + (slot) * G_STAGE + (wave + 8 * i) * 1024), 16, 0, 0); } while (0)
; DI void gemm_tile(const u16* __restrict__ X, int ldx, const u16* __restrict__ Wt, int ldw, int K, char* smem,
;                   f32x16 (&acc)[2][2]) {
;     ...
;   for (int kt = 0; kt < nk; ++kt) {
;     const int nxt = (cur >= 1) ? cur - 1 : 2;
;     if (kt + 2 < nk) GLDS_STAGE(nxt, kt + 2);
;     __builtin_amdgcn_sched_barrier(0);
;     const char* st = smem + cur * G_STAGE;
; #pragma unroll
;     for (int ks = 0; ks < 4; ++ks) {
;       bf16x8 a[2], b[2];
; #pragma unroll
;       for (int ft = 0; ft < 2; ++ft) a[ft] = *reinterpret_cast<const bf16x8*>(st + offA[ft] + (((ks * 2 + lh) ^ xa[ft]) << 4));
; #pragma unroll
;       for (int tt = 0; tt < 2; ++tt) b[tt] = *reinterpret_cast<const bf16x8*>(st + offB[tt] + (((ks * 2 + lh) ^ xb[tt]) << 4));
; #pragma unroll
;       for (int ft = 0; ft < 2; ++ft)
; #pragma unroll
;         for (int tt = 0; tt < 2; ++tt) acc[ft][tt] = MFMA(a[ft], b[tt], acc[ft][tt]);
;     }
;     if (kt + 2 < nk) { WAIT_V(6); } else { WAIT_V(0); }
;     RAW_BARRIER();
;     cur = (cur == 2) ? 0 : cur + 1;
	ds_read_b128 v[184:187], v235 offset:32768
	ds_read_b128 v[188:191], v235 offset:36864
	ds_read_b128 v[192:195], v236
	ds_read_b128 v[196:199], v236 offset:4096
	s_waitcnt lgkmcnt(4)
	v_mfma_f32_32x32x16_bf16 v[48:63], v[68:71], v[76:79], v[48:63]
	v_mfma_f32_32x32x16_bf16 v[16:31], v[68:71], v[80:83], v[16:31]
	v_lshl_add_u64 v[68:69], v[66:67], 0, s[52:53]
	global_load_lds_dwordx4 v[68:69], off
	v_lshl_add_u64 v[68:69], v[66:67], 0, s[64:65]
	s_mov_b32 m0, s31
	v_readfirstlane_b32 s31, v173
	global_load_lds_dwordx4 v[68:69], off
	v_lshl_add_u64 v[68:69], v[66:67], 0, s[34:35]
	s_mov_b32 m0, s31
	s_mov_b64 s[34:35], 0x60680
	v_readfirstlane_b32 s31, v200
	global_load_lds_dwordx4 v[68:69], off
	v_lshl_add_u64 v[68:69], v[66:67], 0, s[34:35]
	s_mov_b32 m0, s31
	v_readfirstlane_b32 s31, v201
	global_load_lds_dwordx4 v[68:69], off
	v_lshl_add_u64 v[68:69], v[64:65], 0, s[52:53]
	s_mov_b32 m0, s31
	v_readfirstlane_b32 s31, v202
	global_load_lds_dwordx4 v[68:69], off
	v_lshl_add_u64 v[68:69], v[64:65], 0, s[64:65]
	s_mov_b32 m0, s31
	v_mfma_f32_32x32x16_bf16 v[32:47], v[72:75], v[76:79], v[32:47]
	global_load_lds_dwordx4 v[68:69], off
	v_mfma_f32_32x32x16_bf16 v[0:15], v[72:75], v[80:83], v[0:15]
	s_mov_b32 m0, s30
	s_mov_b64 s[30:31], 0x40700
	ds_read_b128 v[68:71], v237 offset:32768
	ds_read_b128 v[72:75], v237 offset:36864
	ds_read_b128 v[76:79], v238
	ds_read_b128 v[80:83], v238 offset:4096
	s_waitcnt lgkmcnt(4)
	v_mfma_f32_32x32x16_bf16 v[48:63], v[184:187], v[192:195], v[48:63]
	v_mfma_f32_32x32x16_bf16 v[16:31], v[184:187], v[196:199], v[16:31]
	v_mfma_f32_32x32x16_bf16 v[32:47], v[188:191], v[192:195], v[32:47]
	v_mfma_f32_32x32x16_bf16 v[0:15], v[188:191], v[196:199], v[0:15]
	ds_read_b128 v[184:187], v239 offset:32768
	ds_read_b128 v[188:191], v239 offset:36864
	ds_read_b128 v[192:195], v240
	ds_read_b128 v[196:199], v240 offset:4096
	s_waitcnt lgkmcnt(4)
	v_mfma_f32_32x32x16_bf16 v[48:63], v[68:71], v[76:79], v[48:63]
	v_mfma_f32_32x32x16_bf16 v[16:31], v[68:71], v[80:83], v[16:31]
	v_mfma_f32_32x32x16_bf16 v[32:47], v[72:75], v[76:79], v[32:47]
	v_mfma_f32_32x32x16_bf16 v[0:15], v[72:75], v[80:83], v[0:15]
	ds_read_b128 v[68:71], v241 offset:32768
	ds_read_b128 v[72:75], v241 offset:36864
	ds_read_b128 v[76:79], v242
	ds_read_b128 v[80:83], v242 offset:4096
	s_waitcnt lgkmcnt(4)
	v_mfma_f32_32x32x16_bf16 v[48:63], v[184:187], v[192:195], v[48:63]
	v_mfma_f32_32x32x16_bf16 v[16:31], v[184:187], v[196:199], v[16:31]
	v_mfma_f32_32x32x16_bf16 v[32:47], v[188:191], v[192:195], v[32:47]
	v_mfma_f32_32x32x16_bf16 v[0:15], v[188:191], v[196:199], v[0:15]
	s_waitcnt vmcnt(6)
	s_waitcnt lgkmcnt(0)
	s_barrier
	ds_read_b128 v[184:187], v223 offset:32768
	ds_read_b128 v[188:191], v223 offset:36864
	ds_read_b128 v[192:195], v224
	ds_read_b128 v[196:199], v224 offset:4096
	s_waitcnt lgkmcnt(4)
	v_mfma_f32_32x32x16_bf16 v[48:63], v[68:71], v[76:79], v[48:63]
	v_mfma_f32_32x32x16_bf16 v[16:31], v[68:71], v[80:83], v[16:31]
	v_lshl_add_u64 v[68:69], v[66:67], 0, s[20:21]
	global_load_lds_dwordx4 v[68:69], off
	v_lshl_add_u64 v[68:69], v[66:67], 0, s[36:37]
	s_mov_b32 m0, s15
	s_nop 0
	global_load_lds_dwordx4 v[68:69], off
	v_lshl_add_u64 v[68:69], v[66:67], 0, s[30:31]
	s_mov_b32 m0, s16
	s_mov_b64 s[30:31], 0x60700
	global_load_lds_dwordx4 v[68:69], off
	v_lshl_add_u64 v[68:69], v[66:67], 0, s[30:31]
	s_mov_b32 m0, s18
	v_mfma_f32_32x32x16_bf16 v[32:47], v[72:75], v[76:79], v[32:47]
	global_load_lds_dwordx4 v[68:69], off
	v_lshl_add_u64 v[68:69], v[64:65], 0, s[20:21]
	s_mov_b32 m0, s17
	s_nop 0
	global_load_lds_dwordx4 v[68:69], off
	v_lshl_add_u64 v[68:69], v[64:65], 0, s[36:37]
	s_mov_b32 m0, s24
	v_mfma_f32_32x32x16_bf16 v[0:15], v[72:75], v[80:83], v[0:15]
	global_load_lds_dwordx4 v[68:69], off
	s_mov_b32 m0, s25
	s_mov_b64 s[16:17], 0x40780
	ds_read_b128 v[68:71], v225 offset:32768
	ds_read_b128 v[72:75], v225 offset:36864
	ds_read_b128 v[76:79], v226
	ds_read_b128 v[80:83], v226 offset:4096
	s_waitcnt lgkmcnt(4)
	v_mfma_f32_32x32x16_bf16 v[48:63], v[184:187], v[192:195], v[48:63]
	v_mfma_f32_32x32x16_bf16 v[16:31], v[184:187], v[196:199], v[16:31]
	v_mfma_f32_32x32x16_bf16 v[32:47], v[188:191], v[192:195], v[32:47]
	v_mfma_f32_32x32x16_bf16 v[0:15], v[188:191], v[196:199], v[0:15]
	ds_read_b128 v[184:187], v227 offset:32768
	ds_read_b128 v[188:191], v227 offset:36864
	ds_read_b128 v[192:195], v228
	ds_read_b128 v[196:199], v228 offset:4096
	s_waitcnt lgkmcnt(4)
	v_mfma_f32_32x32x16_bf16 v[48:63], v[68:71], v[76:79], v[48:63]
	v_mfma_f32_32x32x16_bf16 v[16:31], v[68:71], v[80:83], v[16:31]
	v_mfma_f32_32x32x16_bf16 v[32:47], v[72:75], v[76:79], v[32:47]
	v_mfma_f32_32x32x16_bf16 v[0:15], v[72:75], v[80:83], v[0:15]
	s_waitcnt lgkmcnt(0)
	v_mfma_f32_32x32x16_bf16 v[48:63], v[184:187], v[192:195], v[48:63]
	v_mfma_f32_32x32x16_bf16 v[16:31], v[184:187], v[196:199], v[16:31]
	v_mfma_f32_32x32x16_bf16 v[32:47], v[188:191], v[192:195], v[32:47]
	v_mfma_f32_32x32x16_bf16 v[0:15], v[188:191], v[196:199], v[0:15]
	ds_read_b128 v[68:71], v229 offset:32768
	ds_read_b128 v[72:75], v229 offset:36864
	ds_read_b128 v[76:79], v230
	ds_read_b128 v[80:83], v230 offset:4096
	s_waitcnt vmcnt(6)
	s_waitcnt lgkmcnt(0)
	s_barrier
; #define MFMA(a, b, c) __builtin_amdgcn_mfma_f32_32x32x16_bf16((a), (b), (c), 0, 0, 0)
; #define WAIT_V(n) asm volatile("s_waitcnt vmcnt(%0)" ::"n"(n) : "memory")
; #define RAW_BARRIER() do { asm volatile("s_waitcnt lgkmcnt(0)" ::: "memory"); __builtin_amdgcn_s_barrier(); asm volatile("" ::: "memory"); } while (0)
; #define GLDS_STAGE(slot, kt) do { _Pragma("unroll") for (int i = 0; i < 6; ++i) \
;     __builtin_amdgcn_global_load_lds((const unsigned*)(src[i] + (kt) * 64), (__attribute__((address_space(3))) unsigned*)(smem + (slot) * G_STAGE + (wave + 8 * i) * 1024), 16, 0, 0); } while (0)
; DI void gemm_tile(const u16* __restrict__ X, int ldx, const u16* __restrict__ Wt, int ldw, int K, char* smem,
;                   f32x16 (&acc)[2][2]) {
;     ...
;   for (int kt = 0; kt < nk; ++kt) {
;     const int nxt = (cur >= 1) ? cur - 1 : 2;
;     if (kt + 2 < nk) GLDS_STAGE(nxt, kt + 2);
;     __builtin_amdgcn_sched_barrier(0);
;     const char* st = smem + cur * G_STAGE;
; #pragma unroll
;     for (int ks = 0; ks < 4; ++ks) {
;       bf16x8 a[2], b[2];
; #pragma unroll
;       for (int ft = 0; ft < 2; ++ft) a[ft] = *reinterpret_cast<const bf16x8*>(st + offA[ft] + (((ks * 2 + lh) ^ xa[ft]) << 4));
; #pragma unroll
;       for (int tt = 0; tt < 2; ++tt) b[tt] = *reinterpret_cast<const bf16x8*>(st + offB[tt] + (((ks * 2 + lh) ^ xb[tt]) << 4));
; #pragma unroll
;       for (int ft = 0; ft < 2; ++ft)
; #pragma unroll
;         for (int tt = 0; tt < 2; ++tt) acc[ft][tt] = MFMA(a[ft], b[tt], acc[ft][tt]);
;     }
;     if (kt + 2 < nk) { WAIT_V(6); } else { WAIT_V(0); }
;     RAW_BARRIER();
;     cur = (cur == 2) ? 0 : cur + 1;
	s_waitcnt lgkmcnt(0)
	v_mfma_f32_32x32x16_bf16 v[48:63], v[68:71], v[76:79], v[48:63]
	v_mfma_f32_32x32x16_bf16 v[16:31], v[68:71], v[80:83], v[16:31]
	v_lshl_add_u64 v[68:69], v[66:67], 0, s[86:87]
	global_load_lds_dwordx4 v[68:69], off
	v_lshl_add_u64 v[68:69], v[66:67], 0, s[46:47]
	s_mov_b32 m0, s9
	s_nop 0
	global_load_lds_dwordx4 v[68:69], off
	v_lshl_add_u64 v[68:69], v[66:67], 0, s[16:17]
	s_mov_b32 m0, s11
	s_mov_b64 s[16:17], 0x60780
	global_load_lds_dwordx4 v[68:69], off
	v_lshl_add_u64 v[66:67], v[66:67], 0, s[16:17]
	s_mov_b32 m0, s13
	v_mfma_f32_32x32x16_bf16 v[32:47], v[72:75], v[76:79], v[32:47]
	global_load_lds_dwordx4 v[66:67], off
	v_lshl_add_u64 v[66:67], v[64:65], 0, s[86:87]
	s_mov_b32 m0, s12
	v_lshl_add_u64 v[64:65], v[64:65], 0, s[46:47]
	global_load_lds_dwordx4 v[66:67], off
	s_mov_b32 m0, s14
	v_mfma_f32_32x32x16_bf16 v[0:15], v[72:75], v[80:83], v[0:15]
	global_load_lds_dwordx4 v[64:65], off
	ds_read_b128 v[64:67], v231 offset:32768
	ds_read_b128 v[68:71], v224 offset:49152
	ds_read_b128 v[72:75], v224 offset:53248
	s_waitcnt lgkmcnt(0)
	v_mfma_f32_32x32x16_bf16 v[48:63], v[64:67], v[68:71], v[48:63]
	v_mfma_f32_32x32x16_bf16 v[16:31], v[64:67], v[72:75], v[16:31]
	ds_read_b128 v[64:67], v231 offset:36864
	s_waitcnt lgkmcnt(0)
	v_mfma_f32_32x32x16_bf16 v[32:47], v[64:67], v[68:71], v[32:47]
	v_mfma_f32_32x32x16_bf16 v[0:15], v[64:67], v[72:75], v[0:15]
	ds_read_b128 v[64:67], v232 offset:32768
	ds_read_b128 v[68:71], v226 offset:49152
	ds_read_b128 v[72:75], v226 offset:53248
	s_waitcnt lgkmcnt(0)
	v_mfma_f32_32x32x16_bf16 v[48:63], v[64:67], v[68:71], v[48:63]
	v_mfma_f32_32x32x16_bf16 v[16:31], v[64:67], v[72:75], v[16:31]
	ds_read_b128 v[64:67], v232 offset:36864
	s_waitcnt lgkmcnt(0)
	v_mfma_f32_32x32x16_bf16 v[32:47], v[64:67], v[68:71], v[32:47]
	v_mfma_f32_32x32x16_bf16 v[0:15], v[64:67], v[72:75], v[0:15]
	ds_read_b128 v[64:67], v233 offset:32768
	ds_read_b128 v[68:71], v228 offset:49152
	ds_read_b128 v[72:75], v228 offset:53248
	s_waitcnt lgkmcnt(0)
	v_mfma_f32_32x32x16_bf16 v[48:63], v[64:67], v[68:71], v[48:63]
	v_mfma_f32_32x32x16_bf16 v[16:31], v[64:67], v[72:75], v[16:31]
	ds_read_b128 v[64:67], v233 offset:36864
	s_waitcnt lgkmcnt(0)
	v_mfma_f32_32x32x16_bf16 v[32:47], v[64:67], v[68:71], v[32:47]
	v_mfma_f32_32x32x16_bf16 v[0:15], v[64:67], v[72:75], v[0:15]
	ds_read_b128 v[64:67], v234 offset:32768
	ds_read_b128 v[68:71], v230 offset:49152
	ds_read_b128 v[72:75], v230 offset:53248
	s_waitcnt lgkmcnt(0)
	v_mfma_f32_32x32x16_bf16 v[48:63], v[64:67], v[68:71], v[48:63]
	v_mfma_f32_32x32x16_bf16 v[16:31], v[64:67], v[72:75], v[16:31]
	ds_read_b128 v[64:67], v234 offset:36864
	s_waitcnt vmcnt(6)
	s_waitcnt lgkmcnt(0)
	s_barrier
	s_waitcnt lgkmcnt(0)
	v_mfma_f32_32x32x16_bf16 v[32:47], v[64:67], v[68:71], v[32:47]
	v_mfma_f32_32x32x16_bf16 v[0:15], v[64:67], v[72:75], v[0:15]
	ds_read_b128 v[64:67], v235 offset:32768
	ds_read_b128 v[68:71], v236
	ds_read_b128 v[72:75], v236 offset:4096
	s_waitcnt lgkmcnt(0)
	v_mfma_f32_32x32x16_bf16 v[48:63], v[64:67], v[68:71], v[48:63]
	v_mfma_f32_32x32x16_bf16 v[16:31], v[64:67], v[72:75], v[16:31]
	ds_read_b128 v[64:67], v235 offset:36864
	s_waitcnt lgkmcnt(0)
	v_mfma_f32_32x32x16_bf16 v[32:47], v[64:67], v[68:71], v[32:47]
	v_mfma_f32_32x32x16_bf16 v[0:15], v[64:67], v[72:75], v[0:15]
	ds_read_b128 v[64:67], v237 offset:32768
	ds_read_b128 v[68:71], v238
	ds_read_b128 v[72:75], v238 offset:4096
	s_waitcnt lgkmcnt(0)
	v_mfma_f32_32x32x16_bf16 v[48:63], v[64:67], v[68:71], v[48:63]
	v_mfma_f32_32x32x16_bf16 v[16:31], v[64:67], v[72:75], v[16:31]
	ds_read_b128 v[64:67], v237 offset:36864
	s_waitcnt lgkmcnt(0)
	v_mfma_f32_32x32x16_bf16 v[32:47], v[64:67], v[68:71], v[32:47]
	v_mfma_f32_32x32x16_bf16 v[0:15], v[64:67], v[72:75], v[0:15]
	ds_read_b128 v[64:67], v239 offset:32768
	ds_read_b128 v[68:71], v240
	ds_read_b128 v[72:75], v240 offset:4096
	s_waitcnt lgkmcnt(0)
	v_mfma_f32_32x32x16_bf16 v[48:63], v[64:67], v[68:71], v[48:63]
	v_mfma_f32_32x32x16_bf16 v[16:31], v[64:67], v[72:75], v[16:31]
	ds_read_b128 v[64:67], v239 offset:36864
	s_waitcnt lgkmcnt(0)
	v_mfma_f32_32x32x16_bf16 v[32:47], v[64:67], v[68:71], v[32:47]
	v_mfma_f32_32x32x16_bf16 v[0:15], v[64:67], v[72:75], v[0:15]
	ds_read_b128 v[64:67], v241 offset:32768
	ds_read_b128 v[68:71], v242
	ds_read_b128 v[72:75], v242 offset:4096
	s_waitcnt lgkmcnt(0)
	v_mfma_f32_32x32x16_bf16 v[48:63], v[64:67], v[68:71], v[48:63]
	v_mfma_f32_32x32x16_bf16 v[16:31], v[64:67], v[72:75], v[16:31]
	ds_read_b128 v[64:67], v241 offset:36864
	s_waitcnt vmcnt(0)
	s_waitcnt lgkmcnt(0)
	s_barrier
; #define MFMA(a, b, c) __builtin_amdgcn_mfma_f32_32x32x16_bf16((a), (b), (c), 0, 0, 0)
; DI u16 f2bf(float a) { return (u16)(pk_bf16(a, 0.f) & 0xffffu); }
; DI int crow(int i, int h) { return (i & 3) + 8 * (i >> 2) + 4 * h; }
; DI void gemm_tile(const u16* __restrict__ X, int ldx, const u16* __restrict__ Wt, int ldw, int K, char* smem,
;                   f32x16 (&acc)[2][2]) {
;     ...
; #pragma unroll
;     for (int ks = 0; ks < 4; ++ks) {
;       bf16x8 a[2], b[2];
; #pragma unroll
;       for (int ft = 0; ft < 2; ++ft) a[ft] = *reinterpret_cast<const bf16x8*>(st + offA[ft] + (((ks * 2 + lh) ^ xa[ft]) << 4));
; #pragma unroll
;       for (int tt = 0; tt < 2; ++tt) b[tt] = *reinterpret_cast<const bf16x8*>(st + offB[tt] + (((ks * 2 + lh) ^ xb[tt]) << 4));
; #pragma unroll
;       for (int ft = 0; ft < 2; ++ft)
; #pragma unroll
;         for (int tt = 0; tt < 2; ++tt) acc[ft][tt] = MFMA(a[ft], b[tt], acc[ft][tt]);
;     }
;     if (kt + 2 < nk) { WAIT_V(6); } else { WAIT_V(0); }
;     RAW_BARRIER();
;     cur = (cur == 2) ? 0 : cur + 1;
;   }
; DI void phase_inproj(const Params& p, char* smem) {
;     ...
; #pragma unroll
;       for (int tt = 0; tt < 2; ++tt) {
;         const int tok = mt * 256 + tq * 64 + tt * 32 + lr;
;         const int bb = tok >> 8, mm = tok & 255, hh = nt >> 1, kt = mm >> 5;
;         if (which == 0) {
;           u16* mk = (u16*)(p.ws + OFF_MEMK);
; #pragma unroll
;           for (int ft = 0; ft < 2; ++ft)
; #pragma unroll
;             for (int g = 0; g < 4; ++g) {
;               const int ks = (nt & 1) * 8 + fw * 4 + ft * 2 + (g >> 1), lane2 = (g & 1) * 32 + lr;
;               st4bf(mk + ((((size_t)(bb * 4 + hh) * 8 + kt) * 16 + ks) * 64 + lane2) * 8 + 4 * lh, acc[ft][tt][4 * g], acc[ft][tt][4 * g + 1], acc[ft][tt][4 * g + 2], acc[ft][tt][4 * g + 3]);
;             }
;         } else {
;           u16* mv = (u16*)(p.ws + OFF_MEMVT);
;           const int s = lr >> 4, r16 = lr & 15, j = 4 * (r16 >> 3) + (r16 & 3), lh2 = (r16 >> 2) & 1;
; #pragma unroll
;           for (int ft = 0; ft < 2; ++ft) {
;             const int dt = (nt & 1) * 4 + fw * 2 + ft;
; #pragma unroll
;             for (int i = 0; i < 16; ++i) {
;               const int lane2 = lh2 * 32 + crow(i, lh);
;               mv[((((((size_t)(bb * 4 + hh) * 8 + dt) * 8 + kt) * 2 + s) * 64 + lane2) * 8) + j] = f2bf(acc[ft][tt][i]);
;             }
;           }
	s_waitcnt lgkmcnt(0)
	v_mfma_f32_32x32x16_bf16 v[32:47], v[64:67], v[68:71], v[32:47]
	v_mfma_f32_32x32x16_bf16 v[0:15], v[64:67], v[72:75], v[0:15]
	ds_read_b128 v[64:67], v223 offset:32768
	ds_read_b128 v[68:71], v224
	ds_read_b128 v[72:75], v224 offset:4096
	s_and_b64 vcc, exec, s[6:7]
	s_waitcnt lgkmcnt(0)
	v_mfma_f32_32x32x16_bf16 v[48:63], v[64:67], v[68:71], v[48:63]
	v_mfma_f32_32x32x16_bf16 v[16:31], v[64:67], v[72:75], v[16:31]
	ds_read_b128 v[64:67], v223 offset:36864
	s_waitcnt lgkmcnt(0)
	v_mfma_f32_32x32x16_bf16 v[32:47], v[64:67], v[68:71], v[32:47]
	v_mfma_f32_32x32x16_bf16 v[0:15], v[64:67], v[72:75], v[0:15]
	ds_read_b128 v[64:67], v225 offset:32768
	ds_read_b128 v[68:71], v226
	ds_read_b128 v[72:75], v226 offset:4096
	s_waitcnt lgkmcnt(0)
	v_mfma_f32_32x32x16_bf16 v[48:63], v[64:67], v[68:71], v[48:63]
	v_mfma_f32_32x32x16_bf16 v[16:31], v[64:67], v[72:75], v[16:31]
	ds_read_b128 v[64:67], v225 offset:36864
	s_waitcnt lgkmcnt(0)
	v_mfma_f32_32x32x16_bf16 v[32:47], v[64:67], v[68:71], v[32:47]
	v_mfma_f32_32x32x16_bf16 v[0:15], v[64:67], v[72:75], v[0:15]
	ds_read_b128 v[64:67], v227 offset:32768
	ds_read_b128 v[68:71], v228
	ds_read_b128 v[72:75], v228 offset:4096
	s_waitcnt lgkmcnt(0)
	v_mfma_f32_32x32x16_bf16 v[48:63], v[64:67], v[68:71], v[48:63]
	v_mfma_f32_32x32x16_bf16 v[16:31], v[64:67], v[72:75], v[16:31]
	ds_read_b128 v[64:67], v227 offset:36864
	s_waitcnt lgkmcnt(0)
	v_mfma_f32_32x32x16_bf16 v[32:47], v[64:67], v[68:71], v[32:47]
	v_mfma_f32_32x32x16_bf16 v[0:15], v[64:67], v[72:75], v[0:15]
	ds_read_b128 v[64:67], v229 offset:32768
	ds_read_b128 v[68:71], v230
	ds_read_b128 v[72:75], v230 offset:4096
	ds_read_b128 v[76:79], v229 offset:36864
	s_waitcnt vmcnt(0)
	s_waitcnt lgkmcnt(0)
	s_barrier
	s_waitcnt lgkmcnt(0)
	v_mfma_f32_32x32x16_bf16 v[48:63], v[64:67], v[68:71], v[48:63]
	v_mfma_f32_32x32x16_bf16 v[16:31], v[64:67], v[72:75], v[16:31]
	v_add_u32_e32 v64, s8, v107
	s_lshl_b32 s8, s10, 2
	s_and_b32 s9, s8, 4
	s_and_b32 s8, s8, 24
	v_lshl_or_b32 v64, v64, 5, s8
	v_or3_b32 v65, s9, v109, v64
	s_mov_b64 s[8:9], -1
	v_mfma_f32_32x32x16_bf16 v[32:47], v[76:79], v[68:71], v[32:47]
	v_mfma_f32_32x32x16_bf16 v[0:15], v[76:79], v[72:75], v[0:15]
	s_cbranch_vccz .LBB0_147
	v_lshl_or_b32 v66, v65, 14, v243
	v_mov_b32_e32 v67, v87
	v_lshl_add_u64 v[68:69], v[160:161], 0, v[66:67]
	v_cvt_pk_bf16_f32 v67, v48, s0
	v_lshl_add_u64 v[70:71], v[68:69], 0, v[128:129]
	global_store_short v[70:71], v67, off
	v_cvt_pk_bf16_f32 v67, v49, s0
	v_lshl_add_u64 v[70:71], v[68:69], 0, v[130:131]
	global_store_short v[70:71], v67, off
	v_cvt_pk_bf16_f32 v67, v50, s0
	v_lshl_add_u64 v[70:71], v[68:69], 0, v[132:133]
	global_store_short v[70:71], v67, off
	v_cvt_pk_bf16_f32 v67, v51, s0
	v_lshl_add_u64 v[70:71], v[68:69], 0, v[134:135]
	global_store_short v[70:71], v67, off
	v_cvt_pk_bf16_f32 v67, v52, s0
	v_lshl_add_u64 v[70:71], v[68:69], 0, v[136:137]
	global_store_short v[70:71], v67, off
	v_cvt_pk_bf16_f32 v67, v53, s0
	v_lshl_add_u64 v[70:71], v[68:69], 0, v[138:139]
	global_store_short v[70:71], v67, off
	v_cvt_pk_bf16_f32 v67, v54, s0
	v_lshl_add_u64 v[70:71], v[68:69], 0, v[140:141]
	global_store_short v[70:71], v67, off
	v_cvt_pk_bf16_f32 v67, v55, s0
	v_lshl_add_u64 v[70:71], v[68:69], 0, v[142:143]
	global_store_short v[70:71], v67, off
	v_cvt_pk_bf16_f32 v67, v56, s0
	v_lshl_add_u64 v[70:71], v[68:69], 0, v[144:145]
	global_store_short v[70:71], v67, off
	v_cvt_pk_bf16_f32 v67, v57, s0
	v_lshl_add_u64 v[70:71], v[68:69], 0, v[146:147]
	global_store_short v[70:71], v67, off
	v_cvt_pk_bf16_f32 v67, v58, s0
	v_lshl_add_u64 v[70:71], v[68:69], 0, v[148:149]
	global_store_short v[70:71], v67, off
	v_cvt_pk_bf16_f32 v67, v59, s0
	v_lshl_add_u64 v[70:71], v[68:69], 0, v[150:151]
	global_store_short v[70:71], v67, off
	v_cvt_pk_bf16_f32 v67, v60, s0
	v_lshl_add_u64 v[70:71], v[68:69], 0, v[152:153]
	global_store_short v[70:71], v67, off
	v_cvt_pk_bf16_f32 v67, v61, s0
	v_lshl_add_u64 v[70:71], v[68:69], 0, v[154:155]
	global_store_short v[70:71], v67, off
	v_cvt_pk_bf16_f32 v67, v62, s0
	v_lshl_add_u64 v[70:71], v[68:69], 0, v[156:157]
	global_store_short v[70:71], v67, off
	v_cvt_pk_bf16_f32 v67, v63, s0
	v_lshl_add_u64 v[68:69], v[68:69], 0, v[158:159]
	global_store_short v[68:69], v67, off
	v_or_b32_e32 v66, 0x4000, v66
	v_mov_b32_e32 v67, v87
	v_lshl_add_u64 v[66:67], v[160:161], 0, v[66:67]
	v_cvt_pk_bf16_f32 v70, v32, s0
	v_lshl_add_u64 v[68:69], v[66:67], 0, v[128:129]
	global_store_short v[68:69], v70, off
	v_cvt_pk_bf16_f32 v70, v33, s0
	v_lshl_add_u64 v[68:69], v[66:67], 0, v[130:131]
	global_store_short v[68:69], v70, off
	v_cvt_pk_bf16_f32 v70, v34, s0
	v_lshl_add_u64 v[68:69], v[66:67], 0, v[132:133]
	global_store_short v[68:69], v70, off
	v_cvt_pk_bf16_f32 v70, v35, s0
	v_lshl_add_u64 v[68:69], v[66:67], 0, v[134:135]
	global_store_short v[68:69], v70, off
	v_cvt_pk_bf16_f32 v70, v36, s0
	v_lshl_add_u64 v[68:69], v[66:67], 0, v[136:137]
	global_store_short v[68:69], v70, off
	v_cvt_pk_bf16_f32 v70, v37, s0
	v_lshl_add_u64 v[68:69], v[66:67], 0, v[138:139]
	global_store_short v[68:69], v70, off
	v_cvt_pk_bf16_f32 v70, v38, s0
	v_lshl_add_u64 v[68:69], v[66:67], 0, v[140:141]
	global_store_short v[68:69], v70, off
	v_cvt_pk_bf16_f32 v70, v39, s0
	v_lshl_add_u64 v[68:69], v[66:67], 0, v[142:143]
	global_store_short v[68:69], v70, off
	v_cvt_pk_bf16_f32 v70, v40, s0
	v_lshl_add_u64 v[68:69], v[66:67], 0, v[144:145]
	global_store_short v[68:69], v70, off
	v_cvt_pk_bf16_f32 v70, v41, s0
	v_lshl_add_u64 v[68:69], v[66:67], 0, v[146:147]
	global_store_short v[68:69], v70, off
	v_cvt_pk_bf16_f32 v70, v42, s0
	v_lshl_add_u64 v[68:69], v[66:67], 0, v[148:149]
	global_store_short v[68:69], v70, off
	v_cvt_pk_bf16_f32 v70, v43, s0
	v_lshl_add_u64 v[68:69], v[66:67], 0, v[150:151]
	global_store_short v[68:69], v70, off
	v_cvt_pk_bf16_f32 v70, v44, s0
	v_lshl_add_u64 v[68:69], v[66:67], 0, v[152:153]
	global_store_short v[68:69], v70, off
	v_cvt_pk_bf16_f32 v70, v45, s0
	v_lshl_add_u64 v[68:69], v[66:67], 0, v[154:155]
	global_store_short v[68:69], v70, off
	v_cvt_pk_bf16_f32 v70, v46, s0
	v_lshl_add_u64 v[68:69], v[66:67], 0, v[156:157]
	global_store_short v[68:69], v70, off
	v_cvt_pk_bf16_f32 v68, v47, s0
	v_lshl_add_u64 v[66:67], v[66:67], 0, v[158:159]
	global_store_short v[66:67], v68, off
	s_mov_b64 s[8:9], 0

; #define MFMA(a, b, c) __builtin_amdgcn_mfma_f32_32x32x16_bf16((a), (b), (c), 0, 0, 0)
; #define WAIT_V(n) asm volatile("s_waitcnt vmcnt(%0)" ::"n"(n) : "memory")
; DI void gemm_tile(const u16* __restrict__ X, int ldx, const u16* __restrict__ Wt, int ldw, int K, char* smem,
;                   f32x16 (&acc)[2][2]) {
;     ...
;   const int nk = K / 64;
;   const u16* src[6];
; #pragma unroll
;   for (int i = 0; i < 6; ++i) {
;     const int R = 8 * (wave + 8 * i) + (lane >> 3);
;     const int c = (lane & 7) ^ ((R >> 1) & 7);
;     src[i] = (i < 4) ? (X + (size_t)R * ldx + c * 8) : (Wt + (size_t)(R - 256) * ldw + c * 8);
;   }
;     ...
;   int offA[2], offB[2], xa[2], xb[2];
; #pragma unroll
;   for (int ft = 0; ft < 2; ++ft) { const int R = 256 + fw * 64 + ft * 32 + lr; offA[ft] = R * 128; xa[ft] = (R >> 1) & 7; }
; #pragma unroll
;   for (int tt = 0; tt < 2; ++tt) { const int R = tq * 64 + tt * 32 + lr; offB[tt] = R * 128; xb[tt] = (R >> 1) & 7; }
;   GLDS_STAGE(0, 0); GLDS_STAGE(1, 1); WAIT_V(6); RAW_BARRIER();
;   int cur = 0;
;   for (int kt = 0; kt < nk; ++kt) {
;     const int nxt = (cur >= 1) ? cur - 1 : 2;
;     if (kt + 2 < nk) GLDS_STAGE(nxt, kt + 2);
;     __builtin_amdgcn_sched_barrier(0);
;     const char* st = smem + cur * G_STAGE;
; #pragma unroll
;     for (int ks = 0; ks < 4; ++ks) {
;       bf16x8 a[2], b[2];
; #pragma unroll
;       for (int ft = 0; ft < 2; ++ft) a[ft] = *reinterpret_cast<const bf16x8*>(st + offA[ft] + (((ks * 2 + lh) ^ xa[ft]) << 4));
; #pragma unroll
;       for (int tt = 0; tt < 2; ++tt) b[tt] = *reinterpret_cast<const bf16x8*>(st + offB[tt] + (((ks * 2 + lh) ^ xb[tt]) << 4));
; #pragma unroll
;       for (int ft = 0; ft < 2; ++ft)
; #pragma unroll
;         for (int tt = 0; tt < 2; ++tt) acc[ft][tt] = MFMA(a[ft], b[tt], acc[ft][tt]);
;     }
;     if (kt + 2 < nk) { WAIT_V(6); } else { WAIT_V(0); }
;     RAW_BARRIER();
; template <int MODE>
; DI void phase_gemm(const Params& p, const u16* X, const u16* Wt, int N, const float* resid, float* outf, u16* outb, int ldo, char* smem) {
;     ...
;   for (int u = xi; u < per_group; u += xn) {
;     const int mt = xg + 8 * (u / ntn), nt = u % ntn;
;     f32x16 acc[2][2];
;     gemm_tile(X + (size_t)mt * 256 * 1024, 1024, Wt + (size_t)nt * 128 * 1024, 1024, 1024, smem, acc);
.LBB0_566:
	s_lshl_b32 s0, s77, 8
	s_and_b32 s0, s0, 0x7800
	s_and_b32 s4, s3, 7
	v_add_u32_e32 v0, s0, v105
	v_lshl_or_b32 v1, s4, 9, v108
	v_lshl_or_b32 v64, v0, 12, v1
	v_add_u32_e32 v0, s0, v106
	v_lshl_add_u64 v[72:73], s[82:83], 0, v[64:65]
	v_lshl_add_u64 v[74:75], s[80:81], 0, v[64:65]
	v_lshl_or_b32 v64, v0, 12, v1
	v_add_u32_e32 v0, s0, v107
	v_lshl_add_u64 v[76:77], s[82:83], 0, v[64:65]
	v_lshl_add_u64 v[78:79], s[80:81], 0, v[64:65]
	v_lshl_or_b32 v64, v0, 12, v1
	v_add_u32_e32 v0, s0, v104
	s_and_b32 s0, s77, 0x78
	s_or_b32 s0, s0, s33
	s_and_b32 s6, s77, 7
	s_lshl_b32 s0, s0, 19
	v_lshl_add_u64 v[80:81], s[82:83], 0, v[64:65]
	v_lshl_add_u64 v[82:83], s[80:81], 0, v[64:65]
	v_lshl_or_b32 v64, v0, 12, v1
	v_lshl_add_u64 v[0:1], v[66:67], 0, s[0:1]
	s_lshl_b32 s0, s6, 18
	v_readfirstlane_b32 s6, v143
	v_lshl_add_u64 v[88:89], v[0:1], 0, v[70:71]
	s_mov_b32 m0, s6
	v_readfirstlane_b32 s86, v109
	v_lshl_add_u64 v[0:1], v[88:89], 0, s[8:9]
	s_mov_b64 s[4:5], 0x40000
	global_load_lds_dwordx4 v[88:89], off
	s_mov_b32 m0, s86
	v_readfirstlane_b32 s85, v110
	v_lshl_add_u64 v[2:3], v[88:89], 0, s[4:5]
	s_mov_b64 s[4:5], 0x60000
	global_load_lds_dwordx4 v[0:1], off
	s_mov_b32 m0, s85
	v_readfirstlane_b32 s84, v111
	v_lshl_add_u64 v[4:5], v[88:89], 0, s[4:5]
	v_lshl_add_u64 v[6:7], v[68:69], 0, s[0:1]
	global_load_lds_dwordx4 v[2:3], off
	s_mov_b32 m0, s84
	v_readfirstlane_b32 s79, v112
	v_lshl_add_u64 v[90:91], v[6:7], 0, v[70:71]
	global_load_lds_dwordx4 v[4:5], off
	s_mov_b32 m0, s79
	v_readfirstlane_b32 s55, v113
	v_lshl_add_u64 v[6:7], v[90:91], 0, s[8:9]
	global_load_lds_dwordx4 v[90:91], off
	s_mov_b32 m0, s55
	v_readfirstlane_b32 s54, v92
	global_load_lds_dwordx4 v[6:7], off
	v_lshl_add_u64 v[0:1], v[88:89], 0, s[10:11]
	s_mov_b32 m0, s54
	v_readfirstlane_b32 s0, v114
	global_load_lds_dwordx4 v[0:1], off
	v_lshl_add_u64 v[0:1], v[88:89], 0, s[14:15]
	s_mov_b32 m0, s0
	s_mov_b64 s[4:5], 0x40080
	global_load_lds_dwordx4 v[0:1], off
	v_lshl_add_u64 v[0:1], v[88:89], 0, s[4:5]
	v_readfirstlane_b32 s4, v115
	s_mov_b32 m0, s4
	s_mov_b64 s[4:5], 0x60080
	global_load_lds_dwordx4 v[0:1], off
	v_lshl_add_u64 v[0:1], v[88:89], 0, s[4:5]
	v_readfirstlane_b32 s4, v116
	s_mov_b32 m0, s4
	v_readfirstlane_b32 s4, v117
	global_load_lds_dwordx4 v[0:1], off
	v_lshl_add_u64 v[0:1], v[90:91], 0, s[10:11]
	s_mov_b32 m0, s4
	v_readfirstlane_b32 s4, v118
	global_load_lds_dwordx4 v[0:1], off
	v_lshl_add_u64 v[0:1], v[90:91], 0, s[14:15]
	s_mov_b32 m0, s4
	v_readfirstlane_b32 s4, v93
	global_load_lds_dwordx4 v[0:1], off
	s_waitcnt vmcnt(6)
	s_waitcnt lgkmcnt(0)
	s_barrier
	v_lshl_add_u64 v[0:1], v[88:89], 0, s[16:17]
	s_mov_b32 m0, s4
	v_readfirstlane_b32 s90, v94
	global_load_lds_dwordx4 v[0:1], off
	v_lshl_add_u64 v[0:1], v[88:89], 0, s[18:19]
	s_mov_b32 m0, s90
	s_mov_b64 s[88:89], 0x40100
	global_load_lds_dwordx4 v[0:1], off
	v_lshl_add_u64 v[0:1], v[88:89], 0, s[88:89]
	v_readfirstlane_b32 s88, v95
	s_mov_b32 m0, s88
	s_mov_b64 s[92:93], 0x60100
	v_readfirstlane_b32 s89, v96
	global_load_lds_dwordx4 v[0:1], off
	v_lshl_add_u64 v[0:1], v[88:89], 0, s[92:93]
	s_mov_b32 m0, s89
	v_readfirstlane_b32 s7, v97
	global_load_lds_dwordx4 v[0:1], off
	v_lshl_add_u64 v[0:1], v[90:91], 0, s[16:17]
	s_mov_b32 m0, s7
	v_readfirstlane_b32 s87, v98
	global_load_lds_dwordx4 v[0:1], off
	v_lshl_add_u64 v[0:1], v[90:91], 0, s[18:19]
	s_mov_b32 m0, s87
	v_lshl_add_u64 v[84:85], s[80:81], 0, v[64:65]
	global_load_lds_dwordx4 v[0:1], off
	v_lshl_add_u64 v[86:87], s[82:83], 0, v[64:65]
	ds_read_b128 v[0:3], v119 offset:32768
	ds_read_b128 v[4:7], v119 offset:36864
	ds_read_b128 v[8:11], v120
	ds_read_b128 v[12:15], v120 offset:4096
	ds_read_b128 v[150:153], v121 offset:32768
	ds_read_b128 v[154:157], v121 offset:36864
	ds_read_b128 v[158:161], v122
	ds_read_b128 v[180:183], v122 offset:4096
	s_mov_b32 m0, s6
	s_mov_b64 s[92:93], 0x40180
	s_waitcnt lgkmcnt(0)
	v_mfma_f32_32x32x16_bf16 v[48:63], v[0:3], v[8:11], 0
	v_mfma_f32_32x32x16_bf16 v[16:31], v[0:3], v[12:15], 0
	s_waitcnt vmcnt(0)
	v_mfma_f32_32x32x16_bf16 v[32:47], v[4:7], v[8:11], 0
	v_mfma_f32_32x32x16_bf16 v[0:15], v[4:7], v[12:15], 0
	ds_read_b128 v[184:187], v123 offset:32768
	ds_read_b128 v[188:191], v123 offset:36864
	ds_read_b128 v[192:195], v124
	ds_read_b128 v[196:199], v124 offset:4096
	s_waitcnt lgkmcnt(4)
	v_mfma_f32_32x32x16_bf16 v[48:63], v[150:153], v[158:161], v[48:63]
	v_mfma_f32_32x32x16_bf16 v[16:31], v[150:153], v[180:183], v[16:31]
	v_mfma_f32_32x32x16_bf16 v[32:47], v[154:157], v[158:161], v[32:47]
	v_mfma_f32_32x32x16_bf16 v[0:15], v[154:157], v[180:183], v[0:15]
	ds_read_b128 v[150:153], v125 offset:32768
	ds_read_b128 v[154:157], v125 offset:36864
	ds_read_b128 v[158:161], v126
	ds_read_b128 v[180:183], v126 offset:4096
	s_waitcnt lgkmcnt(4)
	v_mfma_f32_32x32x16_bf16 v[48:63], v[184:187], v[192:195], v[48:63]
	v_mfma_f32_32x32x16_bf16 v[16:31], v[184:187], v[196:199], v[16:31]
	v_mfma_f32_32x32x16_bf16 v[32:47], v[188:191], v[192:195], v[32:47]
	v_mfma_f32_32x32x16_bf16 v[0:15], v[188:191], v[196:199], v[0:15]
	s_waitcnt vmcnt(6)
	s_waitcnt lgkmcnt(0)
	s_barrier
; #define MFMA(a, b, c) __builtin_amdgcn_mfma_f32_32x32x16_bf16((a), (b), (c), 0, 0, 0)
; #define WAIT_V(n) asm volatile("s_waitcnt vmcnt(%0)" ::"n"(n) : "memory")
; #define RAW_BARRIER() do { asm volatile("s_waitcnt lgkmcnt(0)" ::: "memory"); __builtin_amdgcn_s_barrier(); asm volatile("" ::: "memory"); } while (0)
; #define GLDS_STAGE(slot, kt) do { _Pragma("unroll") for (int i = 0; i < 6; ++i) \
;     __builtin_amdgcn_global_load_lds((const unsigned*)(src[i] + (kt) * 64), (__attribute__((address_space(3))) unsigned*)(smem + (slot) * G_STAGE + (wave + 8 * i) * 1024), 16, 0, 0); } while (0)
; DI void gemm_tile(const u16* __restrict__ X, int ldx, const u16* __restrict__ Wt, int ldw, int K, char* smem,
;                   f32x16 (&acc)[2][2]) {
;     ...
;   for (int kt = 0; kt < nk; ++kt) {
;     const int nxt = (cur >= 1) ? cur - 1 : 2;
;     if (kt + 2 < nk) GLDS_STAGE(nxt, kt + 2);
;     __builtin_amdgcn_sched_barrier(0);
;     const char* st = smem + cur * G_STAGE;
; #pragma unroll
;     for (int ks = 0; ks < 4; ++ks) {
;       bf16x8 a[2], b[2];
; #pragma unroll
;       for (int ft = 0; ft < 2; ++ft) a[ft] = *reinterpret_cast<const bf16x8*>(st + offA[ft] + (((ks * 2 + lh) ^ xa[ft]) << 4));
; #pragma unroll
;       for (int tt = 0; tt < 2; ++tt) b[tt] = *reinterpret_cast<const bf16x8*>(st + offB[tt] + (((ks * 2 + lh) ^ xb[tt]) << 4));
; #pragma unroll
;       for (int ft = 0; ft < 2; ++ft)
; #pragma unroll
;         for (int tt = 0; tt < 2; ++tt) acc[ft][tt] = MFMA(a[ft], b[tt], acc[ft][tt]);
;     }
;     if (kt + 2 < nk) { WAIT_V(6); } else { WAIT_V(0); }
;     RAW_BARRIER();
;     cur = (cur == 2) ? 0 : cur + 1;
	ds_read_b128 v[184:187], v127 offset:32768
	ds_read_b128 v[188:191], v127 offset:36864
	ds_read_b128 v[192:195], v120 offset:49152
	ds_read_b128 v[196:199], v120 offset:53248
	s_waitcnt lgkmcnt(4)
	v_mfma_f32_32x32x16_bf16 v[48:63], v[150:153], v[158:161], v[48:63]
	v_mfma_f32_32x32x16_bf16 v[16:31], v[150:153], v[180:183], v[16:31]
	v_lshl_add_u64 v[150:151], v[88:89], 0, s[20:21]
	global_load_lds_dwordx4 v[150:151], off
	v_lshl_add_u64 v[150:151], v[88:89], 0, s[22:23]
	s_mov_b32 m0, s86
	s_nop 0
	global_load_lds_dwordx4 v[150:151], off
	v_lshl_add_u64 v[150:151], v[88:89], 0, s[92:93]
	s_mov_b32 m0, s85
	s_mov_b64 s[92:93], 0x60180
	global_load_lds_dwordx4 v[150:151], off
	v_lshl_add_u64 v[150:151], v[88:89], 0, s[92:93]
	s_mov_b32 m0, s84
	v_mfma_f32_32x32x16_bf16 v[0:15], v[154:157], v[180:183], v[0:15]
	global_load_lds_dwordx4 v[150:151], off
	v_lshl_add_u64 v[150:151], v[90:91], 0, s[20:21]
	s_mov_b32 m0, s79
	s_nop 0
	global_load_lds_dwordx4 v[150:151], off
	v_lshl_add_u64 v[150:151], v[90:91], 0, s[22:23]
	s_mov_b32 m0, s55
	v_mfma_f32_32x32x16_bf16 v[32:47], v[154:157], v[158:161], v[32:47]
	global_load_lds_dwordx4 v[150:151], off
	s_mov_b32 m0, s54
	s_mov_b64 s[92:93], 0x40200
	v_readfirstlane_b32 s91, v99
	ds_read_b128 v[150:153], v128 offset:32768
	ds_read_b128 v[154:157], v128 offset:36864
	ds_read_b128 v[158:161], v122 offset:49152
	ds_read_b128 v[180:183], v122 offset:53248
	s_waitcnt lgkmcnt(4)
	v_mfma_f32_32x32x16_bf16 v[48:63], v[184:187], v[192:195], v[48:63]
	v_readfirstlane_b32 s95, v102
	v_mfma_f32_32x32x16_bf16 v[16:31], v[184:187], v[196:199], v[16:31]
	v_mfma_f32_32x32x16_bf16 v[32:47], v[188:191], v[192:195], v[32:47]
	v_mfma_f32_32x32x16_bf16 v[0:15], v[188:191], v[196:199], v[0:15]
	ds_read_b128 v[184:187], v129 offset:32768
	ds_read_b128 v[188:191], v129 offset:36864
	ds_read_b128 v[192:195], v124 offset:49152
	ds_read_b128 v[196:199], v124 offset:53248
	s_waitcnt lgkmcnt(4)
	v_mfma_f32_32x32x16_bf16 v[48:63], v[150:153], v[158:161], v[48:63]
	v_mfma_f32_32x32x16_bf16 v[16:31], v[150:153], v[180:183], v[16:31]
	v_mfma_f32_32x32x16_bf16 v[32:47], v[154:157], v[158:161], v[32:47]
	v_mfma_f32_32x32x16_bf16 v[0:15], v[154:157], v[180:183], v[0:15]
	ds_read_b128 v[150:153], v130 offset:32768
	ds_read_b128 v[154:157], v130 offset:36864
	ds_read_b128 v[158:161], v126 offset:49152
	ds_read_b128 v[180:183], v126 offset:53248
	s_waitcnt lgkmcnt(4)
	v_mfma_f32_32x32x16_bf16 v[48:63], v[184:187], v[192:195], v[48:63]
	v_mfma_f32_32x32x16_bf16 v[16:31], v[184:187], v[196:199], v[16:31]
	v_mfma_f32_32x32x16_bf16 v[32:47], v[188:191], v[192:195], v[32:47]
	v_mfma_f32_32x32x16_bf16 v[0:15], v[188:191], v[196:199], v[0:15]
	s_waitcnt vmcnt(6)
	s_waitcnt lgkmcnt(0)
	s_barrier
	ds_read_b128 v[184:187], v131 offset:32768
	ds_read_b128 v[188:191], v131 offset:36864
	ds_read_b128 v[192:195], v132
	ds_read_b128 v[196:199], v132 offset:4096
	s_waitcnt lgkmcnt(4)
	v_mfma_f32_32x32x16_bf16 v[48:63], v[150:153], v[158:161], v[48:63]
	v_mfma_f32_32x32x16_bf16 v[16:31], v[150:153], v[180:183], v[16:31]
	v_lshl_add_u64 v[150:151], v[88:89], 0, s[24:25]
	global_load_lds_dwordx4 v[150:151], off
	v_lshl_add_u64 v[150:151], v[88:89], 0, s[26:27]
	s_mov_b32 m0, s0
	s_nop 0
	global_load_lds_dwordx4 v[150:151], off
	v_lshl_add_u64 v[150:151], v[88:89], 0, s[92:93]
	s_mov_b32 m0, s91
	s_mov_b64 s[92:93], 0x60200
	global_load_lds_dwordx4 v[150:151], off
	v_lshl_add_u64 v[150:151], v[88:89], 0, s[92:93]
	v_readfirstlane_b32 s93, v100
	s_mov_b32 m0, s93
	v_readfirstlane_b32 s92, v101
	global_load_lds_dwordx4 v[150:151], off
	v_lshl_add_u64 v[150:151], v[90:91], 0, s[24:25]
	s_mov_b32 m0, s92
	v_mfma_f32_32x32x16_bf16 v[0:15], v[154:157], v[180:183], v[0:15]
	global_load_lds_dwordx4 v[150:151], off
	v_lshl_add_u64 v[150:151], v[90:91], 0, s[26:27]
	s_mov_b32 m0, s95
	s_nop 0
	global_load_lds_dwordx4 v[150:151], off
	v_mfma_f32_32x32x16_bf16 v[32:47], v[154:157], v[158:161], v[32:47]
	s_mov_b32 m0, s4
	s_mov_b64 vcc, 0x40280
	ds_read_b128 v[150:153], v133 offset:32768
	ds_read_b128 v[154:157], v133 offset:36864
	ds_read_b128 v[158:161], v134
	ds_read_b128 v[180:183], v134 offset:4096
	s_waitcnt lgkmcnt(4)
	v_mfma_f32_32x32x16_bf16 v[48:63], v[184:187], v[192:195], v[48:63]
	v_mfma_f32_32x32x16_bf16 v[16:31], v[184:187], v[196:199], v[16:31]
	v_mfma_f32_32x32x16_bf16 v[32:47], v[188:191], v[192:195], v[32:47]
	v_mfma_f32_32x32x16_bf16 v[0:15], v[188:191], v[196:199], v[0:15]
	ds_read_b128 v[184:187], v135 offset:32768
	ds_read_b128 v[188:191], v135 offset:36864
	ds_read_b128 v[192:195], v136
	ds_read_b128 v[196:199], v136 offset:4096
	s_waitcnt lgkmcnt(4)
	v_mfma_f32_32x32x16_bf16 v[48:63], v[150:153], v[158:161], v[48:63]
	v_mfma_f32_32x32x16_bf16 v[16:31], v[150:153], v[180:183], v[16:31]
	v_mfma_f32_32x32x16_bf16 v[32:47], v[154:157], v[158:161], v[32:47]
	v_mfma_f32_32x32x16_bf16 v[0:15], v[154:157], v[180:183], v[0:15]
	ds_read_b128 v[150:153], v137 offset:32768
	ds_read_b128 v[154:157], v137 offset:36864
	ds_read_b128 v[158:161], v138
	ds_read_b128 v[180:183], v138 offset:4096
	s_waitcnt lgkmcnt(4)
	v_mfma_f32_32x32x16_bf16 v[48:63], v[184:187], v[192:195], v[48:63]
	v_mfma_f32_32x32x16_bf16 v[16:31], v[184:187], v[196:199], v[16:31]
	v_mfma_f32_32x32x16_bf16 v[32:47], v[188:191], v[192:195], v[32:47]
	v_mfma_f32_32x32x16_bf16 v[0:15], v[188:191], v[196:199], v[0:15]
	s_waitcnt vmcnt(6)
	s_waitcnt lgkmcnt(0)
	s_barrier
; #define MFMA(a, b, c) __builtin_amdgcn_mfma_f32_32x32x16_bf16((a), (b), (c), 0, 0, 0)
; #define WAIT_V(n) asm volatile("s_waitcnt vmcnt(%0)" ::"n"(n) : "memory")
; #define RAW_BARRIER() do { asm volatile("s_waitcnt lgkmcnt(0)" ::: "memory"); __builtin_amdgcn_s_barrier(); asm volatile("" ::: "memory"); } while (0)
; #define GLDS_STAGE(slot, kt) do { _Pragma("unroll") for (int i = 0; i < 6; ++i) \
;     __builtin_amdgcn_global_load_lds((const unsigned*)(src[i] + (kt) * 64), (__attribute__((address_space(3))) unsigned*)(smem + (slot) * G_STAGE + (wave + 8 * i) * 1024), 16, 0, 0); } while (0)
; DI void gemm_tile(const u16* __restrict__ X, int ldx, const u16* __restrict__ Wt, int ldw, int K, char* smem,
;                   f32x16 (&acc)[2][2]) {
;     ...
;   for (int kt = 0; kt < nk; ++kt) {
;     const int nxt = (cur >= 1) ? cur - 1 : 2;
;     if (kt + 2 < nk) GLDS_STAGE(nxt, kt + 2);
;     __builtin_amdgcn_sched_barrier(0);
;     const char* st = smem + cur * G_STAGE;
; #pragma unroll
;     for (int ks = 0; ks < 4; ++ks) {
;       bf16x8 a[2], b[2];
; #pragma unroll
;       for (int ft = 0; ft < 2; ++ft) a[ft] = *reinterpret_cast<const bf16x8*>(st + offA[ft] + (((ks * 2 + lh) ^ xa[ft]) << 4));
; #pragma unroll
;       for (int tt = 0; tt < 2; ++tt) b[tt] = *reinterpret_cast<const bf16x8*>(st + offB[tt] + (((ks * 2 + lh) ^ xb[tt]) << 4));
; #pragma unroll
;       for (int ft = 0; ft < 2; ++ft)
; #pragma unroll
;         for (int tt = 0; tt < 2; ++tt) acc[ft][tt] = MFMA(a[ft], b[tt], acc[ft][tt]);
;     }
;     if (kt + 2 < nk) { WAIT_V(6); } else { WAIT_V(0); }
;     RAW_BARRIER();
;     cur = (cur == 2) ? 0 : cur + 1;
	ds_read_b128 v[184:187], v119 offset:32768
	ds_read_b128 v[188:191], v119 offset:36864
	ds_read_b128 v[192:195], v120
	ds_read_b128 v[196:199], v120 offset:4096
	s_waitcnt lgkmcnt(4)
	v_mfma_f32_32x32x16_bf16 v[48:63], v[150:153], v[158:161], v[48:63]
	v_mfma_f32_32x32x16_bf16 v[16:31], v[150:153], v[180:183], v[16:31]
	v_lshl_add_u64 v[150:151], v[88:89], 0, s[28:29]
	global_load_lds_dwordx4 v[150:151], off
	v_lshl_add_u64 v[150:151], v[88:89], 0, s[30:31]
	s_mov_b32 m0, s90
	s_nop 0
	global_load_lds_dwordx4 v[150:151], off
	v_lshl_add_u64 v[150:151], v[88:89], 0, vcc
	s_mov_b32 m0, s88
	s_mov_b64 vcc, 0x60280
	global_load_lds_dwordx4 v[150:151], off
	v_lshl_add_u64 v[150:151], v[88:89], 0, vcc
	s_mov_b32 m0, s89
	v_mfma_f32_32x32x16_bf16 v[0:15], v[154:157], v[180:183], v[0:15]
	global_load_lds_dwordx4 v[150:151], off
	v_lshl_add_u64 v[150:151], v[90:91], 0, s[28:29]
	s_mov_b32 m0, s7
	s_nop 0
	global_load_lds_dwordx4 v[150:151], off
	v_lshl_add_u64 v[150:151], v[90:91], 0, s[30:31]
	s_mov_b32 m0, s87
	v_mfma_f32_32x32x16_bf16 v[32:47], v[154:157], v[158:161], v[32:47]
	global_load_lds_dwordx4 v[150:151], off
	s_mov_b32 m0, s6
	s_mov_b64 vcc, 0x40300
	ds_read_b128 v[150:153], v121 offset:32768
	ds_read_b128 v[154:157], v121 offset:36864
	ds_read_b128 v[158:161], v122
	ds_read_b128 v[180:183], v122 offset:4096
	s_waitcnt lgkmcnt(4)
	v_mfma_f32_32x32x16_bf16 v[48:63], v[184:187], v[192:195], v[48:63]
	v_mfma_f32_32x32x16_bf16 v[16:31], v[184:187], v[196:199], v[16:31]
	v_mfma_f32_32x32x16_bf16 v[32:47], v[188:191], v[192:195], v[32:47]
	v_mfma_f32_32x32x16_bf16 v[0:15], v[188:191], v[196:199], v[0:15]
	ds_read_b128 v[184:187], v123 offset:32768
	ds_read_b128 v[188:191], v123 offset:36864
	ds_read_b128 v[192:195], v124
	ds_read_b128 v[196:199], v124 offset:4096
	s_waitcnt lgkmcnt(4)
	v_mfma_f32_32x32x16_bf16 v[48:63], v[150:153], v[158:161], v[48:63]
	v_mfma_f32_32x32x16_bf16 v[16:31], v[150:153], v[180:183], v[16:31]
	v_mfma_f32_32x32x16_bf16 v[32:47], v[154:157], v[158:161], v[32:47]
	v_mfma_f32_32x32x16_bf16 v[0:15], v[154:157], v[180:183], v[0:15]
	ds_read_b128 v[150:153], v125 offset:32768
	ds_read_b128 v[154:157], v125 offset:36864
	ds_read_b128 v[158:161], v126
	ds_read_b128 v[180:183], v126 offset:4096
	s_waitcnt lgkmcnt(4)
	v_mfma_f32_32x32x16_bf16 v[48:63], v[184:187], v[192:195], v[48:63]
	v_mfma_f32_32x32x16_bf16 v[16:31], v[184:187], v[196:199], v[16:31]
	v_mfma_f32_32x32x16_bf16 v[32:47], v[188:191], v[192:195], v[32:47]
	v_mfma_f32_32x32x16_bf16 v[0:15], v[188:191], v[196:199], v[0:15]
	s_waitcnt vmcnt(6)
	s_waitcnt lgkmcnt(0)
	s_barrier
	ds_read_b128 v[184:187], v127 offset:32768
	ds_read_b128 v[188:191], v127 offset:36864
	ds_read_b128 v[192:195], v120 offset:49152
	ds_read_b128 v[196:199], v120 offset:53248
	s_waitcnt lgkmcnt(4)
	v_mfma_f32_32x32x16_bf16 v[48:63], v[150:153], v[158:161], v[48:63]
	v_mfma_f32_32x32x16_bf16 v[16:31], v[150:153], v[180:183], v[16:31]
	v_lshl_add_u64 v[150:151], v[88:89], 0, s[34:35]
	global_load_lds_dwordx4 v[150:151], off
	v_lshl_add_u64 v[150:151], v[88:89], 0, s[36:37]
	s_mov_b32 m0, s86
	s_nop 0
	global_load_lds_dwordx4 v[150:151], off
	v_lshl_add_u64 v[150:151], v[88:89], 0, vcc
	s_mov_b32 m0, s85
	s_mov_b64 vcc, 0x60300
	global_load_lds_dwordx4 v[150:151], off
	v_lshl_add_u64 v[150:151], v[88:89], 0, vcc
	s_mov_b32 m0, s84
	v_mfma_f32_32x32x16_bf16 v[0:15], v[154:157], v[180:183], v[0:15]
	global_load_lds_dwordx4 v[150:151], off
	v_lshl_add_u64 v[150:151], v[90:91], 0, s[34:35]
	s_mov_b32 m0, s79
	s_nop 0
	global_load_lds_dwordx4 v[150:151], off
	v_lshl_add_u64 v[150:151], v[90:91], 0, s[36:37]
	s_mov_b32 m0, s55
	v_mfma_f32_32x32x16_bf16 v[32:47], v[154:157], v[158:161], v[32:47]
	global_load_lds_dwordx4 v[150:151], off
	s_mov_b32 m0, s54
	s_mov_b64 vcc, 0x40380
	ds_read_b128 v[150:153], v128 offset:32768
	ds_read_b128 v[154:157], v128 offset:36864
	ds_read_b128 v[158:161], v122 offset:49152
	ds_read_b128 v[180:183], v122 offset:53248
	s_waitcnt lgkmcnt(4)
	v_mfma_f32_32x32x16_bf16 v[48:63], v[184:187], v[192:195], v[48:63]
	v_mfma_f32_32x32x16_bf16 v[16:31], v[184:187], v[196:199], v[16:31]
	v_mfma_f32_32x32x16_bf16 v[32:47], v[188:191], v[192:195], v[32:47]
	v_mfma_f32_32x32x16_bf16 v[0:15], v[188:191], v[196:199], v[0:15]
	ds_read_b128 v[184:187], v129 offset:32768
	ds_read_b128 v[188:191], v129 offset:36864
	ds_read_b128 v[192:195], v124 offset:49152
	ds_read_b128 v[196:199], v124 offset:53248
	s_waitcnt lgkmcnt(4)
	v_mfma_f32_32x32x16_bf16 v[48:63], v[150:153], v[158:161], v[48:63]
	v_mfma_f32_32x32x16_bf16 v[16:31], v[150:153], v[180:183], v[16:31]
	v_mfma_f32_32x32x16_bf16 v[32:47], v[154:157], v[158:161], v[32:47]
	v_mfma_f32_32x32x16_bf16 v[0:15], v[154:157], v[180:183], v[0:15]
	ds_read_b128 v[150:153], v130 offset:32768
	ds_read_b128 v[154:157], v130 offset:36864
	ds_read_b128 v[158:161], v126 offset:49152
	ds_read_b128 v[180:183], v126 offset:53248
	s_waitcnt lgkmcnt(4)
	v_mfma_f32_32x32x16_bf16 v[48:63], v[184:187], v[192:195], v[48:63]
	v_mfma_f32_32x32x16_bf16 v[16:31], v[184:187], v[196:199], v[16:31]
	v_mfma_f32_32x32x16_bf16 v[32:47], v[188:191], v[192:195], v[32:47]
	v_mfma_f32_32x32x16_bf16 v[0:15], v[188:191], v[196:199], v[0:15]
	s_waitcnt vmcnt(6)
	s_waitcnt lgkmcnt(0)
	s_barrier
; #define MFMA(a, b, c) __builtin_amdgcn_mfma_f32_32x32x16_bf16((a), (b), (c), 0, 0, 0)
; #define WAIT_V(n) asm volatile("s_waitcnt vmcnt(%0)" ::"n"(n) : "memory")
; #define RAW_BARRIER() do { asm volatile("s_waitcnt lgkmcnt(0)" ::: "memory"); __builtin_amdgcn_s_barrier(); asm volatile("" ::: "memory"); } while (0)
; #define GLDS_STAGE(slot, kt) do { _Pragma("unroll") for (int i = 0; i < 6; ++i) \
;     __builtin_amdgcn_global_load_lds((const unsigned*)(src[i] + (kt) * 64), (__attribute__((address_space(3))) unsigned*)(smem + (slot) * G_STAGE + (wave + 8 * i) * 1024), 16, 0, 0); } while (0)
; DI void gemm_tile(const u16* __restrict__ X, int ldx, const u16* __restrict__ Wt, int ldw, int K, char* smem,
;                   f32x16 (&acc)[2][2]) {
;     ...
;   for (int kt = 0; kt < nk; ++kt) {
;     const int nxt = (cur >= 1) ? cur - 1 : 2;
;     if (kt + 2 < nk) GLDS_STAGE(nxt, kt + 2);
;     __builtin_amdgcn_sched_barrier(0);
;     const char* st = smem + cur * G_STAGE;
; #pragma unroll
;     for (int ks = 0; ks < 4; ++ks) {
;       bf16x8 a[2], b[2];
; #pragma unroll
;       for (int ft = 0; ft < 2; ++ft) a[ft] = *reinterpret_cast<const bf16x8*>(st + offA[ft] + (((ks * 2 + lh) ^ xa[ft]) << 4));
; #pragma unroll
;       for (int tt = 0; tt < 2; ++tt) b[tt] = *reinterpret_cast<const bf16x8*>(st + offB[tt] + (((ks * 2 + lh) ^ xb[tt]) << 4));
; #pragma unroll
;       for (int ft = 0; ft < 2; ++ft)
; #pragma unroll
;         for (int tt = 0; tt < 2; ++tt) acc[ft][tt] = MFMA(a[ft], b[tt], acc[ft][tt]);
;     }
;     if (kt + 2 < nk) { WAIT_V(6); } else { WAIT_V(0); }
;     RAW_BARRIER();
;     cur = (cur == 2) ? 0 : cur + 1;
	ds_read_b128 v[184:187], v131 offset:32768
	ds_read_b128 v[188:191], v131 offset:36864
	ds_read_b128 v[192:195], v132
	ds_read_b128 v[196:199], v132 offset:4096
	s_waitcnt lgkmcnt(4)
	v_mfma_f32_32x32x16_bf16 v[48:63], v[150:153], v[158:161], v[48:63]
	v_mfma_f32_32x32x16_bf16 v[16:31], v[150:153], v[180:183], v[16:31]
	v_lshl_add_u64 v[150:151], v[88:89], 0, s[38:39]
	global_load_lds_dwordx4 v[150:151], off
	v_lshl_add_u64 v[150:151], v[88:89], 0, s[40:41]
	s_mov_b32 m0, s0
	s_nop 0
	global_load_lds_dwordx4 v[150:151], off
	v_lshl_add_u64 v[150:151], v[88:89], 0, vcc
	s_mov_b32 m0, s91
	s_mov_b64 vcc, 0x60380
	global_load_lds_dwordx4 v[150:151], off
	v_lshl_add_u64 v[150:151], v[88:89], 0, vcc
	s_mov_b32 m0, s93
	v_mfma_f32_32x32x16_bf16 v[0:15], v[154:157], v[180:183], v[0:15]
	global_load_lds_dwordx4 v[150:151], off
	v_lshl_add_u64 v[150:151], v[90:91], 0, s[38:39]
	s_mov_b32 m0, s92
	s_nop 0
	global_load_lds_dwordx4 v[150:151], off
	v_lshl_add_u64 v[150:151], v[90:91], 0, s[40:41]
	s_mov_b32 m0, s95
	v_mfma_f32_32x32x16_bf16 v[32:47], v[154:157], v[158:161], v[32:47]
	global_load_lds_dwordx4 v[150:151], off
	s_mov_b32 m0, s4
	s_mov_b64 s[4:5], 0x40400
	ds_read_b128 v[150:153], v133 offset:32768
	ds_read_b128 v[154:157], v133 offset:36864
	ds_read_b128 v[158:161], v134
	ds_read_b128 v[180:183], v134 offset:4096
	s_waitcnt lgkmcnt(4)
	v_mfma_f32_32x32x16_bf16 v[48:63], v[184:187], v[192:195], v[48:63]
	v_mfma_f32_32x32x16_bf16 v[16:31], v[184:187], v[196:199], v[16:31]
	v_mfma_f32_32x32x16_bf16 v[32:47], v[188:191], v[192:195], v[32:47]
	v_mfma_f32_32x32x16_bf16 v[0:15], v[188:191], v[196:199], v[0:15]
	ds_read_b128 v[184:187], v135 offset:32768
	ds_read_b128 v[188:191], v135 offset:36864
	ds_read_b128 v[192:195], v136
	ds_read_b128 v[196:199], v136 offset:4096
	s_waitcnt lgkmcnt(4)
	v_mfma_f32_32x32x16_bf16 v[48:63], v[150:153], v[158:161], v[48:63]
	v_mfma_f32_32x32x16_bf16 v[16:31], v[150:153], v[180:183], v[16:31]
	v_mfma_f32_32x32x16_bf16 v[32:47], v[154:157], v[158:161], v[32:47]
	v_mfma_f32_32x32x16_bf16 v[0:15], v[154:157], v[180:183], v[0:15]
	ds_read_b128 v[150:153], v137 offset:32768
	ds_read_b128 v[154:157], v137 offset:36864
	ds_read_b128 v[158:161], v138
	ds_read_b128 v[180:183], v138 offset:4096
	s_waitcnt lgkmcnt(4)
	v_mfma_f32_32x32x16_bf16 v[48:63], v[184:187], v[192:195], v[48:63]
	v_mfma_f32_32x32x16_bf16 v[16:31], v[184:187], v[196:199], v[16:31]
	v_mfma_f32_32x32x16_bf16 v[32:47], v[188:191], v[192:195], v[32:47]
	v_mfma_f32_32x32x16_bf16 v[0:15], v[188:191], v[196:199], v[0:15]
	s_waitcnt vmcnt(6)
	s_waitcnt lgkmcnt(0)
	s_barrier
	ds_read_b128 v[184:187], v119 offset:32768
	ds_read_b128 v[188:191], v119 offset:36864
	ds_read_b128 v[192:195], v120
	ds_read_b128 v[196:199], v120 offset:4096
	s_waitcnt lgkmcnt(4)
	v_mfma_f32_32x32x16_bf16 v[48:63], v[150:153], v[158:161], v[48:63]
	v_mfma_f32_32x32x16_bf16 v[16:31], v[150:153], v[180:183], v[16:31]
	v_lshl_add_u64 v[150:151], v[88:89], 0, s[42:43]
	global_load_lds_dwordx4 v[150:151], off
	v_lshl_add_u64 v[150:151], v[88:89], 0, s[44:45]
	s_mov_b32 m0, s90
	s_nop 0
	global_load_lds_dwordx4 v[150:151], off
	v_lshl_add_u64 v[150:151], v[88:89], 0, s[4:5]
	s_mov_b32 m0, s88
	s_mov_b64 s[4:5], 0x60400
	global_load_lds_dwordx4 v[150:151], off
	v_lshl_add_u64 v[150:151], v[88:89], 0, s[4:5]
	s_mov_b32 m0, s89
	v_mfma_f32_32x32x16_bf16 v[0:15], v[154:157], v[180:183], v[0:15]
	global_load_lds_dwordx4 v[150:151], off
	v_lshl_add_u64 v[150:151], v[90:91], 0, s[42:43]
	s_mov_b32 m0, s7
	s_nop 0
	global_load_lds_dwordx4 v[150:151], off
	v_lshl_add_u64 v[150:151], v[90:91], 0, s[44:45]
	s_mov_b32 m0, s87
	v_mfma_f32_32x32x16_bf16 v[32:47], v[154:157], v[158:161], v[32:47]
	global_load_lds_dwordx4 v[150:151], off
	s_mov_b32 m0, s6
	s_mov_b64 s[4:5], 0x40480
	ds_read_b128 v[150:153], v121 offset:32768
	ds_read_b128 v[154:157], v121 offset:36864
	ds_read_b128 v[158:161], v122
	ds_read_b128 v[180:183], v122 offset:4096
	s_waitcnt lgkmcnt(4)
	v_mfma_f32_32x32x16_bf16 v[48:63], v[184:187], v[192:195], v[48:63]
	v_mfma_f32_32x32x16_bf16 v[16:31], v[184:187], v[196:199], v[16:31]
	v_mfma_f32_32x32x16_bf16 v[32:47], v[188:191], v[192:195], v[32:47]
	v_mfma_f32_32x32x16_bf16 v[0:15], v[188:191], v[196:199], v[0:15]
	ds_read_b128 v[184:187], v123 offset:32768
	ds_read_b128 v[188:191], v123 offset:36864
	ds_read_b128 v[192:195], v124
	ds_read_b128 v[196:199], v124 offset:4096
	s_waitcnt lgkmcnt(4)
	v_mfma_f32_32x32x16_bf16 v[48:63], v[150:153], v[158:161], v[48:63]
	v_mfma_f32_32x32x16_bf16 v[16:31], v[150:153], v[180:183], v[16:31]
	v_mfma_f32_32x32x16_bf16 v[32:47], v[154:157], v[158:161], v[32:47]
	v_mfma_f32_32x32x16_bf16 v[0:15], v[154:157], v[180:183], v[0:15]
	ds_read_b128 v[150:153], v125 offset:32768
	ds_read_b128 v[154:157], v125 offset:36864
	ds_read_b128 v[158:161], v126
	ds_read_b128 v[180:183], v126 offset:4096
	s_waitcnt lgkmcnt(4)
	v_mfma_f32_32x32x16_bf16 v[48:63], v[184:187], v[192:195], v[48:63]
	v_mfma_f32_32x32x16_bf16 v[16:31], v[184:187], v[196:199], v[16:31]
	v_mfma_f32_32x32x16_bf16 v[32:47], v[188:191], v[192:195], v[32:47]
	v_mfma_f32_32x32x16_bf16 v[0:15], v[188:191], v[196:199], v[0:15]
	s_waitcnt vmcnt(6)
	s_waitcnt lgkmcnt(0)
	s_barrier
; #define MFMA(a, b, c) __builtin_amdgcn_mfma_f32_32x32x16_bf16((a), (b), (c), 0, 0, 0)
; #define WAIT_V(n) asm volatile("s_waitcnt vmcnt(%0)" ::"n"(n) : "memory")
; #define RAW_BARRIER() do { asm volatile("s_waitcnt lgkmcnt(0)" ::: "memory"); __builtin_amdgcn_s_barrier(); asm volatile("" ::: "memory"); } while (0)
; #define GLDS_STAGE(slot, kt) do { _Pragma("unroll") for (int i = 0; i < 6; ++i) \
;     __builtin_amdgcn_global_load_lds((const unsigned*)(src[i] + (kt) * 64), (__attribute__((address_space(3))) unsigned*)(smem + (slot) * G_STAGE + (wave + 8 * i) * 1024), 16, 0, 0); } while (0)
; DI void gemm_tile(const u16* __restrict__ X, int ldx, const u16* __restrict__ Wt, int ldw, int K, char* smem,
;                   f32x16 (&acc)[2][2]) {
;     ...
;   for (int kt = 0; kt < nk; ++kt) {
;     const int nxt = (cur >= 1) ? cur - 1 : 2;
;     if (kt + 2 < nk) GLDS_STAGE(nxt, kt + 2);
;     __builtin_amdgcn_sched_barrier(0);
;     const char* st = smem + cur * G_STAGE;
; #pragma unroll
;     for (int ks = 0; ks < 4; ++ks) {
;       bf16x8 a[2], b[2];
; #pragma unroll
;       for (int ft = 0; ft < 2; ++ft) a[ft] = *reinterpret_cast<const bf16x8*>(st + offA[ft] + (((ks * 2 + lh) ^ xa[ft]) << 4));
; #pragma unroll
;       for (int tt = 0; tt < 2; ++tt) b[tt] = *reinterpret_cast<const bf16x8*>(st + offB[tt] + (((ks * 2 + lh) ^ xb[tt]) << 4));
; #pragma unroll
;       for (int ft = 0; ft < 2; ++ft)
; #pragma unroll
;         for (int tt = 0; tt < 2; ++tt) acc[ft][tt] = MFMA(a[ft], b[tt], acc[ft][tt]);
;     }
;     if (kt + 2 < nk) { WAIT_V(6); } else { WAIT_V(0); }
;     RAW_BARRIER();
;     cur = (cur == 2) ? 0 : cur + 1;
	ds_read_b128 v[184:187], v127 offset:32768
	ds_read_b128 v[188:191], v127 offset:36864
	ds_read_b128 v[192:195], v120 offset:49152
	ds_read_b128 v[196:199], v120 offset:53248
	s_waitcnt lgkmcnt(4)
	v_mfma_f32_32x32x16_bf16 v[48:63], v[150:153], v[158:161], v[48:63]
	v_mfma_f32_32x32x16_bf16 v[16:31], v[150:153], v[180:183], v[16:31]
	v_lshl_add_u64 v[150:151], v[88:89], 0, s[46:47]
	global_load_lds_dwordx4 v[150:151], off
	v_lshl_add_u64 v[150:151], v[88:89], 0, s[48:49]
	s_mov_b32 m0, s86
	s_nop 0
	global_load_lds_dwordx4 v[150:151], off
	v_lshl_add_u64 v[150:151], v[88:89], 0, s[4:5]
	s_mov_b32 m0, s85
	s_mov_b64 s[4:5], 0x60480
	global_load_lds_dwordx4 v[150:151], off
	v_lshl_add_u64 v[150:151], v[88:89], 0, s[4:5]
	s_mov_b32 m0, s84
	v_mfma_f32_32x32x16_bf16 v[0:15], v[154:157], v[180:183], v[0:15]
	global_load_lds_dwordx4 v[150:151], off
	v_lshl_add_u64 v[150:151], v[90:91], 0, s[46:47]
	s_mov_b32 m0, s79
	s_nop 0
	global_load_lds_dwordx4 v[150:151], off
	v_lshl_add_u64 v[150:151], v[90:91], 0, s[48:49]
	s_mov_b32 m0, s55
	v_mfma_f32_32x32x16_bf16 v[32:47], v[154:157], v[158:161], v[32:47]
	global_load_lds_dwordx4 v[150:151], off
	s_mov_b32 m0, s54
	s_mov_b64 s[4:5], 0x40500
	ds_read_b128 v[150:153], v128 offset:32768
	ds_read_b128 v[154:157], v128 offset:36864
	ds_read_b128 v[158:161], v122 offset:49152
	ds_read_b128 v[180:183], v122 offset:53248
	s_waitcnt lgkmcnt(4)
	v_mfma_f32_32x32x16_bf16 v[48:63], v[184:187], v[192:195], v[48:63]
	v_mfma_f32_32x32x16_bf16 v[16:31], v[184:187], v[196:199], v[16:31]
	v_mfma_f32_32x32x16_bf16 v[32:47], v[188:191], v[192:195], v[32:47]
	v_mfma_f32_32x32x16_bf16 v[0:15], v[188:191], v[196:199], v[0:15]
	ds_read_b128 v[184:187], v129 offset:32768
	ds_read_b128 v[188:191], v129 offset:36864
	ds_read_b128 v[192:195], v124 offset:49152
	ds_read_b128 v[196:199], v124 offset:53248
	s_waitcnt lgkmcnt(4)
	v_mfma_f32_32x32x16_bf16 v[48:63], v[150:153], v[158:161], v[48:63]
	v_mfma_f32_32x32x16_bf16 v[16:31], v[150:153], v[180:183], v[16:31]
	v_mfma_f32_32x32x16_bf16 v[32:47], v[154:157], v[158:161], v[32:47]
	v_mfma_f32_32x32x16_bf16 v[0:15], v[154:157], v[180:183], v[0:15]
	ds_read_b128 v[150:153], v130 offset:32768
	ds_read_b128 v[154:157], v130 offset:36864
	ds_read_b128 v[158:161], v126 offset:49152
	ds_read_b128 v[180:183], v126 offset:53248
	s_waitcnt lgkmcnt(4)
	v_mfma_f32_32x32x16_bf16 v[48:63], v[184:187], v[192:195], v[48:63]
	v_mfma_f32_32x32x16_bf16 v[16:31], v[184:187], v[196:199], v[16:31]
	v_mfma_f32_32x32x16_bf16 v[32:47], v[188:191], v[192:195], v[32:47]
	v_mfma_f32_32x32x16_bf16 v[0:15], v[188:191], v[196:199], v[0:15]
	s_waitcnt vmcnt(6)
	s_waitcnt lgkmcnt(0)
	s_barrier
	ds_read_b128 v[184:187], v131 offset:32768
	ds_read_b128 v[188:191], v131 offset:36864
	ds_read_b128 v[192:195], v132
	ds_read_b128 v[196:199], v132 offset:4096
	s_waitcnt lgkmcnt(4)
	v_mfma_f32_32x32x16_bf16 v[48:63], v[150:153], v[158:161], v[48:63]
	v_mfma_f32_32x32x16_bf16 v[16:31], v[150:153], v[180:183], v[16:31]
	v_lshl_add_u64 v[150:151], v[88:89], 0, s[50:51]
	global_load_lds_dwordx4 v[150:151], off
	v_lshl_add_u64 v[150:151], v[88:89], 0, s[52:53]
	s_mov_b32 m0, s0
	s_nop 0
	global_load_lds_dwordx4 v[150:151], off
	v_lshl_add_u64 v[150:151], v[88:89], 0, s[4:5]
	s_mov_b32 m0, s91
	s_mov_b64 s[4:5], 0x60500
	global_load_lds_dwordx4 v[150:151], off
	v_lshl_add_u64 v[150:151], v[88:89], 0, s[4:5]
	s_mov_b32 m0, s93
	v_mfma_f32_32x32x16_bf16 v[0:15], v[154:157], v[180:183], v[0:15]
	global_load_lds_dwordx4 v[150:151], off
	v_lshl_add_u64 v[150:151], v[90:91], 0, s[50:51]
	s_mov_b32 m0, s92
	s_nop 0
	global_load_lds_dwordx4 v[150:151], off
	v_lshl_add_u64 v[150:151], v[90:91], 0, s[52:53]
	s_mov_b32 m0, s95
	v_mfma_f32_32x32x16_bf16 v[32:47], v[154:157], v[158:161], v[32:47]
	global_load_lds_dwordx4 v[150:151], off
	v_readfirstlane_b32 s87, v93
	s_mov_b32 m0, s87
	v_readfirstlane_b32 s54, v94
	ds_read_b128 v[150:153], v133 offset:32768
	ds_read_b128 v[154:157], v133 offset:36864
	ds_read_b128 v[158:161], v134
	ds_read_b128 v[180:183], v134 offset:4096
	s_waitcnt lgkmcnt(4)
	v_mfma_f32_32x32x16_bf16 v[48:63], v[184:187], v[192:195], v[48:63]
	s_mov_b64 s[4:5], 0x40580
	v_readfirstlane_b32 s55, v95
	v_readfirstlane_b32 s84, v96
	v_readfirstlane_b32 s79, v97
	v_readfirstlane_b32 s85, v98
	v_mfma_f32_32x32x16_bf16 v[16:31], v[184:187], v[196:199], v[16:31]
	v_mfma_f32_32x32x16_bf16 v[32:47], v[188:191], v[192:195], v[32:47]
	v_mfma_f32_32x32x16_bf16 v[0:15], v[188:191], v[196:199], v[0:15]
	ds_read_b128 v[184:187], v135 offset:32768
	ds_read_b128 v[188:191], v135 offset:36864
	ds_read_b128 v[192:195], v136
	ds_read_b128 v[196:199], v136 offset:4096
	s_waitcnt lgkmcnt(4)
	v_mfma_f32_32x32x16_bf16 v[48:63], v[150:153], v[158:161], v[48:63]
	v_mfma_f32_32x32x16_bf16 v[16:31], v[150:153], v[180:183], v[16:31]
	v_mfma_f32_32x32x16_bf16 v[32:47], v[154:157], v[158:161], v[32:47]
	v_mfma_f32_32x32x16_bf16 v[0:15], v[154:157], v[180:183], v[0:15]
	ds_read_b128 v[150:153], v137 offset:32768
	ds_read_b128 v[154:157], v137 offset:36864
	ds_read_b128 v[158:161], v138
	ds_read_b128 v[180:183], v138 offset:4096
	s_waitcnt lgkmcnt(4)
	v_mfma_f32_32x32x16_bf16 v[48:63], v[184:187], v[192:195], v[48:63]
	v_mfma_f32_32x32x16_bf16 v[16:31], v[184:187], v[196:199], v[16:31]
	v_mfma_f32_32x32x16_bf16 v[32:47], v[188:191], v[192:195], v[32:47]
	v_mfma_f32_32x32x16_bf16 v[0:15], v[188:191], v[196:199], v[0:15]
	s_waitcnt vmcnt(6)
	s_waitcnt lgkmcnt(0)
	s_barrier
; #define MFMA(a, b, c) __builtin_amdgcn_mfma_f32_32x32x16_bf16((a), (b), (c), 0, 0, 0)
; #define WAIT_V(n) asm volatile("s_waitcnt vmcnt(%0)" ::"n"(n) : "memory")
; #define RAW_BARRIER() do { asm volatile("s_waitcnt lgkmcnt(0)" ::: "memory"); __builtin_amdgcn_s_barrier(); asm volatile("" ::: "memory"); } while (0)
; #define GLDS_STAGE(slot, kt) do { _Pragma("unroll") for (int i = 0; i < 6; ++i) \
;     __builtin_amdgcn_global_load_lds((const unsigned*)(src[i] + (kt) * 64), (__attribute__((address_space(3))) unsigned*)(smem + (slot) * G_STAGE + (wave + 8 * i) * 1024), 16, 0, 0); } while (0)
; DI void gemm_tile(const u16* __restrict__ X, int ldx, const u16* __restrict__ Wt, int ldw, int K, char* smem,
;                   f32x16 (&acc)[2][2]) {
;     ...
;   for (int kt = 0; kt < nk; ++kt) {
;     const int nxt = (cur >= 1) ? cur - 1 : 2;
;     if (kt + 2 < nk) GLDS_STAGE(nxt, kt + 2);
;     __builtin_amdgcn_sched_barrier(0);
;     const char* st = smem + cur * G_STAGE;
; #pragma unroll
;     for (int ks = 0; ks < 4; ++ks) {
;       bf16x8 a[2], b[2];
; #pragma unroll
;       for (int ft = 0; ft < 2; ++ft) a[ft] = *reinterpret_cast<const bf16x8*>(st + offA[ft] + (((ks * 2 + lh) ^ xa[ft]) << 4));
; #pragma unroll
;       for (int tt = 0; tt < 2; ++tt) b[tt] = *reinterpret_cast<const bf16x8*>(st + offB[tt] + (((ks * 2 + lh) ^ xb[tt]) << 4));
; #pragma unroll
;       for (int ft = 0; ft < 2; ++ft)
; #pragma unroll
;         for (int tt = 0; tt < 2; ++tt) acc[ft][tt] = MFMA(a[ft], b[tt], acc[ft][tt]);
;     }
;     if (kt + 2 < nk) { WAIT_V(6); } else { WAIT_V(0); }
;     RAW_BARRIER();
;     cur = (cur == 2) ? 0 : cur + 1;
	ds_read_b128 v[184:187], v119 offset:32768
	ds_read_b128 v[188:191], v119 offset:36864
	ds_read_b128 v[192:195], v120
	ds_read_b128 v[196:199], v120 offset:4096
	s_waitcnt lgkmcnt(4)
	v_mfma_f32_32x32x16_bf16 v[48:63], v[150:153], v[158:161], v[48:63]
	v_mfma_f32_32x32x16_bf16 v[16:31], v[150:153], v[180:183], v[16:31]
	v_lshl_add_u64 v[150:151], v[88:89], 0, s[56:57]
	global_load_lds_dwordx4 v[150:151], off
	v_lshl_add_u64 v[150:151], v[88:89], 0, s[58:59]
	s_mov_b32 m0, s54
	s_nop 0
	global_load_lds_dwordx4 v[150:151], off
	v_lshl_add_u64 v[150:151], v[88:89], 0, s[4:5]
	s_mov_b32 m0, s55
	s_mov_b64 s[4:5], 0x60580
	global_load_lds_dwordx4 v[150:151], off
	v_lshl_add_u64 v[150:151], v[88:89], 0, s[4:5]
	s_mov_b32 m0, s84
	v_mfma_f32_32x32x16_bf16 v[0:15], v[154:157], v[180:183], v[0:15]
	global_load_lds_dwordx4 v[150:151], off
	v_lshl_add_u64 v[150:151], v[90:91], 0, s[56:57]
	s_mov_b32 m0, s79
	s_nop 0
	global_load_lds_dwordx4 v[150:151], off
	v_lshl_add_u64 v[150:151], v[90:91], 0, s[58:59]
	s_mov_b32 m0, s85
	v_mfma_f32_32x32x16_bf16 v[32:47], v[154:157], v[158:161], v[32:47]
	global_load_lds_dwordx4 v[150:151], off
	v_readfirstlane_b32 s86, v143
	s_mov_b32 m0, s86
	v_readfirstlane_b32 s0, v109
	ds_read_b128 v[150:153], v121 offset:32768
	ds_read_b128 v[154:157], v121 offset:36864
	ds_read_b128 v[158:161], v122
	ds_read_b128 v[180:183], v122 offset:4096
	s_waitcnt lgkmcnt(4)
	v_mfma_f32_32x32x16_bf16 v[48:63], v[184:187], v[192:195], v[48:63]
	s_mov_b64 s[4:5], 0x40600
	s_mov_b64 s[6:7], 0x60600
	v_mfma_f32_32x32x16_bf16 v[16:31], v[184:187], v[196:199], v[16:31]
	v_mfma_f32_32x32x16_bf16 v[32:47], v[188:191], v[192:195], v[32:47]
	v_mfma_f32_32x32x16_bf16 v[0:15], v[188:191], v[196:199], v[0:15]
	ds_read_b128 v[184:187], v123 offset:32768
	ds_read_b128 v[188:191], v123 offset:36864
	ds_read_b128 v[192:195], v124
	ds_read_b128 v[196:199], v124 offset:4096
	s_waitcnt lgkmcnt(4)
	v_mfma_f32_32x32x16_bf16 v[48:63], v[150:153], v[158:161], v[48:63]
	v_mfma_f32_32x32x16_bf16 v[16:31], v[150:153], v[180:183], v[16:31]
	v_mfma_f32_32x32x16_bf16 v[32:47], v[154:157], v[158:161], v[32:47]
	v_mfma_f32_32x32x16_bf16 v[0:15], v[154:157], v[180:183], v[0:15]
	ds_read_b128 v[150:153], v125 offset:32768
	ds_read_b128 v[154:157], v125 offset:36864
	ds_read_b128 v[158:161], v126
	ds_read_b128 v[180:183], v126 offset:4096
	s_waitcnt lgkmcnt(4)
	v_mfma_f32_32x32x16_bf16 v[48:63], v[184:187], v[192:195], v[48:63]
	v_mfma_f32_32x32x16_bf16 v[16:31], v[184:187], v[196:199], v[16:31]
	v_mfma_f32_32x32x16_bf16 v[32:47], v[188:191], v[192:195], v[32:47]
	v_mfma_f32_32x32x16_bf16 v[0:15], v[188:191], v[196:199], v[0:15]
	s_waitcnt vmcnt(6)
	s_waitcnt lgkmcnt(0)
	s_barrier
	ds_read_b128 v[184:187], v127 offset:32768
	ds_read_b128 v[188:191], v127 offset:36864
	ds_read_b128 v[192:195], v120 offset:49152
	ds_read_b128 v[196:199], v120 offset:53248
	s_waitcnt lgkmcnt(4)
	v_mfma_f32_32x32x16_bf16 v[48:63], v[150:153], v[158:161], v[48:63]
	v_mfma_f32_32x32x16_bf16 v[16:31], v[150:153], v[180:183], v[16:31]
	v_lshl_add_u64 v[150:151], v[88:89], 0, s[60:61]
	global_load_lds_dwordx4 v[150:151], off
	v_lshl_add_u64 v[150:151], v[88:89], 0, s[62:63]
	s_mov_b32 m0, s0
	s_nop 0
	global_load_lds_dwordx4 v[150:151], off
	v_lshl_add_u64 v[150:151], v[88:89], 0, s[4:5]
	v_readfirstlane_b32 s4, v110
	s_mov_b32 m0, s4
	v_readfirstlane_b32 s5, v112
	global_load_lds_dwordx4 v[150:151], off
	v_lshl_add_u64 v[150:151], v[88:89], 0, s[6:7]
	v_readfirstlane_b32 s6, v111
	s_mov_b32 m0, s6
	v_readfirstlane_b32 s7, v113
	global_load_lds_dwordx4 v[150:151], off
	v_lshl_add_u64 v[150:151], v[90:91], 0, s[60:61]
	s_mov_b32 m0, s5
	v_mfma_f32_32x32x16_bf16 v[0:15], v[154:157], v[180:183], v[0:15]
	global_load_lds_dwordx4 v[150:151], off
	v_lshl_add_u64 v[150:151], v[90:91], 0, s[62:63]
	s_mov_b32 m0, s7
	s_nop 0
	global_load_lds_dwordx4 v[150:151], off
	v_mfma_f32_32x32x16_bf16 v[32:47], v[154:157], v[158:161], v[32:47]
	v_readfirstlane_b32 s88, v92
	s_mov_b32 m0, s88
	v_readfirstlane_b32 s88, v114
	ds_read_b128 v[150:153], v128 offset:32768
	ds_read_b128 v[154:157], v128 offset:36864
	ds_read_b128 v[158:161], v122 offset:49152
	ds_read_b128 v[180:183], v122 offset:53248
	s_waitcnt lgkmcnt(4)
	v_mfma_f32_32x32x16_bf16 v[48:63], v[184:187], v[192:195], v[48:63]
	v_mfma_f32_32x32x16_bf16 v[16:31], v[184:187], v[196:199], v[16:31]
	v_mfma_f32_32x32x16_bf16 v[32:47], v[188:191], v[192:195], v[32:47]
	v_mfma_f32_32x32x16_bf16 v[0:15], v[188:191], v[196:199], v[0:15]
	ds_read_b128 v[184:187], v129 offset:32768
	ds_read_b128 v[188:191], v129 offset:36864
	ds_read_b128 v[192:195], v124 offset:49152
	ds_read_b128 v[196:199], v124 offset:53248
	s_waitcnt lgkmcnt(4)
	v_mfma_f32_32x32x16_bf16 v[48:63], v[150:153], v[158:161], v[48:63]
	v_mfma_f32_32x32x16_bf16 v[16:31], v[150:153], v[180:183], v[16:31]
	v_mfma_f32_32x32x16_bf16 v[32:47], v[154:157], v[158:161], v[32:47]
	v_mfma_f32_32x32x16_bf16 v[0:15], v[154:157], v[180:183], v[0:15]
	ds_read_b128 v[150:153], v130 offset:32768
	ds_read_b128 v[154:157], v130 offset:36864
	ds_read_b128 v[158:161], v126 offset:49152
	ds_read_b128 v[180:183], v126 offset:53248
	s_waitcnt lgkmcnt(4)
	v_mfma_f32_32x32x16_bf16 v[48:63], v[184:187], v[192:195], v[48:63]
	v_mfma_f32_32x32x16_bf16 v[16:31], v[184:187], v[196:199], v[16:31]
	v_mfma_f32_32x32x16_bf16 v[32:47], v[188:191], v[192:195], v[32:47]
	v_mfma_f32_32x32x16_bf16 v[0:15], v[188:191], v[196:199], v[0:15]
	s_waitcnt vmcnt(6)
	s_waitcnt lgkmcnt(0)
	s_barrier
; #define MFMA(a, b, c) __builtin_amdgcn_mfma_f32_32x32x16_bf16((a), (b), (c), 0, 0, 0)
; #define WAIT_V(n) asm volatile("s_waitcnt vmcnt(%0)" ::"n"(n) : "memory")
; #define RAW_BARRIER() do { asm volatile("s_waitcnt lgkmcnt(0)" ::: "memory"); __builtin_amdgcn_s_barrier(); asm volatile("" ::: "memory"); } while (0)
; #define GLDS_STAGE(slot, kt) do { _Pragma("unroll") for (int i = 0; i < 6; ++i) \
;     __builtin_amdgcn_global_load_lds((const unsigned*)(src[i] + (kt) * 64), (__attribute__((address_space(3))) unsigned*)(smem + (slot) * G_STAGE + (wave + 8 * i) * 1024), 16, 0, 0); } while (0)
; DI void gemm_tile(const u16* __restrict__ X, int ldx, const u16* __restrict__ Wt, int ldw, int K, char* smem,
;                   f32x16 (&acc)[2][2]) {
;     ...
;   for (int kt = 0; kt < nk; ++kt) {
;     const int nxt = (cur >= 1) ? cur - 1 : 2;
;     if (kt + 2 < nk) GLDS_STAGE(nxt, kt + 2);
;     __builtin_amdgcn_sched_barrier(0);
;     const char* st = smem + cur * G_STAGE;
; #pragma unroll
;     for (int ks = 0; ks < 4; ++ks) {
;       bf16x8 a[2], b[2];
; #pragma unroll
;       for (int ft = 0; ft < 2; ++ft) a[ft] = *reinterpret_cast<const bf16x8*>(st + offA[ft] + (((ks * 2 + lh) ^ xa[ft]) << 4));
; #pragma unroll
;       for (int tt = 0; tt < 2; ++tt) b[tt] = *reinterpret_cast<const bf16x8*>(st + offB[tt] + (((ks * 2 + lh) ^ xb[tt]) << 4));
; #pragma unroll
;       for (int ft = 0; ft < 2; ++ft)
; #pragma unroll
;         for (int tt = 0; tt < 2; ++tt) acc[ft][tt] = MFMA(a[ft], b[tt], acc[ft][tt]);
;     }
;     if (kt + 2 < nk) { WAIT_V(6); } else { WAIT_V(0); }
;     RAW_BARRIER();
;     cur = (cur == 2) ? 0 : cur + 1;
	ds_read_b128 v[184:187], v131 offset:32768
	ds_read_b128 v[188:191], v131 offset:36864
	ds_read_b128 v[192:195], v132
	ds_read_b128 v[196:199], v132 offset:4096
	s_waitcnt lgkmcnt(4)
	v_mfma_f32_32x32x16_bf16 v[48:63], v[150:153], v[158:161], v[48:63]
	v_mfma_f32_32x32x16_bf16 v[16:31], v[150:153], v[180:183], v[16:31]
	v_lshl_add_u64 v[150:151], v[88:89], 0, s[64:65]
	global_load_lds_dwordx4 v[150:151], off
	v_lshl_add_u64 v[150:151], v[88:89], 0, s[66:67]
	s_mov_b32 m0, s88
	s_mov_b64 s[88:89], 0x40680
	global_load_lds_dwordx4 v[150:151], off
	v_lshl_add_u64 v[150:151], v[88:89], 0, s[88:89]
	v_readfirstlane_b32 s88, v99
	s_mov_b32 m0, s88
	s_mov_b64 s[88:89], 0x60680
	global_load_lds_dwordx4 v[150:151], off
	v_lshl_add_u64 v[150:151], v[88:89], 0, s[88:89]
	v_readfirstlane_b32 s88, v100
	s_mov_b32 m0, s88
	v_readfirstlane_b32 s88, v101
	global_load_lds_dwordx4 v[150:151], off
	v_lshl_add_u64 v[150:151], v[90:91], 0, s[64:65]
	s_mov_b32 m0, s88
	v_readfirstlane_b32 s88, v102
	global_load_lds_dwordx4 v[150:151], off
	v_lshl_add_u64 v[150:151], v[90:91], 0, s[66:67]
	s_mov_b32 m0, s88
	v_mfma_f32_32x32x16_bf16 v[0:15], v[154:157], v[180:183], v[0:15]
	global_load_lds_dwordx4 v[150:151], off
	v_mfma_f32_32x32x16_bf16 v[32:47], v[154:157], v[158:161], v[32:47]
	s_mov_b32 m0, s87
	s_mov_b64 s[88:89], 0x40700
	ds_read_b128 v[150:153], v133 offset:32768
	ds_read_b128 v[154:157], v133 offset:36864
	ds_read_b128 v[158:161], v134
	ds_read_b128 v[180:183], v134 offset:4096
	s_waitcnt lgkmcnt(4)
	v_mfma_f32_32x32x16_bf16 v[48:63], v[184:187], v[192:195], v[48:63]
	v_mfma_f32_32x32x16_bf16 v[16:31], v[184:187], v[196:199], v[16:31]
	v_mfma_f32_32x32x16_bf16 v[32:47], v[188:191], v[192:195], v[32:47]
	v_mfma_f32_32x32x16_bf16 v[0:15], v[188:191], v[196:199], v[0:15]
	ds_read_b128 v[184:187], v135 offset:32768
	ds_read_b128 v[188:191], v135 offset:36864
	ds_read_b128 v[192:195], v136
	ds_read_b128 v[196:199], v136 offset:4096
	s_waitcnt lgkmcnt(4)
	v_mfma_f32_32x32x16_bf16 v[48:63], v[150:153], v[158:161], v[48:63]
	v_mfma_f32_32x32x16_bf16 v[16:31], v[150:153], v[180:183], v[16:31]
	v_mfma_f32_32x32x16_bf16 v[32:47], v[154:157], v[158:161], v[32:47]
	v_mfma_f32_32x32x16_bf16 v[0:15], v[154:157], v[180:183], v[0:15]
	ds_read_b128 v[150:153], v137 offset:32768
	ds_read_b128 v[154:157], v137 offset:36864
	ds_read_b128 v[158:161], v138
	ds_read_b128 v[180:183], v138 offset:4096
	s_waitcnt lgkmcnt(4)
	v_mfma_f32_32x32x16_bf16 v[48:63], v[184:187], v[192:195], v[48:63]
	v_mfma_f32_32x32x16_bf16 v[16:31], v[184:187], v[196:199], v[16:31]
	v_mfma_f32_32x32x16_bf16 v[32:47], v[188:191], v[192:195], v[32:47]
	v_mfma_f32_32x32x16_bf16 v[0:15], v[188:191], v[196:199], v[0:15]
	s_waitcnt vmcnt(6)
	s_waitcnt lgkmcnt(0)
	s_barrier
	ds_read_b128 v[184:187], v119 offset:32768
	ds_read_b128 v[188:191], v119 offset:36864
	ds_read_b128 v[192:195], v120
	ds_read_b128 v[196:199], v120 offset:4096
	s_waitcnt lgkmcnt(4)
	v_mfma_f32_32x32x16_bf16 v[48:63], v[150:153], v[158:161], v[48:63]
	v_mfma_f32_32x32x16_bf16 v[16:31], v[150:153], v[180:183], v[16:31]
	v_lshl_add_u64 v[150:151], v[88:89], 0, s[68:69]
	global_load_lds_dwordx4 v[150:151], off
	v_lshl_add_u64 v[150:151], v[88:89], 0, s[70:71]
	s_mov_b32 m0, s54
	s_nop 0
	global_load_lds_dwordx4 v[150:151], off
	v_lshl_add_u64 v[150:151], v[88:89], 0, s[88:89]
	s_mov_b32 m0, s55
	s_mov_b64 s[54:55], 0x60700
	global_load_lds_dwordx4 v[150:151], off
	v_lshl_add_u64 v[150:151], v[88:89], 0, s[54:55]
	s_mov_b32 m0, s84
	v_mfma_f32_32x32x16_bf16 v[0:15], v[154:157], v[180:183], v[0:15]
	global_load_lds_dwordx4 v[150:151], off
	v_lshl_add_u64 v[150:151], v[90:91], 0, s[68:69]
	s_mov_b32 m0, s79
	s_nop 0
	global_load_lds_dwordx4 v[150:151], off
	v_lshl_add_u64 v[150:151], v[90:91], 0, s[70:71]
	s_mov_b32 m0, s85
	v_mfma_f32_32x32x16_bf16 v[32:47], v[154:157], v[158:161], v[32:47]
	global_load_lds_dwordx4 v[150:151], off
	s_mov_b32 m0, s86
	s_mov_b64 s[54:55], 0x40780
	ds_read_b128 v[150:153], v121 offset:32768
	ds_read_b128 v[154:157], v121 offset:36864
	ds_read_b128 v[158:161], v122
	ds_read_b128 v[180:183], v122 offset:4096
	s_waitcnt lgkmcnt(4)
	v_mfma_f32_32x32x16_bf16 v[48:63], v[184:187], v[192:195], v[48:63]
	v_mfma_f32_32x32x16_bf16 v[16:31], v[184:187], v[196:199], v[16:31]
	v_mfma_f32_32x32x16_bf16 v[32:47], v[188:191], v[192:195], v[32:47]
	v_mfma_f32_32x32x16_bf16 v[0:15], v[188:191], v[196:199], v[0:15]
	ds_read_b128 v[184:187], v123 offset:32768
	ds_read_b128 v[188:191], v123 offset:36864
	ds_read_b128 v[192:195], v124
	ds_read_b128 v[196:199], v124 offset:4096
	s_waitcnt lgkmcnt(4)
	v_mfma_f32_32x32x16_bf16 v[48:63], v[150:153], v[158:161], v[48:63]
	v_mfma_f32_32x32x16_bf16 v[16:31], v[150:153], v[180:183], v[16:31]
	v_mfma_f32_32x32x16_bf16 v[32:47], v[154:157], v[158:161], v[32:47]
	v_mfma_f32_32x32x16_bf16 v[0:15], v[154:157], v[180:183], v[0:15]
	s_waitcnt lgkmcnt(0)
	v_mfma_f32_32x32x16_bf16 v[48:63], v[184:187], v[192:195], v[48:63]
	v_mfma_f32_32x32x16_bf16 v[16:31], v[184:187], v[196:199], v[16:31]
	v_mfma_f32_32x32x16_bf16 v[32:47], v[188:191], v[192:195], v[32:47]
	v_mfma_f32_32x32x16_bf16 v[0:15], v[188:191], v[196:199], v[0:15]
	ds_read_b128 v[150:153], v125 offset:32768
	ds_read_b128 v[154:157], v125 offset:36864
	ds_read_b128 v[158:161], v126
	ds_read_b128 v[180:183], v126 offset:4096
	s_waitcnt vmcnt(6)
	s_waitcnt lgkmcnt(0)
	s_barrier
; #define MFMA(a, b, c) __builtin_amdgcn_mfma_f32_32x32x16_bf16((a), (b), (c), 0, 0, 0)
; #define WAIT_V(n) asm volatile("s_waitcnt vmcnt(%0)" ::"n"(n) : "memory")
; #define RAW_BARRIER() do { asm volatile("s_waitcnt lgkmcnt(0)" ::: "memory"); __builtin_amdgcn_s_barrier(); asm volatile("" ::: "memory"); } while (0)
; #define GLDS_STAGE(slot, kt) do { _Pragma("unroll") for (int i = 0; i < 6; ++i) \
;     __builtin_amdgcn_global_load_lds((const unsigned*)(src[i] + (kt) * 64), (__attribute__((address_space(3))) unsigned*)(smem + (slot) * G_STAGE + (wave + 8 * i) * 1024), 16, 0, 0); } while (0)
; DI void gemm_tile(const u16* __restrict__ X, int ldx, const u16* __restrict__ Wt, int ldw, int K, char* smem,
;                   f32x16 (&acc)[2][2]) {
;     ...
;   for (int kt = 0; kt < nk; ++kt) {
;     const int nxt = (cur >= 1) ? cur - 1 : 2;
;     if (kt + 2 < nk) GLDS_STAGE(nxt, kt + 2);
;     __builtin_amdgcn_sched_barrier(0);
;     const char* st = smem + cur * G_STAGE;
; #pragma unroll
;     for (int ks = 0; ks < 4; ++ks) {
;       bf16x8 a[2], b[2];
; #pragma unroll
;       for (int ft = 0; ft < 2; ++ft) a[ft] = *reinterpret_cast<const bf16x8*>(st + offA[ft] + (((ks * 2 + lh) ^ xa[ft]) << 4));
; #pragma unroll
;       for (int tt = 0; tt < 2; ++tt) b[tt] = *reinterpret_cast<const bf16x8*>(st + offB[tt] + (((ks * 2 + lh) ^ xb[tt]) << 4));
; #pragma unroll
;       for (int ft = 0; ft < 2; ++ft)
; #pragma unroll
;         for (int tt = 0; tt < 2; ++tt) acc[ft][tt] = MFMA(a[ft], b[tt], acc[ft][tt]);
;     }
;     if (kt + 2 < nk) { WAIT_V(6); } else { WAIT_V(0); }
;     RAW_BARRIER();
;     cur = (cur == 2) ? 0 : cur + 1;
	s_waitcnt lgkmcnt(0)
	v_mfma_f32_32x32x16_bf16 v[48:63], v[150:153], v[158:161], v[48:63]
	v_mfma_f32_32x32x16_bf16 v[16:31], v[150:153], v[180:183], v[16:31]
	v_lshl_add_u64 v[150:151], v[88:89], 0, s[72:73]
	global_load_lds_dwordx4 v[150:151], off
	v_lshl_add_u64 v[150:151], v[88:89], 0, s[74:75]
	s_mov_b32 m0, s0
	s_nop 0
	global_load_lds_dwordx4 v[150:151], off
	v_lshl_add_u64 v[150:151], v[88:89], 0, s[54:55]
	s_mov_b32 m0, s4
	s_mov_b64 s[54:55], 0x60780
	global_load_lds_dwordx4 v[150:151], off
	v_lshl_add_u64 v[88:89], v[88:89], 0, s[54:55]
	s_mov_b32 m0, s6
	v_mfma_f32_32x32x16_bf16 v[0:15], v[154:157], v[180:183], v[0:15]
	global_load_lds_dwordx4 v[88:89], off
	v_lshl_add_u64 v[88:89], v[90:91], 0, s[72:73]
	s_mov_b32 m0, s5
	s_nop 0
	global_load_lds_dwordx4 v[88:89], off
	v_lshl_add_u64 v[88:89], v[90:91], 0, s[74:75]
	s_mov_b32 m0, s7
	v_mfma_f32_32x32x16_bf16 v[32:47], v[154:157], v[158:161], v[32:47]
	global_load_lds_dwordx4 v[88:89], off
	ds_read_b128 v[88:91], v127 offset:32768
	ds_read_b128 v[150:153], v120 offset:49152
	ds_read_b128 v[154:157], v120 offset:53248
	s_waitcnt lgkmcnt(0)
	v_mfma_f32_32x32x16_bf16 v[48:63], v[88:91], v[150:153], v[48:63]
	v_mfma_f32_32x32x16_bf16 v[16:31], v[88:91], v[154:157], v[16:31]
	ds_read_b128 v[88:91], v127 offset:36864
	s_waitcnt lgkmcnt(0)
	v_mfma_f32_32x32x16_bf16 v[32:47], v[88:91], v[150:153], v[32:47]
	v_mfma_f32_32x32x16_bf16 v[0:15], v[88:91], v[154:157], v[0:15]
	ds_read_b128 v[88:91], v128 offset:32768
	ds_read_b128 v[150:153], v122 offset:49152
	ds_read_b128 v[154:157], v122 offset:53248
	s_waitcnt lgkmcnt(0)
	v_mfma_f32_32x32x16_bf16 v[48:63], v[88:91], v[150:153], v[48:63]
	v_mfma_f32_32x32x16_bf16 v[16:31], v[88:91], v[154:157], v[16:31]
	ds_read_b128 v[88:91], v128 offset:36864
	s_waitcnt lgkmcnt(0)
	v_mfma_f32_32x32x16_bf16 v[32:47], v[88:91], v[150:153], v[32:47]
	v_mfma_f32_32x32x16_bf16 v[0:15], v[88:91], v[154:157], v[0:15]
	ds_read_b128 v[88:91], v129 offset:32768
	ds_read_b128 v[150:153], v124 offset:49152
	ds_read_b128 v[154:157], v124 offset:53248
	s_waitcnt lgkmcnt(0)
	v_mfma_f32_32x32x16_bf16 v[48:63], v[88:91], v[150:153], v[48:63]
	v_mfma_f32_32x32x16_bf16 v[16:31], v[88:91], v[154:157], v[16:31]
	ds_read_b128 v[88:91], v129 offset:36864
	s_waitcnt lgkmcnt(0)
	v_mfma_f32_32x32x16_bf16 v[32:47], v[88:91], v[150:153], v[32:47]
	v_mfma_f32_32x32x16_bf16 v[0:15], v[88:91], v[154:157], v[0:15]
	ds_read_b128 v[88:91], v130 offset:32768
	ds_read_b128 v[150:153], v126 offset:49152
	ds_read_b128 v[154:157], v126 offset:53248
	s_waitcnt lgkmcnt(0)
	v_mfma_f32_32x32x16_bf16 v[48:63], v[88:91], v[150:153], v[48:63]
	v_mfma_f32_32x32x16_bf16 v[16:31], v[88:91], v[154:157], v[16:31]
	ds_read_b128 v[88:91], v130 offset:36864
	s_waitcnt vmcnt(6)
	s_waitcnt lgkmcnt(0)
	s_barrier
; #define MFMA(a, b, c) __builtin_amdgcn_mfma_f32_32x32x16_bf16((a), (b), (c), 0, 0, 0)
; #define WAIT_V(n) asm volatile("s_waitcnt vmcnt(%0)" ::"n"(n) : "memory")
; #define RAW_BARRIER() do { asm volatile("s_waitcnt lgkmcnt(0)" ::: "memory"); __builtin_amdgcn_s_barrier(); asm volatile("" ::: "memory"); } while (0)
; DI void gemm_tile(const u16* __restrict__ X, int ldx, const u16* __restrict__ Wt, int ldw, int K, char* smem,
;                   f32x16 (&acc)[2][2]) {
;     ...
; #pragma unroll
;     for (int ks = 0; ks < 4; ++ks) {
;       bf16x8 a[2], b[2];
; #pragma unroll
;       for (int ft = 0; ft < 2; ++ft) a[ft] = *reinterpret_cast<const bf16x8*>(st + offA[ft] + (((ks * 2 + lh) ^ xa[ft]) << 4));
; #pragma unroll
;       for (int tt = 0; tt < 2; ++tt) b[tt] = *reinterpret_cast<const bf16x8*>(st + offB[tt] + (((ks * 2 + lh) ^ xb[tt]) << 4));
; #pragma unroll
;       for (int ft = 0; ft < 2; ++ft)
; #pragma unroll
;         for (int tt = 0; tt < 2; ++tt) acc[ft][tt] = MFMA(a[ft], b[tt], acc[ft][tt]);
;     }
;     if (kt + 2 < nk) { WAIT_V(6); } else { WAIT_V(0); }
;     RAW_BARRIER();
;     cur = (cur == 2) ? 0 : cur + 1;
;   }
; template <int MODE>
; DI void phase_gemm(const Params& p, const u16* X, const u16* Wt, int N, const float* resid, float* outf, u16* outb, int ldo, char* smem) {
;     ...
;       float* wl = (float*)(smem + wave * 17408);
; #pragma unroll
;       for (int tt = 0; tt < 2; ++tt)
; #pragma unroll
;         for (int ft = 0; ft < 2; ++ft)
; #pragma unroll
;           for (int g = 0; g < 4; ++g) {
;             f32x4 v = {acc[ft][tt][4 * g], acc[ft][tt][4 * g + 1], acc[ft][tt][4 * g + 2], acc[ft][tt][4 * g + 3]};
;             *reinterpret_cast<f32x4*>(wl + (tt * 32 + lr) * 68 + ft * 32 + 8 * g + 4 * lh) = v;
;           }
	s_waitcnt lgkmcnt(0)
	v_mfma_f32_32x32x16_bf16 v[0:15], v[88:91], v[154:157], v[0:15]
	v_mfma_f32_32x32x16_bf16 v[32:47], v[88:91], v[150:153], v[32:47]
	ds_read_b128 v[88:91], v131 offset:32768
	ds_read_b128 v[150:153], v132
	ds_read_b128 v[154:157], v132 offset:4096
	s_waitcnt lgkmcnt(0)
	v_mfma_f32_32x32x16_bf16 v[48:63], v[88:91], v[150:153], v[48:63]
	v_mfma_f32_32x32x16_bf16 v[16:31], v[88:91], v[154:157], v[16:31]
	ds_read_b128 v[88:91], v131 offset:36864
	s_waitcnt lgkmcnt(0)
	v_mfma_f32_32x32x16_bf16 v[32:47], v[88:91], v[150:153], v[32:47]
	v_mfma_f32_32x32x16_bf16 v[0:15], v[88:91], v[154:157], v[0:15]
	ds_read_b128 v[88:91], v133 offset:32768
	ds_read_b128 v[150:153], v134
	ds_read_b128 v[154:157], v134 offset:4096
	s_waitcnt lgkmcnt(0)
	v_mfma_f32_32x32x16_bf16 v[48:63], v[88:91], v[150:153], v[48:63]
	v_mfma_f32_32x32x16_bf16 v[16:31], v[88:91], v[154:157], v[16:31]
	ds_read_b128 v[88:91], v133 offset:36864
	s_waitcnt lgkmcnt(0)
	v_mfma_f32_32x32x16_bf16 v[32:47], v[88:91], v[150:153], v[32:47]
	v_mfma_f32_32x32x16_bf16 v[0:15], v[88:91], v[154:157], v[0:15]
	ds_read_b128 v[88:91], v135 offset:32768
	ds_read_b128 v[150:153], v136
	ds_read_b128 v[154:157], v136 offset:4096
	s_waitcnt lgkmcnt(0)
	v_mfma_f32_32x32x16_bf16 v[48:63], v[88:91], v[150:153], v[48:63]
	v_mfma_f32_32x32x16_bf16 v[16:31], v[88:91], v[154:157], v[16:31]
	ds_read_b128 v[88:91], v135 offset:36864
	s_waitcnt lgkmcnt(0)
	v_mfma_f32_32x32x16_bf16 v[32:47], v[88:91], v[150:153], v[32:47]
	v_mfma_f32_32x32x16_bf16 v[0:15], v[88:91], v[154:157], v[0:15]
	ds_read_b128 v[88:91], v137 offset:32768
	ds_read_b128 v[150:153], v138
	ds_read_b128 v[154:157], v138 offset:4096
	s_waitcnt lgkmcnt(0)
	v_mfma_f32_32x32x16_bf16 v[48:63], v[88:91], v[150:153], v[48:63]
	v_mfma_f32_32x32x16_bf16 v[16:31], v[88:91], v[154:157], v[16:31]
	ds_read_b128 v[88:91], v137 offset:36864
	s_waitcnt vmcnt(0)
	s_waitcnt lgkmcnt(0)
	s_barrier
	s_waitcnt lgkmcnt(0)
	v_mfma_f32_32x32x16_bf16 v[0:15], v[88:91], v[154:157], v[0:15]
	v_mfma_f32_32x32x16_bf16 v[32:47], v[88:91], v[150:153], v[32:47]
	ds_read_b128 v[88:91], v119 offset:32768
	ds_read_b128 v[150:153], v120
	ds_read_b128 v[154:157], v119 offset:36864
	ds_read_b128 v[158:161], v120 offset:4096
	s_mov_b64 s[54:55], 0
	s_waitcnt lgkmcnt(0)
	v_mfma_f32_32x32x16_bf16 v[48:63], v[88:91], v[150:153], v[48:63]
	v_mfma_f32_32x32x16_bf16 v[32:47], v[154:157], v[150:153], v[32:47]
	v_mfma_f32_32x32x16_bf16 v[0:15], v[154:157], v[158:161], v[0:15]
	v_mfma_f32_32x32x16_bf16 v[16:31], v[88:91], v[158:161], v[16:31]
	ds_read_b128 v[88:91], v121 offset:32768
	ds_read_b128 v[150:153], v122
	ds_read_b128 v[154:157], v121 offset:36864
	ds_read_b128 v[158:161], v122 offset:4096
	s_waitcnt lgkmcnt(0)
	v_mfma_f32_32x32x16_bf16 v[48:63], v[88:91], v[150:153], v[48:63]
	v_mfma_f32_32x32x16_bf16 v[32:47], v[154:157], v[150:153], v[32:47]
	v_mfma_f32_32x32x16_bf16 v[0:15], v[154:157], v[158:161], v[0:15]
	v_mfma_f32_32x32x16_bf16 v[16:31], v[88:91], v[158:161], v[16:31]
	ds_read_b128 v[88:91], v123 offset:32768
	ds_read_b128 v[150:153], v124
	ds_read_b128 v[154:157], v123 offset:36864
	ds_read_b128 v[158:161], v124 offset:4096
	s_waitcnt lgkmcnt(0)
	v_mfma_f32_32x32x16_bf16 v[48:63], v[88:91], v[150:153], v[48:63]
	v_mfma_f32_32x32x16_bf16 v[32:47], v[154:157], v[150:153], v[32:47]
	v_mfma_f32_32x32x16_bf16 v[0:15], v[154:157], v[158:161], v[0:15]
	v_mfma_f32_32x32x16_bf16 v[16:31], v[88:91], v[158:161], v[16:31]
	ds_read_b128 v[88:91], v125 offset:32768
	ds_read_b128 v[150:153], v126
	ds_read_b128 v[154:157], v125 offset:36864
	ds_read_b128 v[158:161], v126 offset:4096
	s_waitcnt vmcnt(0)
	s_waitcnt lgkmcnt(0)
	s_barrier
	s_waitcnt lgkmcnt(0)
	v_mfma_f32_32x32x16_bf16 v[48:63], v[88:91], v[150:153], v[48:63]
	v_mfma_f32_32x32x16_bf16 v[32:47], v[154:157], v[150:153], v[32:47]
	s_nop 10
	ds_write_b128 v139, v[48:51]
	ds_write_b128 v139, v[52:55] offset:32
	ds_write_b128 v139, v[56:59] offset:64
	ds_write_b128 v139, v[60:63] offset:96
	ds_write_b128 v139, v[32:35] offset:128
	v_mfma_f32_32x32x16_bf16 v[0:15], v[154:157], v[158:161], v[0:15]
	v_mfma_f32_32x32x16_bf16 v[16:31], v[88:91], v[158:161], v[16:31]
	ds_write_b128 v139, v[36:39] offset:160
	ds_write_b128 v139, v[40:43] offset:192
	ds_write_b128 v139, v[44:47] offset:224
	s_nop 8
	ds_write_b128 v139, v[16:19] offset:8704
	ds_write_b128 v139, v[20:23] offset:8736
	ds_write_b128 v139, v[24:27] offset:8768
	ds_write_b128 v139, v[28:31] offset:8800
	ds_write_b128 v139, v[0:3] offset:8832
	ds_write_b128 v139, v[4:7] offset:8864
	ds_write_b128 v139, v[8:11] offset:8896
	ds_write_b128 v139, v[12:15] offset:8928
	v_mov_b32_e32 v0, v103

; #define MFMA(a, b, c) __builtin_amdgcn_mfma_f32_32x32x16_bf16((a), (b), (c), 0, 0, 0)
; #define WAIT_V(n) asm volatile("s_waitcnt vmcnt(%0)" ::"n"(n) : "memory")
; DI void gemm_tile(const u16* __restrict__ X, int ldx, const u16* __restrict__ Wt, int ldw, int K, char* smem,
;                   f32x16 (&acc)[2][2]) {
;     ...
;   const int nk = K / 64;
;   const u16* src[6];
; #pragma unroll
;   for (int i = 0; i < 6; ++i) {
;     const int R = 8 * (wave + 8 * i) + (lane >> 3);
;     const int c = (lane & 7) ^ ((R >> 1) & 7);
;     src[i] = (i < 4) ? (X + (size_t)R * ldx + c * 8) : (Wt + (size_t)(R - 256) * ldw + c * 8);
;   }
;     ...
;   int offA[2], offB[2], xa[2], xb[2];
; #pragma unroll
;   for (int ft = 0; ft < 2; ++ft) { const int R = 256 + fw * 64 + ft * 32 + lr; offA[ft] = R * 128; xa[ft] = (R >> 1) & 7; }
; #pragma unroll
;   for (int tt = 0; tt < 2; ++tt) { const int R = tq * 64 + tt * 32 + lr; offB[tt] = R * 128; xb[tt] = (R >> 1) & 7; }
;   GLDS_STAGE(0, 0); GLDS_STAGE(1, 1); WAIT_V(6); RAW_BARRIER();
;   int cur = 0;
;   for (int kt = 0; kt < nk; ++kt) {
;     const int nxt = (cur >= 1) ? cur - 1 : 2;
;     if (kt + 2 < nk) GLDS_STAGE(nxt, kt + 2);
;     __builtin_amdgcn_sched_barrier(0);
;     const char* st = smem + cur * G_STAGE;
; #pragma unroll
;     for (int ks = 0; ks < 4; ++ks) {
;       bf16x8 a[2], b[2];
; #pragma unroll
;       for (int ft = 0; ft < 2; ++ft) a[ft] = *reinterpret_cast<const bf16x8*>(st + offA[ft] + (((ks * 2 + lh) ^ xa[ft]) << 4));
; #pragma unroll
;       for (int tt = 0; tt < 2; ++tt) b[tt] = *reinterpret_cast<const bf16x8*>(st + offB[tt] + (((ks * 2 + lh) ^ xb[tt]) << 4));
; #pragma unroll
;       for (int ft = 0; ft < 2; ++ft)
; #pragma unroll
;         for (int tt = 0; tt < 2; ++tt) acc[ft][tt] = MFMA(a[ft], b[tt], acc[ft][tt]);
;     }
;     if (kt + 2 < nk) { WAIT_V(6); } else { WAIT_V(0); }
;     RAW_BARRIER();
; template <int MODE>
; DI void phase_gemm(const Params& p, const u16* X, const u16* Wt, int N, const float* resid, float* outf, u16* outb, int ldo, char* smem) {
;     ...
;   for (int u = xi; u < per_group; u += xn) {
;     const int mt = xg + 8 * (u / ntn), nt = u % ntn;
;     f32x16 acc[2][2];
;     gemm_tile(X + (size_t)mt * 256 * 1024, 1024, Wt + (size_t)nt * 128 * 1024, 1024, 1024, smem, acc);
.LBB0_678:
	s_and_b32 s0, s54, 0x78
	s_or_b32 s89, s0, s33
	s_lshl_b32 s12, s89, 19
	v_lshl_add_u64 v[0:1], v[66:67], 0, s[12:13]
	v_readfirstlane_b32 s7, v143
	v_lshl_add_u64 v[74:75], v[0:1], 0, v[72:73]
	s_mov_b32 m0, s7
	v_readfirstlane_b32 s6, v90
	s_and_b32 s4, s87, 0xe0000
	v_lshl_add_u64 v[0:1], v[74:75], 0, s[14:15]
	s_mov_b64 s[0:1], 0x40000
	global_load_lds_dwordx4 v[74:75], off
	s_mov_b32 m0, s6
	v_readfirstlane_b32 s95, v91
	v_lshl_add_u64 v[2:3], v[74:75], 0, s[0:1]
	s_mov_b64 s[0:1], 0x60000
	s_lshl_b32 s12, s4, 1
	global_load_lds_dwordx4 v[0:1], off
	s_mov_b32 m0, s95
	v_readfirstlane_b32 s93, v92
	v_lshl_add_u64 v[4:5], v[74:75], 0, s[0:1]
	v_lshl_add_u64 v[6:7], v[68:69], 0, s[12:13]
	global_load_lds_dwordx4 v[2:3], off
	s_mov_b32 m0, s93
	v_readfirstlane_b32 s92, v93
	v_lshl_add_u64 v[76:77], v[6:7], 0, v[72:73]
	global_load_lds_dwordx4 v[4:5], off
	s_mov_b32 m0, s92
	v_readfirstlane_b32 s91, v94
	v_lshl_add_u64 v[6:7], v[76:77], 0, s[14:15]
	global_load_lds_dwordx4 v[76:77], off
	s_mov_b32 m0, s91
	v_readfirstlane_b32 s90, v78
	global_load_lds_dwordx4 v[6:7], off
	v_lshl_add_u64 v[0:1], v[74:75], 0, s[16:17]
	s_mov_b32 m0, s90
	v_readfirstlane_b32 s12, v95
	global_load_lds_dwordx4 v[0:1], off
	v_lshl_add_u64 v[0:1], v[74:75], 0, s[18:19]
	s_mov_b32 m0, s12
	s_mov_b64 s[0:1], 0x40080
	global_load_lds_dwordx4 v[0:1], off
	v_lshl_add_u64 v[0:1], v[74:75], 0, s[0:1]
	v_readfirstlane_b32 s0, v96
	s_mov_b32 m0, s0
	s_mov_b64 s[0:1], 0x60080
	global_load_lds_dwordx4 v[0:1], off
	v_lshl_add_u64 v[0:1], v[74:75], 0, s[0:1]
	v_readfirstlane_b32 s0, v97
	s_mov_b32 m0, s0
	v_readfirstlane_b32 s0, v98
	global_load_lds_dwordx4 v[0:1], off
	v_lshl_add_u64 v[0:1], v[76:77], 0, s[16:17]
	s_mov_b32 m0, s0
	v_readfirstlane_b32 s0, v99
	global_load_lds_dwordx4 v[0:1], off
	v_lshl_add_u64 v[0:1], v[76:77], 0, s[18:19]
	s_mov_b32 m0, s0
	v_readfirstlane_b32 s5, v79
	global_load_lds_dwordx4 v[0:1], off
	s_waitcnt vmcnt(6)
	s_waitcnt lgkmcnt(0)
	s_barrier
	v_lshl_add_u64 v[0:1], v[74:75], 0, s[20:21]
	s_mov_b32 m0, s5
	v_readfirstlane_b32 s4, v80
	global_load_lds_dwordx4 v[0:1], off
	v_lshl_add_u64 v[0:1], v[74:75], 0, s[22:23]
	s_mov_b32 m0, s4
	s_mov_b64 s[0:1], 0x40100
	global_load_lds_dwordx4 v[0:1], off
	v_lshl_add_u64 v[0:1], v[74:75], 0, s[0:1]
	v_readfirstlane_b32 s0, v81
	s_mov_b32 m0, s0
	s_mov_b64 s[8:9], 0x60100
	v_readfirstlane_b32 s1, v82
	global_load_lds_dwordx4 v[0:1], off
	v_lshl_add_u64 v[0:1], v[74:75], 0, s[8:9]
	s_mov_b32 m0, s1
	v_readfirstlane_b32 s10, v83
	global_load_lds_dwordx4 v[0:1], off
	v_lshl_add_u64 v[0:1], v[76:77], 0, s[20:21]
	s_mov_b32 m0, s10
	v_readfirstlane_b32 s11, v84
	global_load_lds_dwordx4 v[0:1], off
	v_lshl_add_u64 v[0:1], v[76:77], 0, s[22:23]
	s_mov_b32 m0, s11
	s_nop 0
	global_load_lds_dwordx4 v[0:1], off
	ds_read_b128 v[0:3], v100 offset:32768
	ds_read_b128 v[4:7], v100 offset:36864
	ds_read_b128 v[8:11], v101
	ds_read_b128 v[12:15], v101 offset:4096
	ds_read_b128 v[120:123], v102 offset:32768
	ds_read_b128 v[124:127], v102 offset:36864
	ds_read_b128 v[128:131], v103
	ds_read_b128 v[132:135], v103 offset:4096
	s_mov_b32 m0, s7
	s_mov_b64 s[8:9], 0x40180
	s_waitcnt lgkmcnt(0)
	v_mfma_f32_32x32x16_bf16 v[48:63], v[0:3], v[8:11], 0
	v_mfma_f32_32x32x16_bf16 v[16:31], v[0:3], v[12:15], 0
	v_mfma_f32_32x32x16_bf16 v[32:47], v[4:7], v[8:11], 0
	v_mfma_f32_32x32x16_bf16 v[0:15], v[4:7], v[12:15], 0
	ds_read_b128 v[184:187], v104 offset:32768
	ds_read_b128 v[188:191], v104 offset:36864
	ds_read_b128 v[192:195], v105
	ds_read_b128 v[196:199], v105 offset:4096
	s_waitcnt lgkmcnt(4)
	v_mfma_f32_32x32x16_bf16 v[48:63], v[120:123], v[128:131], v[48:63]
	v_mfma_f32_32x32x16_bf16 v[16:31], v[120:123], v[132:135], v[16:31]
	v_mfma_f32_32x32x16_bf16 v[32:47], v[124:127], v[128:131], v[32:47]
	v_mfma_f32_32x32x16_bf16 v[0:15], v[124:127], v[132:135], v[0:15]
	ds_read_b128 v[120:123], v106 offset:32768
	ds_read_b128 v[124:127], v106 offset:36864
	ds_read_b128 v[128:131], v107
	ds_read_b128 v[132:135], v107 offset:4096
	s_waitcnt lgkmcnt(4)
	v_mfma_f32_32x32x16_bf16 v[48:63], v[184:187], v[192:195], v[48:63]
	v_mfma_f32_32x32x16_bf16 v[16:31], v[184:187], v[196:199], v[16:31]
	v_mfma_f32_32x32x16_bf16 v[32:47], v[188:191], v[192:195], v[32:47]
	v_mfma_f32_32x32x16_bf16 v[0:15], v[188:191], v[196:199], v[0:15]
	s_waitcnt vmcnt(6)
	s_waitcnt lgkmcnt(0)
	s_barrier
; #define MFMA(a, b, c) __builtin_amdgcn_mfma_f32_32x32x16_bf16((a), (b), (c), 0, 0, 0)
; #define WAIT_V(n) asm volatile("s_waitcnt vmcnt(%0)" ::"n"(n) : "memory")
; #define RAW_BARRIER() do { asm volatile("s_waitcnt lgkmcnt(0)" ::: "memory"); __builtin_amdgcn_s_barrier(); asm volatile("" ::: "memory"); } while (0)
; #define GLDS_STAGE(slot, kt) do { _Pragma("unroll") for (int i = 0; i < 6; ++i) \
;     __builtin_amdgcn_global_load_lds((const unsigned*)(src[i] + (kt) * 64), (__attribute__((address_space(3))) unsigned*)(smem + (slot) * G_STAGE + (wave + 8 * i) * 1024), 16, 0, 0); } while (0)
; DI void gemm_tile(const u16* __restrict__ X, int ldx, const u16* __restrict__ Wt, int ldw, int K, char* smem,
;                   f32x16 (&acc)[2][2]) {
;     ...
;   for (int kt = 0; kt < nk; ++kt) {
;     const int nxt = (cur >= 1) ? cur - 1 : 2;
;     if (kt + 2 < nk) GLDS_STAGE(nxt, kt + 2);
;     __builtin_amdgcn_sched_barrier(0);
;     const char* st = smem + cur * G_STAGE;
; #pragma unroll
;     for (int ks = 0; ks < 4; ++ks) {
;       bf16x8 a[2], b[2];
; #pragma unroll
;       for (int ft = 0; ft < 2; ++ft) a[ft] = *reinterpret_cast<const bf16x8*>(st + offA[ft] + (((ks * 2 + lh) ^ xa[ft]) << 4));
; #pragma unroll
;       for (int tt = 0; tt < 2; ++tt) b[tt] = *reinterpret_cast<const bf16x8*>(st + offB[tt] + (((ks * 2 + lh) ^ xb[tt]) << 4));
; #pragma unroll
;       for (int ft = 0; ft < 2; ++ft)
; #pragma unroll
;         for (int tt = 0; tt < 2; ++tt) acc[ft][tt] = MFMA(a[ft], b[tt], acc[ft][tt]);
;     }
;     if (kt + 2 < nk) { WAIT_V(6); } else { WAIT_V(0); }
;     RAW_BARRIER();
	ds_read_b128 v[184:187], v108 offset:32768
	ds_read_b128 v[188:191], v108 offset:36864
	ds_read_b128 v[192:195], v101 offset:49152
	ds_read_b128 v[196:199], v101 offset:53248
	s_waitcnt lgkmcnt(4)
	v_mfma_f32_32x32x16_bf16 v[48:63], v[120:123], v[128:131], v[48:63]
	v_mfma_f32_32x32x16_bf16 v[16:31], v[120:123], v[132:135], v[16:31]
	v_lshl_add_u64 v[120:121], v[74:75], 0, s[24:25]
	global_load_lds_dwordx4 v[120:121], off
	v_lshl_add_u64 v[120:121], v[74:75], 0, s[26:27]
	s_mov_b32 m0, s6
	s_nop 0
	global_load_lds_dwordx4 v[120:121], off
	v_lshl_add_u64 v[120:121], v[74:75], 0, s[8:9]
	s_mov_b32 m0, s95
	s_mov_b64 s[8:9], 0x60180
	global_load_lds_dwordx4 v[120:121], off
	v_lshl_add_u64 v[120:121], v[74:75], 0, s[8:9]
	s_mov_b32 m0, s93
	v_mfma_f32_32x32x16_bf16 v[32:47], v[124:127], v[128:131], v[32:47]
	global_load_lds_dwordx4 v[120:121], off
	v_lshl_add_u64 v[120:121], v[76:77], 0, s[24:25]
	s_mov_b32 m0, s92
	s_nop 0
	global_load_lds_dwordx4 v[120:121], off
	v_lshl_add_u64 v[120:121], v[76:77], 0, s[26:27]
	s_mov_b32 m0, s91
	v_mfma_f32_32x32x16_bf16 v[0:15], v[124:127], v[132:135], v[0:15]
	global_load_lds_dwordx4 v[120:121], off
	s_mov_b32 m0, s90
	s_mov_b64 s[8:9], 0x40200
	s_mov_b64 s[46:47], 0x60200
	ds_read_b128 v[120:123], v109 offset:32768
	ds_read_b128 v[124:127], v109 offset:36864
	ds_read_b128 v[128:131], v103 offset:49152
	ds_read_b128 v[132:135], v103 offset:53248
	s_waitcnt lgkmcnt(4)
	v_mfma_f32_32x32x16_bf16 v[48:63], v[184:187], v[192:195], v[48:63]
	v_mfma_f32_32x32x16_bf16 v[16:31], v[184:187], v[196:199], v[16:31]
	v_mfma_f32_32x32x16_bf16 v[32:47], v[188:191], v[192:195], v[32:47]
	v_mfma_f32_32x32x16_bf16 v[0:15], v[188:191], v[196:199], v[0:15]
	ds_read_b128 v[184:187], v110 offset:32768
	ds_read_b128 v[188:191], v110 offset:36864
	ds_read_b128 v[192:195], v105 offset:49152
	ds_read_b128 v[196:199], v105 offset:53248
	s_waitcnt lgkmcnt(4)
	v_mfma_f32_32x32x16_bf16 v[48:63], v[120:123], v[128:131], v[48:63]
	v_mfma_f32_32x32x16_bf16 v[16:31], v[120:123], v[132:135], v[16:31]
	v_mfma_f32_32x32x16_bf16 v[32:47], v[124:127], v[128:131], v[32:47]
	v_mfma_f32_32x32x16_bf16 v[0:15], v[124:127], v[132:135], v[0:15]
	ds_read_b128 v[120:123], v111 offset:32768
	ds_read_b128 v[124:127], v111 offset:36864
	ds_read_b128 v[128:131], v107 offset:49152
	ds_read_b128 v[132:135], v107 offset:53248
	s_waitcnt lgkmcnt(4)
	v_mfma_f32_32x32x16_bf16 v[48:63], v[184:187], v[192:195], v[48:63]
	v_mfma_f32_32x32x16_bf16 v[16:31], v[184:187], v[196:199], v[16:31]
	v_mfma_f32_32x32x16_bf16 v[32:47], v[188:191], v[192:195], v[32:47]
	v_mfma_f32_32x32x16_bf16 v[0:15], v[188:191], v[196:199], v[0:15]
	s_waitcnt vmcnt(6)
	s_waitcnt lgkmcnt(0)
	s_barrier
	ds_read_b128 v[184:187], v112 offset:32768
	ds_read_b128 v[188:191], v112 offset:36864
	ds_read_b128 v[192:195], v113
	ds_read_b128 v[196:199], v113 offset:4096
	s_waitcnt lgkmcnt(4)
	v_mfma_f32_32x32x16_bf16 v[48:63], v[120:123], v[128:131], v[48:63]
	v_mfma_f32_32x32x16_bf16 v[16:31], v[120:123], v[132:135], v[16:31]
	v_lshl_add_u64 v[120:121], v[74:75], 0, s[28:29]
	global_load_lds_dwordx4 v[120:121], off
	v_lshl_add_u64 v[120:121], v[74:75], 0, s[30:31]
	s_mov_b32 m0, s12
	s_nop 0
	global_load_lds_dwordx4 v[120:121], off
	v_lshl_add_u64 v[120:121], v[74:75], 0, s[8:9]
	v_readfirstlane_b32 s8, v85
	s_mov_b32 m0, s8
	v_readfirstlane_b32 s9, v87
	global_load_lds_dwordx4 v[120:121], off
	v_lshl_add_u64 v[120:121], v[74:75], 0, s[46:47]
	v_readfirstlane_b32 s46, v86
	s_mov_b32 m0, s46
	v_readfirstlane_b32 s47, v88
	global_load_lds_dwordx4 v[120:121], off
	v_lshl_add_u64 v[120:121], v[76:77], 0, s[28:29]
	s_mov_b32 m0, s9
	v_mfma_f32_32x32x16_bf16 v[32:47], v[124:127], v[128:131], v[32:47]
	global_load_lds_dwordx4 v[120:121], off
	v_lshl_add_u64 v[120:121], v[76:77], 0, s[30:31]
	s_mov_b32 m0, s47
	s_nop 0
	global_load_lds_dwordx4 v[120:121], off
	v_mfma_f32_32x32x16_bf16 v[0:15], v[124:127], v[132:135], v[0:15]
	s_mov_b32 m0, s5
	s_mov_b64 vcc, 0x40280
	ds_read_b128 v[120:123], v114 offset:32768
	ds_read_b128 v[124:127], v114 offset:36864
	ds_read_b128 v[128:131], v115
	ds_read_b128 v[132:135], v115 offset:4096
	s_waitcnt lgkmcnt(4)
	v_mfma_f32_32x32x16_bf16 v[48:63], v[184:187], v[192:195], v[48:63]
	v_mfma_f32_32x32x16_bf16 v[16:31], v[184:187], v[196:199], v[16:31]
	v_mfma_f32_32x32x16_bf16 v[32:47], v[188:191], v[192:195], v[32:47]
	v_mfma_f32_32x32x16_bf16 v[0:15], v[188:191], v[196:199], v[0:15]
	ds_read_b128 v[184:187], v116 offset:32768
	ds_read_b128 v[188:191], v116 offset:36864
	ds_read_b128 v[192:195], v117
	ds_read_b128 v[196:199], v117 offset:4096
	s_waitcnt lgkmcnt(4)
	v_mfma_f32_32x32x16_bf16 v[48:63], v[120:123], v[128:131], v[48:63]
	v_mfma_f32_32x32x16_bf16 v[16:31], v[120:123], v[132:135], v[16:31]
	v_mfma_f32_32x32x16_bf16 v[32:47], v[124:127], v[128:131], v[32:47]
	v_mfma_f32_32x32x16_bf16 v[0:15], v[124:127], v[132:135], v[0:15]
	ds_read_b128 v[120:123], v118 offset:32768
	ds_read_b128 v[124:127], v118 offset:36864
	ds_read_b128 v[128:131], v119
	ds_read_b128 v[132:135], v119 offset:4096
	s_waitcnt lgkmcnt(4)
	v_mfma_f32_32x32x16_bf16 v[48:63], v[184:187], v[192:195], v[48:63]
	v_mfma_f32_32x32x16_bf16 v[16:31], v[184:187], v[196:199], v[16:31]
	v_mfma_f32_32x32x16_bf16 v[32:47], v[188:191], v[192:195], v[32:47]
	v_mfma_f32_32x32x16_bf16 v[0:15], v[188:191], v[196:199], v[0:15]
	s_waitcnt vmcnt(6)
	s_waitcnt lgkmcnt(0)
	s_barrier
; #define MFMA(a, b, c) __builtin_amdgcn_mfma_f32_32x32x16_bf16((a), (b), (c), 0, 0, 0)
; #define WAIT_V(n) asm volatile("s_waitcnt vmcnt(%0)" ::"n"(n) : "memory")
; #define RAW_BARRIER() do { asm volatile("s_waitcnt lgkmcnt(0)" ::: "memory"); __builtin_amdgcn_s_barrier(); asm volatile("" ::: "memory"); } while (0)
; #define GLDS_STAGE(slot, kt) do { _Pragma("unroll") for (int i = 0; i < 6; ++i) \
;     __builtin_amdgcn_global_load_lds((const unsigned*)(src[i] + (kt) * 64), (__attribute__((address_space(3))) unsigned*)(smem + (slot) * G_STAGE + (wave + 8 * i) * 1024), 16, 0, 0); } while (0)
; DI void gemm_tile(const u16* __restrict__ X, int ldx, const u16* __restrict__ Wt, int ldw, int K, char* smem,
;                   f32x16 (&acc)[2][2]) {
;     ...
;   for (int kt = 0; kt < nk; ++kt) {
;     const int nxt = (cur >= 1) ? cur - 1 : 2;
;     if (kt + 2 < nk) GLDS_STAGE(nxt, kt + 2);
;     __builtin_amdgcn_sched_barrier(0);
;     const char* st = smem + cur * G_STAGE;
; #pragma unroll
;     for (int ks = 0; ks < 4; ++ks) {
;       bf16x8 a[2], b[2];
; #pragma unroll
;       for (int ft = 0; ft < 2; ++ft) a[ft] = *reinterpret_cast<const bf16x8*>(st + offA[ft] + (((ks * 2 + lh) ^ xa[ft]) << 4));
; #pragma unroll
;       for (int tt = 0; tt < 2; ++tt) b[tt] = *reinterpret_cast<const bf16x8*>(st + offB[tt] + (((ks * 2 + lh) ^ xb[tt]) << 4));
; #pragma unroll
;       for (int ft = 0; ft < 2; ++ft)
; #pragma unroll
;         for (int tt = 0; tt < 2; ++tt) acc[ft][tt] = MFMA(a[ft], b[tt], acc[ft][tt]);
;     }
;     if (kt + 2 < nk) { WAIT_V(6); } else { WAIT_V(0); }
;     RAW_BARRIER();
	ds_read_b128 v[184:187], v100 offset:32768
	ds_read_b128 v[188:191], v100 offset:36864
	ds_read_b128 v[192:195], v101
	ds_read_b128 v[196:199], v101 offset:4096
	s_waitcnt lgkmcnt(4)
	v_mfma_f32_32x32x16_bf16 v[48:63], v[120:123], v[128:131], v[48:63]
	v_mfma_f32_32x32x16_bf16 v[16:31], v[120:123], v[132:135], v[16:31]
	v_lshl_add_u64 v[120:121], v[74:75], 0, s[34:35]
	global_load_lds_dwordx4 v[120:121], off
	v_lshl_add_u64 v[120:121], v[74:75], 0, s[36:37]
	s_mov_b32 m0, s4
	s_nop 0
	global_load_lds_dwordx4 v[120:121], off
	v_lshl_add_u64 v[120:121], v[74:75], 0, vcc
	s_mov_b32 m0, s0
	s_mov_b64 vcc, 0x60280
	global_load_lds_dwordx4 v[120:121], off
	v_lshl_add_u64 v[120:121], v[74:75], 0, vcc
	s_mov_b32 m0, s1
	v_mfma_f32_32x32x16_bf16 v[32:47], v[124:127], v[128:131], v[32:47]
	global_load_lds_dwordx4 v[120:121], off
	v_lshl_add_u64 v[120:121], v[76:77], 0, s[34:35]
	s_mov_b32 m0, s10
	s_nop 0
	global_load_lds_dwordx4 v[120:121], off
	v_lshl_add_u64 v[120:121], v[76:77], 0, s[36:37]
	s_mov_b32 m0, s11
	v_mfma_f32_32x32x16_bf16 v[0:15], v[124:127], v[132:135], v[0:15]
	global_load_lds_dwordx4 v[120:121], off
	s_mov_b32 m0, s7
	s_mov_b64 vcc, 0x40300
	ds_read_b128 v[120:123], v102 offset:32768
	ds_read_b128 v[124:127], v102 offset:36864
	ds_read_b128 v[128:131], v103
	ds_read_b128 v[132:135], v103 offset:4096
	s_waitcnt lgkmcnt(4)
	v_mfma_f32_32x32x16_bf16 v[48:63], v[184:187], v[192:195], v[48:63]
	v_mfma_f32_32x32x16_bf16 v[16:31], v[184:187], v[196:199], v[16:31]
	v_mfma_f32_32x32x16_bf16 v[32:47], v[188:191], v[192:195], v[32:47]
	v_mfma_f32_32x32x16_bf16 v[0:15], v[188:191], v[196:199], v[0:15]
	ds_read_b128 v[184:187], v104 offset:32768
	ds_read_b128 v[188:191], v104 offset:36864
	ds_read_b128 v[192:195], v105
	ds_read_b128 v[196:199], v105 offset:4096
	s_waitcnt lgkmcnt(4)
	v_mfma_f32_32x32x16_bf16 v[48:63], v[120:123], v[128:131], v[48:63]
	v_mfma_f32_32x32x16_bf16 v[16:31], v[120:123], v[132:135], v[16:31]
	v_mfma_f32_32x32x16_bf16 v[32:47], v[124:127], v[128:131], v[32:47]
	v_mfma_f32_32x32x16_bf16 v[0:15], v[124:127], v[132:135], v[0:15]
	ds_read_b128 v[120:123], v106 offset:32768
	ds_read_b128 v[124:127], v106 offset:36864
	ds_read_b128 v[128:131], v107
	ds_read_b128 v[132:135], v107 offset:4096
	s_waitcnt lgkmcnt(4)
	v_mfma_f32_32x32x16_bf16 v[48:63], v[184:187], v[192:195], v[48:63]
	v_mfma_f32_32x32x16_bf16 v[16:31], v[184:187], v[196:199], v[16:31]
	v_mfma_f32_32x32x16_bf16 v[32:47], v[188:191], v[192:195], v[32:47]
	v_mfma_f32_32x32x16_bf16 v[0:15], v[188:191], v[196:199], v[0:15]
	s_waitcnt vmcnt(6)
	s_waitcnt lgkmcnt(0)
	s_barrier
	ds_read_b128 v[184:187], v108 offset:32768
	ds_read_b128 v[188:191], v108 offset:36864
	ds_read_b128 v[192:195], v101 offset:49152
	ds_read_b128 v[196:199], v101 offset:53248
	s_waitcnt lgkmcnt(4)
	v_mfma_f32_32x32x16_bf16 v[48:63], v[120:123], v[128:131], v[48:63]
	v_mfma_f32_32x32x16_bf16 v[16:31], v[120:123], v[132:135], v[16:31]
	v_lshl_add_u64 v[120:121], v[74:75], 0, s[38:39]
	global_load_lds_dwordx4 v[120:121], off
	v_lshl_add_u64 v[120:121], v[74:75], 0, s[40:41]
	s_mov_b32 m0, s6
	s_nop 0
	global_load_lds_dwordx4 v[120:121], off
	v_lshl_add_u64 v[120:121], v[74:75], 0, vcc
	s_mov_b32 m0, s95
	s_mov_b64 vcc, 0x60300
	global_load_lds_dwordx4 v[120:121], off
	v_lshl_add_u64 v[120:121], v[74:75], 0, vcc
	s_mov_b32 m0, s93
	v_mfma_f32_32x32x16_bf16 v[32:47], v[124:127], v[128:131], v[32:47]
	global_load_lds_dwordx4 v[120:121], off
	v_lshl_add_u64 v[120:121], v[76:77], 0, s[38:39]
	s_mov_b32 m0, s92
	s_nop 0
	global_load_lds_dwordx4 v[120:121], off
	v_lshl_add_u64 v[120:121], v[76:77], 0, s[40:41]
	s_mov_b32 m0, s91
	v_mfma_f32_32x32x16_bf16 v[0:15], v[124:127], v[132:135], v[0:15]
	global_load_lds_dwordx4 v[120:121], off
	s_mov_b32 m0, s90
	s_mov_b64 vcc, 0x40380
	ds_read_b128 v[120:123], v109 offset:32768
	ds_read_b128 v[124:127], v109 offset:36864
	ds_read_b128 v[128:131], v103 offset:49152
	ds_read_b128 v[132:135], v103 offset:53248
	s_waitcnt lgkmcnt(4)
	v_mfma_f32_32x32x16_bf16 v[48:63], v[184:187], v[192:195], v[48:63]
	v_mfma_f32_32x32x16_bf16 v[16:31], v[184:187], v[196:199], v[16:31]
	v_mfma_f32_32x32x16_bf16 v[32:47], v[188:191], v[192:195], v[32:47]
	v_mfma_f32_32x32x16_bf16 v[0:15], v[188:191], v[196:199], v[0:15]
	ds_read_b128 v[184:187], v110 offset:32768
	ds_read_b128 v[188:191], v110 offset:36864
	ds_read_b128 v[192:195], v105 offset:49152
	ds_read_b128 v[196:199], v105 offset:53248
	s_waitcnt lgkmcnt(4)
	v_mfma_f32_32x32x16_bf16 v[48:63], v[120:123], v[128:131], v[48:63]
	v_mfma_f32_32x32x16_bf16 v[16:31], v[120:123], v[132:135], v[16:31]
	v_mfma_f32_32x32x16_bf16 v[32:47], v[124:127], v[128:131], v[32:47]
	v_mfma_f32_32x32x16_bf16 v[0:15], v[124:127], v[132:135], v[0:15]
	ds_read_b128 v[120:123], v111 offset:32768
	ds_read_b128 v[124:127], v111 offset:36864
	ds_read_b128 v[128:131], v107 offset:49152
	ds_read_b128 v[132:135], v107 offset:53248
	s_waitcnt lgkmcnt(4)
	v_mfma_f32_32x32x16_bf16 v[48:63], v[184:187], v[192:195], v[48:63]
	v_mfma_f32_32x32x16_bf16 v[16:31], v[184:187], v[196:199], v[16:31]
	v_mfma_f32_32x32x16_bf16 v[32:47], v[188:191], v[192:195], v[32:47]
	v_mfma_f32_32x32x16_bf16 v[0:15], v[188:191], v[196:199], v[0:15]
	s_waitcnt vmcnt(6)
	s_waitcnt lgkmcnt(0)
	s_barrier
; #define MFMA(a, b, c) __builtin_amdgcn_mfma_f32_32x32x16_bf16((a), (b), (c), 0, 0, 0)
; #define WAIT_V(n) asm volatile("s_waitcnt vmcnt(%0)" ::"n"(n) : "memory")
; #define RAW_BARRIER() do { asm volatile("s_waitcnt lgkmcnt(0)" ::: "memory"); __builtin_amdgcn_s_barrier(); asm volatile("" ::: "memory"); } while (0)
; #define GLDS_STAGE(slot, kt) do { _Pragma("unroll") for (int i = 0; i < 6; ++i) \
;     __builtin_amdgcn_global_load_lds((const unsigned*)(src[i] + (kt) * 64), (__attribute__((address_space(3))) unsigned*)(smem + (slot) * G_STAGE + (wave + 8 * i) * 1024), 16, 0, 0); } while (0)
; DI void gemm_tile(const u16* __restrict__ X, int ldx, const u16* __restrict__ Wt, int ldw, int K, char* smem,
;                   f32x16 (&acc)[2][2]) {
;     ...
;   for (int kt = 0; kt < nk; ++kt) {
;     const int nxt = (cur >= 1) ? cur - 1 : 2;
;     if (kt + 2 < nk) GLDS_STAGE(nxt, kt + 2);
;     __builtin_amdgcn_sched_barrier(0);
;     const char* st = smem + cur * G_STAGE;
; #pragma unroll
;     for (int ks = 0; ks < 4; ++ks) {
;       bf16x8 a[2], b[2];
; #pragma unroll
;       for (int ft = 0; ft < 2; ++ft) a[ft] = *reinterpret_cast<const bf16x8*>(st + offA[ft] + (((ks * 2 + lh) ^ xa[ft]) << 4));
; #pragma unroll
;       for (int tt = 0; tt < 2; ++tt) b[tt] = *reinterpret_cast<const bf16x8*>(st + offB[tt] + (((ks * 2 + lh) ^ xb[tt]) << 4));
; #pragma unroll
;       for (int ft = 0; ft < 2; ++ft)
; #pragma unroll
;         for (int tt = 0; tt < 2; ++tt) acc[ft][tt] = MFMA(a[ft], b[tt], acc[ft][tt]);
;     }
;     if (kt + 2 < nk) { WAIT_V(6); } else { WAIT_V(0); }
;     RAW_BARRIER();
	ds_read_b128 v[184:187], v112 offset:32768
	ds_read_b128 v[188:191], v112 offset:36864
	ds_read_b128 v[192:195], v113
	ds_read_b128 v[196:199], v113 offset:4096
	s_waitcnt lgkmcnt(4)
	v_mfma_f32_32x32x16_bf16 v[48:63], v[120:123], v[128:131], v[48:63]
	v_mfma_f32_32x32x16_bf16 v[16:31], v[120:123], v[132:135], v[16:31]
	v_lshl_add_u64 v[120:121], v[74:75], 0, s[42:43]
	global_load_lds_dwordx4 v[120:121], off
	v_lshl_add_u64 v[120:121], v[74:75], 0, s[44:45]
	s_mov_b32 m0, s12
	s_nop 0
	global_load_lds_dwordx4 v[120:121], off
	v_lshl_add_u64 v[120:121], v[74:75], 0, vcc
	s_mov_b32 m0, s8
	s_mov_b64 vcc, 0x60380
	global_load_lds_dwordx4 v[120:121], off
	v_lshl_add_u64 v[120:121], v[74:75], 0, vcc
	s_mov_b32 m0, s46
	v_mfma_f32_32x32x16_bf16 v[32:47], v[124:127], v[128:131], v[32:47]
	global_load_lds_dwordx4 v[120:121], off
	v_lshl_add_u64 v[120:121], v[76:77], 0, s[42:43]
	s_mov_b32 m0, s9
	s_nop 0
	global_load_lds_dwordx4 v[120:121], off
	v_lshl_add_u64 v[120:121], v[76:77], 0, s[44:45]
	s_mov_b32 m0, s47
	v_mfma_f32_32x32x16_bf16 v[0:15], v[124:127], v[132:135], v[0:15]
	global_load_lds_dwordx4 v[120:121], off
	s_mov_b32 m0, s5
	ds_read_b128 v[120:123], v114 offset:32768
	ds_read_b128 v[124:127], v114 offset:36864
	ds_read_b128 v[128:131], v115
	ds_read_b128 v[132:135], v115 offset:4096
	s_waitcnt lgkmcnt(4)
	v_mfma_f32_32x32x16_bf16 v[48:63], v[184:187], v[192:195], v[48:63]
	v_mfma_f32_32x32x16_bf16 v[16:31], v[184:187], v[196:199], v[16:31]
	v_mfma_f32_32x32x16_bf16 v[32:47], v[188:191], v[192:195], v[32:47]
	v_mfma_f32_32x32x16_bf16 v[0:15], v[188:191], v[196:199], v[0:15]
	ds_read_b128 v[184:187], v116 offset:32768
	ds_read_b128 v[188:191], v116 offset:36864
	ds_read_b128 v[192:195], v117
	ds_read_b128 v[196:199], v117 offset:4096
	s_waitcnt lgkmcnt(4)
	v_mfma_f32_32x32x16_bf16 v[48:63], v[120:123], v[128:131], v[48:63]
	v_mfma_f32_32x32x16_bf16 v[16:31], v[120:123], v[132:135], v[16:31]
	v_mfma_f32_32x32x16_bf16 v[32:47], v[124:127], v[128:131], v[32:47]
	v_mfma_f32_32x32x16_bf16 v[0:15], v[124:127], v[132:135], v[0:15]
	ds_read_b128 v[120:123], v118 offset:32768
	ds_read_b128 v[124:127], v118 offset:36864
	ds_read_b128 v[128:131], v119
	ds_read_b128 v[132:135], v119 offset:4096
	s_waitcnt lgkmcnt(4)
	v_mfma_f32_32x32x16_bf16 v[48:63], v[184:187], v[192:195], v[48:63]
	v_mfma_f32_32x32x16_bf16 v[16:31], v[184:187], v[196:199], v[16:31]
	v_mfma_f32_32x32x16_bf16 v[32:47], v[188:191], v[192:195], v[32:47]
	v_mfma_f32_32x32x16_bf16 v[0:15], v[188:191], v[196:199], v[0:15]
	s_waitcnt vmcnt(6)
	s_waitcnt lgkmcnt(0)
	s_barrier
	ds_read_b128 v[184:187], v100 offset:32768
	ds_read_b128 v[188:191], v100 offset:36864
	ds_read_b128 v[192:195], v101
	ds_read_b128 v[196:199], v101 offset:4096
	s_waitcnt lgkmcnt(4)
	v_mfma_f32_32x32x16_bf16 v[48:63], v[120:123], v[128:131], v[48:63]
	v_mfma_f32_32x32x16_bf16 v[16:31], v[120:123], v[132:135], v[16:31]
	v_lshl_add_u64 v[120:121], v[74:75], 0, s[48:49]
	global_load_lds_dwordx4 v[120:121], off
	v_lshl_add_u64 v[120:121], v[74:75], 0, s[50:51]
	s_mov_b32 m0, s4
	s_mov_b64 s[4:5], 0x40400
	global_load_lds_dwordx4 v[120:121], off
	v_lshl_add_u64 v[120:121], v[74:75], 0, s[4:5]
	s_mov_b32 m0, s0
	s_mov_b64 s[4:5], 0x60400
	global_load_lds_dwordx4 v[120:121], off
	v_lshl_add_u64 v[120:121], v[74:75], 0, s[4:5]
	s_mov_b32 m0, s1
	v_mfma_f32_32x32x16_bf16 v[32:47], v[124:127], v[128:131], v[32:47]
	global_load_lds_dwordx4 v[120:121], off
	v_lshl_add_u64 v[120:121], v[76:77], 0, s[48:49]
	s_mov_b32 m0, s10
	s_nop 0
	global_load_lds_dwordx4 v[120:121], off
	v_lshl_add_u64 v[120:121], v[76:77], 0, s[50:51]
	s_mov_b32 m0, s11
	v_mfma_f32_32x32x16_bf16 v[0:15], v[124:127], v[132:135], v[0:15]
	global_load_lds_dwordx4 v[120:121], off
	s_mov_b32 m0, s7
	s_mov_b64 s[0:1], 0x40480
	ds_read_b128 v[120:123], v102 offset:32768
	ds_read_b128 v[124:127], v102 offset:36864
	ds_read_b128 v[128:131], v103
	ds_read_b128 v[132:135], v103 offset:4096
	s_waitcnt lgkmcnt(4)
	v_mfma_f32_32x32x16_bf16 v[48:63], v[184:187], v[192:195], v[48:63]
	v_mfma_f32_32x32x16_bf16 v[16:31], v[184:187], v[196:199], v[16:31]
	v_mfma_f32_32x32x16_bf16 v[32:47], v[188:191], v[192:195], v[32:47]
	v_mfma_f32_32x32x16_bf16 v[0:15], v[188:191], v[196:199], v[0:15]
	ds_read_b128 v[184:187], v104 offset:32768
	ds_read_b128 v[188:191], v104 offset:36864
	ds_read_b128 v[192:195], v105
	ds_read_b128 v[196:199], v105 offset:4096
	s_waitcnt lgkmcnt(4)
	v_mfma_f32_32x32x16_bf16 v[48:63], v[120:123], v[128:131], v[48:63]
	v_mfma_f32_32x32x16_bf16 v[16:31], v[120:123], v[132:135], v[16:31]
	v_mfma_f32_32x32x16_bf16 v[32:47], v[124:127], v[128:131], v[32:47]
	v_mfma_f32_32x32x16_bf16 v[0:15], v[124:127], v[132:135], v[0:15]
	ds_read_b128 v[120:123], v106 offset:32768
	ds_read_b128 v[124:127], v106 offset:36864
	ds_read_b128 v[128:131], v107
	ds_read_b128 v[132:135], v107 offset:4096
	s_waitcnt lgkmcnt(4)
	v_mfma_f32_32x32x16_bf16 v[48:63], v[184:187], v[192:195], v[48:63]
	v_mfma_f32_32x32x16_bf16 v[16:31], v[184:187], v[196:199], v[16:31]
	v_mfma_f32_32x32x16_bf16 v[32:47], v[188:191], v[192:195], v[32:47]
	v_mfma_f32_32x32x16_bf16 v[0:15], v[188:191], v[196:199], v[0:15]
	s_waitcnt vmcnt(6)
	s_waitcnt lgkmcnt(0)
	s_barrier
; #define MFMA(a, b, c) __builtin_amdgcn_mfma_f32_32x32x16_bf16((a), (b), (c), 0, 0, 0)
; #define WAIT_V(n) asm volatile("s_waitcnt vmcnt(%0)" ::"n"(n) : "memory")
; #define RAW_BARRIER() do { asm volatile("s_waitcnt lgkmcnt(0)" ::: "memory"); __builtin_amdgcn_s_barrier(); asm volatile("" ::: "memory"); } while (0)
; #define GLDS_STAGE(slot, kt) do { _Pragma("unroll") for (int i = 0; i < 6; ++i) \
;     __builtin_amdgcn_global_load_lds((const unsigned*)(src[i] + (kt) * 64), (__attribute__((address_space(3))) unsigned*)(smem + (slot) * G_STAGE + (wave + 8 * i) * 1024), 16, 0, 0); } while (0)
; DI void gemm_tile(const u16* __restrict__ X, int ldx, const u16* __restrict__ Wt, int ldw, int K, char* smem,
;                   f32x16 (&acc)[2][2]) {
;     ...
;   for (int kt = 0; kt < nk; ++kt) {
;     const int nxt = (cur >= 1) ? cur - 1 : 2;
;     if (kt + 2 < nk) GLDS_STAGE(nxt, kt + 2);
;     __builtin_amdgcn_sched_barrier(0);
;     const char* st = smem + cur * G_STAGE;
; #pragma unroll
;     for (int ks = 0; ks < 4; ++ks) {
;       bf16x8 a[2], b[2];
; #pragma unroll
;       for (int ft = 0; ft < 2; ++ft) a[ft] = *reinterpret_cast<const bf16x8*>(st + offA[ft] + (((ks * 2 + lh) ^ xa[ft]) << 4));
; #pragma unroll
;       for (int tt = 0; tt < 2; ++tt) b[tt] = *reinterpret_cast<const bf16x8*>(st + offB[tt] + (((ks * 2 + lh) ^ xb[tt]) << 4));
; #pragma unroll
;       for (int ft = 0; ft < 2; ++ft)
; #pragma unroll
;         for (int tt = 0; tt < 2; ++tt) acc[ft][tt] = MFMA(a[ft], b[tt], acc[ft][tt]);
;     }
;     if (kt + 2 < nk) { WAIT_V(6); } else { WAIT_V(0); }
;     RAW_BARRIER();
	ds_read_b128 v[184:187], v108 offset:32768
	ds_read_b128 v[188:191], v108 offset:36864
	ds_read_b128 v[192:195], v101 offset:49152
	ds_read_b128 v[196:199], v101 offset:53248
	s_waitcnt lgkmcnt(4)
	v_mfma_f32_32x32x16_bf16 v[48:63], v[120:123], v[128:131], v[48:63]
	v_mfma_f32_32x32x16_bf16 v[16:31], v[120:123], v[132:135], v[16:31]
	v_lshl_add_u64 v[120:121], v[74:75], 0, s[52:53]
	global_load_lds_dwordx4 v[120:121], off
	v_lshl_add_u64 v[120:121], v[74:75], 0, s[56:57]
	s_mov_b32 m0, s6
	s_nop 0
	global_load_lds_dwordx4 v[120:121], off
	v_lshl_add_u64 v[120:121], v[74:75], 0, s[0:1]
	s_mov_b32 m0, s95
	s_mov_b64 s[0:1], 0x60480
	global_load_lds_dwordx4 v[120:121], off
	v_lshl_add_u64 v[120:121], v[74:75], 0, s[0:1]
	s_mov_b32 m0, s93
	v_mfma_f32_32x32x16_bf16 v[32:47], v[124:127], v[128:131], v[32:47]
	global_load_lds_dwordx4 v[120:121], off
	v_lshl_add_u64 v[120:121], v[76:77], 0, s[52:53]
	s_mov_b32 m0, s92
	s_nop 0
	global_load_lds_dwordx4 v[120:121], off
	v_lshl_add_u64 v[120:121], v[76:77], 0, s[56:57]
	s_mov_b32 m0, s91
	v_mfma_f32_32x32x16_bf16 v[0:15], v[124:127], v[132:135], v[0:15]
	global_load_lds_dwordx4 v[120:121], off
	s_mov_b32 m0, s90
	s_mov_b64 s[0:1], 0x40500
	ds_read_b128 v[120:123], v109 offset:32768
	ds_read_b128 v[124:127], v109 offset:36864
	ds_read_b128 v[128:131], v103 offset:49152
	ds_read_b128 v[132:135], v103 offset:53248
	s_waitcnt lgkmcnt(4)
	v_mfma_f32_32x32x16_bf16 v[48:63], v[184:187], v[192:195], v[48:63]
	v_mfma_f32_32x32x16_bf16 v[16:31], v[184:187], v[196:199], v[16:31]
	v_mfma_f32_32x32x16_bf16 v[32:47], v[188:191], v[192:195], v[32:47]
	v_mfma_f32_32x32x16_bf16 v[0:15], v[188:191], v[196:199], v[0:15]
	ds_read_b128 v[184:187], v110 offset:32768
	ds_read_b128 v[188:191], v110 offset:36864
	ds_read_b128 v[192:195], v105 offset:49152
	ds_read_b128 v[196:199], v105 offset:53248
	s_waitcnt lgkmcnt(4)
	v_mfma_f32_32x32x16_bf16 v[48:63], v[120:123], v[128:131], v[48:63]
	v_mfma_f32_32x32x16_bf16 v[16:31], v[120:123], v[132:135], v[16:31]
	v_mfma_f32_32x32x16_bf16 v[32:47], v[124:127], v[128:131], v[32:47]
	v_mfma_f32_32x32x16_bf16 v[0:15], v[124:127], v[132:135], v[0:15]
	ds_read_b128 v[120:123], v111 offset:32768
	ds_read_b128 v[124:127], v111 offset:36864
	ds_read_b128 v[128:131], v107 offset:49152
	ds_read_b128 v[132:135], v107 offset:53248
	s_waitcnt lgkmcnt(4)
	v_mfma_f32_32x32x16_bf16 v[48:63], v[184:187], v[192:195], v[48:63]
	v_mfma_f32_32x32x16_bf16 v[16:31], v[184:187], v[196:199], v[16:31]
	v_mfma_f32_32x32x16_bf16 v[32:47], v[188:191], v[192:195], v[32:47]
	v_mfma_f32_32x32x16_bf16 v[0:15], v[188:191], v[196:199], v[0:15]
	s_waitcnt vmcnt(6)
	s_waitcnt lgkmcnt(0)
	s_barrier
	ds_read_b128 v[184:187], v112 offset:32768
	ds_read_b128 v[188:191], v112 offset:36864
	ds_read_b128 v[192:195], v113
	ds_read_b128 v[196:199], v113 offset:4096
	s_waitcnt lgkmcnt(4)
	v_mfma_f32_32x32x16_bf16 v[48:63], v[120:123], v[128:131], v[48:63]
	v_mfma_f32_32x32x16_bf16 v[16:31], v[120:123], v[132:135], v[16:31]
	v_lshl_add_u64 v[120:121], v[74:75], 0, s[58:59]
	global_load_lds_dwordx4 v[120:121], off
	v_lshl_add_u64 v[120:121], v[74:75], 0, s[60:61]
	s_mov_b32 m0, s12
	s_nop 0
	global_load_lds_dwordx4 v[120:121], off
	v_lshl_add_u64 v[120:121], v[74:75], 0, s[0:1]
	s_mov_b32 m0, s8
	s_mov_b64 s[0:1], 0x60500
	global_load_lds_dwordx4 v[120:121], off
	v_lshl_add_u64 v[120:121], v[74:75], 0, s[0:1]
	s_mov_b32 m0, s46
	v_mfma_f32_32x32x16_bf16 v[32:47], v[124:127], v[128:131], v[32:47]
	global_load_lds_dwordx4 v[120:121], off
	v_lshl_add_u64 v[120:121], v[76:77], 0, s[58:59]
	s_mov_b32 m0, s9
	s_nop 0
	global_load_lds_dwordx4 v[120:121], off
	v_lshl_add_u64 v[120:121], v[76:77], 0, s[60:61]
	s_mov_b32 m0, s47
	v_mfma_f32_32x32x16_bf16 v[0:15], v[124:127], v[132:135], v[0:15]
	global_load_lds_dwordx4 v[120:121], off
	v_readfirstlane_b32 s46, v79
	s_mov_b32 m0, s46
	v_readfirstlane_b32 s7, v80
	ds_read_b128 v[120:123], v114 offset:32768
	ds_read_b128 v[124:127], v114 offset:36864
	ds_read_b128 v[128:131], v115
	ds_read_b128 v[132:135], v115 offset:4096
	s_waitcnt lgkmcnt(4)
	v_mfma_f32_32x32x16_bf16 v[48:63], v[184:187], v[192:195], v[48:63]
	s_mov_b64 s[0:1], 0x40580
	v_readfirstlane_b32 s8, v81
	v_readfirstlane_b32 s10, v82
	v_readfirstlane_b32 s9, v83
	v_readfirstlane_b32 s11, v84
	v_mfma_f32_32x32x16_bf16 v[16:31], v[184:187], v[196:199], v[16:31]
	v_mfma_f32_32x32x16_bf16 v[32:47], v[188:191], v[192:195], v[32:47]
	v_mfma_f32_32x32x16_bf16 v[0:15], v[188:191], v[196:199], v[0:15]
	ds_read_b128 v[184:187], v116 offset:32768
	ds_read_b128 v[188:191], v116 offset:36864
	ds_read_b128 v[192:195], v117
	ds_read_b128 v[196:199], v117 offset:4096
	s_waitcnt lgkmcnt(4)
	v_mfma_f32_32x32x16_bf16 v[48:63], v[120:123], v[128:131], v[48:63]
	v_mfma_f32_32x32x16_bf16 v[16:31], v[120:123], v[132:135], v[16:31]
	v_mfma_f32_32x32x16_bf16 v[32:47], v[124:127], v[128:131], v[32:47]
	v_mfma_f32_32x32x16_bf16 v[0:15], v[124:127], v[132:135], v[0:15]
	ds_read_b128 v[120:123], v118 offset:32768
	ds_read_b128 v[124:127], v118 offset:36864
	ds_read_b128 v[128:131], v119
	ds_read_b128 v[132:135], v119 offset:4096
	s_waitcnt lgkmcnt(4)
	v_mfma_f32_32x32x16_bf16 v[48:63], v[184:187], v[192:195], v[48:63]
	v_mfma_f32_32x32x16_bf16 v[16:31], v[184:187], v[196:199], v[16:31]
	v_mfma_f32_32x32x16_bf16 v[32:47], v[188:191], v[192:195], v[32:47]
	v_mfma_f32_32x32x16_bf16 v[0:15], v[188:191], v[196:199], v[0:15]
	s_waitcnt vmcnt(6)
	s_waitcnt lgkmcnt(0)
	s_barrier
; #define MFMA(a, b, c) __builtin_amdgcn_mfma_f32_32x32x16_bf16((a), (b), (c), 0, 0, 0)
; #define WAIT_V(n) asm volatile("s_waitcnt vmcnt(%0)" ::"n"(n) : "memory")
; #define RAW_BARRIER() do { asm volatile("s_waitcnt lgkmcnt(0)" ::: "memory"); __builtin_amdgcn_s_barrier(); asm volatile("" ::: "memory"); } while (0)
; #define GLDS_STAGE(slot, kt) do { _Pragma("unroll") for (int i = 0; i < 6; ++i) \
;     __builtin_amdgcn_global_load_lds((const unsigned*)(src[i] + (kt) * 64), (__attribute__((address_space(3))) unsigned*)(smem + (slot) * G_STAGE + (wave + 8 * i) * 1024), 16, 0, 0); } while (0)
; DI void gemm_tile(const u16* __restrict__ X, int ldx, const u16* __restrict__ Wt, int ldw, int K, char* smem,
;                   f32x16 (&acc)[2][2]) {
;     ...
;   for (int kt = 0; kt < nk; ++kt) {
;     const int nxt = (cur >= 1) ? cur - 1 : 2;
;     if (kt + 2 < nk) GLDS_STAGE(nxt, kt + 2);
;     __builtin_amdgcn_sched_barrier(0);
;     const char* st = smem + cur * G_STAGE;
; #pragma unroll
;     for (int ks = 0; ks < 4; ++ks) {
;       bf16x8 a[2], b[2];
; #pragma unroll
;       for (int ft = 0; ft < 2; ++ft) a[ft] = *reinterpret_cast<const bf16x8*>(st + offA[ft] + (((ks * 2 + lh) ^ xa[ft]) << 4));
; #pragma unroll
;       for (int tt = 0; tt < 2; ++tt) b[tt] = *reinterpret_cast<const bf16x8*>(st + offB[tt] + (((ks * 2 + lh) ^ xb[tt]) << 4));
; #pragma unroll
;       for (int ft = 0; ft < 2; ++ft)
; #pragma unroll
;         for (int tt = 0; tt < 2; ++tt) acc[ft][tt] = MFMA(a[ft], b[tt], acc[ft][tt]);
;     }
;     if (kt + 2 < nk) { WAIT_V(6); } else { WAIT_V(0); }
;     RAW_BARRIER();
	ds_read_b128 v[184:187], v100 offset:32768
	ds_read_b128 v[188:191], v100 offset:36864
	ds_read_b128 v[192:195], v101
	ds_read_b128 v[196:199], v101 offset:4096
	s_waitcnt lgkmcnt(4)
	v_mfma_f32_32x32x16_bf16 v[48:63], v[120:123], v[128:131], v[48:63]
	v_mfma_f32_32x32x16_bf16 v[16:31], v[120:123], v[132:135], v[16:31]
	v_lshl_add_u64 v[120:121], v[74:75], 0, s[62:63]
	global_load_lds_dwordx4 v[120:121], off
	v_lshl_add_u64 v[120:121], v[74:75], 0, s[64:65]
	s_mov_b32 m0, s7
	s_nop 0
	global_load_lds_dwordx4 v[120:121], off
	v_lshl_add_u64 v[120:121], v[74:75], 0, s[0:1]
	s_mov_b32 m0, s8
	s_mov_b64 s[0:1], 0x60580
	global_load_lds_dwordx4 v[120:121], off
	v_lshl_add_u64 v[120:121], v[74:75], 0, s[0:1]
	s_mov_b32 m0, s10
	v_mfma_f32_32x32x16_bf16 v[32:47], v[124:127], v[128:131], v[32:47]
	global_load_lds_dwordx4 v[120:121], off
	v_lshl_add_u64 v[120:121], v[76:77], 0, s[62:63]
	s_mov_b32 m0, s9
	s_nop 0
	global_load_lds_dwordx4 v[120:121], off
	v_lshl_add_u64 v[120:121], v[76:77], 0, s[64:65]
	s_mov_b32 m0, s11
	v_mfma_f32_32x32x16_bf16 v[0:15], v[124:127], v[132:135], v[0:15]
	global_load_lds_dwordx4 v[120:121], off
	v_readfirstlane_b32 s12, v143
	s_mov_b32 m0, s12
	v_readfirstlane_b32 s0, v90
	ds_read_b128 v[120:123], v102 offset:32768
	ds_read_b128 v[124:127], v102 offset:36864
	ds_read_b128 v[128:131], v103
	ds_read_b128 v[132:135], v103 offset:4096
	s_waitcnt lgkmcnt(4)
	v_mfma_f32_32x32x16_bf16 v[48:63], v[184:187], v[192:195], v[48:63]
	s_mov_b64 s[4:5], 0x40600
	v_readfirstlane_b32 s1, v91
	v_readfirstlane_b32 s6, v94
	v_mfma_f32_32x32x16_bf16 v[16:31], v[184:187], v[196:199], v[16:31]
	v_mfma_f32_32x32x16_bf16 v[32:47], v[188:191], v[192:195], v[32:47]
	v_mfma_f32_32x32x16_bf16 v[0:15], v[188:191], v[196:199], v[0:15]
	ds_read_b128 v[184:187], v104 offset:32768
	ds_read_b128 v[188:191], v104 offset:36864
	ds_read_b128 v[192:195], v105
	ds_read_b128 v[196:199], v105 offset:4096
	s_waitcnt lgkmcnt(4)
	v_mfma_f32_32x32x16_bf16 v[48:63], v[120:123], v[128:131], v[48:63]
	v_mfma_f32_32x32x16_bf16 v[16:31], v[120:123], v[132:135], v[16:31]
	v_mfma_f32_32x32x16_bf16 v[32:47], v[124:127], v[128:131], v[32:47]
	v_mfma_f32_32x32x16_bf16 v[0:15], v[124:127], v[132:135], v[0:15]
	ds_read_b128 v[120:123], v106 offset:32768
	ds_read_b128 v[124:127], v106 offset:36864
	ds_read_b128 v[128:131], v107
	ds_read_b128 v[132:135], v107 offset:4096
	s_waitcnt lgkmcnt(4)
	v_mfma_f32_32x32x16_bf16 v[48:63], v[184:187], v[192:195], v[48:63]
	v_mfma_f32_32x32x16_bf16 v[16:31], v[184:187], v[196:199], v[16:31]
	v_mfma_f32_32x32x16_bf16 v[32:47], v[188:191], v[192:195], v[32:47]
	v_mfma_f32_32x32x16_bf16 v[0:15], v[188:191], v[196:199], v[0:15]
	s_waitcnt vmcnt(6)
	s_waitcnt lgkmcnt(0)
	s_barrier
	ds_read_b128 v[184:187], v108 offset:32768
	ds_read_b128 v[188:191], v108 offset:36864
	ds_read_b128 v[192:195], v101 offset:49152
	ds_read_b128 v[196:199], v101 offset:53248
	s_waitcnt lgkmcnt(4)
	v_mfma_f32_32x32x16_bf16 v[48:63], v[120:123], v[128:131], v[48:63]
	v_mfma_f32_32x32x16_bf16 v[16:31], v[120:123], v[132:135], v[16:31]
	v_lshl_add_u64 v[120:121], v[74:75], 0, s[66:67]
	global_load_lds_dwordx4 v[120:121], off
	v_lshl_add_u64 v[120:121], v[74:75], 0, s[68:69]
	s_mov_b32 m0, s0
	s_nop 0
	global_load_lds_dwordx4 v[120:121], off
	v_lshl_add_u64 v[120:121], v[74:75], 0, s[4:5]
	s_mov_b32 m0, s1
	s_mov_b64 s[4:5], 0x60600
	global_load_lds_dwordx4 v[120:121], off
	v_lshl_add_u64 v[120:121], v[74:75], 0, s[4:5]
	v_readfirstlane_b32 s5, v92
	s_mov_b32 m0, s5
	v_readfirstlane_b32 s4, v93
	global_load_lds_dwordx4 v[120:121], off
	v_lshl_add_u64 v[120:121], v[76:77], 0, s[66:67]
	s_mov_b32 m0, s4
	v_mfma_f32_32x32x16_bf16 v[32:47], v[124:127], v[128:131], v[32:47]
	global_load_lds_dwordx4 v[120:121], off
	v_lshl_add_u64 v[120:121], v[76:77], 0, s[68:69]
	s_mov_b32 m0, s6
	s_nop 0
	global_load_lds_dwordx4 v[120:121], off
	v_mfma_f32_32x32x16_bf16 v[0:15], v[124:127], v[132:135], v[0:15]
	v_readfirstlane_b32 s47, v78
	s_mov_b32 m0, s47
	v_readfirstlane_b32 s47, v95
	ds_read_b128 v[120:123], v109 offset:32768
	ds_read_b128 v[124:127], v109 offset:36864
	ds_read_b128 v[128:131], v103 offset:49152
	ds_read_b128 v[132:135], v103 offset:53248
	s_waitcnt lgkmcnt(4)
	v_mfma_f32_32x32x16_bf16 v[48:63], v[184:187], v[192:195], v[48:63]
	s_mov_b64 s[90:91], 0x40680
	v_mfma_f32_32x32x16_bf16 v[16:31], v[184:187], v[196:199], v[16:31]
	v_mfma_f32_32x32x16_bf16 v[32:47], v[188:191], v[192:195], v[32:47]
	v_mfma_f32_32x32x16_bf16 v[0:15], v[188:191], v[196:199], v[0:15]
	ds_read_b128 v[184:187], v110 offset:32768
	ds_read_b128 v[188:191], v110 offset:36864
	ds_read_b128 v[192:195], v105 offset:49152
	ds_read_b128 v[196:199], v105 offset:53248
	s_waitcnt lgkmcnt(4)
	v_mfma_f32_32x32x16_bf16 v[48:63], v[120:123], v[128:131], v[48:63]
	v_mfma_f32_32x32x16_bf16 v[16:31], v[120:123], v[132:135], v[16:31]
	v_mfma_f32_32x32x16_bf16 v[32:47], v[124:127], v[128:131], v[32:47]
	v_mfma_f32_32x32x16_bf16 v[0:15], v[124:127], v[132:135], v[0:15]
	ds_read_b128 v[120:123], v111 offset:32768
	ds_read_b128 v[124:127], v111 offset:36864
	ds_read_b128 v[128:131], v107 offset:49152
	ds_read_b128 v[132:135], v107 offset:53248
	s_waitcnt lgkmcnt(4)
	v_mfma_f32_32x32x16_bf16 v[48:63], v[184:187], v[192:195], v[48:63]
	v_mfma_f32_32x32x16_bf16 v[16:31], v[184:187], v[196:199], v[16:31]
	v_mfma_f32_32x32x16_bf16 v[32:47], v[188:191], v[192:195], v[32:47]
	v_mfma_f32_32x32x16_bf16 v[0:15], v[188:191], v[196:199], v[0:15]
	s_waitcnt vmcnt(6)
	s_waitcnt lgkmcnt(0)
	s_barrier
; #define MFMA(a, b, c) __builtin_amdgcn_mfma_f32_32x32x16_bf16((a), (b), (c), 0, 0, 0)
; #define WAIT_V(n) asm volatile("s_waitcnt vmcnt(%0)" ::"n"(n) : "memory")
; #define RAW_BARRIER() do { asm volatile("s_waitcnt lgkmcnt(0)" ::: "memory"); __builtin_amdgcn_s_barrier(); asm volatile("" ::: "memory"); } while (0)
; #define GLDS_STAGE(slot, kt) do { _Pragma("unroll") for (int i = 0; i < 6; ++i) \
;     __builtin_amdgcn_global_load_lds((const unsigned*)(src[i] + (kt) * 64), (__attribute__((address_space(3))) unsigned*)(smem + (slot) * G_STAGE + (wave + 8 * i) * 1024), 16, 0, 0); } while (0)
; DI void gemm_tile(const u16* __restrict__ X, int ldx, const u16* __restrict__ Wt, int ldw, int K, char* smem,
;                   f32x16 (&acc)[2][2]) {
;     ...
;   for (int kt = 0; kt < nk; ++kt) {
;     const int nxt = (cur >= 1) ? cur - 1 : 2;
;     if (kt + 2 < nk) GLDS_STAGE(nxt, kt + 2);
;     __builtin_amdgcn_sched_barrier(0);
;     const char* st = smem + cur * G_STAGE;
; #pragma unroll
;     for (int ks = 0; ks < 4; ++ks) {
;       bf16x8 a[2], b[2];
; #pragma unroll
;       for (int ft = 0; ft < 2; ++ft) a[ft] = *reinterpret_cast<const bf16x8*>(st + offA[ft] + (((ks * 2 + lh) ^ xa[ft]) << 4));
; #pragma unroll
;       for (int tt = 0; tt < 2; ++tt) b[tt] = *reinterpret_cast<const bf16x8*>(st + offB[tt] + (((ks * 2 + lh) ^ xb[tt]) << 4));
; #pragma unroll
;       for (int ft = 0; ft < 2; ++ft)
; #pragma unroll
;         for (int tt = 0; tt < 2; ++tt) acc[ft][tt] = MFMA(a[ft], b[tt], acc[ft][tt]);
;     }
;     if (kt + 2 < nk) { WAIT_V(6); } else { WAIT_V(0); }
;     RAW_BARRIER();
	ds_read_b128 v[184:187], v112 offset:32768
	ds_read_b128 v[188:191], v112 offset:36864
	ds_read_b128 v[192:195], v113
	ds_read_b128 v[196:199], v113 offset:4096
	s_waitcnt lgkmcnt(4)
	v_mfma_f32_32x32x16_bf16 v[48:63], v[120:123], v[128:131], v[48:63]
	v_mfma_f32_32x32x16_bf16 v[16:31], v[120:123], v[132:135], v[16:31]
	v_lshl_add_u64 v[120:121], v[74:75], 0, s[70:71]
	global_load_lds_dwordx4 v[120:121], off
	v_lshl_add_u64 v[120:121], v[74:75], 0, s[72:73]
	s_mov_b32 m0, s47
	v_readfirstlane_b32 s47, v85
	global_load_lds_dwordx4 v[120:121], off
	v_lshl_add_u64 v[120:121], v[74:75], 0, s[90:91]
	s_mov_b32 m0, s47
	s_mov_b64 s[90:91], 0x60680
	v_readfirstlane_b32 s47, v86
	global_load_lds_dwordx4 v[120:121], off
	v_lshl_add_u64 v[120:121], v[74:75], 0, s[90:91]
	s_mov_b32 m0, s47
	v_readfirstlane_b32 s47, v87
	global_load_lds_dwordx4 v[120:121], off
	v_lshl_add_u64 v[120:121], v[76:77], 0, s[70:71]
	s_mov_b32 m0, s47
	v_readfirstlane_b32 s47, v88
	global_load_lds_dwordx4 v[120:121], off
	v_lshl_add_u64 v[120:121], v[76:77], 0, s[72:73]
	s_mov_b32 m0, s47
	v_mfma_f32_32x32x16_bf16 v[32:47], v[124:127], v[128:131], v[32:47]
	global_load_lds_dwordx4 v[120:121], off
	v_mfma_f32_32x32x16_bf16 v[0:15], v[124:127], v[132:135], v[0:15]
	s_mov_b32 m0, s46
	s_mov_b64 s[46:47], 0x40700
	ds_read_b128 v[120:123], v114 offset:32768
	ds_read_b128 v[124:127], v114 offset:36864
	ds_read_b128 v[128:131], v115
	ds_read_b128 v[132:135], v115 offset:4096
	s_waitcnt lgkmcnt(4)
	v_mfma_f32_32x32x16_bf16 v[48:63], v[184:187], v[192:195], v[48:63]
	v_mfma_f32_32x32x16_bf16 v[16:31], v[184:187], v[196:199], v[16:31]
	v_mfma_f32_32x32x16_bf16 v[32:47], v[188:191], v[192:195], v[32:47]
	v_mfma_f32_32x32x16_bf16 v[0:15], v[188:191], v[196:199], v[0:15]
	ds_read_b128 v[184:187], v116 offset:32768
	ds_read_b128 v[188:191], v116 offset:36864
	ds_read_b128 v[192:195], v117
	ds_read_b128 v[196:199], v117 offset:4096
	s_waitcnt lgkmcnt(4)
	v_mfma_f32_32x32x16_bf16 v[48:63], v[120:123], v[128:131], v[48:63]
	v_mfma_f32_32x32x16_bf16 v[16:31], v[120:123], v[132:135], v[16:31]
	v_mfma_f32_32x32x16_bf16 v[32:47], v[124:127], v[128:131], v[32:47]
	v_mfma_f32_32x32x16_bf16 v[0:15], v[124:127], v[132:135], v[0:15]
	ds_read_b128 v[120:123], v118 offset:32768
	ds_read_b128 v[124:127], v118 offset:36864
	ds_read_b128 v[128:131], v119
	ds_read_b128 v[132:135], v119 offset:4096
	s_waitcnt lgkmcnt(4)
	v_mfma_f32_32x32x16_bf16 v[48:63], v[184:187], v[192:195], v[48:63]
	v_mfma_f32_32x32x16_bf16 v[16:31], v[184:187], v[196:199], v[16:31]
	v_mfma_f32_32x32x16_bf16 v[32:47], v[188:191], v[192:195], v[32:47]
	v_mfma_f32_32x32x16_bf16 v[0:15], v[188:191], v[196:199], v[0:15]
	s_waitcnt vmcnt(6)
	s_waitcnt lgkmcnt(0)
	s_barrier
	ds_read_b128 v[184:187], v100 offset:32768
	ds_read_b128 v[188:191], v100 offset:36864
	ds_read_b128 v[192:195], v101
	ds_read_b128 v[196:199], v101 offset:4096
	s_waitcnt lgkmcnt(4)
	v_mfma_f32_32x32x16_bf16 v[48:63], v[120:123], v[128:131], v[48:63]
	v_mfma_f32_32x32x16_bf16 v[16:31], v[120:123], v[132:135], v[16:31]
	v_lshl_add_u64 v[120:121], v[74:75], 0, s[74:75]
	global_load_lds_dwordx4 v[120:121], off
	v_lshl_add_u64 v[120:121], v[74:75], 0, s[76:77]
	s_mov_b32 m0, s7
	s_nop 0
	global_load_lds_dwordx4 v[120:121], off
	v_lshl_add_u64 v[120:121], v[74:75], 0, s[46:47]
	s_mov_b32 m0, s8
	s_mov_b64 s[46:47], 0x60700
	global_load_lds_dwordx4 v[120:121], off
	v_lshl_add_u64 v[120:121], v[74:75], 0, s[46:47]
	s_mov_b32 m0, s10
	v_mfma_f32_32x32x16_bf16 v[32:47], v[124:127], v[128:131], v[32:47]
	global_load_lds_dwordx4 v[120:121], off
	v_lshl_add_u64 v[120:121], v[76:77], 0, s[74:75]
	s_mov_b32 m0, s9
	s_nop 0
	global_load_lds_dwordx4 v[120:121], off
	v_lshl_add_u64 v[120:121], v[76:77], 0, s[76:77]
	s_mov_b32 m0, s11
	v_mfma_f32_32x32x16_bf16 v[0:15], v[124:127], v[132:135], v[0:15]
	global_load_lds_dwordx4 v[120:121], off
	s_mov_b32 m0, s12
	s_mov_b64 s[8:9], 0x40780
	ds_read_b128 v[120:123], v102 offset:32768
	ds_read_b128 v[124:127], v102 offset:36864
	ds_read_b128 v[128:131], v103
	ds_read_b128 v[132:135], v103 offset:4096
	s_waitcnt lgkmcnt(4)
	v_mfma_f32_32x32x16_bf16 v[48:63], v[184:187], v[192:195], v[48:63]
	v_mfma_f32_32x32x16_bf16 v[16:31], v[184:187], v[196:199], v[16:31]
	v_mfma_f32_32x32x16_bf16 v[32:47], v[188:191], v[192:195], v[32:47]
	v_mfma_f32_32x32x16_bf16 v[0:15], v[188:191], v[196:199], v[0:15]
	ds_read_b128 v[184:187], v104 offset:32768
	ds_read_b128 v[188:191], v104 offset:36864
	ds_read_b128 v[192:195], v105
	ds_read_b128 v[196:199], v105 offset:4096
	s_waitcnt lgkmcnt(4)
	v_mfma_f32_32x32x16_bf16 v[48:63], v[120:123], v[128:131], v[48:63]
	v_mfma_f32_32x32x16_bf16 v[16:31], v[120:123], v[132:135], v[16:31]
	v_mfma_f32_32x32x16_bf16 v[32:47], v[124:127], v[128:131], v[32:47]
	v_mfma_f32_32x32x16_bf16 v[0:15], v[124:127], v[132:135], v[0:15]
	s_waitcnt lgkmcnt(0)
	v_mfma_f32_32x32x16_bf16 v[48:63], v[184:187], v[192:195], v[48:63]
	v_mfma_f32_32x32x16_bf16 v[16:31], v[184:187], v[196:199], v[16:31]
	v_mfma_f32_32x32x16_bf16 v[32:47], v[188:191], v[192:195], v[32:47]
	v_mfma_f32_32x32x16_bf16 v[0:15], v[188:191], v[196:199], v[0:15]
	ds_read_b128 v[120:123], v106 offset:32768
	ds_read_b128 v[124:127], v106 offset:36864
	ds_read_b128 v[128:131], v107
	ds_read_b128 v[132:135], v107 offset:4096
	s_waitcnt vmcnt(6)
	s_waitcnt lgkmcnt(0)
	s_barrier
; #define MFMA(a, b, c) __builtin_amdgcn_mfma_f32_32x32x16_bf16((a), (b), (c), 0, 0, 0)
; #define WAIT_V(n) asm volatile("s_waitcnt vmcnt(%0)" ::"n"(n) : "memory")
; #define RAW_BARRIER() do { asm volatile("s_waitcnt lgkmcnt(0)" ::: "memory"); __builtin_amdgcn_s_barrier(); asm volatile("" ::: "memory"); } while (0)
; #define GLDS_STAGE(slot, kt) do { _Pragma("unroll") for (int i = 0; i < 6; ++i) \
;     __builtin_amdgcn_global_load_lds((const unsigned*)(src[i] + (kt) * 64), (__attribute__((address_space(3))) unsigned*)(smem + (slot) * G_STAGE + (wave + 8 * i) * 1024), 16, 0, 0); } while (0)
; DI void gemm_tile(const u16* __restrict__ X, int ldx, const u16* __restrict__ Wt, int ldw, int K, char* smem,
;                   f32x16 (&acc)[2][2]) {
;     ...
;   for (int kt = 0; kt < nk; ++kt) {
;     const int nxt = (cur >= 1) ? cur - 1 : 2;
;     if (kt + 2 < nk) GLDS_STAGE(nxt, kt + 2);
;     __builtin_amdgcn_sched_barrier(0);
;     const char* st = smem + cur * G_STAGE;
; #pragma unroll
;     for (int ks = 0; ks < 4; ++ks) {
;       bf16x8 a[2], b[2];
; #pragma unroll
;       for (int ft = 0; ft < 2; ++ft) a[ft] = *reinterpret_cast<const bf16x8*>(st + offA[ft] + (((ks * 2 + lh) ^ xa[ft]) << 4));
; #pragma unroll
;       for (int tt = 0; tt < 2; ++tt) b[tt] = *reinterpret_cast<const bf16x8*>(st + offB[tt] + (((ks * 2 + lh) ^ xb[tt]) << 4));
; #pragma unroll
;       for (int ft = 0; ft < 2; ++ft)
; #pragma unroll
;         for (int tt = 0; tt < 2; ++tt) acc[ft][tt] = MFMA(a[ft], b[tt], acc[ft][tt]);
;     }
;     if (kt + 2 < nk) { WAIT_V(6); } else { WAIT_V(0); }
;     RAW_BARRIER();
	s_waitcnt lgkmcnt(0)
	v_mfma_f32_32x32x16_bf16 v[48:63], v[120:123], v[128:131], v[48:63]
	v_mfma_f32_32x32x16_bf16 v[16:31], v[120:123], v[132:135], v[16:31]
	v_lshl_add_u64 v[120:121], v[74:75], 0, s[80:81]
	global_load_lds_dwordx4 v[120:121], off
	v_lshl_add_u64 v[120:121], v[74:75], 0, s[84:85]
	s_mov_b32 m0, s0
	s_nop 0
	global_load_lds_dwordx4 v[120:121], off
	v_lshl_add_u64 v[120:121], v[74:75], 0, s[8:9]
	s_mov_b32 m0, s1
	s_mov_b64 s[0:1], 0x60780
	global_load_lds_dwordx4 v[120:121], off
	v_lshl_add_u64 v[74:75], v[74:75], 0, s[0:1]
	s_mov_b32 m0, s5
	v_mfma_f32_32x32x16_bf16 v[32:47], v[124:127], v[128:131], v[32:47]
	global_load_lds_dwordx4 v[74:75], off
	v_lshl_add_u64 v[74:75], v[76:77], 0, s[80:81]
	s_mov_b32 m0, s4
	s_nop 0
	global_load_lds_dwordx4 v[74:75], off
	v_lshl_add_u64 v[74:75], v[76:77], 0, s[84:85]
	s_mov_b32 m0, s6
	v_mfma_f32_32x32x16_bf16 v[0:15], v[124:127], v[132:135], v[0:15]
	global_load_lds_dwordx4 v[74:75], off
	ds_read_b128 v[74:77], v108 offset:32768
	ds_read_b128 v[120:123], v101 offset:49152
	ds_read_b128 v[124:127], v101 offset:53248
	s_waitcnt lgkmcnt(0)
	v_mfma_f32_32x32x16_bf16 v[48:63], v[74:77], v[120:123], v[48:63]
	v_mfma_f32_32x32x16_bf16 v[16:31], v[74:77], v[124:127], v[16:31]
	ds_read_b128 v[74:77], v108 offset:36864
	s_waitcnt lgkmcnt(0)
	v_mfma_f32_32x32x16_bf16 v[32:47], v[74:77], v[120:123], v[32:47]
	v_mfma_f32_32x32x16_bf16 v[0:15], v[74:77], v[124:127], v[0:15]
	ds_read_b128 v[74:77], v109 offset:32768
	ds_read_b128 v[120:123], v103 offset:49152
	ds_read_b128 v[124:127], v103 offset:53248
	s_waitcnt lgkmcnt(0)
	v_mfma_f32_32x32x16_bf16 v[48:63], v[74:77], v[120:123], v[48:63]
	v_mfma_f32_32x32x16_bf16 v[16:31], v[74:77], v[124:127], v[16:31]
	ds_read_b128 v[74:77], v109 offset:36864
	s_waitcnt lgkmcnt(0)
	v_mfma_f32_32x32x16_bf16 v[32:47], v[74:77], v[120:123], v[32:47]
	v_mfma_f32_32x32x16_bf16 v[0:15], v[74:77], v[124:127], v[0:15]
	ds_read_b128 v[74:77], v110 offset:32768
	ds_read_b128 v[120:123], v105 offset:49152
	ds_read_b128 v[124:127], v105 offset:53248
	s_waitcnt lgkmcnt(0)
	v_mfma_f32_32x32x16_bf16 v[48:63], v[74:77], v[120:123], v[48:63]
	v_mfma_f32_32x32x16_bf16 v[16:31], v[74:77], v[124:127], v[16:31]
	ds_read_b128 v[74:77], v110 offset:36864
	s_waitcnt lgkmcnt(0)
	v_mfma_f32_32x32x16_bf16 v[32:47], v[74:77], v[120:123], v[32:47]
	v_mfma_f32_32x32x16_bf16 v[0:15], v[74:77], v[124:127], v[0:15]
	ds_read_b128 v[74:77], v111 offset:32768
	ds_read_b128 v[120:123], v107 offset:49152
	ds_read_b128 v[124:127], v107 offset:53248
	s_waitcnt lgkmcnt(0)
	v_mfma_f32_32x32x16_bf16 v[48:63], v[74:77], v[120:123], v[48:63]
	v_mfma_f32_32x32x16_bf16 v[16:31], v[74:77], v[124:127], v[16:31]
	ds_read_b128 v[74:77], v111 offset:36864
	s_waitcnt vmcnt(6)
	s_waitcnt lgkmcnt(0)
	s_barrier
	s_waitcnt lgkmcnt(0)
	v_mfma_f32_32x32x16_bf16 v[32:47], v[74:77], v[120:123], v[32:47]
	v_mfma_f32_32x32x16_bf16 v[0:15], v[74:77], v[124:127], v[0:15]
	ds_read_b128 v[74:77], v112 offset:32768
	ds_read_b128 v[120:123], v113
	ds_read_b128 v[124:127], v113 offset:4096
	s_waitcnt lgkmcnt(0)
	v_mfma_f32_32x32x16_bf16 v[48:63], v[74:77], v[120:123], v[48:63]
	v_mfma_f32_32x32x16_bf16 v[16:31], v[74:77], v[124:127], v[16:31]
	ds_read_b128 v[74:77], v112 offset:36864
	s_waitcnt lgkmcnt(0)
	v_mfma_f32_32x32x16_bf16 v[32:47], v[74:77], v[120:123], v[32:47]
	v_mfma_f32_32x32x16_bf16 v[0:15], v[74:77], v[124:127], v[0:15]
	ds_read_b128 v[74:77], v114 offset:32768
	ds_read_b128 v[120:123], v115
	ds_read_b128 v[124:127], v115 offset:4096
	s_waitcnt lgkmcnt(0)
	v_mfma_f32_32x32x16_bf16 v[48:63], v[74:77], v[120:123], v[48:63]
	v_mfma_f32_32x32x16_bf16 v[16:31], v[74:77], v[124:127], v[16:31]
	ds_read_b128 v[74:77], v114 offset:36864
	s_waitcnt lgkmcnt(0)
	v_mfma_f32_32x32x16_bf16 v[32:47], v[74:77], v[120:123], v[32:47]
	v_mfma_f32_32x32x16_bf16 v[0:15], v[74:77], v[124:127], v[0:15]
	ds_read_b128 v[74:77], v116 offset:32768
	ds_read_b128 v[120:123], v117
	ds_read_b128 v[124:127], v117 offset:4096
	s_waitcnt lgkmcnt(0)
	v_mfma_f32_32x32x16_bf16 v[48:63], v[74:77], v[120:123], v[48:63]
	v_mfma_f32_32x32x16_bf16 v[16:31], v[74:77], v[124:127], v[16:31]
	ds_read_b128 v[74:77], v116 offset:36864
	s_waitcnt lgkmcnt(0)
	v_mfma_f32_32x32x16_bf16 v[32:47], v[74:77], v[120:123], v[32:47]
	v_mfma_f32_32x32x16_bf16 v[0:15], v[74:77], v[124:127], v[0:15]
	ds_read_b128 v[74:77], v118 offset:32768
	ds_read_b128 v[120:123], v119
	ds_read_b128 v[124:127], v119 offset:4096
	s_waitcnt lgkmcnt(0)
	v_mfma_f32_32x32x16_bf16 v[48:63], v[74:77], v[120:123], v[48:63]
	v_mfma_f32_32x32x16_bf16 v[16:31], v[74:77], v[124:127], v[16:31]
	ds_read_b128 v[74:77], v118 offset:36864
	s_waitcnt vmcnt(0)
	s_waitcnt lgkmcnt(0)
	s_barrier
; #define WAIT_V(n) asm volatile("s_waitcnt vmcnt(%0)" ::"n"(n) : "memory")
; #define RAW_BARRIER() do { asm volatile("s_waitcnt lgkmcnt(0)" ::: "memory"); __builtin_amdgcn_s_barrier(); asm volatile("" ::: "memory"); } while (0)
; DI void gemm_tile(const u16* __restrict__ X, int ldx, const u16* __restrict__ Wt, int ldw, int K, char* smem,
;                   f32x16 (&acc)[2][2]) {
;     ...
;     if (kt + 2 < nk) { WAIT_V(6); } else { WAIT_V(0); }
;     RAW_BARRIER();
;     cur = (cur == 2) ? 0 : cur + 1;
;   }
; template <int MODE>
; DI void phase_gemm(const Params& p, const u16* X, const u16* Wt, int N, const float* resid, float* outf, u16* outb, int ldo, char* smem) {
;     ...
; #pragma unroll
;       for (int tt = 0; tt < 2; ++tt) {
;         const int tok = mt * 256 + tq * 64 + tt * 32 + lr;
; #pragma unroll
;         for (int ft = 0; ft < 2; ++ft)
; #pragma unroll
;           for (int g = 0; g < 4; ++g) {
;             const int f = nt * 128 + fw * 64 + ft * 32 + 8 * g + 4 * lh;
;             if (MODE == 2) {
;               const int hh = f >> 8, fh = f & 255, ks = fh >> 4, lane2 = ((fh >> 3) & 1) * 32 + lr;
;               st4bf(outb + ((((size_t)(tok >> 5) * 4 + hh) * 16 + ks) * 64 + lane2) * 8 + 4 * lh, acc[ft][tt][4 * g], acc[ft][tt][4 * g + 1], acc[ft][tt][4 * g + 2], acc[ft][tt][4 * g + 3]);
;             } else {
;               const int hh = f >> 8, fq = f & 127, half = (f >> 7) & 1, ks = fq >> 4, lane2 = ((fq >> 3) & 1) * 32 + lr;
;               st4bf(outb + (((((size_t)(tok >> 5) * 8 + hh) * 2 + half) * 8 + ks) * 64 + lane2) * 8 + 4 * lh, acc[ft][tt][4 * g], acc[ft][tt][4 * g + 1], acc[ft][tt][4 * g + 2], acc[ft][tt][4 * g + 3]);
;             }
;           }
;       }
	s_waitcnt lgkmcnt(0)
	v_mfma_f32_32x32x16_bf16 v[32:47], v[74:77], v[120:123], v[32:47]
	v_mfma_f32_32x32x16_bf16 v[0:15], v[74:77], v[124:127], v[0:15]
	ds_read_b128 v[74:77], v100 offset:32768
	ds_read_b128 v[120:123], v100 offset:36864
	ds_read_b128 v[124:127], v101
	ds_read_b128 v[128:131], v101 offset:4096
	s_and_b32 s0, s55, 0x80
	v_or_b32_e32 v64, s0, v209
	s_add_i32 s54, s54, s94
	s_waitcnt lgkmcnt(0)
	v_mfma_f32_32x32x16_bf16 v[48:63], v[74:77], v[124:127], v[48:63]
	s_add_i32 s55, s55, s86
	s_add_i32 s87, s87, s88
	v_mfma_f32_32x32x16_bf16 v[16:31], v[74:77], v[128:131], v[16:31]
	v_mfma_f32_32x32x16_bf16 v[32:47], v[120:123], v[124:127], v[32:47]
	v_mfma_f32_32x32x16_bf16 v[0:15], v[120:123], v[128:131], v[0:15]
	ds_read_b128 v[74:77], v102 offset:32768
	ds_read_b128 v[120:123], v102 offset:36864
	ds_read_b128 v[124:127], v103
	ds_read_b128 v[128:131], v103 offset:4096
	s_waitcnt lgkmcnt(0)
	v_mfma_f32_32x32x16_bf16 v[48:63], v[74:77], v[124:127], v[48:63]
	v_mfma_f32_32x32x16_bf16 v[16:31], v[74:77], v[128:131], v[16:31]
	v_mfma_f32_32x32x16_bf16 v[32:47], v[120:123], v[124:127], v[32:47]
	v_mfma_f32_32x32x16_bf16 v[0:15], v[120:123], v[128:131], v[0:15]
	ds_read_b128 v[74:77], v104 offset:32768
	ds_read_b128 v[120:123], v104 offset:36864
	ds_read_b128 v[124:127], v105
	ds_read_b128 v[128:131], v105 offset:4096
	s_waitcnt lgkmcnt(0)
	v_mfma_f32_32x32x16_bf16 v[48:63], v[74:77], v[124:127], v[48:63]
	v_mfma_f32_32x32x16_bf16 v[16:31], v[74:77], v[128:131], v[16:31]
	v_mfma_f32_32x32x16_bf16 v[32:47], v[120:123], v[124:127], v[32:47]
	v_mfma_f32_32x32x16_bf16 v[0:15], v[120:123], v[128:131], v[0:15]
	ds_read_b128 v[74:77], v106 offset:32768
	ds_read_b128 v[120:123], v106 offset:36864
	ds_read_b128 v[124:127], v107
	ds_read_b128 v[128:131], v107 offset:4096
	s_waitcnt vmcnt(0)
	s_waitcnt lgkmcnt(0)
	s_barrier
	s_waitcnt lgkmcnt(0)
	v_mfma_f32_32x32x16_bf16 v[48:63], v[74:77], v[124:127], v[48:63]
	v_mfma_f32_32x32x16_bf16 v[16:31], v[74:77], v[128:131], v[16:31]
	v_lshrrev_b32_e32 v76, 4, v64
	v_lshl_add_u32 v64, s89, 9, v89
	s_nop 8
	v_cvt_pk_bf16_f32 v48, v48, v49
	v_cvt_pk_bf16_f32 v49, v50, v51
	v_cvt_pk_bf16_f32 v50, v56, v57
	v_cvt_pk_bf16_f32 v51, v58, v59
	v_or_b32_e32 v77, 2, v76
	v_mfma_f32_32x32x16_bf16 v[32:47], v[120:123], v[124:127], v[32:47]
	v_cvt_pk_bf16_f32 v16, v16, v17
	v_cvt_pk_bf16_f32 v17, v18, v19
	v_cvt_pk_bf16_f32 v18, v24, v25
	v_cvt_pk_bf16_f32 v19, v26, v27
	v_mfma_f32_32x32x16_bf16 v[0:15], v[120:123], v[128:131], v[0:15]
	v_and_or_b32 v120, s79, 48, v64
	v_or_b32_e32 v64, v120, v76
	v_lshlrev_b32_e32 v64, 10, v64
	v_lshl_add_u64 v[74:75], v[70:71], 0, v[64:65]
	global_store_dwordx2 v[74:75], v[48:49], off
	v_cvt_pk_bf16_f32 v48, v52, v53
	v_cvt_pk_bf16_f32 v49, v54, v55
	v_or_b32_e32 v52, 1, v76
	global_store_dwordx2 v[74:75], v[48:49], off offset:512
	v_or_b32_e32 v48, v52, v120
	v_lshlrev_b32_e32 v64, 10, v48
	v_lshl_add_u64 v[48:49], v[70:71], 0, v[64:65]
	global_store_dwordx2 v[48:49], v[50:51], off
	v_cvt_pk_bf16_f32 v50, v60, v61
	v_cvt_pk_bf16_f32 v51, v62, v63
	global_store_dwordx2 v[48:49], v[50:51], off offset:512
	v_or_b32_e32 v48, v77, v120
	v_lshlrev_b32_e32 v64, 10, v48
	v_lshl_add_u64 v[48:49], v[70:71], 0, v[64:65]
	v_cvt_pk_bf16_f32 v32, v32, v33
	v_cvt_pk_bf16_f32 v33, v34, v35
	global_store_dwordx2 v[48:49], v[32:33], off
	v_cvt_pk_bf16_f32 v32, v36, v37
	v_cvt_pk_bf16_f32 v33, v38, v39
	v_or_b32_e32 v36, 3, v76
	global_store_dwordx2 v[48:49], v[32:33], off offset:512
	v_or_b32_e32 v32, v36, v120
	v_lshlrev_b32_e32 v64, 10, v32
	v_lshl_add_u64 v[32:33], v[70:71], 0, v[64:65]
	v_cvt_pk_bf16_f32 v34, v40, v41
	v_cvt_pk_bf16_f32 v35, v42, v43
	global_store_dwordx2 v[32:33], v[34:35], off
	v_cvt_pk_bf16_f32 v34, v44, v45
	v_cvt_pk_bf16_f32 v35, v46, v47
	global_store_dwordx2 v[32:33], v[34:35], off offset:512
	v_or_b32_e32 v34, 64, v120
	v_or_b32_e32 v64, v34, v76
	v_lshlrev_b64 v[32:33], 10, v[64:65]
	v_lshl_add_u64 v[32:33], v[70:71], 0, v[32:33]
	global_store_dwordx2 v[32:33], v[16:17], off
	v_cvt_pk_bf16_f32 v16, v20, v21
	v_cvt_pk_bf16_f32 v17, v22, v23
	v_or_b32_e32 v64, v34, v52
	global_store_dwordx2 v[32:33], v[16:17], off offset:512
	v_lshlrev_b64 v[16:17], 10, v[64:65]
	v_lshl_add_u64 v[16:17], v[70:71], 0, v[16:17]
	global_store_dwordx2 v[16:17], v[18:19], off
	v_cvt_pk_bf16_f32 v18, v28, v29
	v_cvt_pk_bf16_f32 v19, v30, v31
	v_or_b32_e32 v64, v34, v77
	global_store_dwordx2 v[16:17], v[18:19], off offset:512
	v_lshlrev_b64 v[16:17], 10, v[64:65]
	v_lshl_add_u64 v[16:17], v[70:71], 0, v[16:17]
	v_cvt_pk_bf16_f32 v0, v0, v1
	v_cvt_pk_bf16_f32 v1, v2, v3
	global_store_dwordx2 v[16:17], v[0:1], off
	v_cvt_pk_bf16_f32 v0, v4, v5
	v_cvt_pk_bf16_f32 v1, v6, v7
	v_or_b32_e32 v64, v34, v36
	global_store_dwordx2 v[16:17], v[0:1], off offset:512
	v_lshlrev_b64 v[0:1], 10, v[64:65]
	v_lshl_add_u64 v[0:1], v[70:71], 0, v[0:1]
	v_cvt_pk_bf16_f32 v2, v8, v9
	v_cvt_pk_bf16_f32 v3, v10, v11
	s_add_i32 s79, s79, s3
	global_store_dwordx2 v[0:1], v[2:3], off
	v_cvt_pk_bf16_f32 v2, v12, v13
	v_cvt_pk_bf16_f32 v3, v14, v15
	s_cmpk_lt_u32 s54, 0x80
	global_store_dwordx2 v[0:1], v[2:3], off offset:512
	s_cbranch_scc1 .LBB0_678
	v_readlane_b32 s52, v255, 23
	v_readlane_b32 s60, v255, 31
	v_readlane_b32 s61, v255, 32
	v_readlane_b32 s60, v255, 43
	v_readlane_b32 s8, v255, 49
	v_readlane_b32 s64, v255, 35
	v_readlane_b32 s65, v255, 36
	v_readlane_b32 s66, v255, 37
	v_readlane_b32 s67, v255, 38
	v_readlane_b32 s61, v255, 44
	v_readlane_b32 s9, v255, 50
	v_readlane_b32 s53, v255, 24
	v_readlane_b32 s54, v255, 25
	v_readlane_b32 s55, v255, 26
	v_readlane_b32 s56, v255, 27
	v_readlane_b32 s57, v255, 28
	v_readlane_b32 s58, v255, 29
	v_readlane_b32 s59, v255, 30
	v_readlane_b32 s62, v255, 33
	v_readlane_b32 s63, v255, 34

; #define MFMA(a, b, c) __builtin_amdgcn_mfma_f32_32x32x16_bf16((a), (b), (c), 0, 0, 0)
; #define WAIT_V(n) asm volatile("s_waitcnt vmcnt(%0)" ::"n"(n) : "memory")
; #define RAW_BARRIER() do { asm volatile("s_waitcnt lgkmcnt(0)" ::: "memory"); __builtin_amdgcn_s_barrier(); asm volatile("" ::: "memory"); } while (0)
; #define GLDS_STAGE(slot, kt) do { _Pragma("unroll") for (int i = 0; i < 6; ++i) \
;     __builtin_amdgcn_global_load_lds((const unsigned*)(src[i] + (kt) * 64), (__attribute__((address_space(3))) unsigned*)(smem + (slot) * G_STAGE + (wave + 8 * i) * 1024), 16, 0, 0); } while (0)
; DI void gemm_tile(const u16* __restrict__ X, int ldx, const u16* __restrict__ Wt, int ldw, int K, char* smem,
;                   f32x16 (&acc)[2][2]) {
;     ...
;   const int nk = K / 64;
;   const u16* src[6];
; #pragma unroll
;   for (int i = 0; i < 6; ++i) {
;     const int R = 8 * (wave + 8 * i) + (lane >> 3);
;     const int c = (lane & 7) ^ ((R >> 1) & 7);
;     src[i] = (i < 4) ? (X + (size_t)R * ldx + c * 8) : (Wt + (size_t)(R - 256) * ldw + c * 8);
;   }
;     ...
;   int offA[2], offB[2], xa[2], xb[2];
; #pragma unroll
;   for (int ft = 0; ft < 2; ++ft) { const int R = 256 + fw * 64 + ft * 32 + lr; offA[ft] = R * 128; xa[ft] = (R >> 1) & 7; }
; #pragma unroll
;   for (int tt = 0; tt < 2; ++tt) { const int R = tq * 64 + tt * 32 + lr; offB[tt] = R * 128; xb[tt] = (R >> 1) & 7; }
;   GLDS_STAGE(0, 0); GLDS_STAGE(1, 1); WAIT_V(6); RAW_BARRIER();
;   int cur = 0;
;   for (int kt = 0; kt < nk; ++kt) {
;     const int nxt = (cur >= 1) ? cur - 1 : 2;
;     if (kt + 2 < nk) GLDS_STAGE(nxt, kt + 2);
;     __builtin_amdgcn_sched_barrier(0);
;     const char* st = smem + cur * G_STAGE;
; #pragma unroll
;     for (int ks = 0; ks < 4; ++ks) {
;       bf16x8 a[2], b[2];
; #pragma unroll
;       for (int ft = 0; ft < 2; ++ft) a[ft] = *reinterpret_cast<const bf16x8*>(st + offA[ft] + (((ks * 2 + lh) ^ xa[ft]) << 4));
; #pragma unroll
;       for (int tt = 0; tt < 2; ++tt) b[tt] = *reinterpret_cast<const bf16x8*>(st + offB[tt] + (((ks * 2 + lh) ^ xb[tt]) << 4));
; #pragma unroll
;       for (int ft = 0; ft < 2; ++ft)
; #pragma unroll
;         for (int tt = 0; tt < 2; ++tt) acc[ft][tt] = MFMA(a[ft], b[tt], acc[ft][tt]);
.LBB0_793:
	s_and_b32 s0, s85, 0x78
	s_or_b32 s0, s0, s33
	s_lshl_b32 s10, s0, 19
	v_lshl_add_u64 v[0:1], v[66:67], 0, s[10:11]
	v_readfirstlane_b32 s6, v143
	v_lshl_add_u64 v[80:81], v[0:1], 0, v[70:71]
	s_mov_b32 m0, s6
	v_readfirstlane_b32 s89, v101
	s_and_b32 s4, s85, 7
	v_lshl_add_u64 v[0:1], v[80:81], 0, s[12:13]
	s_mov_b64 s[0:1], 0x40000
	global_load_lds_dwordx4 v[80:81], off
	s_mov_b32 m0, s89
	v_readfirstlane_b32 s88, v102
	v_lshl_add_u64 v[2:3], v[80:81], 0, s[0:1]
	s_mov_b64 s[0:1], 0x60000
	s_lshl_b32 s10, s4, 18
	global_load_lds_dwordx4 v[0:1], off
	s_mov_b32 m0, s88
	v_readfirstlane_b32 s87, v103
	v_lshl_add_u64 v[4:5], v[80:81], 0, s[0:1]
	v_lshl_add_u64 v[6:7], v[68:69], 0, s[10:11]
	global_load_lds_dwordx4 v[2:3], off
	s_mov_b32 m0, s87
	v_readfirstlane_b32 s86, v104
	v_lshl_add_u64 v[82:83], v[6:7], 0, v[70:71]
	global_load_lds_dwordx4 v[4:5], off
	s_mov_b32 m0, s86
	v_readfirstlane_b32 s55, v105
	v_lshl_add_u64 v[6:7], v[82:83], 0, s[12:13]
	global_load_lds_dwordx4 v[82:83], off
	s_mov_b32 m0, s55
	v_readfirstlane_b32 s54, v84
	global_load_lds_dwordx4 v[6:7], off
	v_lshl_add_u64 v[0:1], v[80:81], 0, s[14:15]
	s_mov_b32 m0, s54
	v_readfirstlane_b32 s10, v106
	global_load_lds_dwordx4 v[0:1], off
	v_lshl_add_u64 v[0:1], v[80:81], 0, s[16:17]
	s_mov_b32 m0, s10
	s_mov_b64 s[0:1], 0x40080
	global_load_lds_dwordx4 v[0:1], off
	v_lshl_add_u64 v[0:1], v[80:81], 0, s[0:1]
	v_readfirstlane_b32 s0, v107
	s_mov_b32 m0, s0
	s_mov_b64 s[0:1], 0x60080
	global_load_lds_dwordx4 v[0:1], off
	v_lshl_add_u64 v[0:1], v[80:81], 0, s[0:1]
	v_readfirstlane_b32 s0, v108
	s_mov_b32 m0, s0
	v_readfirstlane_b32 s0, v109
	global_load_lds_dwordx4 v[0:1], off
	v_lshl_add_u64 v[0:1], v[82:83], 0, s[14:15]
	s_mov_b32 m0, s0
	v_readfirstlane_b32 s0, v110
	global_load_lds_dwordx4 v[0:1], off
	v_lshl_add_u64 v[0:1], v[82:83], 0, s[16:17]
	s_mov_b32 m0, s0
	v_readfirstlane_b32 s0, v85
	global_load_lds_dwordx4 v[0:1], off
	s_waitcnt vmcnt(6)
	s_waitcnt lgkmcnt(0)
	s_barrier
	v_lshl_add_u64 v[0:1], v[80:81], 0, s[18:19]
	s_mov_b32 m0, s0
	v_readfirstlane_b32 s93, v86
	global_load_lds_dwordx4 v[0:1], off
	v_lshl_add_u64 v[0:1], v[80:81], 0, s[20:21]
	s_mov_b32 m0, s93
	s_mov_b64 s[4:5], 0x40100
	v_readfirstlane_b32 s91, v87
	global_load_lds_dwordx4 v[0:1], off
	v_lshl_add_u64 v[0:1], v[80:81], 0, s[4:5]
	s_mov_b32 m0, s91
	s_mov_b64 s[4:5], 0x60100
	v_readfirstlane_b32 s92, v88
	global_load_lds_dwordx4 v[0:1], off
	v_lshl_add_u64 v[0:1], v[80:81], 0, s[4:5]
	s_mov_b32 m0, s92
	v_readfirstlane_b32 s7, v89
	global_load_lds_dwordx4 v[0:1], off
	v_lshl_add_u64 v[0:1], v[82:83], 0, s[18:19]
	s_mov_b32 m0, s7
	v_readfirstlane_b32 s90, v90
	global_load_lds_dwordx4 v[0:1], off
	v_lshl_add_u64 v[0:1], v[82:83], 0, s[20:21]
	s_mov_b32 m0, s90
	s_lshl_b32 s1, s85, 8
	global_load_lds_dwordx4 v[0:1], off
	s_and_b32 s4, s79, 7
	s_and_b32 s1, s1, 0x7800
	s_lshl_b32 s4, s4, 7
	v_add_lshl_u32 v64, v97, s1, 12
	v_add_lshl_u32 v0, v98, s4, 2
	v_mov_b32_e32 v1, v65
	v_lshl_add_u64 v[2:3], v[64:65], 0, v[0:1]
	v_add_lshl_u32 v64, v99, s1, 12
	v_lshl_add_u64 v[72:73], s[82:83], 0, v[2:3]
	v_lshl_add_u64 v[2:3], v[64:65], 0, v[0:1]
	v_add_lshl_u32 v64, v100, s1, 12
	v_lshl_add_u64 v[74:75], s[82:83], 0, v[2:3]
	v_lshl_add_u64 v[2:3], v[64:65], 0, v[0:1]
	v_add_lshl_u32 v64, v96, s1, 12
	v_lshl_add_u64 v[0:1], v[64:65], 0, v[0:1]
	v_lshl_add_u64 v[76:77], s[82:83], 0, v[2:3]
	v_lshl_add_u64 v[78:79], s[82:83], 0, v[0:1]
	ds_read_b128 v[0:3], v111 offset:32768
	ds_read_b128 v[4:7], v111 offset:36864
	ds_read_b128 v[8:11], v112
	ds_read_b128 v[12:15], v112 offset:4096
	ds_read_b128 v[132:135], v113 offset:32768
	ds_read_b128 v[136:139], v113 offset:36864
	ds_read_b128 v[152:155], v114
	ds_read_b128 v[156:159], v114 offset:4096
	s_mov_b32 m0, s6
	s_mov_b64 s[4:5], 0x40180
	s_waitcnt lgkmcnt(0)
	v_mfma_f32_32x32x16_bf16 v[48:63], v[0:3], v[8:11], 0
	v_mfma_f32_32x32x16_bf16 v[16:31], v[0:3], v[12:15], 0
	v_mfma_f32_32x32x16_bf16 v[32:47], v[4:7], v[8:11], 0
	v_mfma_f32_32x32x16_bf16 v[0:15], v[4:7], v[12:15], 0
	ds_read_b128 v[184:187], v115 offset:32768
	ds_read_b128 v[188:191], v115 offset:36864
	ds_read_b128 v[192:195], v116
	ds_read_b128 v[196:199], v116 offset:4096
	s_waitcnt lgkmcnt(4)
	v_mfma_f32_32x32x16_bf16 v[48:63], v[132:135], v[152:155], v[48:63]
	v_mfma_f32_32x32x16_bf16 v[16:31], v[132:135], v[156:159], v[16:31]
	v_mfma_f32_32x32x16_bf16 v[32:47], v[136:139], v[152:155], v[32:47]
	v_mfma_f32_32x32x16_bf16 v[0:15], v[136:139], v[156:159], v[0:15]
	ds_read_b128 v[132:135], v117 offset:32768
	ds_read_b128 v[136:139], v117 offset:36864
	ds_read_b128 v[152:155], v118
	ds_read_b128 v[156:159], v118 offset:4096
	s_waitcnt lgkmcnt(4)
	v_mfma_f32_32x32x16_bf16 v[48:63], v[184:187], v[192:195], v[48:63]
	v_mfma_f32_32x32x16_bf16 v[16:31], v[184:187], v[196:199], v[16:31]
	v_mfma_f32_32x32x16_bf16 v[32:47], v[188:191], v[192:195], v[32:47]
	v_mfma_f32_32x32x16_bf16 v[0:15], v[188:191], v[196:199], v[0:15]
	s_waitcnt vmcnt(6)
	s_waitcnt lgkmcnt(0)
	s_barrier
; #define MFMA(a, b, c) __builtin_amdgcn_mfma_f32_32x32x16_bf16((a), (b), (c), 0, 0, 0)
; #define WAIT_V(n) asm volatile("s_waitcnt vmcnt(%0)" ::"n"(n) : "memory")
; #define RAW_BARRIER() do { asm volatile("s_waitcnt lgkmcnt(0)" ::: "memory"); __builtin_amdgcn_s_barrier(); asm volatile("" ::: "memory"); } while (0)
; #define GLDS_STAGE(slot, kt) do { _Pragma("unroll") for (int i = 0; i < 6; ++i) \
;     __builtin_amdgcn_global_load_lds((const unsigned*)(src[i] + (kt) * 64), (__attribute__((address_space(3))) unsigned*)(smem + (slot) * G_STAGE + (wave + 8 * i) * 1024), 16, 0, 0); } while (0)
; DI void gemm_tile(const u16* __restrict__ X, int ldx, const u16* __restrict__ Wt, int ldw, int K, char* smem,
;                   f32x16 (&acc)[2][2]) {
;     ...
;   for (int kt = 0; kt < nk; ++kt) {
;     const int nxt = (cur >= 1) ? cur - 1 : 2;
;     if (kt + 2 < nk) GLDS_STAGE(nxt, kt + 2);
;     __builtin_amdgcn_sched_barrier(0);
;     const char* st = smem + cur * G_STAGE;
; #pragma unroll
;     for (int ks = 0; ks < 4; ++ks) {
;       bf16x8 a[2], b[2];
; #pragma unroll
;       for (int ft = 0; ft < 2; ++ft) a[ft] = *reinterpret_cast<const bf16x8*>(st + offA[ft] + (((ks * 2 + lh) ^ xa[ft]) << 4));
; #pragma unroll
;       for (int tt = 0; tt < 2; ++tt) b[tt] = *reinterpret_cast<const bf16x8*>(st + offB[tt] + (((ks * 2 + lh) ^ xb[tt]) << 4));
; #pragma unroll
;       for (int ft = 0; ft < 2; ++ft)
; #pragma unroll
;         for (int tt = 0; tt < 2; ++tt) acc[ft][tt] = MFMA(a[ft], b[tt], acc[ft][tt]);
;     }
;     if (kt + 2 < nk) { WAIT_V(6); } else { WAIT_V(0); }
;     RAW_BARRIER();
	ds_read_b128 v[184:187], v119 offset:32768
	ds_read_b128 v[188:191], v119 offset:36864
	ds_read_b128 v[192:195], v112 offset:49152
	ds_read_b128 v[196:199], v112 offset:53248
	s_waitcnt lgkmcnt(4)
	v_mfma_f32_32x32x16_bf16 v[48:63], v[132:135], v[152:155], v[48:63]
	v_mfma_f32_32x32x16_bf16 v[16:31], v[132:135], v[156:159], v[16:31]
	v_lshl_add_u64 v[132:133], v[80:81], 0, s[22:23]
	global_load_lds_dwordx4 v[132:133], off
	v_lshl_add_u64 v[132:133], v[80:81], 0, s[24:25]
	s_mov_b32 m0, s89
	s_nop 0
	global_load_lds_dwordx4 v[132:133], off
	v_lshl_add_u64 v[132:133], v[80:81], 0, s[4:5]
	s_mov_b32 m0, s88
	s_mov_b64 s[4:5], 0x60180
	global_load_lds_dwordx4 v[132:133], off
	v_lshl_add_u64 v[132:133], v[80:81], 0, s[4:5]
	s_mov_b32 m0, s87
	v_mfma_f32_32x32x16_bf16 v[0:15], v[136:139], v[156:159], v[0:15]
	global_load_lds_dwordx4 v[132:133], off
	v_lshl_add_u64 v[132:133], v[82:83], 0, s[22:23]
	s_mov_b32 m0, s86
	s_nop 0
	global_load_lds_dwordx4 v[132:133], off
	v_lshl_add_u64 v[132:133], v[82:83], 0, s[24:25]
	s_mov_b32 m0, s55
	v_mfma_f32_32x32x16_bf16 v[32:47], v[136:139], v[152:155], v[32:47]
	global_load_lds_dwordx4 v[132:133], off
	s_mov_b32 m0, s54
	s_mov_b64 s[4:5], 0x40200
	v_readfirstlane_b32 s95, v91
	ds_read_b128 v[132:135], v120 offset:32768
	ds_read_b128 v[136:139], v120 offset:36864
	ds_read_b128 v[152:155], v114 offset:49152
	ds_read_b128 v[156:159], v114 offset:53248
	s_waitcnt lgkmcnt(4)
	v_mfma_f32_32x32x16_bf16 v[48:63], v[184:187], v[192:195], v[48:63]
	v_readfirstlane_b32 s9, v92
	v_readfirstlane_b32 s8, v93
	v_readfirstlane_b32 s46, v94
	v_mfma_f32_32x32x16_bf16 v[16:31], v[184:187], v[196:199], v[16:31]
	v_mfma_f32_32x32x16_bf16 v[32:47], v[188:191], v[192:195], v[32:47]
	v_mfma_f32_32x32x16_bf16 v[0:15], v[188:191], v[196:199], v[0:15]
	ds_read_b128 v[184:187], v121 offset:32768
	ds_read_b128 v[188:191], v121 offset:36864
	ds_read_b128 v[192:195], v116 offset:49152
	ds_read_b128 v[196:199], v116 offset:53248
	s_waitcnt lgkmcnt(4)
	v_mfma_f32_32x32x16_bf16 v[48:63], v[132:135], v[152:155], v[48:63]
	v_mfma_f32_32x32x16_bf16 v[16:31], v[132:135], v[156:159], v[16:31]
	v_mfma_f32_32x32x16_bf16 v[32:47], v[136:139], v[152:155], v[32:47]
	v_mfma_f32_32x32x16_bf16 v[0:15], v[136:139], v[156:159], v[0:15]
	ds_read_b128 v[132:135], v122 offset:32768
	ds_read_b128 v[136:139], v122 offset:36864
	ds_read_b128 v[152:155], v118 offset:49152
	ds_read_b128 v[156:159], v118 offset:53248
	s_waitcnt lgkmcnt(4)
	v_mfma_f32_32x32x16_bf16 v[48:63], v[184:187], v[192:195], v[48:63]
	v_mfma_f32_32x32x16_bf16 v[16:31], v[184:187], v[196:199], v[16:31]
	v_mfma_f32_32x32x16_bf16 v[32:47], v[188:191], v[192:195], v[32:47]
	v_mfma_f32_32x32x16_bf16 v[0:15], v[188:191], v[196:199], v[0:15]
	s_waitcnt vmcnt(6)
	s_waitcnt lgkmcnt(0)
	s_barrier
	ds_read_b128 v[184:187], v123 offset:32768
	ds_read_b128 v[188:191], v123 offset:36864
	ds_read_b128 v[192:195], v124
	ds_read_b128 v[196:199], v124 offset:4096
	s_waitcnt lgkmcnt(4)
	v_mfma_f32_32x32x16_bf16 v[48:63], v[132:135], v[152:155], v[48:63]
	v_mfma_f32_32x32x16_bf16 v[16:31], v[132:135], v[156:159], v[16:31]
	v_lshl_add_u64 v[132:133], v[80:81], 0, s[26:27]
	global_load_lds_dwordx4 v[132:133], off
	v_lshl_add_u64 v[132:133], v[80:81], 0, s[28:29]
	s_mov_b32 m0, s10
	s_nop 0
	global_load_lds_dwordx4 v[132:133], off
	v_lshl_add_u64 v[132:133], v[80:81], 0, s[4:5]
	s_mov_b32 m0, s95
	s_mov_b64 s[4:5], 0x60200
	global_load_lds_dwordx4 v[132:133], off
	v_lshl_add_u64 v[132:133], v[80:81], 0, s[4:5]
	s_mov_b32 m0, s9
	v_mfma_f32_32x32x16_bf16 v[0:15], v[136:139], v[156:159], v[0:15]
	global_load_lds_dwordx4 v[132:133], off
	v_lshl_add_u64 v[132:133], v[82:83], 0, s[26:27]
	s_mov_b32 m0, s8
	s_nop 0
	global_load_lds_dwordx4 v[132:133], off
	v_lshl_add_u64 v[132:133], v[82:83], 0, s[28:29]
	s_mov_b32 m0, s46
	v_mfma_f32_32x32x16_bf16 v[32:47], v[136:139], v[152:155], v[32:47]
	global_load_lds_dwordx4 v[132:133], off
	s_mov_b32 m0, s0
	s_mov_b64 s[4:5], 0x40280
	ds_read_b128 v[132:135], v125 offset:32768
	ds_read_b128 v[136:139], v125 offset:36864
	ds_read_b128 v[152:155], v126
	ds_read_b128 v[156:159], v126 offset:4096
	s_waitcnt lgkmcnt(4)
	v_mfma_f32_32x32x16_bf16 v[48:63], v[184:187], v[192:195], v[48:63]
	v_mfma_f32_32x32x16_bf16 v[16:31], v[184:187], v[196:199], v[16:31]
	v_mfma_f32_32x32x16_bf16 v[32:47], v[188:191], v[192:195], v[32:47]
	v_mfma_f32_32x32x16_bf16 v[0:15], v[188:191], v[196:199], v[0:15]
	ds_read_b128 v[184:187], v127 offset:32768
	ds_read_b128 v[188:191], v127 offset:36864
	ds_read_b128 v[192:195], v128
	ds_read_b128 v[196:199], v128 offset:4096
	s_waitcnt lgkmcnt(4)
	v_mfma_f32_32x32x16_bf16 v[48:63], v[132:135], v[152:155], v[48:63]
	v_mfma_f32_32x32x16_bf16 v[16:31], v[132:135], v[156:159], v[16:31]
	v_mfma_f32_32x32x16_bf16 v[32:47], v[136:139], v[152:155], v[32:47]
	v_mfma_f32_32x32x16_bf16 v[0:15], v[136:139], v[156:159], v[0:15]
	ds_read_b128 v[132:135], v129 offset:32768
	ds_read_b128 v[136:139], v129 offset:36864
	ds_read_b128 v[152:155], v130
	ds_read_b128 v[156:159], v130 offset:4096
	s_waitcnt lgkmcnt(4)
	v_mfma_f32_32x32x16_bf16 v[48:63], v[184:187], v[192:195], v[48:63]
	v_mfma_f32_32x32x16_bf16 v[16:31], v[184:187], v[196:199], v[16:31]
	v_mfma_f32_32x32x16_bf16 v[32:47], v[188:191], v[192:195], v[32:47]
	v_mfma_f32_32x32x16_bf16 v[0:15], v[188:191], v[196:199], v[0:15]
	s_waitcnt vmcnt(6)
	s_waitcnt lgkmcnt(0)
	s_barrier
; #define MFMA(a, b, c) __builtin_amdgcn_mfma_f32_32x32x16_bf16((a), (b), (c), 0, 0, 0)
; #define WAIT_V(n) asm volatile("s_waitcnt vmcnt(%0)" ::"n"(n) : "memory")
; #define RAW_BARRIER() do { asm volatile("s_waitcnt lgkmcnt(0)" ::: "memory"); __builtin_amdgcn_s_barrier(); asm volatile("" ::: "memory"); } while (0)
; #define GLDS_STAGE(slot, kt) do { _Pragma("unroll") for (int i = 0; i < 6; ++i) \
;     __builtin_amdgcn_global_load_lds((const unsigned*)(src[i] + (kt) * 64), (__attribute__((address_space(3))) unsigned*)(smem + (slot) * G_STAGE + (wave + 8 * i) * 1024), 16, 0, 0); } while (0)
; DI void gemm_tile(const u16* __restrict__ X, int ldx, const u16* __restrict__ Wt, int ldw, int K, char* smem,
;                   f32x16 (&acc)[2][2]) {
;     ...
;   for (int kt = 0; kt < nk; ++kt) {
;     const int nxt = (cur >= 1) ? cur - 1 : 2;
;     if (kt + 2 < nk) GLDS_STAGE(nxt, kt + 2);
;     __builtin_amdgcn_sched_barrier(0);
;     const char* st = smem + cur * G_STAGE;
; #pragma unroll
;     for (int ks = 0; ks < 4; ++ks) {
;       bf16x8 a[2], b[2];
; #pragma unroll
;       for (int ft = 0; ft < 2; ++ft) a[ft] = *reinterpret_cast<const bf16x8*>(st + offA[ft] + (((ks * 2 + lh) ^ xa[ft]) << 4));
; #pragma unroll
;       for (int tt = 0; tt < 2; ++tt) b[tt] = *reinterpret_cast<const bf16x8*>(st + offB[tt] + (((ks * 2 + lh) ^ xb[tt]) << 4));
; #pragma unroll
;       for (int ft = 0; ft < 2; ++ft)
; #pragma unroll
;         for (int tt = 0; tt < 2; ++tt) acc[ft][tt] = MFMA(a[ft], b[tt], acc[ft][tt]);
;     }
;     if (kt + 2 < nk) { WAIT_V(6); } else { WAIT_V(0); }
;     RAW_BARRIER();
	ds_read_b128 v[184:187], v111 offset:32768
	ds_read_b128 v[188:191], v111 offset:36864
	ds_read_b128 v[192:195], v112
	ds_read_b128 v[196:199], v112 offset:4096
	s_waitcnt lgkmcnt(4)
	v_mfma_f32_32x32x16_bf16 v[48:63], v[132:135], v[152:155], v[48:63]
	v_mfma_f32_32x32x16_bf16 v[16:31], v[132:135], v[156:159], v[16:31]
	v_lshl_add_u64 v[132:133], v[80:81], 0, s[30:31]
	global_load_lds_dwordx4 v[132:133], off
	v_lshl_add_u64 v[132:133], v[80:81], 0, s[34:35]
	s_mov_b32 m0, s93
	s_nop 0
	global_load_lds_dwordx4 v[132:133], off
	v_lshl_add_u64 v[132:133], v[80:81], 0, s[4:5]
	s_mov_b32 m0, s91
	s_mov_b64 s[4:5], 0x60280
	global_load_lds_dwordx4 v[132:133], off
	v_lshl_add_u64 v[132:133], v[80:81], 0, s[4:5]
	s_mov_b32 m0, s92
	v_mfma_f32_32x32x16_bf16 v[0:15], v[136:139], v[156:159], v[0:15]
	global_load_lds_dwordx4 v[132:133], off
	v_lshl_add_u64 v[132:133], v[82:83], 0, s[30:31]
	s_mov_b32 m0, s7
	s_nop 0
	global_load_lds_dwordx4 v[132:133], off
	v_lshl_add_u64 v[132:133], v[82:83], 0, s[34:35]
	s_mov_b32 m0, s90
	v_mfma_f32_32x32x16_bf16 v[32:47], v[136:139], v[152:155], v[32:47]
	global_load_lds_dwordx4 v[132:133], off
	s_mov_b32 m0, s6
	s_mov_b64 s[4:5], 0x40300
	ds_read_b128 v[132:135], v113 offset:32768
	ds_read_b128 v[136:139], v113 offset:36864
	ds_read_b128 v[152:155], v114
	ds_read_b128 v[156:159], v114 offset:4096
	s_waitcnt lgkmcnt(4)
	v_mfma_f32_32x32x16_bf16 v[48:63], v[184:187], v[192:195], v[48:63]
	v_mfma_f32_32x32x16_bf16 v[16:31], v[184:187], v[196:199], v[16:31]
	v_mfma_f32_32x32x16_bf16 v[32:47], v[188:191], v[192:195], v[32:47]
	v_mfma_f32_32x32x16_bf16 v[0:15], v[188:191], v[196:199], v[0:15]
	ds_read_b128 v[184:187], v115 offset:32768
	ds_read_b128 v[188:191], v115 offset:36864
	ds_read_b128 v[192:195], v116
	ds_read_b128 v[196:199], v116 offset:4096
	s_waitcnt lgkmcnt(4)
	v_mfma_f32_32x32x16_bf16 v[48:63], v[132:135], v[152:155], v[48:63]
	v_mfma_f32_32x32x16_bf16 v[16:31], v[132:135], v[156:159], v[16:31]
	v_mfma_f32_32x32x16_bf16 v[32:47], v[136:139], v[152:155], v[32:47]
	v_mfma_f32_32x32x16_bf16 v[0:15], v[136:139], v[156:159], v[0:15]
	ds_read_b128 v[132:135], v117 offset:32768
	ds_read_b128 v[136:139], v117 offset:36864
	ds_read_b128 v[152:155], v118
	ds_read_b128 v[156:159], v118 offset:4096
	s_waitcnt lgkmcnt(4)
	v_mfma_f32_32x32x16_bf16 v[48:63], v[184:187], v[192:195], v[48:63]
	v_mfma_f32_32x32x16_bf16 v[16:31], v[184:187], v[196:199], v[16:31]
	v_mfma_f32_32x32x16_bf16 v[32:47], v[188:191], v[192:195], v[32:47]
	v_mfma_f32_32x32x16_bf16 v[0:15], v[188:191], v[196:199], v[0:15]
	s_waitcnt vmcnt(6)
	s_waitcnt lgkmcnt(0)
	s_barrier
	ds_read_b128 v[184:187], v119 offset:32768
	ds_read_b128 v[188:191], v119 offset:36864
	ds_read_b128 v[192:195], v112 offset:49152
	ds_read_b128 v[196:199], v112 offset:53248
	s_waitcnt lgkmcnt(4)
	v_mfma_f32_32x32x16_bf16 v[48:63], v[132:135], v[152:155], v[48:63]
	v_mfma_f32_32x32x16_bf16 v[16:31], v[132:135], v[156:159], v[16:31]
	v_lshl_add_u64 v[132:133], v[80:81], 0, s[36:37]
	global_load_lds_dwordx4 v[132:133], off
	v_lshl_add_u64 v[132:133], v[80:81], 0, s[38:39]
	s_mov_b32 m0, s89
	s_nop 0
	global_load_lds_dwordx4 v[132:133], off
	v_lshl_add_u64 v[132:133], v[80:81], 0, s[4:5]
	s_mov_b32 m0, s88
	s_mov_b64 s[4:5], 0x60300
	global_load_lds_dwordx4 v[132:133], off
	v_lshl_add_u64 v[132:133], v[80:81], 0, s[4:5]
	s_mov_b32 m0, s87
	v_mfma_f32_32x32x16_bf16 v[0:15], v[136:139], v[156:159], v[0:15]
	global_load_lds_dwordx4 v[132:133], off
	v_lshl_add_u64 v[132:133], v[82:83], 0, s[36:37]
	s_mov_b32 m0, s86
	s_nop 0
	global_load_lds_dwordx4 v[132:133], off
	v_lshl_add_u64 v[132:133], v[82:83], 0, s[38:39]
	s_mov_b32 m0, s55
	v_mfma_f32_32x32x16_bf16 v[32:47], v[136:139], v[152:155], v[32:47]
	global_load_lds_dwordx4 v[132:133], off
	s_mov_b32 m0, s54
	s_mov_b64 s[4:5], 0x40380
	ds_read_b128 v[132:135], v120 offset:32768
	ds_read_b128 v[136:139], v120 offset:36864
	ds_read_b128 v[152:155], v114 offset:49152
	ds_read_b128 v[156:159], v114 offset:53248
	s_waitcnt lgkmcnt(4)
	v_mfma_f32_32x32x16_bf16 v[48:63], v[184:187], v[192:195], v[48:63]
	v_mfma_f32_32x32x16_bf16 v[16:31], v[184:187], v[196:199], v[16:31]
	v_mfma_f32_32x32x16_bf16 v[32:47], v[188:191], v[192:195], v[32:47]
	v_mfma_f32_32x32x16_bf16 v[0:15], v[188:191], v[196:199], v[0:15]
	ds_read_b128 v[184:187], v121 offset:32768
	ds_read_b128 v[188:191], v121 offset:36864
	ds_read_b128 v[192:195], v116 offset:49152
	ds_read_b128 v[196:199], v116 offset:53248
	s_waitcnt lgkmcnt(4)
	v_mfma_f32_32x32x16_bf16 v[48:63], v[132:135], v[152:155], v[48:63]
	v_mfma_f32_32x32x16_bf16 v[16:31], v[132:135], v[156:159], v[16:31]
	v_mfma_f32_32x32x16_bf16 v[32:47], v[136:139], v[152:155], v[32:47]
	v_mfma_f32_32x32x16_bf16 v[0:15], v[136:139], v[156:159], v[0:15]
	ds_read_b128 v[132:135], v122 offset:32768
	ds_read_b128 v[136:139], v122 offset:36864
	ds_read_b128 v[152:155], v118 offset:49152
	ds_read_b128 v[156:159], v118 offset:53248
	s_waitcnt lgkmcnt(4)
	v_mfma_f32_32x32x16_bf16 v[48:63], v[184:187], v[192:195], v[48:63]
	v_mfma_f32_32x32x16_bf16 v[16:31], v[184:187], v[196:199], v[16:31]
	v_mfma_f32_32x32x16_bf16 v[32:47], v[188:191], v[192:195], v[32:47]
	v_mfma_f32_32x32x16_bf16 v[0:15], v[188:191], v[196:199], v[0:15]
	s_waitcnt vmcnt(6)
	s_waitcnt lgkmcnt(0)
	s_barrier
; #define MFMA(a, b, c) __builtin_amdgcn_mfma_f32_32x32x16_bf16((a), (b), (c), 0, 0, 0)
; #define WAIT_V(n) asm volatile("s_waitcnt vmcnt(%0)" ::"n"(n) : "memory")
; #define RAW_BARRIER() do { asm volatile("s_waitcnt lgkmcnt(0)" ::: "memory"); __builtin_amdgcn_s_barrier(); asm volatile("" ::: "memory"); } while (0)
; #define GLDS_STAGE(slot, kt) do { _Pragma("unroll") for (int i = 0; i < 6; ++i) \
;     __builtin_amdgcn_global_load_lds((const unsigned*)(src[i] + (kt) * 64), (__attribute__((address_space(3))) unsigned*)(smem + (slot) * G_STAGE + (wave + 8 * i) * 1024), 16, 0, 0); } while (0)
; DI void gemm_tile(const u16* __restrict__ X, int ldx, const u16* __restrict__ Wt, int ldw, int K, char* smem,
;                   f32x16 (&acc)[2][2]) {
;     ...
;   for (int kt = 0; kt < nk; ++kt) {
;     const int nxt = (cur >= 1) ? cur - 1 : 2;
;     if (kt + 2 < nk) GLDS_STAGE(nxt, kt + 2);
;     __builtin_amdgcn_sched_barrier(0);
;     const char* st = smem + cur * G_STAGE;
; #pragma unroll
;     for (int ks = 0; ks < 4; ++ks) {
;       bf16x8 a[2], b[2];
; #pragma unroll
;       for (int ft = 0; ft < 2; ++ft) a[ft] = *reinterpret_cast<const bf16x8*>(st + offA[ft] + (((ks * 2 + lh) ^ xa[ft]) << 4));
; #pragma unroll
;       for (int tt = 0; tt < 2; ++tt) b[tt] = *reinterpret_cast<const bf16x8*>(st + offB[tt] + (((ks * 2 + lh) ^ xb[tt]) << 4));
; #pragma unroll
;       for (int ft = 0; ft < 2; ++ft)
; #pragma unroll
;         for (int tt = 0; tt < 2; ++tt) acc[ft][tt] = MFMA(a[ft], b[tt], acc[ft][tt]);
;     }
;     if (kt + 2 < nk) { WAIT_V(6); } else { WAIT_V(0); }
;     RAW_BARRIER();
	ds_read_b128 v[184:187], v123 offset:32768
	ds_read_b128 v[188:191], v123 offset:36864
	ds_read_b128 v[192:195], v124
	ds_read_b128 v[196:199], v124 offset:4096
	s_waitcnt lgkmcnt(4)
	v_mfma_f32_32x32x16_bf16 v[48:63], v[132:135], v[152:155], v[48:63]
	v_mfma_f32_32x32x16_bf16 v[16:31], v[132:135], v[156:159], v[16:31]
	v_lshl_add_u64 v[132:133], v[80:81], 0, s[40:41]
	global_load_lds_dwordx4 v[132:133], off
	v_lshl_add_u64 v[132:133], v[80:81], 0, s[42:43]
	s_mov_b32 m0, s10
	s_nop 0
	global_load_lds_dwordx4 v[132:133], off
	v_lshl_add_u64 v[132:133], v[80:81], 0, s[4:5]
	s_mov_b32 m0, s95
	s_mov_b64 s[4:5], 0x60380
	global_load_lds_dwordx4 v[132:133], off
	v_lshl_add_u64 v[132:133], v[80:81], 0, s[4:5]
	s_mov_b32 m0, s9
	v_mfma_f32_32x32x16_bf16 v[0:15], v[136:139], v[156:159], v[0:15]
	global_load_lds_dwordx4 v[132:133], off
	v_lshl_add_u64 v[132:133], v[82:83], 0, s[40:41]
	s_mov_b32 m0, s8
	s_nop 0
	global_load_lds_dwordx4 v[132:133], off
	v_lshl_add_u64 v[132:133], v[82:83], 0, s[42:43]
	s_mov_b32 m0, s46
	v_mfma_f32_32x32x16_bf16 v[32:47], v[136:139], v[152:155], v[32:47]
	global_load_lds_dwordx4 v[132:133], off
	s_mov_b32 m0, s0
	s_mov_b64 s[0:1], 0x40400
	ds_read_b128 v[132:135], v125 offset:32768
	ds_read_b128 v[136:139], v125 offset:36864
	ds_read_b128 v[152:155], v126
	ds_read_b128 v[156:159], v126 offset:4096
	s_waitcnt lgkmcnt(4)
	v_mfma_f32_32x32x16_bf16 v[48:63], v[184:187], v[192:195], v[48:63]
	v_mfma_f32_32x32x16_bf16 v[16:31], v[184:187], v[196:199], v[16:31]
	v_mfma_f32_32x32x16_bf16 v[32:47], v[188:191], v[192:195], v[32:47]
	v_mfma_f32_32x32x16_bf16 v[0:15], v[188:191], v[196:199], v[0:15]
	ds_read_b128 v[184:187], v127 offset:32768
	ds_read_b128 v[188:191], v127 offset:36864
	ds_read_b128 v[192:195], v128
	ds_read_b128 v[196:199], v128 offset:4096
	s_waitcnt lgkmcnt(4)
	v_mfma_f32_32x32x16_bf16 v[48:63], v[132:135], v[152:155], v[48:63]
	v_mfma_f32_32x32x16_bf16 v[16:31], v[132:135], v[156:159], v[16:31]
	v_mfma_f32_32x32x16_bf16 v[32:47], v[136:139], v[152:155], v[32:47]
	v_mfma_f32_32x32x16_bf16 v[0:15], v[136:139], v[156:159], v[0:15]
	ds_read_b128 v[132:135], v129 offset:32768
	ds_read_b128 v[136:139], v129 offset:36864
	ds_read_b128 v[152:155], v130
	ds_read_b128 v[156:159], v130 offset:4096
	s_waitcnt lgkmcnt(4)
	v_mfma_f32_32x32x16_bf16 v[48:63], v[184:187], v[192:195], v[48:63]
	v_mfma_f32_32x32x16_bf16 v[16:31], v[184:187], v[196:199], v[16:31]
	v_mfma_f32_32x32x16_bf16 v[32:47], v[188:191], v[192:195], v[32:47]
	v_mfma_f32_32x32x16_bf16 v[0:15], v[188:191], v[196:199], v[0:15]
	s_waitcnt vmcnt(6)
	s_waitcnt lgkmcnt(0)
	s_barrier
	ds_read_b128 v[184:187], v111 offset:32768
	ds_read_b128 v[188:191], v111 offset:36864
	ds_read_b128 v[192:195], v112
	ds_read_b128 v[196:199], v112 offset:4096
	s_waitcnt lgkmcnt(4)
	v_mfma_f32_32x32x16_bf16 v[48:63], v[132:135], v[152:155], v[48:63]
	v_mfma_f32_32x32x16_bf16 v[16:31], v[132:135], v[156:159], v[16:31]
	v_lshl_add_u64 v[132:133], v[80:81], 0, s[44:45]
	global_load_lds_dwordx4 v[132:133], off
	v_lshl_add_u64 v[132:133], v[80:81], 0, s[48:49]
	s_mov_b32 m0, s93
	s_nop 0
	global_load_lds_dwordx4 v[132:133], off
	v_lshl_add_u64 v[132:133], v[80:81], 0, s[0:1]
	s_mov_b32 m0, s91
	s_mov_b64 s[0:1], 0x60400
	global_load_lds_dwordx4 v[132:133], off
	v_lshl_add_u64 v[132:133], v[80:81], 0, s[0:1]
	s_mov_b32 m0, s92
	v_mfma_f32_32x32x16_bf16 v[0:15], v[136:139], v[156:159], v[0:15]
	global_load_lds_dwordx4 v[132:133], off
	v_lshl_add_u64 v[132:133], v[82:83], 0, s[44:45]
	s_mov_b32 m0, s7
	s_nop 0
	global_load_lds_dwordx4 v[132:133], off
	v_lshl_add_u64 v[132:133], v[82:83], 0, s[48:49]
	s_mov_b32 m0, s90
	v_mfma_f32_32x32x16_bf16 v[32:47], v[136:139], v[152:155], v[32:47]
	global_load_lds_dwordx4 v[132:133], off
	s_mov_b32 m0, s6
	s_mov_b64 s[0:1], 0x40480
	ds_read_b128 v[132:135], v113 offset:32768
	ds_read_b128 v[136:139], v113 offset:36864
	ds_read_b128 v[152:155], v114
	ds_read_b128 v[156:159], v114 offset:4096
	s_waitcnt lgkmcnt(4)
	v_mfma_f32_32x32x16_bf16 v[48:63], v[184:187], v[192:195], v[48:63]
	v_mfma_f32_32x32x16_bf16 v[16:31], v[184:187], v[196:199], v[16:31]
	v_mfma_f32_32x32x16_bf16 v[32:47], v[188:191], v[192:195], v[32:47]
	v_mfma_f32_32x32x16_bf16 v[0:15], v[188:191], v[196:199], v[0:15]
	ds_read_b128 v[184:187], v115 offset:32768
	ds_read_b128 v[188:191], v115 offset:36864
	ds_read_b128 v[192:195], v116
	ds_read_b128 v[196:199], v116 offset:4096
	s_waitcnt lgkmcnt(4)
	v_mfma_f32_32x32x16_bf16 v[48:63], v[132:135], v[152:155], v[48:63]
	v_mfma_f32_32x32x16_bf16 v[16:31], v[132:135], v[156:159], v[16:31]
	v_mfma_f32_32x32x16_bf16 v[32:47], v[136:139], v[152:155], v[32:47]
	v_mfma_f32_32x32x16_bf16 v[0:15], v[136:139], v[156:159], v[0:15]
	ds_read_b128 v[132:135], v117 offset:32768
	ds_read_b128 v[136:139], v117 offset:36864
	ds_read_b128 v[152:155], v118
	ds_read_b128 v[156:159], v118 offset:4096
	s_waitcnt lgkmcnt(4)
	v_mfma_f32_32x32x16_bf16 v[48:63], v[184:187], v[192:195], v[48:63]
	v_mfma_f32_32x32x16_bf16 v[16:31], v[184:187], v[196:199], v[16:31]
	v_mfma_f32_32x32x16_bf16 v[32:47], v[188:191], v[192:195], v[32:47]
	v_mfma_f32_32x32x16_bf16 v[0:15], v[188:191], v[196:199], v[0:15]
	s_waitcnt vmcnt(6)
	s_waitcnt lgkmcnt(0)
	s_barrier
; #define MFMA(a, b, c) __builtin_amdgcn_mfma_f32_32x32x16_bf16((a), (b), (c), 0, 0, 0)
; #define WAIT_V(n) asm volatile("s_waitcnt vmcnt(%0)" ::"n"(n) : "memory")
; #define RAW_BARRIER() do { asm volatile("s_waitcnt lgkmcnt(0)" ::: "memory"); __builtin_amdgcn_s_barrier(); asm volatile("" ::: "memory"); } while (0)
; #define GLDS_STAGE(slot, kt) do { _Pragma("unroll") for (int i = 0; i < 6; ++i) \
;     __builtin_amdgcn_global_load_lds((const unsigned*)(src[i] + (kt) * 64), (__attribute__((address_space(3))) unsigned*)(smem + (slot) * G_STAGE + (wave + 8 * i) * 1024), 16, 0, 0); } while (0)
; DI void gemm_tile(const u16* __restrict__ X, int ldx, const u16* __restrict__ Wt, int ldw, int K, char* smem,
;                   f32x16 (&acc)[2][2]) {
;     ...
;   for (int kt = 0; kt < nk; ++kt) {
;     const int nxt = (cur >= 1) ? cur - 1 : 2;
;     if (kt + 2 < nk) GLDS_STAGE(nxt, kt + 2);
;     __builtin_amdgcn_sched_barrier(0);
;     const char* st = smem + cur * G_STAGE;
; #pragma unroll
;     for (int ks = 0; ks < 4; ++ks) {
;       bf16x8 a[2], b[2];
; #pragma unroll
;       for (int ft = 0; ft < 2; ++ft) a[ft] = *reinterpret_cast<const bf16x8*>(st + offA[ft] + (((ks * 2 + lh) ^ xa[ft]) << 4));
; #pragma unroll
;       for (int tt = 0; tt < 2; ++tt) b[tt] = *reinterpret_cast<const bf16x8*>(st + offB[tt] + (((ks * 2 + lh) ^ xb[tt]) << 4));
; #pragma unroll
;       for (int ft = 0; ft < 2; ++ft)
; #pragma unroll
;         for (int tt = 0; tt < 2; ++tt) acc[ft][tt] = MFMA(a[ft], b[tt], acc[ft][tt]);
;     }
;     if (kt + 2 < nk) { WAIT_V(6); } else { WAIT_V(0); }
;     RAW_BARRIER();
	ds_read_b128 v[184:187], v119 offset:32768
	ds_read_b128 v[188:191], v119 offset:36864
	ds_read_b128 v[192:195], v112 offset:49152
	ds_read_b128 v[196:199], v112 offset:53248
	s_waitcnt lgkmcnt(4)
	v_mfma_f32_32x32x16_bf16 v[48:63], v[132:135], v[152:155], v[48:63]
	v_mfma_f32_32x32x16_bf16 v[16:31], v[132:135], v[156:159], v[16:31]
	v_lshl_add_u64 v[132:133], v[80:81], 0, s[50:51]
	global_load_lds_dwordx4 v[132:133], off
	v_lshl_add_u64 v[132:133], v[80:81], 0, s[52:53]
	s_mov_b32 m0, s89
	s_nop 0
	global_load_lds_dwordx4 v[132:133], off
	v_lshl_add_u64 v[132:133], v[80:81], 0, s[0:1]
	s_mov_b32 m0, s88
	s_mov_b64 s[0:1], 0x60480
	global_load_lds_dwordx4 v[132:133], off
	v_lshl_add_u64 v[132:133], v[80:81], 0, s[0:1]
	s_mov_b32 m0, s87
	v_mfma_f32_32x32x16_bf16 v[0:15], v[136:139], v[156:159], v[0:15]
	global_load_lds_dwordx4 v[132:133], off
	v_lshl_add_u64 v[132:133], v[82:83], 0, s[50:51]
	s_mov_b32 m0, s86
	s_nop 0
	global_load_lds_dwordx4 v[132:133], off
	v_lshl_add_u64 v[132:133], v[82:83], 0, s[52:53]
	s_mov_b32 m0, s55
	v_mfma_f32_32x32x16_bf16 v[32:47], v[136:139], v[152:155], v[32:47]
	global_load_lds_dwordx4 v[132:133], off
	s_mov_b32 m0, s54
	s_mov_b64 s[0:1], 0x40500
	ds_read_b128 v[132:135], v120 offset:32768
	ds_read_b128 v[136:139], v120 offset:36864
	ds_read_b128 v[152:155], v114 offset:49152
	ds_read_b128 v[156:159], v114 offset:53248
	s_waitcnt lgkmcnt(4)
	v_mfma_f32_32x32x16_bf16 v[48:63], v[184:187], v[192:195], v[48:63]
	v_mfma_f32_32x32x16_bf16 v[16:31], v[184:187], v[196:199], v[16:31]
	v_mfma_f32_32x32x16_bf16 v[32:47], v[188:191], v[192:195], v[32:47]
	v_mfma_f32_32x32x16_bf16 v[0:15], v[188:191], v[196:199], v[0:15]
	ds_read_b128 v[184:187], v121 offset:32768
	ds_read_b128 v[188:191], v121 offset:36864
	ds_read_b128 v[192:195], v116 offset:49152
	ds_read_b128 v[196:199], v116 offset:53248
	s_waitcnt lgkmcnt(4)
	v_mfma_f32_32x32x16_bf16 v[48:63], v[132:135], v[152:155], v[48:63]
	v_mfma_f32_32x32x16_bf16 v[16:31], v[132:135], v[156:159], v[16:31]
	v_mfma_f32_32x32x16_bf16 v[32:47], v[136:139], v[152:155], v[32:47]
	v_mfma_f32_32x32x16_bf16 v[0:15], v[136:139], v[156:159], v[0:15]
	ds_read_b128 v[132:135], v122 offset:32768
	ds_read_b128 v[136:139], v122 offset:36864
	ds_read_b128 v[152:155], v118 offset:49152
	ds_read_b128 v[156:159], v118 offset:53248
	s_waitcnt lgkmcnt(4)
	v_mfma_f32_32x32x16_bf16 v[48:63], v[184:187], v[192:195], v[48:63]
	v_mfma_f32_32x32x16_bf16 v[16:31], v[184:187], v[196:199], v[16:31]
	v_mfma_f32_32x32x16_bf16 v[32:47], v[188:191], v[192:195], v[32:47]
	v_mfma_f32_32x32x16_bf16 v[0:15], v[188:191], v[196:199], v[0:15]
	s_waitcnt vmcnt(6)
	s_waitcnt lgkmcnt(0)
	s_barrier
	ds_read_b128 v[184:187], v123 offset:32768
	ds_read_b128 v[188:191], v123 offset:36864
	ds_read_b128 v[192:195], v124
	ds_read_b128 v[196:199], v124 offset:4096
	s_waitcnt lgkmcnt(4)
	v_mfma_f32_32x32x16_bf16 v[48:63], v[132:135], v[152:155], v[48:63]
	v_mfma_f32_32x32x16_bf16 v[16:31], v[132:135], v[156:159], v[16:31]
	v_lshl_add_u64 v[132:133], v[80:81], 0, s[56:57]
	global_load_lds_dwordx4 v[132:133], off
	v_lshl_add_u64 v[132:133], v[80:81], 0, s[58:59]
	s_mov_b32 m0, s10
	s_nop 0
	global_load_lds_dwordx4 v[132:133], off
	v_lshl_add_u64 v[132:133], v[80:81], 0, s[0:1]
	s_mov_b32 m0, s95
	s_mov_b64 s[0:1], 0x60500
	global_load_lds_dwordx4 v[132:133], off
	v_lshl_add_u64 v[132:133], v[80:81], 0, s[0:1]
	s_mov_b32 m0, s9
	v_mfma_f32_32x32x16_bf16 v[0:15], v[136:139], v[156:159], v[0:15]
	global_load_lds_dwordx4 v[132:133], off
	v_lshl_add_u64 v[132:133], v[82:83], 0, s[56:57]
	s_mov_b32 m0, s8
	s_nop 0
	global_load_lds_dwordx4 v[132:133], off
	v_lshl_add_u64 v[132:133], v[82:83], 0, s[58:59]
	s_mov_b32 m0, s46
	v_mfma_f32_32x32x16_bf16 v[32:47], v[136:139], v[152:155], v[32:47]
	global_load_lds_dwordx4 v[132:133], off
	v_readfirstlane_b32 s54, v85
	s_mov_b32 m0, s54
	v_readfirstlane_b32 s7, v86
	ds_read_b128 v[132:135], v125 offset:32768
	ds_read_b128 v[136:139], v125 offset:36864
	ds_read_b128 v[152:155], v126
	ds_read_b128 v[156:159], v126 offset:4096
	s_waitcnt lgkmcnt(4)
	v_mfma_f32_32x32x16_bf16 v[48:63], v[184:187], v[192:195], v[48:63]
	s_mov_b64 s[0:1], 0x40580
	v_readfirstlane_b32 s8, v87
	v_readfirstlane_b32 s10, v88
	v_readfirstlane_b32 s9, v89
	v_readfirstlane_b32 s46, v90
	v_mfma_f32_32x32x16_bf16 v[16:31], v[184:187], v[196:199], v[16:31]
	v_mfma_f32_32x32x16_bf16 v[32:47], v[188:191], v[192:195], v[32:47]
	v_mfma_f32_32x32x16_bf16 v[0:15], v[188:191], v[196:199], v[0:15]
	ds_read_b128 v[184:187], v127 offset:32768
	ds_read_b128 v[188:191], v127 offset:36864
	ds_read_b128 v[192:195], v128
	ds_read_b128 v[196:199], v128 offset:4096
	s_waitcnt lgkmcnt(4)
	v_mfma_f32_32x32x16_bf16 v[48:63], v[132:135], v[152:155], v[48:63]
	v_mfma_f32_32x32x16_bf16 v[16:31], v[132:135], v[156:159], v[16:31]
	v_mfma_f32_32x32x16_bf16 v[32:47], v[136:139], v[152:155], v[32:47]
	v_mfma_f32_32x32x16_bf16 v[0:15], v[136:139], v[156:159], v[0:15]
	ds_read_b128 v[132:135], v129 offset:32768
	ds_read_b128 v[136:139], v129 offset:36864
	ds_read_b128 v[152:155], v130
	ds_read_b128 v[156:159], v130 offset:4096
	s_waitcnt lgkmcnt(4)
	v_mfma_f32_32x32x16_bf16 v[48:63], v[184:187], v[192:195], v[48:63]
	v_mfma_f32_32x32x16_bf16 v[16:31], v[184:187], v[196:199], v[16:31]
	v_mfma_f32_32x32x16_bf16 v[32:47], v[188:191], v[192:195], v[32:47]
	v_mfma_f32_32x32x16_bf16 v[0:15], v[188:191], v[196:199], v[0:15]
	s_waitcnt vmcnt(6)
	s_waitcnt lgkmcnt(0)
	s_barrier
; #define MFMA(a, b, c) __builtin_amdgcn_mfma_f32_32x32x16_bf16((a), (b), (c), 0, 0, 0)
; #define WAIT_V(n) asm volatile("s_waitcnt vmcnt(%0)" ::"n"(n) : "memory")
; #define RAW_BARRIER() do { asm volatile("s_waitcnt lgkmcnt(0)" ::: "memory"); __builtin_amdgcn_s_barrier(); asm volatile("" ::: "memory"); } while (0)
; #define GLDS_STAGE(slot, kt) do { _Pragma("unroll") for (int i = 0; i < 6; ++i) \
;     __builtin_amdgcn_global_load_lds((const unsigned*)(src[i] + (kt) * 64), (__attribute__((address_space(3))) unsigned*)(smem + (slot) * G_STAGE + (wave + 8 * i) * 1024), 16, 0, 0); } while (0)
; DI void gemm_tile(const u16* __restrict__ X, int ldx, const u16* __restrict__ Wt, int ldw, int K, char* smem,
;                   f32x16 (&acc)[2][2]) {
;     ...
;   for (int kt = 0; kt < nk; ++kt) {
;     const int nxt = (cur >= 1) ? cur - 1 : 2;
;     if (kt + 2 < nk) GLDS_STAGE(nxt, kt + 2);
;     __builtin_amdgcn_sched_barrier(0);
;     const char* st = smem + cur * G_STAGE;
; #pragma unroll
;     for (int ks = 0; ks < 4; ++ks) {
;       bf16x8 a[2], b[2];
; #pragma unroll
;       for (int ft = 0; ft < 2; ++ft) a[ft] = *reinterpret_cast<const bf16x8*>(st + offA[ft] + (((ks * 2 + lh) ^ xa[ft]) << 4));
; #pragma unroll
;       for (int tt = 0; tt < 2; ++tt) b[tt] = *reinterpret_cast<const bf16x8*>(st + offB[tt] + (((ks * 2 + lh) ^ xb[tt]) << 4));
; #pragma unroll
;       for (int ft = 0; ft < 2; ++ft)
; #pragma unroll
;         for (int tt = 0; tt < 2; ++tt) acc[ft][tt] = MFMA(a[ft], b[tt], acc[ft][tt]);
;     }
;     if (kt + 2 < nk) { WAIT_V(6); } else { WAIT_V(0); }
;     RAW_BARRIER();
	ds_read_b128 v[184:187], v111 offset:32768
	ds_read_b128 v[188:191], v111 offset:36864
	ds_read_b128 v[192:195], v112
	ds_read_b128 v[196:199], v112 offset:4096
	s_waitcnt lgkmcnt(4)
	v_mfma_f32_32x32x16_bf16 v[48:63], v[132:135], v[152:155], v[48:63]
	v_mfma_f32_32x32x16_bf16 v[16:31], v[132:135], v[156:159], v[16:31]
	v_lshl_add_u64 v[132:133], v[80:81], 0, s[60:61]
	global_load_lds_dwordx4 v[132:133], off
	v_lshl_add_u64 v[132:133], v[80:81], 0, s[62:63]
	s_mov_b32 m0, s7
	s_nop 0
	global_load_lds_dwordx4 v[132:133], off
	v_lshl_add_u64 v[132:133], v[80:81], 0, s[0:1]
	s_mov_b32 m0, s8
	s_mov_b64 s[0:1], 0x60580
	global_load_lds_dwordx4 v[132:133], off
	v_lshl_add_u64 v[132:133], v[80:81], 0, s[0:1]
	s_mov_b32 m0, s10
	v_mfma_f32_32x32x16_bf16 v[0:15], v[136:139], v[156:159], v[0:15]
	global_load_lds_dwordx4 v[132:133], off
	v_lshl_add_u64 v[132:133], v[82:83], 0, s[60:61]
	s_mov_b32 m0, s9
	s_nop 0
	global_load_lds_dwordx4 v[132:133], off
	v_lshl_add_u64 v[132:133], v[82:83], 0, s[62:63]
	s_mov_b32 m0, s46
	v_mfma_f32_32x32x16_bf16 v[32:47], v[136:139], v[152:155], v[32:47]
	global_load_lds_dwordx4 v[132:133], off
	v_readfirstlane_b32 s47, v143
	s_mov_b32 m0, s47
	v_readfirstlane_b32 s0, v101
	ds_read_b128 v[132:135], v113 offset:32768
	ds_read_b128 v[136:139], v113 offset:36864
	ds_read_b128 v[152:155], v114
	ds_read_b128 v[156:159], v114 offset:4096
	s_waitcnt lgkmcnt(4)
	v_mfma_f32_32x32x16_bf16 v[48:63], v[184:187], v[192:195], v[48:63]
	s_mov_b64 s[4:5], 0x40600
	v_readfirstlane_b32 s1, v102
	v_readfirstlane_b32 s6, v105
	v_mfma_f32_32x32x16_bf16 v[16:31], v[184:187], v[196:199], v[16:31]
	v_mfma_f32_32x32x16_bf16 v[32:47], v[188:191], v[192:195], v[32:47]
	v_mfma_f32_32x32x16_bf16 v[0:15], v[188:191], v[196:199], v[0:15]
	ds_read_b128 v[184:187], v115 offset:32768
	ds_read_b128 v[188:191], v115 offset:36864
	ds_read_b128 v[192:195], v116
	ds_read_b128 v[196:199], v116 offset:4096
	s_waitcnt lgkmcnt(4)
	v_mfma_f32_32x32x16_bf16 v[48:63], v[132:135], v[152:155], v[48:63]
	v_mfma_f32_32x32x16_bf16 v[16:31], v[132:135], v[156:159], v[16:31]
	v_mfma_f32_32x32x16_bf16 v[32:47], v[136:139], v[152:155], v[32:47]
	v_mfma_f32_32x32x16_bf16 v[0:15], v[136:139], v[156:159], v[0:15]
	ds_read_b128 v[132:135], v117 offset:32768
	ds_read_b128 v[136:139], v117 offset:36864
	ds_read_b128 v[152:155], v118
	ds_read_b128 v[156:159], v118 offset:4096
	s_waitcnt lgkmcnt(4)
	v_mfma_f32_32x32x16_bf16 v[48:63], v[184:187], v[192:195], v[48:63]
	v_mfma_f32_32x32x16_bf16 v[16:31], v[184:187], v[196:199], v[16:31]
	v_mfma_f32_32x32x16_bf16 v[32:47], v[188:191], v[192:195], v[32:47]
	v_mfma_f32_32x32x16_bf16 v[0:15], v[188:191], v[196:199], v[0:15]
	s_waitcnt vmcnt(6)
	s_waitcnt lgkmcnt(0)
	s_barrier
	ds_read_b128 v[184:187], v119 offset:32768
	ds_read_b128 v[188:191], v119 offset:36864
	ds_read_b128 v[192:195], v112 offset:49152
	ds_read_b128 v[196:199], v112 offset:53248
	s_waitcnt lgkmcnt(4)
	v_mfma_f32_32x32x16_bf16 v[48:63], v[132:135], v[152:155], v[48:63]
	v_mfma_f32_32x32x16_bf16 v[16:31], v[132:135], v[156:159], v[16:31]
	v_lshl_add_u64 v[132:133], v[80:81], 0, s[64:65]
	global_load_lds_dwordx4 v[132:133], off
	v_lshl_add_u64 v[132:133], v[80:81], 0, s[66:67]
	s_mov_b32 m0, s0
	s_nop 0
	global_load_lds_dwordx4 v[132:133], off
	v_lshl_add_u64 v[132:133], v[80:81], 0, s[4:5]
	s_mov_b32 m0, s1
	s_mov_b64 s[4:5], 0x60600
	global_load_lds_dwordx4 v[132:133], off
	v_lshl_add_u64 v[132:133], v[80:81], 0, s[4:5]
	v_readfirstlane_b32 s5, v103
	s_mov_b32 m0, s5
	v_readfirstlane_b32 s4, v104
	global_load_lds_dwordx4 v[132:133], off
	v_lshl_add_u64 v[132:133], v[82:83], 0, s[64:65]
	s_mov_b32 m0, s4
	v_mfma_f32_32x32x16_bf16 v[0:15], v[136:139], v[156:159], v[0:15]
	global_load_lds_dwordx4 v[132:133], off
	v_lshl_add_u64 v[132:133], v[82:83], 0, s[66:67]
	s_mov_b32 m0, s6
	s_nop 0
	global_load_lds_dwordx4 v[132:133], off
	v_mfma_f32_32x32x16_bf16 v[32:47], v[136:139], v[152:155], v[32:47]
	v_readfirstlane_b32 s55, v84
	s_mov_b32 m0, s55
	v_readfirstlane_b32 s55, v106
	ds_read_b128 v[132:135], v120 offset:32768
	ds_read_b128 v[136:139], v120 offset:36864
	ds_read_b128 v[152:155], v114 offset:49152
	ds_read_b128 v[156:159], v114 offset:53248
	s_waitcnt lgkmcnt(4)
	v_mfma_f32_32x32x16_bf16 v[48:63], v[184:187], v[192:195], v[48:63]
	s_mov_b64 s[86:87], 0x40680
	v_mfma_f32_32x32x16_bf16 v[16:31], v[184:187], v[196:199], v[16:31]
	v_mfma_f32_32x32x16_bf16 v[32:47], v[188:191], v[192:195], v[32:47]
	v_mfma_f32_32x32x16_bf16 v[0:15], v[188:191], v[196:199], v[0:15]
	ds_read_b128 v[184:187], v121 offset:32768
	ds_read_b128 v[188:191], v121 offset:36864
	ds_read_b128 v[192:195], v116 offset:49152
	ds_read_b128 v[196:199], v116 offset:53248
	s_waitcnt lgkmcnt(4)
	v_mfma_f32_32x32x16_bf16 v[48:63], v[132:135], v[152:155], v[48:63]
	v_mfma_f32_32x32x16_bf16 v[16:31], v[132:135], v[156:159], v[16:31]
	v_mfma_f32_32x32x16_bf16 v[32:47], v[136:139], v[152:155], v[32:47]
	v_mfma_f32_32x32x16_bf16 v[0:15], v[136:139], v[156:159], v[0:15]
	ds_read_b128 v[132:135], v122 offset:32768
	ds_read_b128 v[136:139], v122 offset:36864
	ds_read_b128 v[152:155], v118 offset:49152
	ds_read_b128 v[156:159], v118 offset:53248
	s_waitcnt lgkmcnt(4)
	v_mfma_f32_32x32x16_bf16 v[48:63], v[184:187], v[192:195], v[48:63]
	v_mfma_f32_32x32x16_bf16 v[16:31], v[184:187], v[196:199], v[16:31]
	v_mfma_f32_32x32x16_bf16 v[32:47], v[188:191], v[192:195], v[32:47]
	v_mfma_f32_32x32x16_bf16 v[0:15], v[188:191], v[196:199], v[0:15]
	s_waitcnt vmcnt(6)
	s_waitcnt lgkmcnt(0)
	s_barrier
; #define MFMA(a, b, c) __builtin_amdgcn_mfma_f32_32x32x16_bf16((a), (b), (c), 0, 0, 0)
; #define WAIT_V(n) asm volatile("s_waitcnt vmcnt(%0)" ::"n"(n) : "memory")
; #define RAW_BARRIER() do { asm volatile("s_waitcnt lgkmcnt(0)" ::: "memory"); __builtin_amdgcn_s_barrier(); asm volatile("" ::: "memory"); } while (0)
; #define GLDS_STAGE(slot, kt) do { _Pragma("unroll") for (int i = 0; i < 6; ++i) \
;     __builtin_amdgcn_global_load_lds((const unsigned*)(src[i] + (kt) * 64), (__attribute__((address_space(3))) unsigned*)(smem + (slot) * G_STAGE + (wave + 8 * i) * 1024), 16, 0, 0); } while (0)
; DI void gemm_tile(const u16* __restrict__ X, int ldx, const u16* __restrict__ Wt, int ldw, int K, char* smem,
;                   f32x16 (&acc)[2][2]) {
;     ...
;   for (int kt = 0; kt < nk; ++kt) {
;     const int nxt = (cur >= 1) ? cur - 1 : 2;
;     if (kt + 2 < nk) GLDS_STAGE(nxt, kt + 2);
;     __builtin_amdgcn_sched_barrier(0);
;     const char* st = smem + cur * G_STAGE;
; #pragma unroll
;     for (int ks = 0; ks < 4; ++ks) {
;       bf16x8 a[2], b[2];
; #pragma unroll
;       for (int ft = 0; ft < 2; ++ft) a[ft] = *reinterpret_cast<const bf16x8*>(st + offA[ft] + (((ks * 2 + lh) ^ xa[ft]) << 4));
; #pragma unroll
;       for (int tt = 0; tt < 2; ++tt) b[tt] = *reinterpret_cast<const bf16x8*>(st + offB[tt] + (((ks * 2 + lh) ^ xb[tt]) << 4));
; #pragma unroll
;       for (int ft = 0; ft < 2; ++ft)
; #pragma unroll
;         for (int tt = 0; tt < 2; ++tt) acc[ft][tt] = MFMA(a[ft], b[tt], acc[ft][tt]);
;     }
;     if (kt + 2 < nk) { WAIT_V(6); } else { WAIT_V(0); }
;     RAW_BARRIER();
	ds_read_b128 v[184:187], v123 offset:32768
	ds_read_b128 v[188:191], v123 offset:36864
	ds_read_b128 v[192:195], v124
	ds_read_b128 v[196:199], v124 offset:4096
	s_waitcnt lgkmcnt(4)
	v_mfma_f32_32x32x16_bf16 v[48:63], v[132:135], v[152:155], v[48:63]
	v_mfma_f32_32x32x16_bf16 v[16:31], v[132:135], v[156:159], v[16:31]
	v_lshl_add_u64 v[132:133], v[80:81], 0, s[68:69]
	global_load_lds_dwordx4 v[132:133], off
	v_lshl_add_u64 v[132:133], v[80:81], 0, s[70:71]
	s_mov_b32 m0, s55
	v_readfirstlane_b32 s55, v91
	global_load_lds_dwordx4 v[132:133], off
	v_lshl_add_u64 v[132:133], v[80:81], 0, s[86:87]
	s_mov_b32 m0, s55
	s_mov_b64 s[86:87], 0x60680
	v_readfirstlane_b32 s55, v92
	global_load_lds_dwordx4 v[132:133], off
	v_lshl_add_u64 v[132:133], v[80:81], 0, s[86:87]
	s_mov_b32 m0, s55
	v_readfirstlane_b32 s55, v93
	global_load_lds_dwordx4 v[132:133], off
	v_lshl_add_u64 v[132:133], v[82:83], 0, s[68:69]
	s_mov_b32 m0, s55
	v_readfirstlane_b32 s55, v94
	global_load_lds_dwordx4 v[132:133], off
	v_lshl_add_u64 v[132:133], v[82:83], 0, s[70:71]
	s_mov_b32 m0, s55
	v_mfma_f32_32x32x16_bf16 v[0:15], v[136:139], v[156:159], v[0:15]
	global_load_lds_dwordx4 v[132:133], off
	v_mfma_f32_32x32x16_bf16 v[32:47], v[136:139], v[152:155], v[32:47]
	s_mov_b32 m0, s54
	s_mov_b64 s[54:55], 0x40700
	ds_read_b128 v[132:135], v125 offset:32768
	ds_read_b128 v[136:139], v125 offset:36864
	ds_read_b128 v[152:155], v126
	ds_read_b128 v[156:159], v126 offset:4096
	s_waitcnt lgkmcnt(4)
	v_mfma_f32_32x32x16_bf16 v[48:63], v[184:187], v[192:195], v[48:63]
	v_mfma_f32_32x32x16_bf16 v[16:31], v[184:187], v[196:199], v[16:31]
	v_mfma_f32_32x32x16_bf16 v[32:47], v[188:191], v[192:195], v[32:47]
	v_mfma_f32_32x32x16_bf16 v[0:15], v[188:191], v[196:199], v[0:15]
	ds_read_b128 v[184:187], v127 offset:32768
	ds_read_b128 v[188:191], v127 offset:36864
	ds_read_b128 v[192:195], v128
	ds_read_b128 v[196:199], v128 offset:4096
	s_waitcnt lgkmcnt(4)
	v_mfma_f32_32x32x16_bf16 v[48:63], v[132:135], v[152:155], v[48:63]
	v_mfma_f32_32x32x16_bf16 v[16:31], v[132:135], v[156:159], v[16:31]
	v_mfma_f32_32x32x16_bf16 v[32:47], v[136:139], v[152:155], v[32:47]
	v_mfma_f32_32x32x16_bf16 v[0:15], v[136:139], v[156:159], v[0:15]
	ds_read_b128 v[132:135], v129 offset:32768
	ds_read_b128 v[136:139], v129 offset:36864
	ds_read_b128 v[152:155], v130
	ds_read_b128 v[156:159], v130 offset:4096
	s_waitcnt lgkmcnt(4)
	v_mfma_f32_32x32x16_bf16 v[48:63], v[184:187], v[192:195], v[48:63]
	v_mfma_f32_32x32x16_bf16 v[16:31], v[184:187], v[196:199], v[16:31]
	v_mfma_f32_32x32x16_bf16 v[32:47], v[188:191], v[192:195], v[32:47]
	v_mfma_f32_32x32x16_bf16 v[0:15], v[188:191], v[196:199], v[0:15]
	s_waitcnt vmcnt(6)
	s_waitcnt lgkmcnt(0)
	s_barrier
	ds_read_b128 v[184:187], v111 offset:32768
	ds_read_b128 v[188:191], v111 offset:36864
	ds_read_b128 v[192:195], v112
	ds_read_b128 v[196:199], v112 offset:4096
	s_waitcnt lgkmcnt(4)
	v_mfma_f32_32x32x16_bf16 v[48:63], v[132:135], v[152:155], v[48:63]
	v_mfma_f32_32x32x16_bf16 v[16:31], v[132:135], v[156:159], v[16:31]
	v_lshl_add_u64 v[132:133], v[80:81], 0, s[72:73]
	global_load_lds_dwordx4 v[132:133], off
	v_lshl_add_u64 v[132:133], v[80:81], 0, s[74:75]
	s_mov_b32 m0, s7
	s_nop 0
	global_load_lds_dwordx4 v[132:133], off
	v_lshl_add_u64 v[132:133], v[80:81], 0, s[54:55]
	s_mov_b32 m0, s8
	s_mov_b64 s[54:55], 0x60700
	global_load_lds_dwordx4 v[132:133], off
	v_lshl_add_u64 v[132:133], v[80:81], 0, s[54:55]
	s_mov_b32 m0, s10
	v_mfma_f32_32x32x16_bf16 v[0:15], v[136:139], v[156:159], v[0:15]
	global_load_lds_dwordx4 v[132:133], off
	v_lshl_add_u64 v[132:133], v[82:83], 0, s[72:73]
	s_mov_b32 m0, s9
	s_nop 0
	global_load_lds_dwordx4 v[132:133], off
	v_lshl_add_u64 v[132:133], v[82:83], 0, s[74:75]
	s_mov_b32 m0, s46
	v_mfma_f32_32x32x16_bf16 v[32:47], v[136:139], v[152:155], v[32:47]
	global_load_lds_dwordx4 v[132:133], off
	s_mov_b32 m0, s47
	s_mov_b64 s[8:9], 0x40780
	ds_read_b128 v[132:135], v113 offset:32768
	ds_read_b128 v[136:139], v113 offset:36864
	ds_read_b128 v[152:155], v114
	ds_read_b128 v[156:159], v114 offset:4096
	s_waitcnt lgkmcnt(4)
	v_mfma_f32_32x32x16_bf16 v[48:63], v[184:187], v[192:195], v[48:63]
	v_mfma_f32_32x32x16_bf16 v[16:31], v[184:187], v[196:199], v[16:31]
	v_mfma_f32_32x32x16_bf16 v[32:47], v[188:191], v[192:195], v[32:47]
	v_mfma_f32_32x32x16_bf16 v[0:15], v[188:191], v[196:199], v[0:15]
	ds_read_b128 v[184:187], v115 offset:32768
	ds_read_b128 v[188:191], v115 offset:36864
	ds_read_b128 v[192:195], v116
	ds_read_b128 v[196:199], v116 offset:4096
	s_waitcnt lgkmcnt(4)
	v_mfma_f32_32x32x16_bf16 v[48:63], v[132:135], v[152:155], v[48:63]
	v_mfma_f32_32x32x16_bf16 v[16:31], v[132:135], v[156:159], v[16:31]
	v_mfma_f32_32x32x16_bf16 v[32:47], v[136:139], v[152:155], v[32:47]
	v_mfma_f32_32x32x16_bf16 v[0:15], v[136:139], v[156:159], v[0:15]
	s_waitcnt lgkmcnt(0)
	v_mfma_f32_32x32x16_bf16 v[48:63], v[184:187], v[192:195], v[48:63]
	v_mfma_f32_32x32x16_bf16 v[16:31], v[184:187], v[196:199], v[16:31]
	v_mfma_f32_32x32x16_bf16 v[32:47], v[188:191], v[192:195], v[32:47]
	v_mfma_f32_32x32x16_bf16 v[0:15], v[188:191], v[196:199], v[0:15]
	ds_read_b128 v[132:135], v117 offset:32768
	ds_read_b128 v[136:139], v117 offset:36864
	ds_read_b128 v[152:155], v118
	ds_read_b128 v[156:159], v118 offset:4096
	s_waitcnt vmcnt(6)
	s_waitcnt lgkmcnt(0)
	s_barrier
; #define MFMA(a, b, c) __builtin_amdgcn_mfma_f32_32x32x16_bf16((a), (b), (c), 0, 0, 0)
; #define WAIT_V(n) asm volatile("s_waitcnt vmcnt(%0)" ::"n"(n) : "memory")
; #define RAW_BARRIER() do { asm volatile("s_waitcnt lgkmcnt(0)" ::: "memory"); __builtin_amdgcn_s_barrier(); asm volatile("" ::: "memory"); } while (0)
; #define GLDS_STAGE(slot, kt) do { _Pragma("unroll") for (int i = 0; i < 6; ++i) \
;     __builtin_amdgcn_global_load_lds((const unsigned*)(src[i] + (kt) * 64), (__attribute__((address_space(3))) unsigned*)(smem + (slot) * G_STAGE + (wave + 8 * i) * 1024), 16, 0, 0); } while (0)
; DI void gemm_tile(const u16* __restrict__ X, int ldx, const u16* __restrict__ Wt, int ldw, int K, char* smem,
;                   f32x16 (&acc)[2][2]) {
;     ...
;   for (int kt = 0; kt < nk; ++kt) {
;     const int nxt = (cur >= 1) ? cur - 1 : 2;
;     if (kt + 2 < nk) GLDS_STAGE(nxt, kt + 2);
;     __builtin_amdgcn_sched_barrier(0);
;     const char* st = smem + cur * G_STAGE;
; #pragma unroll
;     for (int ks = 0; ks < 4; ++ks) {
;       bf16x8 a[2], b[2];
; #pragma unroll
;       for (int ft = 0; ft < 2; ++ft) a[ft] = *reinterpret_cast<const bf16x8*>(st + offA[ft] + (((ks * 2 + lh) ^ xa[ft]) << 4));
; #pragma unroll
;       for (int tt = 0; tt < 2; ++tt) b[tt] = *reinterpret_cast<const bf16x8*>(st + offB[tt] + (((ks * 2 + lh) ^ xb[tt]) << 4));
; #pragma unroll
;       for (int ft = 0; ft < 2; ++ft)
; #pragma unroll
;         for (int tt = 0; tt < 2; ++tt) acc[ft][tt] = MFMA(a[ft], b[tt], acc[ft][tt]);
;     }
;     if (kt + 2 < nk) { WAIT_V(6); } else { WAIT_V(0); }
;     RAW_BARRIER();
	s_waitcnt lgkmcnt(0)
	v_mfma_f32_32x32x16_bf16 v[48:63], v[132:135], v[152:155], v[48:63]
	v_mfma_f32_32x32x16_bf16 v[16:31], v[132:135], v[156:159], v[16:31]
	v_lshl_add_u64 v[132:133], v[80:81], 0, s[76:77]
	global_load_lds_dwordx4 v[132:133], off
	v_lshl_add_u64 v[132:133], v[80:81], 0, s[80:81]
	s_mov_b32 m0, s0
	s_nop 0
	global_load_lds_dwordx4 v[132:133], off
	v_lshl_add_u64 v[132:133], v[80:81], 0, s[8:9]
	s_mov_b32 m0, s1
	s_mov_b64 s[0:1], 0x60780
	global_load_lds_dwordx4 v[132:133], off
	v_lshl_add_u64 v[80:81], v[80:81], 0, s[0:1]
	s_mov_b32 m0, s5
	v_mfma_f32_32x32x16_bf16 v[0:15], v[136:139], v[156:159], v[0:15]
	global_load_lds_dwordx4 v[80:81], off
	v_lshl_add_u64 v[80:81], v[82:83], 0, s[76:77]
	s_mov_b32 m0, s4
	s_nop 0
	global_load_lds_dwordx4 v[80:81], off
	v_lshl_add_u64 v[80:81], v[82:83], 0, s[80:81]
	s_mov_b32 m0, s6
	v_mfma_f32_32x32x16_bf16 v[32:47], v[136:139], v[152:155], v[32:47]
	global_load_lds_dwordx4 v[80:81], off
	ds_read_b128 v[80:83], v119 offset:32768
	ds_read_b128 v[132:135], v112 offset:49152
	ds_read_b128 v[136:139], v112 offset:53248
	s_waitcnt lgkmcnt(0)
	v_mfma_f32_32x32x16_bf16 v[48:63], v[80:83], v[132:135], v[48:63]
	v_mfma_f32_32x32x16_bf16 v[16:31], v[80:83], v[136:139], v[16:31]
	ds_read_b128 v[80:83], v119 offset:36864
	s_waitcnt lgkmcnt(0)
	v_mfma_f32_32x32x16_bf16 v[32:47], v[80:83], v[132:135], v[32:47]
	v_mfma_f32_32x32x16_bf16 v[0:15], v[80:83], v[136:139], v[0:15]
	ds_read_b128 v[80:83], v120 offset:32768
	ds_read_b128 v[132:135], v114 offset:49152
	ds_read_b128 v[136:139], v114 offset:53248
	s_waitcnt lgkmcnt(0)
	v_mfma_f32_32x32x16_bf16 v[48:63], v[80:83], v[132:135], v[48:63]
	v_mfma_f32_32x32x16_bf16 v[16:31], v[80:83], v[136:139], v[16:31]
	ds_read_b128 v[80:83], v120 offset:36864
	s_waitcnt lgkmcnt(0)
	v_mfma_f32_32x32x16_bf16 v[32:47], v[80:83], v[132:135], v[32:47]
	v_mfma_f32_32x32x16_bf16 v[0:15], v[80:83], v[136:139], v[0:15]
	ds_read_b128 v[80:83], v121 offset:32768
	ds_read_b128 v[132:135], v116 offset:49152
	ds_read_b128 v[136:139], v116 offset:53248
	s_waitcnt lgkmcnt(0)
	v_mfma_f32_32x32x16_bf16 v[48:63], v[80:83], v[132:135], v[48:63]
	v_mfma_f32_32x32x16_bf16 v[16:31], v[80:83], v[136:139], v[16:31]
	ds_read_b128 v[80:83], v121 offset:36864
	s_waitcnt lgkmcnt(0)
	v_mfma_f32_32x32x16_bf16 v[32:47], v[80:83], v[132:135], v[32:47]
	v_mfma_f32_32x32x16_bf16 v[0:15], v[80:83], v[136:139], v[0:15]
	ds_read_b128 v[80:83], v122 offset:32768
	ds_read_b128 v[132:135], v118 offset:49152
	ds_read_b128 v[136:139], v118 offset:53248
	s_waitcnt lgkmcnt(0)
	v_mfma_f32_32x32x16_bf16 v[48:63], v[80:83], v[132:135], v[48:63]
	v_mfma_f32_32x32x16_bf16 v[16:31], v[80:83], v[136:139], v[16:31]
	ds_read_b128 v[80:83], v122 offset:36864
	s_waitcnt vmcnt(6)
	s_waitcnt lgkmcnt(0)
	s_barrier
; #define MFMA(a, b, c) __builtin_amdgcn_mfma_f32_32x32x16_bf16((a), (b), (c), 0, 0, 0)
; #define WAIT_V(n) asm volatile("s_waitcnt vmcnt(%0)" ::"n"(n) : "memory")
; #define RAW_BARRIER() do { asm volatile("s_waitcnt lgkmcnt(0)" ::: "memory"); __builtin_amdgcn_s_barrier(); asm volatile("" ::: "memory"); } while (0)
; #define GLDS_STAGE(slot, kt) do { _Pragma("unroll") for (int i = 0; i < 6; ++i) \
;     __builtin_amdgcn_global_load_lds((const unsigned*)(src[i] + (kt) * 64), (__attribute__((address_space(3))) unsigned*)(smem + (slot) * G_STAGE + (wave + 8 * i) * 1024), 16, 0, 0); } while (0)
; DI void gemm_tile(const u16* __restrict__ X, int ldx, const u16* __restrict__ Wt, int ldw, int K, char* smem,
;                   f32x16 (&acc)[2][2]) {
;     ...
;   for (int kt = 0; kt < nk; ++kt) {
;     const int nxt = (cur >= 1) ? cur - 1 : 2;
;     if (kt + 2 < nk) GLDS_STAGE(nxt, kt + 2);
;     __builtin_amdgcn_sched_barrier(0);
;     const char* st = smem + cur * G_STAGE;
; #pragma unroll
;     for (int ks = 0; ks < 4; ++ks) {
;       bf16x8 a[2], b[2];
; #pragma unroll
;       for (int ft = 0; ft < 2; ++ft) a[ft] = *reinterpret_cast<const bf16x8*>(st + offA[ft] + (((ks * 2 + lh) ^ xa[ft]) << 4));
; #pragma unroll
;       for (int tt = 0; tt < 2; ++tt) b[tt] = *reinterpret_cast<const bf16x8*>(st + offB[tt] + (((ks * 2 + lh) ^ xb[tt]) << 4));
; #pragma unroll
;       for (int ft = 0; ft < 2; ++ft)
; #pragma unroll
;         for (int tt = 0; tt < 2; ++tt) acc[ft][tt] = MFMA(a[ft], b[tt], acc[ft][tt]);
;     }
;     if (kt + 2 < nk) { WAIT_V(6); } else { WAIT_V(0); }
;     RAW_BARRIER();
;     cur = (cur == 2) ? 0 : cur + 1;
;   }
; template <int MODE>
; DI void phase_gemm(const Params& p, const u16* X, const u16* Wt, int N, const float* resid, float* outf, u16* outb, int ldo, char* smem) {
;     ...
;       float* wl = (float*)(smem + wave * 17408);
; #pragma unroll
;       for (int tt = 0; tt < 2; ++tt)
; #pragma unroll
;         for (int ft = 0; ft < 2; ++ft)
; #pragma unroll
;           for (int g = 0; g < 4; ++g) {
;             f32x4 v = {acc[ft][tt][4 * g], acc[ft][tt][4 * g + 1], acc[ft][tt][4 * g + 2], acc[ft][tt][4 * g + 3]};
;             *reinterpret_cast<f32x4*>(wl + (tt * 32 + lr) * 68 + ft * 32 + 8 * g + 4 * lh) = v;
;           }
	s_waitcnt lgkmcnt(0)
	v_mfma_f32_32x32x16_bf16 v[0:15], v[80:83], v[136:139], v[0:15]
	v_mfma_f32_32x32x16_bf16 v[32:47], v[80:83], v[132:135], v[32:47]
	ds_read_b128 v[80:83], v123 offset:32768
	ds_read_b128 v[132:135], v124
	ds_read_b128 v[136:139], v124 offset:4096
	s_waitcnt lgkmcnt(0)
	v_mfma_f32_32x32x16_bf16 v[48:63], v[80:83], v[132:135], v[48:63]
	v_mfma_f32_32x32x16_bf16 v[16:31], v[80:83], v[136:139], v[16:31]
	ds_read_b128 v[80:83], v123 offset:36864
	s_waitcnt lgkmcnt(0)
	v_mfma_f32_32x32x16_bf16 v[32:47], v[80:83], v[132:135], v[32:47]
	v_mfma_f32_32x32x16_bf16 v[0:15], v[80:83], v[136:139], v[0:15]
	ds_read_b128 v[80:83], v125 offset:32768
	ds_read_b128 v[132:135], v126
	ds_read_b128 v[136:139], v126 offset:4096
	s_waitcnt lgkmcnt(0)
	v_mfma_f32_32x32x16_bf16 v[48:63], v[80:83], v[132:135], v[48:63]
	v_mfma_f32_32x32x16_bf16 v[16:31], v[80:83], v[136:139], v[16:31]
	ds_read_b128 v[80:83], v125 offset:36864
	s_waitcnt lgkmcnt(0)
	v_mfma_f32_32x32x16_bf16 v[32:47], v[80:83], v[132:135], v[32:47]
	v_mfma_f32_32x32x16_bf16 v[0:15], v[80:83], v[136:139], v[0:15]
	ds_read_b128 v[80:83], v127 offset:32768
	ds_read_b128 v[132:135], v128
	ds_read_b128 v[136:139], v128 offset:4096
	s_waitcnt lgkmcnt(0)
	v_mfma_f32_32x32x16_bf16 v[48:63], v[80:83], v[132:135], v[48:63]
	v_mfma_f32_32x32x16_bf16 v[16:31], v[80:83], v[136:139], v[16:31]
	ds_read_b128 v[80:83], v127 offset:36864
	s_waitcnt lgkmcnt(0)
	v_mfma_f32_32x32x16_bf16 v[32:47], v[80:83], v[132:135], v[32:47]
	v_mfma_f32_32x32x16_bf16 v[0:15], v[80:83], v[136:139], v[0:15]
	ds_read_b128 v[80:83], v129 offset:32768
	ds_read_b128 v[132:135], v130
	ds_read_b128 v[136:139], v130 offset:4096
	s_waitcnt lgkmcnt(0)
	v_mfma_f32_32x32x16_bf16 v[48:63], v[80:83], v[132:135], v[48:63]
	v_mfma_f32_32x32x16_bf16 v[16:31], v[80:83], v[136:139], v[16:31]
	ds_read_b128 v[80:83], v129 offset:36864
	s_waitcnt vmcnt(0)
	s_waitcnt lgkmcnt(0)
	s_barrier
	s_waitcnt lgkmcnt(0)
	v_mfma_f32_32x32x16_bf16 v[0:15], v[80:83], v[136:139], v[0:15]
	v_mfma_f32_32x32x16_bf16 v[32:47], v[80:83], v[132:135], v[32:47]
	ds_read_b128 v[80:83], v111 offset:32768
	ds_read_b128 v[132:135], v112
	ds_read_b128 v[136:139], v111 offset:36864
	ds_read_b128 v[152:155], v112 offset:4096
	s_mov_b64 s[54:55], 0
	s_waitcnt lgkmcnt(0)
	v_mfma_f32_32x32x16_bf16 v[48:63], v[80:83], v[132:135], v[48:63]
	v_mfma_f32_32x32x16_bf16 v[32:47], v[136:139], v[132:135], v[32:47]
	v_mfma_f32_32x32x16_bf16 v[0:15], v[136:139], v[152:155], v[0:15]
	v_mfma_f32_32x32x16_bf16 v[16:31], v[80:83], v[152:155], v[16:31]
	ds_read_b128 v[80:83], v113 offset:32768
	ds_read_b128 v[132:135], v114
	ds_read_b128 v[136:139], v113 offset:36864
	ds_read_b128 v[152:155], v114 offset:4096
	s_waitcnt lgkmcnt(0)
	v_mfma_f32_32x32x16_bf16 v[48:63], v[80:83], v[132:135], v[48:63]
	v_mfma_f32_32x32x16_bf16 v[32:47], v[136:139], v[132:135], v[32:47]
	v_mfma_f32_32x32x16_bf16 v[0:15], v[136:139], v[152:155], v[0:15]
	v_mfma_f32_32x32x16_bf16 v[16:31], v[80:83], v[152:155], v[16:31]
	ds_read_b128 v[80:83], v115 offset:32768
	ds_read_b128 v[132:135], v116
	ds_read_b128 v[136:139], v115 offset:36864
	ds_read_b128 v[152:155], v116 offset:4096
	s_waitcnt lgkmcnt(0)
	v_mfma_f32_32x32x16_bf16 v[48:63], v[80:83], v[132:135], v[48:63]
	v_mfma_f32_32x32x16_bf16 v[32:47], v[136:139], v[132:135], v[32:47]
	v_mfma_f32_32x32x16_bf16 v[0:15], v[136:139], v[152:155], v[0:15]
	v_mfma_f32_32x32x16_bf16 v[16:31], v[80:83], v[152:155], v[16:31]
	ds_read_b128 v[80:83], v117 offset:32768
	ds_read_b128 v[132:135], v118
	ds_read_b128 v[136:139], v117 offset:36864
	ds_read_b128 v[152:155], v118 offset:4096
	s_waitcnt vmcnt(0)
	s_waitcnt lgkmcnt(0)
	s_barrier
	s_waitcnt lgkmcnt(0)
	v_mfma_f32_32x32x16_bf16 v[48:63], v[80:83], v[132:135], v[48:63]
	v_mfma_f32_32x32x16_bf16 v[32:47], v[136:139], v[132:135], v[32:47]
	s_nop 10
	ds_write_b128 v131, v[48:51]
	ds_write_b128 v131, v[52:55] offset:32
	ds_write_b128 v131, v[56:59] offset:64
	ds_write_b128 v131, v[60:63] offset:96
	ds_write_b128 v131, v[32:35] offset:128
	v_mfma_f32_32x32x16_bf16 v[0:15], v[136:139], v[152:155], v[0:15]
	v_mfma_f32_32x32x16_bf16 v[16:31], v[80:83], v[152:155], v[16:31]
	ds_write_b128 v131, v[36:39] offset:160
	ds_write_b128 v131, v[40:43] offset:192
	ds_write_b128 v131, v[44:47] offset:224
	s_nop 8
	ds_write_b128 v131, v[16:19] offset:8704
	ds_write_b128 v131, v[20:23] offset:8736
	ds_write_b128 v131, v[24:27] offset:8768
	ds_write_b128 v131, v[28:31] offset:8800
	ds_write_b128 v131, v[0:3] offset:8832
	ds_write_b128 v131, v[4:7] offset:8864
	ds_write_b128 v131, v[8:11] offset:8896
	ds_write_b128 v131, v[12:15] offset:8928
	v_mov_b32_e32 v0, v95

; #define MFMA(a, b, c) __builtin_amdgcn_mfma_f32_32x32x16_bf16((a), (b), (c), 0, 0, 0)
; #define WAIT_V(n) asm volatile("s_waitcnt vmcnt(%0)" ::"n"(n) : "memory")
; #define RAW_BARRIER() do { asm volatile("s_waitcnt lgkmcnt(0)" ::: "memory"); __builtin_amdgcn_s_barrier(); asm volatile("" ::: "memory"); } while (0)
; DI void gemm_tile(const u16* __restrict__ X, int ldx, const u16* __restrict__ Wt, int ldw, int K, char* smem,
;                   f32x16 (&acc)[2][2]) {
;     ...
;   const int nk = K / 64;
;   const u16* src[6];
; #pragma unroll
;   for (int i = 0; i < 6; ++i) {
;     const int R = 8 * (wave + 8 * i) + (lane >> 3);
;     const int c = (lane & 7) ^ ((R >> 1) & 7);
;     src[i] = (i < 4) ? (X + (size_t)R * ldx + c * 8) : (Wt + (size_t)(R - 256) * ldw + c * 8);
;   }
;     ...
;   int offA[2], offB[2], xa[2], xb[2];
; #pragma unroll
;   for (int ft = 0; ft < 2; ++ft) { const int R = 256 + fw * 64 + ft * 32 + lr; offA[ft] = R * 128; xa[ft] = (R >> 1) & 7; }
; #pragma unroll
;   for (int tt = 0; tt < 2; ++tt) { const int R = tq * 64 + tt * 32 + lr; offB[tt] = R * 128; xb[tt] = (R >> 1) & 7; }
;   GLDS_STAGE(0, 0); GLDS_STAGE(1, 1); WAIT_V(6); RAW_BARRIER();
;   int cur = 0;
;   for (int kt = 0; kt < nk; ++kt) {
;     const int nxt = (cur >= 1) ? cur - 1 : 2;
;     if (kt + 2 < nk) GLDS_STAGE(nxt, kt + 2);
;     __builtin_amdgcn_sched_barrier(0);
;     const char* st = smem + cur * G_STAGE;
; #pragma unroll
;     for (int ks = 0; ks < 4; ++ks) {
;       bf16x8 a[2], b[2];
; #pragma unroll
;       for (int ft = 0; ft < 2; ++ft) a[ft] = *reinterpret_cast<const bf16x8*>(st + offA[ft] + (((ks * 2 + lh) ^ xa[ft]) << 4));
; #pragma unroll
;       for (int tt = 0; tt < 2; ++tt) b[tt] = *reinterpret_cast<const bf16x8*>(st + offB[tt] + (((ks * 2 + lh) ^ xb[tt]) << 4));
; #pragma unroll
;       for (int ft = 0; ft < 2; ++ft)
; #pragma unroll
;         for (int tt = 0; tt < 2; ++tt) acc[ft][tt] = MFMA(a[ft], b[tt], acc[ft][tt]);
; template <int MODE>
; DI void phase_gemm(const Params& p, const u16* X, const u16* Wt, int N, const float* resid, float* outf, u16* outb, int ldo, char* smem) {
;     ...
;     const int mt = xg + 8 * (u / ntn), nt = u % ntn;
;     f32x16 acc[2][2];
;     gemm_tile(X + (size_t)mt * 256 * 1024, 1024, Wt + (size_t)nt * 128 * 1024, 1024, 1024, smem, acc);
.LBB0_906:
	s_lshr_b32 s0, s3, 1
	s_and_b32 s0, s0, 0x78
	s_or_b32 s76, s0, s33
	s_and_b32 s6, s54, 0x1e0000
	s_lshl_b32 s0, s76, 19
	v_lshl_add_u64 v[0:1], v[106:107], 0, s[0:1]
	s_lshl_b32 s0, s6, 1
	v_readfirstlane_b32 s6, v143
	v_lshl_add_u64 v[64:65], v[0:1], 0, v[122:123]
	s_mov_b32 m0, s6
	v_readfirstlane_b32 s85, v131
	v_lshl_add_u64 v[0:1], v[64:65], 0, s[8:9]
	s_mov_b64 s[4:5], 0x40000
	global_load_lds_dwordx4 v[64:65], off
	s_mov_b32 m0, s85
	v_readfirstlane_b32 s84, v132
	v_lshl_add_u64 v[2:3], v[64:65], 0, s[4:5]
	s_mov_b64 s[4:5], 0x60000
	global_load_lds_dwordx4 v[0:1], off
	s_mov_b32 m0, s84
	v_readfirstlane_b32 s81, v133
	v_lshl_add_u64 v[4:5], v[64:65], 0, s[4:5]
	v_lshl_add_u64 v[6:7], v[108:109], 0, s[0:1]
	global_load_lds_dwordx4 v[2:3], off
	s_mov_b32 m0, s81
	v_readfirstlane_b32 s80, v134
	v_lshl_add_u64 v[66:67], v[6:7], 0, v[122:123]
	global_load_lds_dwordx4 v[4:5], off
	s_mov_b32 m0, s80
	v_readfirstlane_b32 s79, v135
	v_lshl_add_u64 v[6:7], v[66:67], 0, s[8:9]
	global_load_lds_dwordx4 v[66:67], off
	s_mov_b32 m0, s79
	v_readfirstlane_b32 s77, v115
	global_load_lds_dwordx4 v[6:7], off
	v_lshl_add_u64 v[0:1], v[64:65], 0, s[10:11]
	s_mov_b32 m0, s77
	v_readfirstlane_b32 s0, v136
	global_load_lds_dwordx4 v[0:1], off
	v_lshl_add_u64 v[0:1], v[64:65], 0, s[12:13]
	s_mov_b32 m0, s0
	s_mov_b64 s[4:5], 0x40080
	global_load_lds_dwordx4 v[0:1], off
	v_lshl_add_u64 v[0:1], v[64:65], 0, s[4:5]
	v_readfirstlane_b32 s4, v137
	s_mov_b32 m0, s4
	s_mov_b64 s[4:5], 0x60080
	global_load_lds_dwordx4 v[0:1], off
	v_lshl_add_u64 v[0:1], v[64:65], 0, s[4:5]
	v_readfirstlane_b32 s4, v138
	s_mov_b32 m0, s4
	v_readfirstlane_b32 s4, v139
	global_load_lds_dwordx4 v[0:1], off
	v_lshl_add_u64 v[0:1], v[66:67], 0, s[10:11]
	s_mov_b32 m0, s4
	v_readfirstlane_b32 s4, v144
	global_load_lds_dwordx4 v[0:1], off
	v_lshl_add_u64 v[0:1], v[66:67], 0, s[12:13]
	s_mov_b32 m0, s4
	v_readfirstlane_b32 s4, v117
	global_load_lds_dwordx4 v[0:1], off
	s_waitcnt vmcnt(6)
	s_waitcnt lgkmcnt(0)
	s_barrier
	v_lshl_add_u64 v[0:1], v[64:65], 0, s[14:15]
	s_mov_b32 m0, s4
	v_readfirstlane_b32 s91, v119
	global_load_lds_dwordx4 v[0:1], off
	v_lshl_add_u64 v[0:1], v[64:65], 0, s[16:17]
	s_mov_b32 m0, s91
	s_mov_b64 s[46:47], 0x40100
	v_readfirstlane_b32 s89, v121
	global_load_lds_dwordx4 v[0:1], off
	v_lshl_add_u64 v[0:1], v[64:65], 0, s[46:47]
	s_mov_b32 m0, s89
	s_mov_b64 s[46:47], 0x60100
	v_readfirstlane_b32 s90, v124
	global_load_lds_dwordx4 v[0:1], off
	v_lshl_add_u64 v[0:1], v[64:65], 0, s[46:47]
	s_mov_b32 m0, s90
	v_readfirstlane_b32 s47, v125
	global_load_lds_dwordx4 v[0:1], off
	v_lshl_add_u64 v[0:1], v[66:67], 0, s[14:15]
	s_mov_b32 m0, s47
	v_readfirstlane_b32 s88, v126
	global_load_lds_dwordx4 v[0:1], off
	v_lshl_add_u64 v[0:1], v[66:67], 0, s[16:17]
	s_mov_b32 m0, s88
	s_nop 0
	global_load_lds_dwordx4 v[0:1], off
	ds_read_b128 v[0:3], v145 offset:32768
	ds_read_b128 v[4:7], v145 offset:36864
	ds_read_b128 v[8:11], v146
	ds_read_b128 v[12:15], v146 offset:4096
	ds_read_b128 v[68:71], v147 offset:32768
	ds_read_b128 v[72:75], v147 offset:36864
	ds_read_b128 v[76:79], v148
	ds_read_b128 v[80:83], v148 offset:4096
	s_mov_b32 m0, s6
	s_mov_b64 s[86:87], 0x40180
	s_waitcnt lgkmcnt(0)
	v_mfma_f32_32x32x16_bf16 v[48:63], v[0:3], v[8:11], 0
	v_mfma_f32_32x32x16_bf16 v[16:31], v[0:3], v[12:15], 0
	v_mfma_f32_32x32x16_bf16 v[32:47], v[4:7], v[8:11], 0
	v_mfma_f32_32x32x16_bf16 v[0:15], v[4:7], v[12:15], 0
	ds_read_b128 v[184:187], v149 offset:32768
	ds_read_b128 v[188:191], v149 offset:36864
	ds_read_b128 v[192:195], v150
	ds_read_b128 v[196:199], v150 offset:4096
	s_waitcnt lgkmcnt(4)
	v_mfma_f32_32x32x16_bf16 v[48:63], v[68:71], v[76:79], v[48:63]
	v_mfma_f32_32x32x16_bf16 v[16:31], v[68:71], v[80:83], v[16:31]
	v_mfma_f32_32x32x16_bf16 v[32:47], v[72:75], v[76:79], v[32:47]
	v_mfma_f32_32x32x16_bf16 v[0:15], v[72:75], v[80:83], v[0:15]
	ds_read_b128 v[68:71], v151 offset:32768
	ds_read_b128 v[72:75], v151 offset:36864
	ds_read_b128 v[76:79], v152
	ds_read_b128 v[80:83], v152 offset:4096
	s_waitcnt lgkmcnt(4)
	v_mfma_f32_32x32x16_bf16 v[48:63], v[184:187], v[192:195], v[48:63]
	v_mfma_f32_32x32x16_bf16 v[16:31], v[184:187], v[196:199], v[16:31]
	v_mfma_f32_32x32x16_bf16 v[32:47], v[188:191], v[192:195], v[32:47]
	v_mfma_f32_32x32x16_bf16 v[0:15], v[188:191], v[196:199], v[0:15]
	s_waitcnt vmcnt(6)
	s_waitcnt lgkmcnt(0)
	s_barrier
; #define MFMA(a, b, c) __builtin_amdgcn_mfma_f32_32x32x16_bf16((a), (b), (c), 0, 0, 0)
; #define WAIT_V(n) asm volatile("s_waitcnt vmcnt(%0)" ::"n"(n) : "memory")
; #define RAW_BARRIER() do { asm volatile("s_waitcnt lgkmcnt(0)" ::: "memory"); __builtin_amdgcn_s_barrier(); asm volatile("" ::: "memory"); } while (0)
; #define GLDS_STAGE(slot, kt) do { _Pragma("unroll") for (int i = 0; i < 6; ++i) \
;     __builtin_amdgcn_global_load_lds((const unsigned*)(src[i] + (kt) * 64), (__attribute__((address_space(3))) unsigned*)(smem + (slot) * G_STAGE + (wave + 8 * i) * 1024), 16, 0, 0); } while (0)
; DI void gemm_tile(const u16* __restrict__ X, int ldx, const u16* __restrict__ Wt, int ldw, int K, char* smem,
;                   f32x16 (&acc)[2][2]) {
;     ...
;   for (int kt = 0; kt < nk; ++kt) {
;     const int nxt = (cur >= 1) ? cur - 1 : 2;
;     if (kt + 2 < nk) GLDS_STAGE(nxt, kt + 2);
;     __builtin_amdgcn_sched_barrier(0);
;     const char* st = smem + cur * G_STAGE;
; #pragma unroll
;     for (int ks = 0; ks < 4; ++ks) {
;       bf16x8 a[2], b[2];
; #pragma unroll
;       for (int ft = 0; ft < 2; ++ft) a[ft] = *reinterpret_cast<const bf16x8*>(st + offA[ft] + (((ks * 2 + lh) ^ xa[ft]) << 4));
; #pragma unroll
;       for (int tt = 0; tt < 2; ++tt) b[tt] = *reinterpret_cast<const bf16x8*>(st + offB[tt] + (((ks * 2 + lh) ^ xb[tt]) << 4));
; #pragma unroll
;       for (int ft = 0; ft < 2; ++ft)
; #pragma unroll
;         for (int tt = 0; tt < 2; ++tt) acc[ft][tt] = MFMA(a[ft], b[tt], acc[ft][tt]);
;     }
;     if (kt + 2 < nk) { WAIT_V(6); } else { WAIT_V(0); }
;     RAW_BARRIER();
	ds_read_b128 v[184:187], v153 offset:32768
	ds_read_b128 v[188:191], v153 offset:36864
	ds_read_b128 v[192:195], v146 offset:49152
	ds_read_b128 v[196:199], v146 offset:53248
	s_waitcnt lgkmcnt(4)
	v_mfma_f32_32x32x16_bf16 v[48:63], v[68:71], v[76:79], v[48:63]
	v_mfma_f32_32x32x16_bf16 v[16:31], v[68:71], v[80:83], v[16:31]
	v_lshl_add_u64 v[68:69], v[64:65], 0, s[18:19]
	global_load_lds_dwordx4 v[68:69], off
	v_lshl_add_u64 v[68:69], v[64:65], 0, s[20:21]
	s_mov_b32 m0, s85
	s_nop 0
	global_load_lds_dwordx4 v[68:69], off
	v_lshl_add_u64 v[68:69], v[64:65], 0, s[86:87]
	s_mov_b32 m0, s84
	s_mov_b64 s[86:87], 0x60180
	global_load_lds_dwordx4 v[68:69], off
	v_lshl_add_u64 v[68:69], v[64:65], 0, s[86:87]
	s_mov_b32 m0, s81
	v_mfma_f32_32x32x16_bf16 v[32:47], v[72:75], v[76:79], v[32:47]
	global_load_lds_dwordx4 v[68:69], off
	v_lshl_add_u64 v[68:69], v[66:67], 0, s[18:19]
	s_mov_b32 m0, s80
	s_nop 0
	global_load_lds_dwordx4 v[68:69], off
	v_lshl_add_u64 v[68:69], v[66:67], 0, s[20:21]
	s_mov_b32 m0, s79
	v_mfma_f32_32x32x16_bf16 v[0:15], v[72:75], v[80:83], v[0:15]
	global_load_lds_dwordx4 v[68:69], off
	s_mov_b32 m0, s77
	s_mov_b64 s[86:87], 0x40200
	v_readfirstlane_b32 s7, v127
	ds_read_b128 v[68:71], v154 offset:32768
	ds_read_b128 v[72:75], v154 offset:36864
	ds_read_b128 v[76:79], v148 offset:49152
	ds_read_b128 v[80:83], v148 offset:53248
	s_waitcnt lgkmcnt(4)
	v_mfma_f32_32x32x16_bf16 v[48:63], v[184:187], v[192:195], v[48:63]
	v_readfirstlane_b32 s46, v130
	v_mfma_f32_32x32x16_bf16 v[16:31], v[184:187], v[196:199], v[16:31]
	v_mfma_f32_32x32x16_bf16 v[32:47], v[188:191], v[192:195], v[32:47]
	v_mfma_f32_32x32x16_bf16 v[0:15], v[188:191], v[196:199], v[0:15]
	ds_read_b128 v[184:187], v155 offset:32768
	ds_read_b128 v[188:191], v155 offset:36864
	ds_read_b128 v[192:195], v150 offset:49152
	ds_read_b128 v[196:199], v150 offset:53248
	s_waitcnt lgkmcnt(4)
	v_mfma_f32_32x32x16_bf16 v[48:63], v[68:71], v[76:79], v[48:63]
	v_mfma_f32_32x32x16_bf16 v[16:31], v[68:71], v[80:83], v[16:31]
	v_mfma_f32_32x32x16_bf16 v[32:47], v[72:75], v[76:79], v[32:47]
	v_mfma_f32_32x32x16_bf16 v[0:15], v[72:75], v[80:83], v[0:15]
	ds_read_b128 v[68:71], v156 offset:32768
	ds_read_b128 v[72:75], v156 offset:36864
	ds_read_b128 v[76:79], v152 offset:49152
	ds_read_b128 v[80:83], v152 offset:53248
	s_waitcnt lgkmcnt(4)
	v_mfma_f32_32x32x16_bf16 v[48:63], v[184:187], v[192:195], v[48:63]
	v_mfma_f32_32x32x16_bf16 v[16:31], v[184:187], v[196:199], v[16:31]
	v_mfma_f32_32x32x16_bf16 v[32:47], v[188:191], v[192:195], v[32:47]
	v_mfma_f32_32x32x16_bf16 v[0:15], v[188:191], v[196:199], v[0:15]
	s_waitcnt vmcnt(6)
	s_waitcnt lgkmcnt(0)
	s_barrier
	ds_read_b128 v[184:187], v157 offset:32768
	ds_read_b128 v[188:191], v157 offset:36864
	ds_read_b128 v[192:195], v158
	ds_read_b128 v[196:199], v158 offset:4096
	s_waitcnt lgkmcnt(4)
	v_mfma_f32_32x32x16_bf16 v[48:63], v[68:71], v[76:79], v[48:63]
	v_mfma_f32_32x32x16_bf16 v[16:31], v[68:71], v[80:83], v[16:31]
	v_lshl_add_u64 v[68:69], v[64:65], 0, s[22:23]
	global_load_lds_dwordx4 v[68:69], off
	v_lshl_add_u64 v[68:69], v[64:65], 0, s[24:25]
	s_mov_b32 m0, s0
	s_nop 0
	global_load_lds_dwordx4 v[68:69], off
	v_lshl_add_u64 v[68:69], v[64:65], 0, s[86:87]
	s_mov_b32 m0, s7
	s_mov_b64 s[86:87], 0x60200
	global_load_lds_dwordx4 v[68:69], off
	v_lshl_add_u64 v[68:69], v[64:65], 0, s[86:87]
	v_readfirstlane_b32 s87, v128
	s_mov_b32 m0, s87
	v_readfirstlane_b32 s86, v129
	global_load_lds_dwordx4 v[68:69], off
	v_lshl_add_u64 v[68:69], v[66:67], 0, s[22:23]
	s_mov_b32 m0, s86
	v_mfma_f32_32x32x16_bf16 v[32:47], v[72:75], v[76:79], v[32:47]
	global_load_lds_dwordx4 v[68:69], off
	v_lshl_add_u64 v[68:69], v[66:67], 0, s[24:25]
	s_mov_b32 m0, s46
	s_nop 0
	global_load_lds_dwordx4 v[68:69], off
	v_mfma_f32_32x32x16_bf16 v[0:15], v[72:75], v[80:83], v[0:15]
	s_mov_b32 m0, s4
	s_mov_b64 s[92:93], 0x40280
	ds_read_b128 v[68:71], v159 offset:32768
	ds_read_b128 v[72:75], v159 offset:36864
	ds_read_b128 v[76:79], v160
	ds_read_b128 v[80:83], v160 offset:4096
	s_waitcnt lgkmcnt(4)
	v_mfma_f32_32x32x16_bf16 v[48:63], v[184:187], v[192:195], v[48:63]
	v_mfma_f32_32x32x16_bf16 v[16:31], v[184:187], v[196:199], v[16:31]
	v_mfma_f32_32x32x16_bf16 v[32:47], v[188:191], v[192:195], v[32:47]
	v_mfma_f32_32x32x16_bf16 v[0:15], v[188:191], v[196:199], v[0:15]
	ds_read_b128 v[184:187], v161 offset:32768
	ds_read_b128 v[188:191], v161 offset:36864
	ds_read_b128 v[192:195], v163
	ds_read_b128 v[196:199], v163 offset:4096
	s_waitcnt lgkmcnt(4)
	v_mfma_f32_32x32x16_bf16 v[48:63], v[68:71], v[76:79], v[48:63]
	v_mfma_f32_32x32x16_bf16 v[16:31], v[68:71], v[80:83], v[16:31]
	v_mfma_f32_32x32x16_bf16 v[32:47], v[72:75], v[76:79], v[32:47]
	v_mfma_f32_32x32x16_bf16 v[0:15], v[72:75], v[80:83], v[0:15]
	ds_read_b128 v[68:71], v165 offset:32768
	ds_read_b128 v[72:75], v165 offset:36864
	ds_read_b128 v[76:79], v167
	ds_read_b128 v[80:83], v167 offset:4096
	s_waitcnt lgkmcnt(4)
	v_mfma_f32_32x32x16_bf16 v[48:63], v[184:187], v[192:195], v[48:63]
	v_mfma_f32_32x32x16_bf16 v[16:31], v[184:187], v[196:199], v[16:31]
	v_mfma_f32_32x32x16_bf16 v[32:47], v[188:191], v[192:195], v[32:47]
	v_mfma_f32_32x32x16_bf16 v[0:15], v[188:191], v[196:199], v[0:15]
	s_waitcnt vmcnt(6)
	s_waitcnt lgkmcnt(0)
	s_barrier
; #define MFMA(a, b, c) __builtin_amdgcn_mfma_f32_32x32x16_bf16((a), (b), (c), 0, 0, 0)
; #define WAIT_V(n) asm volatile("s_waitcnt vmcnt(%0)" ::"n"(n) : "memory")
; #define RAW_BARRIER() do { asm volatile("s_waitcnt lgkmcnt(0)" ::: "memory"); __builtin_amdgcn_s_barrier(); asm volatile("" ::: "memory"); } while (0)
; #define GLDS_STAGE(slot, kt) do { _Pragma("unroll") for (int i = 0; i < 6; ++i) \
;     __builtin_amdgcn_global_load_lds((const unsigned*)(src[i] + (kt) * 64), (__attribute__((address_space(3))) unsigned*)(smem + (slot) * G_STAGE + (wave + 8 * i) * 1024), 16, 0, 0); } while (0)
; DI void gemm_tile(const u16* __restrict__ X, int ldx, const u16* __restrict__ Wt, int ldw, int K, char* smem,
;                   f32x16 (&acc)[2][2]) {
;     ...
;   for (int kt = 0; kt < nk; ++kt) {
;     const int nxt = (cur >= 1) ? cur - 1 : 2;
;     if (kt + 2 < nk) GLDS_STAGE(nxt, kt + 2);
;     __builtin_amdgcn_sched_barrier(0);
;     const char* st = smem + cur * G_STAGE;
; #pragma unroll
;     for (int ks = 0; ks < 4; ++ks) {
;       bf16x8 a[2], b[2];
; #pragma unroll
;       for (int ft = 0; ft < 2; ++ft) a[ft] = *reinterpret_cast<const bf16x8*>(st + offA[ft] + (((ks * 2 + lh) ^ xa[ft]) << 4));
; #pragma unroll
;       for (int tt = 0; tt < 2; ++tt) b[tt] = *reinterpret_cast<const bf16x8*>(st + offB[tt] + (((ks * 2 + lh) ^ xb[tt]) << 4));
; #pragma unroll
;       for (int ft = 0; ft < 2; ++ft)
; #pragma unroll
;         for (int tt = 0; tt < 2; ++tt) acc[ft][tt] = MFMA(a[ft], b[tt], acc[ft][tt]);
;     }
;     if (kt + 2 < nk) { WAIT_V(6); } else { WAIT_V(0); }
;     RAW_BARRIER();
;     cur = (cur == 2) ? 0 : cur + 1;
	ds_read_b128 v[184:187], v145 offset:32768
	ds_read_b128 v[188:191], v145 offset:36864
	ds_read_b128 v[192:195], v146
	ds_read_b128 v[196:199], v146 offset:4096
	s_waitcnt lgkmcnt(4)
	v_mfma_f32_32x32x16_bf16 v[48:63], v[68:71], v[76:79], v[48:63]
	v_mfma_f32_32x32x16_bf16 v[16:31], v[68:71], v[80:83], v[16:31]
	v_lshl_add_u64 v[68:69], v[64:65], 0, s[26:27]
	global_load_lds_dwordx4 v[68:69], off
	v_lshl_add_u64 v[68:69], v[64:65], 0, s[28:29]
	s_mov_b32 m0, s91
	s_nop 0
	global_load_lds_dwordx4 v[68:69], off
	v_lshl_add_u64 v[68:69], v[64:65], 0, s[92:93]
	s_mov_b32 m0, s89
	s_mov_b64 s[92:93], 0x60280
	global_load_lds_dwordx4 v[68:69], off
	v_lshl_add_u64 v[68:69], v[64:65], 0, s[92:93]
	s_mov_b32 m0, s90
	v_mfma_f32_32x32x16_bf16 v[32:47], v[72:75], v[76:79], v[32:47]
	global_load_lds_dwordx4 v[68:69], off
	v_lshl_add_u64 v[68:69], v[66:67], 0, s[26:27]
	s_mov_b32 m0, s47
	s_nop 0
	global_load_lds_dwordx4 v[68:69], off
	v_lshl_add_u64 v[68:69], v[66:67], 0, s[28:29]
	s_mov_b32 m0, s88
	v_mfma_f32_32x32x16_bf16 v[0:15], v[72:75], v[80:83], v[0:15]
	global_load_lds_dwordx4 v[68:69], off
	s_mov_b32 m0, s6
	s_mov_b64 s[92:93], 0x40300
	ds_read_b128 v[68:71], v147 offset:32768
	ds_read_b128 v[72:75], v147 offset:36864
	ds_read_b128 v[76:79], v148
	ds_read_b128 v[80:83], v148 offset:4096
	s_waitcnt lgkmcnt(4)
	v_mfma_f32_32x32x16_bf16 v[48:63], v[184:187], v[192:195], v[48:63]
	v_mfma_f32_32x32x16_bf16 v[16:31], v[184:187], v[196:199], v[16:31]
	v_mfma_f32_32x32x16_bf16 v[32:47], v[188:191], v[192:195], v[32:47]
	v_mfma_f32_32x32x16_bf16 v[0:15], v[188:191], v[196:199], v[0:15]
	ds_read_b128 v[184:187], v149 offset:32768
	ds_read_b128 v[188:191], v149 offset:36864
	ds_read_b128 v[192:195], v150
	ds_read_b128 v[196:199], v150 offset:4096
	s_waitcnt lgkmcnt(4)
	v_mfma_f32_32x32x16_bf16 v[48:63], v[68:71], v[76:79], v[48:63]
	v_mfma_f32_32x32x16_bf16 v[16:31], v[68:71], v[80:83], v[16:31]
	v_mfma_f32_32x32x16_bf16 v[32:47], v[72:75], v[76:79], v[32:47]
	v_mfma_f32_32x32x16_bf16 v[0:15], v[72:75], v[80:83], v[0:15]
	ds_read_b128 v[68:71], v151 offset:32768
	ds_read_b128 v[72:75], v151 offset:36864
	ds_read_b128 v[76:79], v152
	ds_read_b128 v[80:83], v152 offset:4096
	s_waitcnt lgkmcnt(4)
	v_mfma_f32_32x32x16_bf16 v[48:63], v[184:187], v[192:195], v[48:63]
	v_mfma_f32_32x32x16_bf16 v[16:31], v[184:187], v[196:199], v[16:31]
	v_mfma_f32_32x32x16_bf16 v[32:47], v[188:191], v[192:195], v[32:47]
	v_mfma_f32_32x32x16_bf16 v[0:15], v[188:191], v[196:199], v[0:15]
	s_waitcnt vmcnt(6)
	s_waitcnt lgkmcnt(0)
	s_barrier
	ds_read_b128 v[184:187], v153 offset:32768
	ds_read_b128 v[188:191], v153 offset:36864
	ds_read_b128 v[192:195], v146 offset:49152
	ds_read_b128 v[196:199], v146 offset:53248
	s_waitcnt lgkmcnt(4)
	v_mfma_f32_32x32x16_bf16 v[48:63], v[68:71], v[76:79], v[48:63]
	v_mfma_f32_32x32x16_bf16 v[16:31], v[68:71], v[80:83], v[16:31]
	v_lshl_add_u64 v[68:69], v[64:65], 0, s[30:31]
	global_load_lds_dwordx4 v[68:69], off
	v_lshl_add_u64 v[68:69], v[64:65], 0, s[34:35]
	s_mov_b32 m0, s85
	s_nop 0
	global_load_lds_dwordx4 v[68:69], off
	v_lshl_add_u64 v[68:69], v[64:65], 0, s[92:93]
	s_mov_b32 m0, s84
	s_mov_b64 s[92:93], 0x60300
	global_load_lds_dwordx4 v[68:69], off
	v_lshl_add_u64 v[68:69], v[64:65], 0, s[92:93]
	s_mov_b32 m0, s81
	v_mfma_f32_32x32x16_bf16 v[32:47], v[72:75], v[76:79], v[32:47]
	global_load_lds_dwordx4 v[68:69], off
	v_lshl_add_u64 v[68:69], v[66:67], 0, s[30:31]
	s_mov_b32 m0, s80
	s_nop 0
	global_load_lds_dwordx4 v[68:69], off
	v_lshl_add_u64 v[68:69], v[66:67], 0, s[34:35]
	s_mov_b32 m0, s79
	v_mfma_f32_32x32x16_bf16 v[0:15], v[72:75], v[80:83], v[0:15]
	global_load_lds_dwordx4 v[68:69], off
	s_mov_b32 m0, s77
	s_mov_b64 s[92:93], 0x40380
	ds_read_b128 v[68:71], v154 offset:32768
	ds_read_b128 v[72:75], v154 offset:36864
	ds_read_b128 v[76:79], v148 offset:49152
	ds_read_b128 v[80:83], v148 offset:53248
	s_waitcnt lgkmcnt(4)
	v_mfma_f32_32x32x16_bf16 v[48:63], v[184:187], v[192:195], v[48:63]
	v_mfma_f32_32x32x16_bf16 v[16:31], v[184:187], v[196:199], v[16:31]
	v_mfma_f32_32x32x16_bf16 v[32:47], v[188:191], v[192:195], v[32:47]
	v_mfma_f32_32x32x16_bf16 v[0:15], v[188:191], v[196:199], v[0:15]
	ds_read_b128 v[184:187], v155 offset:32768
	ds_read_b128 v[188:191], v155 offset:36864
	ds_read_b128 v[192:195], v150 offset:49152
	ds_read_b128 v[196:199], v150 offset:53248
	s_waitcnt lgkmcnt(4)
	v_mfma_f32_32x32x16_bf16 v[48:63], v[68:71], v[76:79], v[48:63]
	v_mfma_f32_32x32x16_bf16 v[16:31], v[68:71], v[80:83], v[16:31]
	v_mfma_f32_32x32x16_bf16 v[32:47], v[72:75], v[76:79], v[32:47]
	v_mfma_f32_32x32x16_bf16 v[0:15], v[72:75], v[80:83], v[0:15]
	ds_read_b128 v[68:71], v156 offset:32768
	ds_read_b128 v[72:75], v156 offset:36864
	ds_read_b128 v[76:79], v152 offset:49152
	ds_read_b128 v[80:83], v152 offset:53248
	s_waitcnt lgkmcnt(4)
	v_mfma_f32_32x32x16_bf16 v[48:63], v[184:187], v[192:195], v[48:63]
	v_mfma_f32_32x32x16_bf16 v[16:31], v[184:187], v[196:199], v[16:31]
	v_mfma_f32_32x32x16_bf16 v[32:47], v[188:191], v[192:195], v[32:47]
	v_mfma_f32_32x32x16_bf16 v[0:15], v[188:191], v[196:199], v[0:15]
	s_waitcnt vmcnt(6)
	s_waitcnt lgkmcnt(0)
	s_barrier
; #define MFMA(a, b, c) __builtin_amdgcn_mfma_f32_32x32x16_bf16((a), (b), (c), 0, 0, 0)
; #define WAIT_V(n) asm volatile("s_waitcnt vmcnt(%0)" ::"n"(n) : "memory")
; #define RAW_BARRIER() do { asm volatile("s_waitcnt lgkmcnt(0)" ::: "memory"); __builtin_amdgcn_s_barrier(); asm volatile("" ::: "memory"); } while (0)
; #define GLDS_STAGE(slot, kt) do { _Pragma("unroll") for (int i = 0; i < 6; ++i) \
;     __builtin_amdgcn_global_load_lds((const unsigned*)(src[i] + (kt) * 64), (__attribute__((address_space(3))) unsigned*)(smem + (slot) * G_STAGE + (wave + 8 * i) * 1024), 16, 0, 0); } while (0)
; DI void gemm_tile(const u16* __restrict__ X, int ldx, const u16* __restrict__ Wt, int ldw, int K, char* smem,
;                   f32x16 (&acc)[2][2]) {
;     ...
;   for (int kt = 0; kt < nk; ++kt) {
;     const int nxt = (cur >= 1) ? cur - 1 : 2;
;     if (kt + 2 < nk) GLDS_STAGE(nxt, kt + 2);
;     __builtin_amdgcn_sched_barrier(0);
;     const char* st = smem + cur * G_STAGE;
; #pragma unroll
;     for (int ks = 0; ks < 4; ++ks) {
;       bf16x8 a[2], b[2];
; #pragma unroll
;       for (int ft = 0; ft < 2; ++ft) a[ft] = *reinterpret_cast<const bf16x8*>(st + offA[ft] + (((ks * 2 + lh) ^ xa[ft]) << 4));
; #pragma unroll
;       for (int tt = 0; tt < 2; ++tt) b[tt] = *reinterpret_cast<const bf16x8*>(st + offB[tt] + (((ks * 2 + lh) ^ xb[tt]) << 4));
; #pragma unroll
;       for (int ft = 0; ft < 2; ++ft)
; #pragma unroll
;         for (int tt = 0; tt < 2; ++tt) acc[ft][tt] = MFMA(a[ft], b[tt], acc[ft][tt]);
;     }
;     if (kt + 2 < nk) { WAIT_V(6); } else { WAIT_V(0); }
;     RAW_BARRIER();
;     cur = (cur == 2) ? 0 : cur + 1;
	ds_read_b128 v[184:187], v157 offset:32768
	ds_read_b128 v[188:191], v157 offset:36864
	ds_read_b128 v[192:195], v158
	ds_read_b128 v[196:199], v158 offset:4096
	s_waitcnt lgkmcnt(4)
	v_mfma_f32_32x32x16_bf16 v[48:63], v[68:71], v[76:79], v[48:63]
	v_mfma_f32_32x32x16_bf16 v[16:31], v[68:71], v[80:83], v[16:31]
	v_lshl_add_u64 v[68:69], v[64:65], 0, s[36:37]
	global_load_lds_dwordx4 v[68:69], off
	v_lshl_add_u64 v[68:69], v[64:65], 0, s[38:39]
	s_mov_b32 m0, s0
	s_nop 0
	global_load_lds_dwordx4 v[68:69], off
	v_lshl_add_u64 v[68:69], v[64:65], 0, s[92:93]
	s_mov_b32 m0, s7
	s_mov_b64 s[92:93], 0x60380
	global_load_lds_dwordx4 v[68:69], off
	v_lshl_add_u64 v[68:69], v[64:65], 0, s[92:93]
	s_mov_b32 m0, s87
	v_mfma_f32_32x32x16_bf16 v[32:47], v[72:75], v[76:79], v[32:47]
	global_load_lds_dwordx4 v[68:69], off
	v_lshl_add_u64 v[68:69], v[66:67], 0, s[36:37]
	s_mov_b32 m0, s86
	s_nop 0
	global_load_lds_dwordx4 v[68:69], off
	v_lshl_add_u64 v[68:69], v[66:67], 0, s[38:39]
	s_mov_b32 m0, s46
	v_mfma_f32_32x32x16_bf16 v[0:15], v[72:75], v[80:83], v[0:15]
	global_load_lds_dwordx4 v[68:69], off
	s_mov_b32 m0, s4
	s_mov_b64 s[4:5], 0x40400
	ds_read_b128 v[68:71], v159 offset:32768
	ds_read_b128 v[72:75], v159 offset:36864
	ds_read_b128 v[76:79], v160
	ds_read_b128 v[80:83], v160 offset:4096
	s_waitcnt lgkmcnt(4)
	v_mfma_f32_32x32x16_bf16 v[48:63], v[184:187], v[192:195], v[48:63]
	v_mfma_f32_32x32x16_bf16 v[16:31], v[184:187], v[196:199], v[16:31]
	v_mfma_f32_32x32x16_bf16 v[32:47], v[188:191], v[192:195], v[32:47]
	v_mfma_f32_32x32x16_bf16 v[0:15], v[188:191], v[196:199], v[0:15]
	ds_read_b128 v[184:187], v161 offset:32768
	ds_read_b128 v[188:191], v161 offset:36864
	ds_read_b128 v[192:195], v163
	ds_read_b128 v[196:199], v163 offset:4096
	s_waitcnt lgkmcnt(4)
	v_mfma_f32_32x32x16_bf16 v[48:63], v[68:71], v[76:79], v[48:63]
	v_mfma_f32_32x32x16_bf16 v[16:31], v[68:71], v[80:83], v[16:31]
	v_mfma_f32_32x32x16_bf16 v[32:47], v[72:75], v[76:79], v[32:47]
	v_mfma_f32_32x32x16_bf16 v[0:15], v[72:75], v[80:83], v[0:15]
	ds_read_b128 v[68:71], v165 offset:32768
	ds_read_b128 v[72:75], v165 offset:36864
	ds_read_b128 v[76:79], v167
	ds_read_b128 v[80:83], v167 offset:4096
	s_waitcnt lgkmcnt(4)
	v_mfma_f32_32x32x16_bf16 v[48:63], v[184:187], v[192:195], v[48:63]
	v_mfma_f32_32x32x16_bf16 v[16:31], v[184:187], v[196:199], v[16:31]
	v_mfma_f32_32x32x16_bf16 v[32:47], v[188:191], v[192:195], v[32:47]
	v_mfma_f32_32x32x16_bf16 v[0:15], v[188:191], v[196:199], v[0:15]
	s_waitcnt vmcnt(6)
	s_waitcnt lgkmcnt(0)
	s_barrier
	ds_read_b128 v[184:187], v145 offset:32768
	ds_read_b128 v[188:191], v145 offset:36864
	ds_read_b128 v[192:195], v146
	ds_read_b128 v[196:199], v146 offset:4096
	s_waitcnt lgkmcnt(4)
	v_mfma_f32_32x32x16_bf16 v[48:63], v[68:71], v[76:79], v[48:63]
	v_mfma_f32_32x32x16_bf16 v[16:31], v[68:71], v[80:83], v[16:31]
	v_lshl_add_u64 v[68:69], v[64:65], 0, s[40:41]
	global_load_lds_dwordx4 v[68:69], off
	v_lshl_add_u64 v[68:69], v[64:65], 0, s[42:43]
	s_mov_b32 m0, s91
	s_nop 0
	global_load_lds_dwordx4 v[68:69], off
	v_lshl_add_u64 v[68:69], v[64:65], 0, s[4:5]
	s_mov_b32 m0, s89
	s_mov_b64 s[4:5], 0x60400
	global_load_lds_dwordx4 v[68:69], off
	v_lshl_add_u64 v[68:69], v[64:65], 0, s[4:5]
	s_mov_b32 m0, s90
	v_mfma_f32_32x32x16_bf16 v[32:47], v[72:75], v[76:79], v[32:47]
	global_load_lds_dwordx4 v[68:69], off
	v_lshl_add_u64 v[68:69], v[66:67], 0, s[40:41]
	s_mov_b32 m0, s47
	s_nop 0
	global_load_lds_dwordx4 v[68:69], off
	v_lshl_add_u64 v[68:69], v[66:67], 0, s[42:43]
	s_mov_b32 m0, s88
	v_mfma_f32_32x32x16_bf16 v[0:15], v[72:75], v[80:83], v[0:15]
	global_load_lds_dwordx4 v[68:69], off
	s_mov_b32 m0, s6
	s_mov_b64 s[4:5], 0x40480
	ds_read_b128 v[68:71], v147 offset:32768
	ds_read_b128 v[72:75], v147 offset:36864
	ds_read_b128 v[76:79], v148
	ds_read_b128 v[80:83], v148 offset:4096
	s_waitcnt lgkmcnt(4)
	v_mfma_f32_32x32x16_bf16 v[48:63], v[184:187], v[192:195], v[48:63]
	v_mfma_f32_32x32x16_bf16 v[16:31], v[184:187], v[196:199], v[16:31]
	v_mfma_f32_32x32x16_bf16 v[32:47], v[188:191], v[192:195], v[32:47]
	v_mfma_f32_32x32x16_bf16 v[0:15], v[188:191], v[196:199], v[0:15]
	ds_read_b128 v[184:187], v149 offset:32768
	ds_read_b128 v[188:191], v149 offset:36864
	ds_read_b128 v[192:195], v150
	ds_read_b128 v[196:199], v150 offset:4096
	s_waitcnt lgkmcnt(4)
	v_mfma_f32_32x32x16_bf16 v[48:63], v[68:71], v[76:79], v[48:63]
	v_mfma_f32_32x32x16_bf16 v[16:31], v[68:71], v[80:83], v[16:31]
	v_mfma_f32_32x32x16_bf16 v[32:47], v[72:75], v[76:79], v[32:47]
	v_mfma_f32_32x32x16_bf16 v[0:15], v[72:75], v[80:83], v[0:15]
	ds_read_b128 v[68:71], v151 offset:32768
	ds_read_b128 v[72:75], v151 offset:36864
	ds_read_b128 v[76:79], v152
	ds_read_b128 v[80:83], v152 offset:4096
	s_waitcnt lgkmcnt(4)
	v_mfma_f32_32x32x16_bf16 v[48:63], v[184:187], v[192:195], v[48:63]
	v_mfma_f32_32x32x16_bf16 v[16:31], v[184:187], v[196:199], v[16:31]
	v_mfma_f32_32x32x16_bf16 v[32:47], v[188:191], v[192:195], v[32:47]
	v_mfma_f32_32x32x16_bf16 v[0:15], v[188:191], v[196:199], v[0:15]
	s_waitcnt vmcnt(6)
	s_waitcnt lgkmcnt(0)
	s_barrier
; #define MFMA(a, b, c) __builtin_amdgcn_mfma_f32_32x32x16_bf16((a), (b), (c), 0, 0, 0)
; #define WAIT_V(n) asm volatile("s_waitcnt vmcnt(%0)" ::"n"(n) : "memory")
; #define RAW_BARRIER() do { asm volatile("s_waitcnt lgkmcnt(0)" ::: "memory"); __builtin_amdgcn_s_barrier(); asm volatile("" ::: "memory"); } while (0)
; #define GLDS_STAGE(slot, kt) do { _Pragma("unroll") for (int i = 0; i < 6; ++i) \
;     __builtin_amdgcn_global_load_lds((const unsigned*)(src[i] + (kt) * 64), (__attribute__((address_space(3))) unsigned*)(smem + (slot) * G_STAGE + (wave + 8 * i) * 1024), 16, 0, 0); } while (0)
; DI void gemm_tile(const u16* __restrict__ X, int ldx, const u16* __restrict__ Wt, int ldw, int K, char* smem,
;                   f32x16 (&acc)[2][2]) {
;     ...
;   for (int kt = 0; kt < nk; ++kt) {
;     const int nxt = (cur >= 1) ? cur - 1 : 2;
;     if (kt + 2 < nk) GLDS_STAGE(nxt, kt + 2);
;     __builtin_amdgcn_sched_barrier(0);
;     const char* st = smem + cur * G_STAGE;
; #pragma unroll
;     for (int ks = 0; ks < 4; ++ks) {
;       bf16x8 a[2], b[2];
; #pragma unroll
;       for (int ft = 0; ft < 2; ++ft) a[ft] = *reinterpret_cast<const bf16x8*>(st + offA[ft] + (((ks * 2 + lh) ^ xa[ft]) << 4));
; #pragma unroll
;       for (int tt = 0; tt < 2; ++tt) b[tt] = *reinterpret_cast<const bf16x8*>(st + offB[tt] + (((ks * 2 + lh) ^ xb[tt]) << 4));
; #pragma unroll
;       for (int ft = 0; ft < 2; ++ft)
; #pragma unroll
;         for (int tt = 0; tt < 2; ++tt) acc[ft][tt] = MFMA(a[ft], b[tt], acc[ft][tt]);
;     }
;     if (kt + 2 < nk) { WAIT_V(6); } else { WAIT_V(0); }
;     RAW_BARRIER();
;     cur = (cur == 2) ? 0 : cur + 1;
	ds_read_b128 v[184:187], v153 offset:32768
	ds_read_b128 v[188:191], v153 offset:36864
	ds_read_b128 v[192:195], v146 offset:49152
	ds_read_b128 v[196:199], v146 offset:53248
	s_waitcnt lgkmcnt(4)
	v_mfma_f32_32x32x16_bf16 v[48:63], v[68:71], v[76:79], v[48:63]
	v_mfma_f32_32x32x16_bf16 v[16:31], v[68:71], v[80:83], v[16:31]
	v_lshl_add_u64 v[68:69], v[64:65], 0, s[44:45]
	global_load_lds_dwordx4 v[68:69], off
	v_lshl_add_u64 v[68:69], v[64:65], 0, s[48:49]
	s_mov_b32 m0, s85
	s_nop 0
	global_load_lds_dwordx4 v[68:69], off
	v_lshl_add_u64 v[68:69], v[64:65], 0, s[4:5]
	s_mov_b32 m0, s84
	s_mov_b64 s[4:5], 0x60480
	global_load_lds_dwordx4 v[68:69], off
	v_lshl_add_u64 v[68:69], v[64:65], 0, s[4:5]
	s_mov_b32 m0, s81
	v_mfma_f32_32x32x16_bf16 v[32:47], v[72:75], v[76:79], v[32:47]
	global_load_lds_dwordx4 v[68:69], off
	v_lshl_add_u64 v[68:69], v[66:67], 0, s[44:45]
	s_mov_b32 m0, s80
	s_nop 0
	global_load_lds_dwordx4 v[68:69], off
	v_lshl_add_u64 v[68:69], v[66:67], 0, s[48:49]
	s_mov_b32 m0, s79
	v_mfma_f32_32x32x16_bf16 v[0:15], v[72:75], v[80:83], v[0:15]
	global_load_lds_dwordx4 v[68:69], off
	s_mov_b32 m0, s77
	s_mov_b64 s[4:5], 0x40500
	ds_read_b128 v[68:71], v154 offset:32768
	ds_read_b128 v[72:75], v154 offset:36864
	ds_read_b128 v[76:79], v148 offset:49152
	ds_read_b128 v[80:83], v148 offset:53248
	s_waitcnt lgkmcnt(4)
	v_mfma_f32_32x32x16_bf16 v[48:63], v[184:187], v[192:195], v[48:63]
	v_mfma_f32_32x32x16_bf16 v[16:31], v[184:187], v[196:199], v[16:31]
	v_mfma_f32_32x32x16_bf16 v[32:47], v[188:191], v[192:195], v[32:47]
	v_mfma_f32_32x32x16_bf16 v[0:15], v[188:191], v[196:199], v[0:15]
	ds_read_b128 v[184:187], v155 offset:32768
	ds_read_b128 v[188:191], v155 offset:36864
	ds_read_b128 v[192:195], v150 offset:49152
	ds_read_b128 v[196:199], v150 offset:53248
	s_waitcnt lgkmcnt(4)
	v_mfma_f32_32x32x16_bf16 v[48:63], v[68:71], v[76:79], v[48:63]
	v_mfma_f32_32x32x16_bf16 v[16:31], v[68:71], v[80:83], v[16:31]
	v_mfma_f32_32x32x16_bf16 v[32:47], v[72:75], v[76:79], v[32:47]
	v_mfma_f32_32x32x16_bf16 v[0:15], v[72:75], v[80:83], v[0:15]
	ds_read_b128 v[68:71], v156 offset:32768
	ds_read_b128 v[72:75], v156 offset:36864
	ds_read_b128 v[76:79], v152 offset:49152
	ds_read_b128 v[80:83], v152 offset:53248
	s_waitcnt lgkmcnt(4)
	v_mfma_f32_32x32x16_bf16 v[48:63], v[184:187], v[192:195], v[48:63]
	v_mfma_f32_32x32x16_bf16 v[16:31], v[184:187], v[196:199], v[16:31]
	v_mfma_f32_32x32x16_bf16 v[32:47], v[188:191], v[192:195], v[32:47]
	v_mfma_f32_32x32x16_bf16 v[0:15], v[188:191], v[196:199], v[0:15]
	s_waitcnt vmcnt(6)
	s_waitcnt lgkmcnt(0)
	s_barrier
	ds_read_b128 v[184:187], v157 offset:32768
	ds_read_b128 v[188:191], v157 offset:36864
	ds_read_b128 v[192:195], v158
	ds_read_b128 v[196:199], v158 offset:4096
	s_waitcnt lgkmcnt(4)
	v_mfma_f32_32x32x16_bf16 v[48:63], v[68:71], v[76:79], v[48:63]
	v_mfma_f32_32x32x16_bf16 v[16:31], v[68:71], v[80:83], v[16:31]
	v_lshl_add_u64 v[68:69], v[64:65], 0, s[50:51]
	global_load_lds_dwordx4 v[68:69], off
	v_lshl_add_u64 v[68:69], v[64:65], 0, s[52:53]
	s_mov_b32 m0, s0
	s_nop 0
	global_load_lds_dwordx4 v[68:69], off
	v_lshl_add_u64 v[68:69], v[64:65], 0, s[4:5]
	s_mov_b32 m0, s7
	s_mov_b64 s[4:5], 0x60500
	global_load_lds_dwordx4 v[68:69], off
	v_lshl_add_u64 v[68:69], v[64:65], 0, s[4:5]
	s_mov_b32 m0, s87
	v_mfma_f32_32x32x16_bf16 v[32:47], v[72:75], v[76:79], v[32:47]
	global_load_lds_dwordx4 v[68:69], off
	v_lshl_add_u64 v[68:69], v[66:67], 0, s[50:51]
	s_mov_b32 m0, s86
	s_nop 0
	global_load_lds_dwordx4 v[68:69], off
	v_lshl_add_u64 v[68:69], v[66:67], 0, s[52:53]
	s_mov_b32 m0, s46
	v_mfma_f32_32x32x16_bf16 v[0:15], v[72:75], v[80:83], v[0:15]
	global_load_lds_dwordx4 v[68:69], off
	v_readfirstlane_b32 s84, v117
	s_mov_b32 m0, s84
	v_readfirstlane_b32 s46, v119
	ds_read_b128 v[68:71], v159 offset:32768
	ds_read_b128 v[72:75], v159 offset:36864
	ds_read_b128 v[76:79], v160
	ds_read_b128 v[80:83], v160 offset:4096
	s_waitcnt lgkmcnt(4)
	v_mfma_f32_32x32x16_bf16 v[48:63], v[184:187], v[192:195], v[48:63]
	s_mov_b64 s[4:5], 0x40580
	v_readfirstlane_b32 s47, v121
	v_readfirstlane_b32 s79, v124
	v_readfirstlane_b32 s77, v125
	v_readfirstlane_b32 s80, v126
	v_mfma_f32_32x32x16_bf16 v[16:31], v[184:187], v[196:199], v[16:31]
	v_mfma_f32_32x32x16_bf16 v[32:47], v[188:191], v[192:195], v[32:47]
	v_mfma_f32_32x32x16_bf16 v[0:15], v[188:191], v[196:199], v[0:15]
	ds_read_b128 v[184:187], v161 offset:32768
	ds_read_b128 v[188:191], v161 offset:36864
	ds_read_b128 v[192:195], v163
	ds_read_b128 v[196:199], v163 offset:4096
	s_waitcnt lgkmcnt(4)
	v_mfma_f32_32x32x16_bf16 v[48:63], v[68:71], v[76:79], v[48:63]
	v_mfma_f32_32x32x16_bf16 v[16:31], v[68:71], v[80:83], v[16:31]
	v_mfma_f32_32x32x16_bf16 v[32:47], v[72:75], v[76:79], v[32:47]
	v_mfma_f32_32x32x16_bf16 v[0:15], v[72:75], v[80:83], v[0:15]
	ds_read_b128 v[68:71], v165 offset:32768
	ds_read_b128 v[72:75], v165 offset:36864
	ds_read_b128 v[76:79], v167
	ds_read_b128 v[80:83], v167 offset:4096
	s_waitcnt lgkmcnt(4)
	v_mfma_f32_32x32x16_bf16 v[48:63], v[184:187], v[192:195], v[48:63]
	v_mfma_f32_32x32x16_bf16 v[16:31], v[184:187], v[196:199], v[16:31]
	v_mfma_f32_32x32x16_bf16 v[32:47], v[188:191], v[192:195], v[32:47]
	v_mfma_f32_32x32x16_bf16 v[0:15], v[188:191], v[196:199], v[0:15]
	s_waitcnt vmcnt(6)
	s_waitcnt lgkmcnt(0)
	s_barrier
; #define MFMA(a, b, c) __builtin_amdgcn_mfma_f32_32x32x16_bf16((a), (b), (c), 0, 0, 0)
; #define WAIT_V(n) asm volatile("s_waitcnt vmcnt(%0)" ::"n"(n) : "memory")
; #define RAW_BARRIER() do { asm volatile("s_waitcnt lgkmcnt(0)" ::: "memory"); __builtin_amdgcn_s_barrier(); asm volatile("" ::: "memory"); } while (0)
; #define GLDS_STAGE(slot, kt) do { _Pragma("unroll") for (int i = 0; i < 6; ++i) \
;     __builtin_amdgcn_global_load_lds((const unsigned*)(src[i] + (kt) * 64), (__attribute__((address_space(3))) unsigned*)(smem + (slot) * G_STAGE + (wave + 8 * i) * 1024), 16, 0, 0); } while (0)
; DI void gemm_tile(const u16* __restrict__ X, int ldx, const u16* __restrict__ Wt, int ldw, int K, char* smem,
;                   f32x16 (&acc)[2][2]) {
;     ...
;   for (int kt = 0; kt < nk; ++kt) {
;     const int nxt = (cur >= 1) ? cur - 1 : 2;
;     if (kt + 2 < nk) GLDS_STAGE(nxt, kt + 2);
;     __builtin_amdgcn_sched_barrier(0);
;     const char* st = smem + cur * G_STAGE;
; #pragma unroll
;     for (int ks = 0; ks < 4; ++ks) {
;       bf16x8 a[2], b[2];
; #pragma unroll
;       for (int ft = 0; ft < 2; ++ft) a[ft] = *reinterpret_cast<const bf16x8*>(st + offA[ft] + (((ks * 2 + lh) ^ xa[ft]) << 4));
; #pragma unroll
;       for (int tt = 0; tt < 2; ++tt) b[tt] = *reinterpret_cast<const bf16x8*>(st + offB[tt] + (((ks * 2 + lh) ^ xb[tt]) << 4));
; #pragma unroll
;       for (int ft = 0; ft < 2; ++ft)
; #pragma unroll
;         for (int tt = 0; tt < 2; ++tt) acc[ft][tt] = MFMA(a[ft], b[tt], acc[ft][tt]);
;     }
;     if (kt + 2 < nk) { WAIT_V(6); } else { WAIT_V(0); }
;     RAW_BARRIER();
;     cur = (cur == 2) ? 0 : cur + 1;
	ds_read_b128 v[184:187], v145 offset:32768
	ds_read_b128 v[188:191], v145 offset:36864
	ds_read_b128 v[192:195], v146
	ds_read_b128 v[196:199], v146 offset:4096
	s_waitcnt lgkmcnt(4)
	v_mfma_f32_32x32x16_bf16 v[48:63], v[68:71], v[76:79], v[48:63]
	v_mfma_f32_32x32x16_bf16 v[16:31], v[68:71], v[80:83], v[16:31]
	v_lshl_add_u64 v[68:69], v[64:65], 0, s[56:57]
	global_load_lds_dwordx4 v[68:69], off
	v_lshl_add_u64 v[68:69], v[64:65], 0, s[58:59]
	s_mov_b32 m0, s46
	s_nop 0
	global_load_lds_dwordx4 v[68:69], off
	v_lshl_add_u64 v[68:69], v[64:65], 0, s[4:5]
	s_mov_b32 m0, s47
	s_mov_b64 s[4:5], 0x60580
	global_load_lds_dwordx4 v[68:69], off
	v_lshl_add_u64 v[68:69], v[64:65], 0, s[4:5]
	s_mov_b32 m0, s79
	v_mfma_f32_32x32x16_bf16 v[32:47], v[72:75], v[76:79], v[32:47]
	global_load_lds_dwordx4 v[68:69], off
	v_lshl_add_u64 v[68:69], v[66:67], 0, s[56:57]
	s_mov_b32 m0, s77
	s_nop 0
	global_load_lds_dwordx4 v[68:69], off
	v_lshl_add_u64 v[68:69], v[66:67], 0, s[58:59]
	s_mov_b32 m0, s80
	v_mfma_f32_32x32x16_bf16 v[0:15], v[72:75], v[80:83], v[0:15]
	global_load_lds_dwordx4 v[68:69], off
	v_readfirstlane_b32 s81, v143
	s_mov_b32 m0, s81
	v_readfirstlane_b32 s0, v131
	ds_read_b128 v[68:71], v147 offset:32768
	ds_read_b128 v[72:75], v147 offset:36864
	ds_read_b128 v[76:79], v148
	ds_read_b128 v[80:83], v148 offset:4096
	s_waitcnt lgkmcnt(4)
	v_mfma_f32_32x32x16_bf16 v[48:63], v[184:187], v[192:195], v[48:63]
	s_mov_b64 s[4:5], 0x40600
	s_mov_b64 s[6:7], 0x60600
	v_mfma_f32_32x32x16_bf16 v[16:31], v[184:187], v[196:199], v[16:31]
	v_mfma_f32_32x32x16_bf16 v[32:47], v[188:191], v[192:195], v[32:47]
	v_mfma_f32_32x32x16_bf16 v[0:15], v[188:191], v[196:199], v[0:15]
	ds_read_b128 v[184:187], v149 offset:32768
	ds_read_b128 v[188:191], v149 offset:36864
	ds_read_b128 v[192:195], v150
	ds_read_b128 v[196:199], v150 offset:4096
	s_waitcnt lgkmcnt(4)
	v_mfma_f32_32x32x16_bf16 v[48:63], v[68:71], v[76:79], v[48:63]
	v_mfma_f32_32x32x16_bf16 v[16:31], v[68:71], v[80:83], v[16:31]
	v_mfma_f32_32x32x16_bf16 v[32:47], v[72:75], v[76:79], v[32:47]
	v_mfma_f32_32x32x16_bf16 v[0:15], v[72:75], v[80:83], v[0:15]
	ds_read_b128 v[68:71], v151 offset:32768
	ds_read_b128 v[72:75], v151 offset:36864
	ds_read_b128 v[76:79], v152
	ds_read_b128 v[80:83], v152 offset:4096
	s_waitcnt lgkmcnt(4)
	v_mfma_f32_32x32x16_bf16 v[48:63], v[184:187], v[192:195], v[48:63]
	v_mfma_f32_32x32x16_bf16 v[16:31], v[184:187], v[196:199], v[16:31]
	v_mfma_f32_32x32x16_bf16 v[32:47], v[188:191], v[192:195], v[32:47]
	v_mfma_f32_32x32x16_bf16 v[0:15], v[188:191], v[196:199], v[0:15]
	s_waitcnt vmcnt(6)
	s_waitcnt lgkmcnt(0)
	s_barrier
	ds_read_b128 v[184:187], v153 offset:32768
	ds_read_b128 v[188:191], v153 offset:36864
	ds_read_b128 v[192:195], v146 offset:49152
	ds_read_b128 v[196:199], v146 offset:53248
	s_waitcnt lgkmcnt(4)
	v_mfma_f32_32x32x16_bf16 v[48:63], v[68:71], v[76:79], v[48:63]
	v_mfma_f32_32x32x16_bf16 v[16:31], v[68:71], v[80:83], v[16:31]
	v_lshl_add_u64 v[68:69], v[64:65], 0, s[60:61]
	global_load_lds_dwordx4 v[68:69], off
	v_lshl_add_u64 v[68:69], v[64:65], 0, s[62:63]
	s_mov_b32 m0, s0
	s_nop 0
	global_load_lds_dwordx4 v[68:69], off
	v_lshl_add_u64 v[68:69], v[64:65], 0, s[4:5]
	v_readfirstlane_b32 s4, v132
	s_mov_b32 m0, s4
	v_readfirstlane_b32 s5, v134
	global_load_lds_dwordx4 v[68:69], off
	v_lshl_add_u64 v[68:69], v[64:65], 0, s[6:7]
	v_readfirstlane_b32 s6, v133
	s_mov_b32 m0, s6
	v_readfirstlane_b32 s7, v135
	global_load_lds_dwordx4 v[68:69], off
	v_lshl_add_u64 v[68:69], v[66:67], 0, s[60:61]
	s_mov_b32 m0, s5
	v_mfma_f32_32x32x16_bf16 v[32:47], v[72:75], v[76:79], v[32:47]
	global_load_lds_dwordx4 v[68:69], off
	v_lshl_add_u64 v[68:69], v[66:67], 0, s[62:63]
	s_mov_b32 m0, s7
	s_nop 0
	global_load_lds_dwordx4 v[68:69], off
	v_mfma_f32_32x32x16_bf16 v[0:15], v[72:75], v[80:83], v[0:15]
	v_readfirstlane_b32 s85, v115
	s_mov_b32 m0, s85
	v_readfirstlane_b32 s85, v136
	ds_read_b128 v[68:71], v154 offset:32768
	ds_read_b128 v[72:75], v154 offset:36864
	ds_read_b128 v[76:79], v148 offset:49152
	ds_read_b128 v[80:83], v148 offset:53248
	s_waitcnt lgkmcnt(4)
	v_mfma_f32_32x32x16_bf16 v[48:63], v[184:187], v[192:195], v[48:63]
	s_mov_b64 s[86:87], 0x40680
	v_mfma_f32_32x32x16_bf16 v[16:31], v[184:187], v[196:199], v[16:31]
	v_mfma_f32_32x32x16_bf16 v[32:47], v[188:191], v[192:195], v[32:47]
	v_mfma_f32_32x32x16_bf16 v[0:15], v[188:191], v[196:199], v[0:15]
	ds_read_b128 v[184:187], v155 offset:32768
	ds_read_b128 v[188:191], v155 offset:36864
	ds_read_b128 v[192:195], v150 offset:49152
	ds_read_b128 v[196:199], v150 offset:53248
	s_waitcnt lgkmcnt(4)
	v_mfma_f32_32x32x16_bf16 v[48:63], v[68:71], v[76:79], v[48:63]
	v_mfma_f32_32x32x16_bf16 v[16:31], v[68:71], v[80:83], v[16:31]
	v_mfma_f32_32x32x16_bf16 v[32:47], v[72:75], v[76:79], v[32:47]
	v_mfma_f32_32x32x16_bf16 v[0:15], v[72:75], v[80:83], v[0:15]
	ds_read_b128 v[68:71], v156 offset:32768
	ds_read_b128 v[72:75], v156 offset:36864
	ds_read_b128 v[76:79], v152 offset:49152
	ds_read_b128 v[80:83], v152 offset:53248
	s_waitcnt lgkmcnt(4)
	v_mfma_f32_32x32x16_bf16 v[48:63], v[184:187], v[192:195], v[48:63]
	v_mfma_f32_32x32x16_bf16 v[16:31], v[184:187], v[196:199], v[16:31]
	v_mfma_f32_32x32x16_bf16 v[32:47], v[188:191], v[192:195], v[32:47]
	v_mfma_f32_32x32x16_bf16 v[0:15], v[188:191], v[196:199], v[0:15]
	s_waitcnt vmcnt(6)
	s_waitcnt lgkmcnt(0)
	s_barrier
; #define MFMA(a, b, c) __builtin_amdgcn_mfma_f32_32x32x16_bf16((a), (b), (c), 0, 0, 0)
; #define WAIT_V(n) asm volatile("s_waitcnt vmcnt(%0)" ::"n"(n) : "memory")
; #define RAW_BARRIER() do { asm volatile("s_waitcnt lgkmcnt(0)" ::: "memory"); __builtin_amdgcn_s_barrier(); asm volatile("" ::: "memory"); } while (0)
; #define GLDS_STAGE(slot, kt) do { _Pragma("unroll") for (int i = 0; i < 6; ++i) \
;     __builtin_amdgcn_global_load_lds((const unsigned*)(src[i] + (kt) * 64), (__attribute__((address_space(3))) unsigned*)(smem + (slot) * G_STAGE + (wave + 8 * i) * 1024), 16, 0, 0); } while (0)
; DI void gemm_tile(const u16* __restrict__ X, int ldx, const u16* __restrict__ Wt, int ldw, int K, char* smem,
;                   f32x16 (&acc)[2][2]) {
;     ...
;   for (int kt = 0; kt < nk; ++kt) {
;     const int nxt = (cur >= 1) ? cur - 1 : 2;
;     if (kt + 2 < nk) GLDS_STAGE(nxt, kt + 2);
;     __builtin_amdgcn_sched_barrier(0);
;     const char* st = smem + cur * G_STAGE;
; #pragma unroll
;     for (int ks = 0; ks < 4; ++ks) {
;       bf16x8 a[2], b[2];
; #pragma unroll
;       for (int ft = 0; ft < 2; ++ft) a[ft] = *reinterpret_cast<const bf16x8*>(st + offA[ft] + (((ks * 2 + lh) ^ xa[ft]) << 4));
; #pragma unroll
;       for (int tt = 0; tt < 2; ++tt) b[tt] = *reinterpret_cast<const bf16x8*>(st + offB[tt] + (((ks * 2 + lh) ^ xb[tt]) << 4));
; #pragma unroll
;       for (int ft = 0; ft < 2; ++ft)
; #pragma unroll
;         for (int tt = 0; tt < 2; ++tt) acc[ft][tt] = MFMA(a[ft], b[tt], acc[ft][tt]);
;     }
;     if (kt + 2 < nk) { WAIT_V(6); } else { WAIT_V(0); }
;     RAW_BARRIER();
;     cur = (cur == 2) ? 0 : cur + 1;
	ds_read_b128 v[184:187], v157 offset:32768
	ds_read_b128 v[188:191], v157 offset:36864
	ds_read_b128 v[192:195], v158
	ds_read_b128 v[196:199], v158 offset:4096
	s_waitcnt lgkmcnt(4)
	v_mfma_f32_32x32x16_bf16 v[48:63], v[68:71], v[76:79], v[48:63]
	v_mfma_f32_32x32x16_bf16 v[16:31], v[68:71], v[80:83], v[16:31]
	v_lshl_add_u64 v[68:69], v[64:65], 0, s[64:65]
	global_load_lds_dwordx4 v[68:69], off
	v_lshl_add_u64 v[68:69], v[64:65], 0, s[66:67]
	s_mov_b32 m0, s85
	v_readfirstlane_b32 s85, v127
	global_load_lds_dwordx4 v[68:69], off
	v_lshl_add_u64 v[68:69], v[64:65], 0, s[86:87]
	s_mov_b32 m0, s85
	s_mov_b64 s[86:87], 0x60680
	v_readfirstlane_b32 s85, v128
	global_load_lds_dwordx4 v[68:69], off
	v_lshl_add_u64 v[68:69], v[64:65], 0, s[86:87]
	s_mov_b32 m0, s85
	v_readfirstlane_b32 s85, v129
	global_load_lds_dwordx4 v[68:69], off
	v_lshl_add_u64 v[68:69], v[66:67], 0, s[64:65]
	s_mov_b32 m0, s85
	v_readfirstlane_b32 s85, v130
	global_load_lds_dwordx4 v[68:69], off
	v_lshl_add_u64 v[68:69], v[66:67], 0, s[66:67]
	s_mov_b32 m0, s85
	v_mfma_f32_32x32x16_bf16 v[32:47], v[72:75], v[76:79], v[32:47]
	global_load_lds_dwordx4 v[68:69], off
	v_mfma_f32_32x32x16_bf16 v[0:15], v[72:75], v[80:83], v[0:15]
	s_mov_b32 m0, s84
	s_mov_b64 s[84:85], 0x40700
	ds_read_b128 v[68:71], v159 offset:32768
	ds_read_b128 v[72:75], v159 offset:36864
	ds_read_b128 v[76:79], v160
	ds_read_b128 v[80:83], v160 offset:4096
	s_waitcnt lgkmcnt(4)
	v_mfma_f32_32x32x16_bf16 v[48:63], v[184:187], v[192:195], v[48:63]
	v_mfma_f32_32x32x16_bf16 v[16:31], v[184:187], v[196:199], v[16:31]
	v_mfma_f32_32x32x16_bf16 v[32:47], v[188:191], v[192:195], v[32:47]
	v_mfma_f32_32x32x16_bf16 v[0:15], v[188:191], v[196:199], v[0:15]
	ds_read_b128 v[184:187], v161 offset:32768
	ds_read_b128 v[188:191], v161 offset:36864
	ds_read_b128 v[192:195], v163
	ds_read_b128 v[196:199], v163 offset:4096
	s_waitcnt lgkmcnt(4)
	v_mfma_f32_32x32x16_bf16 v[48:63], v[68:71], v[76:79], v[48:63]
	v_mfma_f32_32x32x16_bf16 v[16:31], v[68:71], v[80:83], v[16:31]
	v_mfma_f32_32x32x16_bf16 v[32:47], v[72:75], v[76:79], v[32:47]
	v_mfma_f32_32x32x16_bf16 v[0:15], v[72:75], v[80:83], v[0:15]
	ds_read_b128 v[68:71], v165 offset:32768
	ds_read_b128 v[72:75], v165 offset:36864
	ds_read_b128 v[76:79], v167
	ds_read_b128 v[80:83], v167 offset:4096
	s_waitcnt lgkmcnt(4)
	v_mfma_f32_32x32x16_bf16 v[48:63], v[184:187], v[192:195], v[48:63]
	v_mfma_f32_32x32x16_bf16 v[16:31], v[184:187], v[196:199], v[16:31]
	v_mfma_f32_32x32x16_bf16 v[32:47], v[188:191], v[192:195], v[32:47]
	v_mfma_f32_32x32x16_bf16 v[0:15], v[188:191], v[196:199], v[0:15]
	s_waitcnt vmcnt(6)
	s_waitcnt lgkmcnt(0)
	s_barrier
	ds_read_b128 v[184:187], v145 offset:32768
	ds_read_b128 v[188:191], v145 offset:36864
	ds_read_b128 v[192:195], v146
	ds_read_b128 v[196:199], v146 offset:4096
	s_waitcnt lgkmcnt(4)
	v_mfma_f32_32x32x16_bf16 v[48:63], v[68:71], v[76:79], v[48:63]
	v_mfma_f32_32x32x16_bf16 v[16:31], v[68:71], v[80:83], v[16:31]
	v_lshl_add_u64 v[68:69], v[64:65], 0, s[68:69]
	global_load_lds_dwordx4 v[68:69], off
	v_lshl_add_u64 v[68:69], v[64:65], 0, s[70:71]
	s_mov_b32 m0, s46
	s_nop 0
	global_load_lds_dwordx4 v[68:69], off
	v_lshl_add_u64 v[68:69], v[64:65], 0, s[84:85]
	s_mov_b32 m0, s47
	s_mov_b64 s[46:47], 0x60700
	global_load_lds_dwordx4 v[68:69], off
	v_lshl_add_u64 v[68:69], v[64:65], 0, s[46:47]
	s_mov_b32 m0, s79
	v_mfma_f32_32x32x16_bf16 v[32:47], v[72:75], v[76:79], v[32:47]
	global_load_lds_dwordx4 v[68:69], off
	v_lshl_add_u64 v[68:69], v[66:67], 0, s[68:69]
	s_mov_b32 m0, s77
	s_nop 0
	global_load_lds_dwordx4 v[68:69], off
	v_lshl_add_u64 v[68:69], v[66:67], 0, s[70:71]
	s_mov_b32 m0, s80
	v_mfma_f32_32x32x16_bf16 v[0:15], v[72:75], v[80:83], v[0:15]
	global_load_lds_dwordx4 v[68:69], off
	s_mov_b32 m0, s81
	s_mov_b64 s[46:47], 0x40780
	ds_read_b128 v[68:71], v147 offset:32768
	ds_read_b128 v[72:75], v147 offset:36864
	ds_read_b128 v[76:79], v148
	ds_read_b128 v[80:83], v148 offset:4096
	s_waitcnt lgkmcnt(4)
	v_mfma_f32_32x32x16_bf16 v[48:63], v[184:187], v[192:195], v[48:63]
	v_mfma_f32_32x32x16_bf16 v[16:31], v[184:187], v[196:199], v[16:31]
	v_mfma_f32_32x32x16_bf16 v[32:47], v[188:191], v[192:195], v[32:47]
	v_mfma_f32_32x32x16_bf16 v[0:15], v[188:191], v[196:199], v[0:15]
	ds_read_b128 v[184:187], v149 offset:32768
	ds_read_b128 v[188:191], v149 offset:36864
	ds_read_b128 v[192:195], v150
	ds_read_b128 v[196:199], v150 offset:4096
	s_waitcnt lgkmcnt(4)
	v_mfma_f32_32x32x16_bf16 v[48:63], v[68:71], v[76:79], v[48:63]
	v_mfma_f32_32x32x16_bf16 v[16:31], v[68:71], v[80:83], v[16:31]
	v_mfma_f32_32x32x16_bf16 v[32:47], v[72:75], v[76:79], v[32:47]
	v_mfma_f32_32x32x16_bf16 v[0:15], v[72:75], v[80:83], v[0:15]
	ds_read_b128 v[68:71], v151 offset:32768
	ds_read_b128 v[72:75], v151 offset:36864
	ds_read_b128 v[76:79], v152
	ds_read_b128 v[80:83], v152 offset:4096
	s_waitcnt lgkmcnt(4)
	v_mfma_f32_32x32x16_bf16 v[48:63], v[184:187], v[192:195], v[48:63]
	v_mfma_f32_32x32x16_bf16 v[16:31], v[184:187], v[196:199], v[16:31]
	v_mfma_f32_32x32x16_bf16 v[32:47], v[188:191], v[192:195], v[32:47]
	v_mfma_f32_32x32x16_bf16 v[0:15], v[188:191], v[196:199], v[0:15]
	s_waitcnt vmcnt(6)
	s_waitcnt lgkmcnt(0)
	s_barrier
; #define MFMA(a, b, c) __builtin_amdgcn_mfma_f32_32x32x16_bf16((a), (b), (c), 0, 0, 0)
; #define WAIT_V(n) asm volatile("s_waitcnt vmcnt(%0)" ::"n"(n) : "memory")
; #define RAW_BARRIER() do { asm volatile("s_waitcnt lgkmcnt(0)" ::: "memory"); __builtin_amdgcn_s_barrier(); asm volatile("" ::: "memory"); } while (0)
; #define GLDS_STAGE(slot, kt) do { _Pragma("unroll") for (int i = 0; i < 6; ++i) \
;     __builtin_amdgcn_global_load_lds((const unsigned*)(src[i] + (kt) * 64), (__attribute__((address_space(3))) unsigned*)(smem + (slot) * G_STAGE + (wave + 8 * i) * 1024), 16, 0, 0); } while (0)
; DI void gemm_tile(const u16* __restrict__ X, int ldx, const u16* __restrict__ Wt, int ldw, int K, char* smem,
;                   f32x16 (&acc)[2][2]) {
;     ...
;   for (int kt = 0; kt < nk; ++kt) {
;     const int nxt = (cur >= 1) ? cur - 1 : 2;
;     if (kt + 2 < nk) GLDS_STAGE(nxt, kt + 2);
;     __builtin_amdgcn_sched_barrier(0);
;     const char* st = smem + cur * G_STAGE;
; #pragma unroll
;     for (int ks = 0; ks < 4; ++ks) {
;       bf16x8 a[2], b[2];
; #pragma unroll
;       for (int ft = 0; ft < 2; ++ft) a[ft] = *reinterpret_cast<const bf16x8*>(st + offA[ft] + (((ks * 2 + lh) ^ xa[ft]) << 4));
; #pragma unroll
;       for (int tt = 0; tt < 2; ++tt) b[tt] = *reinterpret_cast<const bf16x8*>(st + offB[tt] + (((ks * 2 + lh) ^ xb[tt]) << 4));
; #pragma unroll
;       for (int ft = 0; ft < 2; ++ft)
; #pragma unroll
;         for (int tt = 0; tt < 2; ++tt) acc[ft][tt] = MFMA(a[ft], b[tt], acc[ft][tt]);
;     }
;     if (kt + 2 < nk) { WAIT_V(6); } else { WAIT_V(0); }
;     RAW_BARRIER();
;     cur = (cur == 2) ? 0 : cur + 1;
	ds_read_b128 v[184:187], v153 offset:32768
	ds_read_b128 v[192:195], v146 offset:49152
	ds_read_b128 v[196:199], v146 offset:53248
	ds_read_b128 v[188:191], v153 offset:36864
	s_waitcnt lgkmcnt(4)
	v_mfma_f32_32x32x16_bf16 v[48:63], v[68:71], v[76:79], v[48:63]
	v_mfma_f32_32x32x16_bf16 v[16:31], v[68:71], v[80:83], v[16:31]
	v_lshl_add_u64 v[68:69], v[64:65], 0, s[72:73]
	global_load_lds_dwordx4 v[68:69], off
	v_lshl_add_u64 v[68:69], v[64:65], 0, s[74:75]
	s_mov_b32 m0, s0
	s_nop 0
	global_load_lds_dwordx4 v[68:69], off
	v_lshl_add_u64 v[68:69], v[64:65], 0, s[46:47]
	s_mov_b32 m0, s4
	s_mov_b64 s[46:47], 0x60780
	global_load_lds_dwordx4 v[68:69], off
	v_lshl_add_u64 v[64:65], v[64:65], 0, s[46:47]
	s_mov_b32 m0, s6
	v_mfma_f32_32x32x16_bf16 v[32:47], v[72:75], v[76:79], v[32:47]
	global_load_lds_dwordx4 v[64:65], off
	v_lshl_add_u64 v[64:65], v[66:67], 0, s[72:73]
	s_mov_b32 m0, s5
	s_nop 0
	global_load_lds_dwordx4 v[64:65], off
	v_lshl_add_u64 v[64:65], v[66:67], 0, s[74:75]
	s_mov_b32 m0, s7
	v_mfma_f32_32x32x16_bf16 v[0:15], v[72:75], v[80:83], v[0:15]
	global_load_lds_dwordx4 v[64:65], off
	ds_read_b128 v[64:67], v154 offset:32768
	ds_read_b128 v[68:71], v148 offset:49152
	ds_read_b128 v[72:75], v148 offset:53248
	ds_read_b128 v[76:79], v154 offset:36864
	s_waitcnt lgkmcnt(4)
	v_mfma_f32_32x32x16_bf16 v[48:63], v[184:187], v[192:195], v[48:63]
	v_mfma_f32_32x32x16_bf16 v[16:31], v[184:187], v[196:199], v[16:31]
	v_mfma_f32_32x32x16_bf16 v[32:47], v[188:191], v[192:195], v[32:47]
	v_mfma_f32_32x32x16_bf16 v[0:15], v[188:191], v[196:199], v[0:15]
	ds_read_b128 v[184:187], v155 offset:32768
	ds_read_b128 v[192:195], v150 offset:49152
	ds_read_b128 v[196:199], v150 offset:53248
	ds_read_b128 v[188:191], v155 offset:36864
	s_waitcnt lgkmcnt(4)
	v_mfma_f32_32x32x16_bf16 v[48:63], v[64:67], v[68:71], v[48:63]
	v_mfma_f32_32x32x16_bf16 v[16:31], v[64:67], v[72:75], v[16:31]
	v_mfma_f32_32x32x16_bf16 v[32:47], v[76:79], v[68:71], v[32:47]
	v_mfma_f32_32x32x16_bf16 v[0:15], v[76:79], v[72:75], v[0:15]
	ds_read_b128 v[64:67], v156 offset:32768
	ds_read_b128 v[68:71], v152 offset:49152
	ds_read_b128 v[72:75], v152 offset:53248
	ds_read_b128 v[76:79], v156 offset:36864
	s_waitcnt lgkmcnt(4)
	v_mfma_f32_32x32x16_bf16 v[48:63], v[184:187], v[192:195], v[48:63]
	v_mfma_f32_32x32x16_bf16 v[16:31], v[184:187], v[196:199], v[16:31]
	v_mfma_f32_32x32x16_bf16 v[32:47], v[188:191], v[192:195], v[32:47]
	v_mfma_f32_32x32x16_bf16 v[0:15], v[188:191], v[196:199], v[0:15]
	s_waitcnt vmcnt(6)
	s_waitcnt lgkmcnt(0)
	s_barrier
	ds_read_b128 v[184:187], v157 offset:32768
	ds_read_b128 v[192:195], v158
	ds_read_b128 v[196:199], v158 offset:4096
	ds_read_b128 v[188:191], v157 offset:36864
	s_waitcnt lgkmcnt(4)
	v_mfma_f32_32x32x16_bf16 v[48:63], v[64:67], v[68:71], v[48:63]
	v_mfma_f32_32x32x16_bf16 v[16:31], v[64:67], v[72:75], v[16:31]
	v_mfma_f32_32x32x16_bf16 v[32:47], v[76:79], v[68:71], v[32:47]
	v_mfma_f32_32x32x16_bf16 v[0:15], v[76:79], v[72:75], v[0:15]
	ds_read_b128 v[64:67], v159 offset:32768
	ds_read_b128 v[68:71], v160
	ds_read_b128 v[72:75], v160 offset:4096
	ds_read_b128 v[76:79], v159 offset:36864
	s_waitcnt lgkmcnt(4)
	v_mfma_f32_32x32x16_bf16 v[48:63], v[184:187], v[192:195], v[48:63]
	v_mfma_f32_32x32x16_bf16 v[16:31], v[184:187], v[196:199], v[16:31]
	v_mfma_f32_32x32x16_bf16 v[32:47], v[188:191], v[192:195], v[32:47]
	v_mfma_f32_32x32x16_bf16 v[0:15], v[188:191], v[196:199], v[0:15]
	ds_read_b128 v[184:187], v161 offset:32768
	ds_read_b128 v[192:195], v163
	ds_read_b128 v[196:199], v163 offset:4096
	ds_read_b128 v[188:191], v161 offset:36864
	s_waitcnt lgkmcnt(4)
	v_mfma_f32_32x32x16_bf16 v[48:63], v[64:67], v[68:71], v[48:63]
	v_mfma_f32_32x32x16_bf16 v[16:31], v[64:67], v[72:75], v[16:31]
	v_mfma_f32_32x32x16_bf16 v[32:47], v[76:79], v[68:71], v[32:47]
	v_mfma_f32_32x32x16_bf16 v[0:15], v[76:79], v[72:75], v[0:15]
	s_waitcnt lgkmcnt(0)
	v_mfma_f32_32x32x16_bf16 v[48:63], v[184:187], v[192:195], v[48:63]
	v_mfma_f32_32x32x16_bf16 v[16:31], v[184:187], v[196:199], v[16:31]
	v_mfma_f32_32x32x16_bf16 v[32:47], v[188:191], v[192:195], v[32:47]
	v_mfma_f32_32x32x16_bf16 v[0:15], v[188:191], v[196:199], v[0:15]
	ds_read_b128 v[64:67], v165 offset:32768
	ds_read_b128 v[68:71], v167
	ds_read_b128 v[72:75], v167 offset:4096
	ds_read_b128 v[76:79], v165 offset:36864
	s_waitcnt vmcnt(0)
	s_waitcnt lgkmcnt(0)
	s_barrier
; #define MFMA(a, b, c) __builtin_amdgcn_mfma_f32_32x32x16_bf16((a), (b), (c), 0, 0, 0)
; #define WAIT_V(n) asm volatile("s_waitcnt vmcnt(%0)" ::"n"(n) : "memory")
; DI void gemm_tile(const u16* __restrict__ X, int ldx, const u16* __restrict__ Wt, int ldw, int K, char* smem,
;                   f32x16 (&acc)[2][2]) {
;     ...
;   for (int kt = 0; kt < nk; ++kt) {
;     const int nxt = (cur >= 1) ? cur - 1 : 2;
;     if (kt + 2 < nk) GLDS_STAGE(nxt, kt + 2);
;     __builtin_amdgcn_sched_barrier(0);
;     const char* st = smem + cur * G_STAGE;
; #pragma unroll
;     for (int ks = 0; ks < 4; ++ks) {
;       bf16x8 a[2], b[2];
; #pragma unroll
;       for (int ft = 0; ft < 2; ++ft) a[ft] = *reinterpret_cast<const bf16x8*>(st + offA[ft] + (((ks * 2 + lh) ^ xa[ft]) << 4));
; #pragma unroll
;       for (int tt = 0; tt < 2; ++tt) b[tt] = *reinterpret_cast<const bf16x8*>(st + offB[tt] + (((ks * 2 + lh) ^ xb[tt]) << 4));
; #pragma unroll
;       for (int ft = 0; ft < 2; ++ft)
; #pragma unroll
;         for (int tt = 0; tt < 2; ++tt) acc[ft][tt] = MFMA(a[ft], b[tt], acc[ft][tt]);
;     }
;     if (kt + 2 < nk) { WAIT_V(6); } else { WAIT_V(0); }
;     RAW_BARRIER();
;     cur = (cur == 2) ? 0 : cur + 1;
; template <int MODE>
; DI void phase_gemm(const Params& p, const u16* X, const u16* Wt, int N, const float* resid, float* outf, u16* outb, int ldo, char* smem) {
;     ...
; #pragma unroll
;       for (int tt = 0; tt < 2; ++tt) {
;         const int tok = mt * 256 + tq * 64 + tt * 32 + lr;
; #pragma unroll
;         for (int ft = 0; ft < 2; ++ft)
; #pragma unroll
;           for (int g = 0; g < 4; ++g) {
;             const int f = nt * 128 + fw * 64 + ft * 32 + 8 * g + 4 * lh;
;             if (MODE == 2) {
;               const int hh = f >> 8, fh = f & 255, ks = fh >> 4, lane2 = ((fh >> 3) & 1) * 32 + lr;
;               st4bf(outb + ((((size_t)(tok >> 5) * 4 + hh) * 16 + ks) * 64 + lane2) * 8 + 4 * lh, acc[ft][tt][4 * g], acc[ft][tt][4 * g + 1], acc[ft][tt][4 * g + 2], acc[ft][tt][4 * g + 3]);
;             } else {
;               const int hh = f >> 8, fq = f & 127, half = (f >> 7) & 1, ks = fq >> 4, lane2 = ((fq >> 3) & 1) * 32 + lr;
;               st4bf(outb + (((((size_t)(tok >> 5) * 8 + hh) * 2 + half) * 8 + ks) * 64 + lane2) * 8 + 4 * lh, acc[ft][tt][4 * g], acc[ft][tt][4 * g + 1], acc[ft][tt][4 * g + 2], acc[ft][tt][4 * g + 3]);
;             }
;           }
;       }
	s_waitcnt lgkmcnt(0)
	v_mfma_f32_32x32x16_bf16 v[48:63], v[64:67], v[68:71], v[48:63]
	v_mfma_f32_32x32x16_bf16 v[16:31], v[64:67], v[72:75], v[16:31]
	v_mfma_f32_32x32x16_bf16 v[32:47], v[76:79], v[68:71], v[32:47]
	v_mfma_f32_32x32x16_bf16 v[0:15], v[76:79], v[72:75], v[0:15]
	ds_read_b128 v[64:67], v145 offset:32768
	ds_read_b128 v[68:71], v146
	ds_read_b128 v[72:75], v145 offset:36864
	ds_read_b128 v[76:79], v146 offset:4096
	v_lshl_add_u32 v104, s76, 8, v111
	s_add_i32 s54, s54, s55
	s_waitcnt lgkmcnt(0)
	v_mfma_f32_32x32x16_bf16 v[48:63], v[64:67], v[68:71], v[48:63]
	v_mfma_f32_32x32x16_bf16 v[16:31], v[64:67], v[76:79], v[16:31]
	v_mfma_f32_32x32x16_bf16 v[32:47], v[72:75], v[68:71], v[32:47]
	ds_read_b128 v[64:67], v147 offset:32768
	ds_read_b128 v[68:71], v148
	ds_read_b128 v[96:99], v147 offset:36864
	ds_read_b128 v[100:103], v148 offset:4096
	v_mfma_f32_32x32x16_bf16 v[0:15], v[72:75], v[76:79], v[0:15]
	ds_read_b128 v[92:95], v149 offset:32768
	ds_read_b128 v[72:75], v149 offset:36864
	ds_read_b128 v[88:91], v150
	ds_read_b128 v[80:83], v150 offset:4096
	s_waitcnt lgkmcnt(0)
	v_mfma_f32_32x32x16_bf16 v[48:63], v[64:67], v[68:71], v[48:63]
	v_mfma_f32_32x32x16_bf16 v[16:31], v[64:67], v[100:103], v[16:31]
	v_mfma_f32_32x32x16_bf16 v[32:47], v[96:99], v[68:71], v[32:47]
	ds_read_b128 v[84:87], v151 offset:32768
	ds_read_b128 v[64:67], v151 offset:36864
	ds_read_b128 v[76:79], v152
	ds_read_b128 v[68:71], v152 offset:4096
	s_waitcnt vmcnt(0)
	s_waitcnt lgkmcnt(0)
	s_barrier
	v_mfma_f32_32x32x16_bf16 v[0:15], v[96:99], v[100:103], v[0:15]
	v_lshrrev_b32_e32 v96, 1, v104
	v_and_or_b32 v169, s3, 15, v96
	v_lshlrev_b32_e32 v96, 9, v169
	v_or_b32_e32 v98, v110, v96
	v_or_b32_e32 v104, v98, v168
	v_or_b32_e32 v99, v118, v96
	v_or_b32_e32 v100, v114, v96
	v_mfma_f32_32x32x16_bf16 v[48:63], v[92:95], v[88:91], v[48:63]
	v_or_b32_e32 v102, v120, v96
	v_lshl_add_u64 v[96:97], v[104:105], 4, v[112:113]
	v_or_b32_e32 v104, v98, v116
	s_add_i32 s3, s3, s94
	s_cmpk_lt_u32 s3, 0x100
	v_mfma_f32_32x32x16_bf16 v[16:31], v[92:95], v[80:83], v[16:31]
	v_lshl_add_u64 v[92:93], v[104:105], 4, v[112:113]
	v_or_b32_e32 v104, v99, v168
	v_lshl_add_u64 v[94:95], v[104:105], 4, v[112:113]
	v_or_b32_e32 v104, v99, v116
	v_lshl_add_u64 v[98:99], v[104:105], 4, v[112:113]
	v_or_b32_e32 v104, v100, v168
	v_mfma_f32_32x32x16_bf16 v[32:47], v[72:75], v[88:91], v[32:47]
	v_lshl_add_u64 v[88:89], v[104:105], 4, v[112:113]
	v_or_b32_e32 v104, v100, v116
	v_lshl_add_u64 v[90:91], v[104:105], 4, v[112:113]
	v_or_b32_e32 v104, v102, v168
	v_lshl_add_u64 v[100:101], v[104:105], 4, v[112:113]
	v_or_b32_e32 v104, v102, v116
	v_lshl_add_u64 v[102:103], v[104:105], 4, v[112:113]
	v_mfma_f32_32x32x16_bf16 v[0:15], v[72:75], v[80:83], v[0:15]
	v_or_b32_e32 v104, 16, v169
	v_lshlrev_b64 v[72:73], 9, v[104:105]
	v_or_b32_e32 v171, v72, v120
	v_or_b32_e32 v80, v72, v110
	v_or_b32_e32 v104, v72, v118
	v_or_b32_e32 v169, v72, v114
	v_or_b32_e32 v72, v171, v168
	s_waitcnt lgkmcnt(0)
	v_mfma_f32_32x32x16_bf16 v[48:63], v[84:87], v[76:79], v[48:63]
	v_mov_b32_e32 v75, v73
	v_mov_b32_e32 v81, v73
	v_mov_b32_e32 v83, v73
	v_mov_b32_e32 v173, v73
	v_mov_b32_e32 v175, v73
	v_mov_b32_e32 v181, v73
	v_or_b32_e32 v74, v80, v168
	v_mfma_f32_32x32x16_bf16 v[16:31], v[84:87], v[68:71], v[16:31]
	v_or_b32_e32 v80, v80, v116
	v_or_b32_e32 v82, v104, v168
	v_or_b32_e32 v172, v104, v116
	v_or_b32_e32 v174, v169, v168
	v_or_b32_e32 v180, v169, v116
	v_lshl_add_u64 v[86:87], v[72:73], 4, v[112:113]
	v_or_b32_e32 v72, v171, v116
	v_mfma_f32_32x32x16_bf16 v[32:47], v[64:67], v[76:79], v[32:47]
	v_cvt_pk_bf16_f32 v48, v48, v49
	v_cvt_pk_bf16_f32 v49, v50, v51
	v_lshl_add_u64 v[74:75], v[74:75], 4, v[112:113]
	v_lshl_add_u64 v[80:81], v[80:81], 4, v[112:113]
	v_lshl_add_u64 v[76:77], v[82:83], 4, v[112:113]
	v_lshl_add_u64 v[78:79], v[172:173], 4, v[112:113]
	v_lshl_add_u64 v[82:83], v[174:175], 4, v[112:113]
	v_mfma_f32_32x32x16_bf16 v[0:15], v[64:67], v[68:71], v[0:15]
	v_lshl_add_u64 v[84:85], v[180:181], 4, v[112:113]
	v_lshl_add_u64 v[72:73], v[72:73], 4, v[112:113]
	v_cvt_pk_bf16_f32 v50, v52, v53
	v_cvt_pk_bf16_f32 v51, v54, v55
	v_cvt_pk_bf16_f32 v52, v56, v57
	v_cvt_pk_bf16_f32 v53, v58, v59
	v_cvt_pk_bf16_f32 v54, v60, v61
	v_cvt_pk_bf16_f32 v55, v62, v63
	v_cvt_pk_bf16_f32 v32, v32, v33
	v_cvt_pk_bf16_f32 v33, v34, v35
	v_cvt_pk_bf16_f32 v34, v36, v37
	v_cvt_pk_bf16_f32 v35, v38, v39
	v_cvt_pk_bf16_f32 v36, v40, v41
	v_cvt_pk_bf16_f32 v37, v42, v43
	v_cvt_pk_bf16_f32 v38, v44, v45
	v_cvt_pk_bf16_f32 v39, v46, v47
	v_cvt_pk_bf16_f32 v16, v16, v17
	v_cvt_pk_bf16_f32 v17, v18, v19
	v_cvt_pk_bf16_f32 v18, v20, v21
	v_cvt_pk_bf16_f32 v19, v22, v23
	v_cvt_pk_bf16_f32 v20, v24, v25
	v_cvt_pk_bf16_f32 v21, v26, v27
	v_cvt_pk_bf16_f32 v22, v28, v29
	v_cvt_pk_bf16_f32 v23, v30, v31
	v_cvt_pk_bf16_f32 v0, v0, v1
	v_cvt_pk_bf16_f32 v1, v2, v3
	v_cvt_pk_bf16_f32 v2, v4, v5
	v_cvt_pk_bf16_f32 v3, v6, v7
	v_cvt_pk_bf16_f32 v4, v8, v9
	v_cvt_pk_bf16_f32 v5, v10, v11
	v_cvt_pk_bf16_f32 v6, v12, v13
	v_cvt_pk_bf16_f32 v7, v14, v15
	global_store_dwordx2 v[96:97], v[48:49], off
	global_store_dwordx2 v[92:93], v[50:51], off
	global_store_dwordx2 v[94:95], v[52:53], off
	global_store_dwordx2 v[98:99], v[54:55], off
	global_store_dwordx2 v[88:89], v[32:33], off
	global_store_dwordx2 v[90:91], v[34:35], off
	global_store_dwordx2 v[100:101], v[36:37], off
	global_store_dwordx2 v[102:103], v[38:39], off
	global_store_dwordx2 v[74:75], v[16:17], off
	global_store_dwordx2 v[80:81], v[18:19], off
	global_store_dwordx2 v[76:77], v[20:21], off
	global_store_dwordx2 v[78:79], v[22:23], off
	global_store_dwordx2 v[82:83], v[0:1], off
	global_store_dwordx2 v[84:85], v[2:3], off
	global_store_dwordx2 v[86:87], v[4:5], off
	global_store_dwordx2 v[72:73], v[6:7], off
	s_cbranch_scc1 .LBB0_906
	v_readlane_b32 s60, v255, 43
	v_readlane_b32 s61, v255, 44
